# also xor-16/32 butterfly hops via v_permlane16/32_swap (65 more ds_bpermute removed)
# speedup vs baseline: 1.0120x; 1.0010x over previous
; __device__ __forceinline__ float bflo(unsigned w) { return __uint_as_float(w << 16); }
; __device__ __forceinline__ float bfhi(unsigned w) { return __uint_as_float(w & 0xffff0000u); }
; #pragma unroll
;     for (int j = 0; j < 8; ++j) mx = fmaxf(mx, fmaxf(fmaxf(fmaxf(fabsf(bflo(w[j].x)), fabsf(bfhi(w[j].x))), fmaxf(fabsf(bflo(w[j].y)), fabsf(bfhi(w[j].y)))), fmaxf(fmaxf(fabsf(bflo(w[j].z)), fabsf(bfhi(w[j].z))), fmaxf(fabsf(bflo(w[j].w)), fabsf(bfhi(w[j].w))))));
; #pragma unroll
;     for (int o = 1; o < 64; o <<= 1) mx = fmaxf(mx, __shfl_xor(mx, o));
;     return mx; }
; __device__ __forceinline__ void quant_store8(const u32x4 (&w)[8], float inv, signed char* dst, int lane) { u32x2* qp = (u32x2*)dst + lane;
; #pragma unroll
;     for (int j = 0; j < 8; ++j) { const unsigned ww[4] = {w[j].x, w[j].y, w[j].z, w[j].w}; unsigned o2[2];
; #pragma unroll
;         for (int h2 = 0; h2 < 2; ++h2) { const int q0 = (int)rintf(bflo(ww[2 * h2]) * inv), q1 = (int)rintf(bfhi(ww[2 * h2]) * inv), q2 = (int)rintf(bflo(ww[2 * h2 + 1]) * inv), q3 = (int)rintf(bfhi(ww[2 * h2 + 1]) * inv);
;             o2[h2] = (unsigned)(q0 & 255) | ((unsigned)(q1 & 255) << 8) | ((unsigned)(q2 & 255) << 16) | ((unsigned)(q3 & 255) << 24); }
;         u32x2 o; o.x = o2[0]; o.y = o2[1]; qp[64 * j] = o; } }
; __device__ __forceinline__ void quant_rows2(const bf16_t* s0, const bf16_t* s1, signed char* d0, signed char* d1, int lane, float& step0, float& step1) {
;     const u32x4* p0 = (const u32x4*)s0 + lane; const u32x4* p1 = (const u32x4*)s1 + lane; u32x4 w0[8], w1[8];
; #pragma unroll
;     for (int j = 0; j < 8; ++j) { w0[j] = p0[64 * j]; w1[j] = p1[64 * j]; }
;     step0 = fmaxf(absmax8(w0), 1e-30f) * (1.0f / 127.0f); step1 = fmaxf(absmax8(w1), 1e-30f) * (1.0f / 127.0f);
.LBB0_64:
	v_lshl_add_u64 v[2:3], s[78:79], 0, v[30:31]
	v_add_co_u32_e32 v4, vcc, 0x800000, v2
	s_nop 1
	v_addc_co_u32_e32 v5, vcc, 0, v3, vcc
	global_load_dwordx4 v[42:45], v[4:5], off
	global_load_dwordx4 v[46:49], v[4:5], off offset:1024
	global_load_dwordx4 v[50:53], v[4:5], off offset:2048
	global_load_dwordx4 v[54:57], v[4:5], off offset:3072
	v_add_co_u32_e32 v6, vcc, 0x802000, v2
	s_waitcnt vmcnt(3)
	v_lshlrev_b32_e32 v83, 16, v42
	v_addc_co_u32_e32 v7, vcc, 0, v3, vcc
	v_add_co_u32_e32 v78, vcc, s17, v2
	global_load_dwordx4 v[58:61], v[6:7], off
	global_load_dwordx4 v[26:29], v[6:7], off offset:1024
	global_load_dwordx4 v[22:25], v[6:7], off offset:2048
	global_load_dwordx4 v[18:21], v[6:7], off offset:3072
	v_addc_co_u32_e32 v79, vcc, 0, v3, vcc
	v_add_co_u32_e32 v80, vcc, s18, v2
	v_and_b32_e32 v84, 0xffff0000, v42
	s_nop 0
	v_addc_co_u32_e32 v81, vcc, 0, v3, vcc
	global_load_dwordx4 v[62:65], v[78:79], off
	global_load_dwordx4 v[66:69], v[78:79], off offset:1024
	global_load_dwordx4 v[70:73], v[78:79], off offset:2048
	global_load_dwordx4 v[74:77], v[78:79], off offset:3072
	global_load_dwordx4 v[14:17], v[80:81], off
	global_load_dwordx4 v[10:13], v[80:81], off offset:1024
	global_load_dwordx4 v[6:9], v[80:81], off offset:2048
	global_load_dwordx4 v[2:5], v[80:81], off offset:3072
	v_lshlrev_b32_e32 v85, 16, v43
	v_and_b32_e32 v86, 0xffff0000, v43
	v_lshlrev_b32_e32 v89, 16, v45
	v_and_b32_e32 v90, 0xffff0000, v45
	s_waitcnt vmcnt(14)
	v_lshlrev_b32_e32 v97, 16, v49
	v_and_b32_e32 v98, 0xffff0000, v49
	v_lshlrev_b32_e32 v87, 16, v44
	v_and_b32_e32 v88, 0xffff0000, v44
	v_lshlrev_b32_e32 v91, 16, v46
	v_and_b32_e32 v92, 0xffff0000, v46
	v_lshlrev_b32_e32 v93, 16, v47
	v_and_b32_e32 v94, 0xffff0000, v47
	s_waitcnt vmcnt(13)
	v_lshlrev_b32_e32 v101, 16, v51
	v_and_b32_e32 v102, 0xffff0000, v51
	v_lshlrev_b32_e32 v103, 16, v52
	v_and_b32_e32 v104, 0xffff0000, v52
	v_max_f32_e64 v41, |v84|, |v84|
	v_max_f32_e64 v42, |v83|, |v83|
	v_max_f32_e64 v43, |v86|, |v86|
	v_max_f32_e64 v44, |v85|, |v85|
	v_max_f32_e64 v45, |v90|, |v90|
	v_max_f32_e64 v46, |v89|, |v89|
	v_max_f32_e64 v51, |v98|, |v98|
	v_max_f32_e64 v52, |v97|, |v97|
	v_lshlrev_b32_e32 v95, 16, v48
	v_and_b32_e32 v96, 0xffff0000, v48
	v_lshlrev_b32_e32 v99, 16, v50
	v_and_b32_e32 v100, 0xffff0000, v50
	v_max_f32_e64 v47, |v92|, |v92|
	v_max_f32_e64 v48, |v91|, |v91|
	v_max_f32_e64 v49, |v94|, |v94|
	v_max_f32_e64 v50, |v93|, |v93|
	v_max_f32_e32 v41, v42, v41
	v_max_f32_e32 v42, v44, v43
	v_max_f32_e32 v43, v46, v45
	v_max_f32_e32 v46, v52, v51
	v_max_f32_e32 v44, v48, v47
	v_max_f32_e32 v45, v50, v49
	v_max3_f32 v43, |v87|, |v88|, v43
	v_max3_f32 v46, |v95|, |v96|, v46
	v_lshlrev_b32_e32 v105, 16, v53
	v_max3_f32 v41, v41, v42, v43
	v_max3_f32 v42, v44, v45, v46
	v_and_b32_e32 v106, 0xffff0000, v53
	v_max3_f32 v41, v41, 0, v42
	v_max_f32_e64 v42, |v106|, |v106|
	v_max_f32_e64 v43, |v105|, |v105|
	s_waitcnt vmcnt(12)
	v_lshlrev_b32_e32 v107, 16, v54
	v_and_b32_e32 v108, 0xffff0000, v54
	v_max_f32_e32 v42, v43, v42
	v_max_f32_e64 v43, |v108|, |v108|
	v_max_f32_e64 v44, |v107|, |v107|
	v_lshlrev_b32_e32 v109, 16, v55
	v_and_b32_e32 v110, 0xffff0000, v55
	v_max_f32_e32 v43, v44, v43
	v_max_f32_e64 v44, |v110|, |v110|
	v_max_f32_e64 v45, |v109|, |v109|
	v_lshlrev_b32_e32 v113, 16, v57
	v_and_b32_e32 v114, 0xffff0000, v57
	v_max_f32_e32 v44, v45, v44
	v_max_f32_e64 v45, |v114|, |v114|
	v_max_f32_e64 v46, |v113|, |v113|
	v_max_f32_e64 v78, |v100|, |v100|
	v_max_f32_e64 v79, |v99|, |v99|
	v_max_f32_e64 v80, |v102|, |v102|
	v_max_f32_e64 v81, |v101|, |v101|
	v_lshlrev_b32_e32 v111, 16, v56
	v_and_b32_e32 v112, 0xffff0000, v56
	v_max_f32_e32 v45, v46, v45
	v_max_f32_e32 v47, v79, v78
	v_max_f32_e32 v48, v81, v80
	v_max3_f32 v42, |v103|, |v104|, v42
	v_max3_f32 v45, |v111|, |v112|, v45
	v_max3_f32 v42, v47, v48, v42
	v_max3_f32 v43, v43, v44, v45
	s_waitcnt vmcnt(7)
	v_lshlrev_b32_e32 v115, 16, v62
	v_and_b32_e32 v116, 0xffff0000, v62
	v_max3_f32 v41, v41, v42, v43
	v_max_f32_e64 v42, |v116|, |v116|
	v_max_f32_e64 v43, |v115|, |v115|
	v_lshlrev_b32_e32 v117, 16, v63
	v_and_b32_e32 v118, 0xffff0000, v63
	v_max_f32_e32 v42, v43, v42
	v_max_f32_e64 v43, |v118|, |v118|
	v_max_f32_e64 v44, |v117|, |v117|
	v_lshlrev_b32_e32 v121, 16, v65
	v_and_b32_e32 v122, 0xffff0000, v65
	v_max_f32_e32 v43, v44, v43
	v_max_f32_e64 v44, |v122|, |v122|
	v_max_f32_e64 v45, |v121|, |v121|
	v_lshlrev_b32_e32 v119, 16, v64
	v_and_b32_e32 v120, 0xffff0000, v64
	v_max_f32_e32 v44, v45, v44
	v_max3_f32 v44, |v119|, |v120|, v44
	s_waitcnt vmcnt(6)
	v_lshlrev_b32_e32 v123, 16, v66
	v_and_b32_e32 v124, 0xffff0000, v66
	v_max3_f32 v42, v42, v43, v44
	v_max_f32_e64 v43, |v124|, |v124|
	v_max_f32_e64 v44, |v123|, |v123|
	v_lshlrev_b32_e32 v125, 16, v67
	v_and_b32_e32 v126, 0xffff0000, v67
	v_max_f32_e32 v43, v44, v43
	v_max_f32_e64 v44, |v126|, |v126|
	v_max_f32_e64 v45, |v125|, |v125|
	v_lshlrev_b32_e32 v129, 16, v69
	v_and_b32_e32 v130, 0xffff0000, v69
	v_max_f32_e32 v44, v45, v44
	v_max_f32_e64 v45, |v130|, |v130|
	v_max_f32_e64 v46, |v129|, |v129|
	v_lshlrev_b32_e32 v127, 16, v68
	v_and_b32_e32 v128, 0xffff0000, v68
	v_max_f32_e32 v45, v46, v45
	v_max3_f32 v45, |v127|, |v128|, v45
	v_max3_f32 v43, v43, v44, v45
	s_waitcnt vmcnt(5)
	v_lshlrev_b32_e32 v131, 16, v70
	v_and_b32_e32 v132, 0xffff0000, v70
	v_max3_f32 v41, v41, v42, v43
	v_max_f32_e64 v42, |v132|, |v132|
	v_max_f32_e64 v43, |v131|, |v131|
	v_lshlrev_b32_e32 v133, 16, v71
	v_and_b32_e32 v134, 0xffff0000, v71
	v_max_f32_e32 v42, v43, v42
	v_max_f32_e64 v43, |v134|, |v134|
	v_max_f32_e64 v44, |v133|, |v133|
	v_lshlrev_b32_e32 v137, 16, v73
	v_and_b32_e32 v138, 0xffff0000, v73
	v_max_f32_e32 v43, v44, v43
	v_max_f32_e64 v44, |v138|, |v138|
	v_max_f32_e64 v45, |v137|, |v137|
	v_lshlrev_b32_e32 v135, 16, v72
	v_and_b32_e32 v136, 0xffff0000, v72
	v_max_f32_e32 v44, v45, v44
	v_max3_f32 v44, |v135|, |v136|, v44
	s_waitcnt vmcnt(4)
; __device__ __forceinline__ float bflo(unsigned w) { return __uint_as_float(w << 16); }
; __device__ __forceinline__ float bfhi(unsigned w) { return __uint_as_float(w & 0xffff0000u); }
; #pragma unroll
;     for (int j = 0; j < 8; ++j) mx = fmaxf(mx, fmaxf(fmaxf(fmaxf(fabsf(bflo(w[j].x)), fabsf(bfhi(w[j].x))), fmaxf(fabsf(bflo(w[j].y)), fabsf(bfhi(w[j].y)))), fmaxf(fmaxf(fabsf(bflo(w[j].z)), fabsf(bfhi(w[j].z))), fmaxf(fabsf(bflo(w[j].w)), fabsf(bfhi(w[j].w))))));
; #pragma unroll
;     for (int o = 1; o < 64; o <<= 1) mx = fmaxf(mx, __shfl_xor(mx, o));
;     return mx; }
	v_lshlrev_b32_e32 v139, 16, v74
	v_and_b32_e32 v140, 0xffff0000, v74
	v_max3_f32 v42, v42, v43, v44
	v_max_f32_e64 v43, |v140|, |v140|
	v_max_f32_e64 v44, |v139|, |v139|
	v_lshlrev_b32_e32 v141, 16, v75
	v_and_b32_e32 v142, 0xffff0000, v75
	v_max_f32_e32 v43, v44, v43
	v_max_f32_e64 v44, |v142|, |v142|
	v_max_f32_e64 v45, |v141|, |v141|
	v_lshlrev_b32_e32 v145, 16, v77
	v_and_b32_e32 v146, 0xffff0000, v77
	v_max_f32_e32 v44, v45, v44
	v_max_f32_e64 v45, |v146|, |v146|
	v_max_f32_e64 v46, |v145|, |v145|
	v_lshlrev_b32_e32 v143, 16, v76
	v_and_b32_e32 v144, 0xffff0000, v76
	v_max_f32_e32 v45, v46, v45
	v_max3_f32 v45, |v143|, |v144|, v45
	v_max3_f32 v43, v43, v44, v45
	v_lshlrev_b32_e32 v82, 16, v58
	v_and_b32_e32 v80, 0xffff0000, v58
	v_max3_f32 v147, v41, v42, v43
	v_max_f32_e64 v41, |v80|, |v80|
	v_max_f32_e64 v42, |v82|, |v82|
	v_lshlrev_b32_e32 v81, 16, v59
	v_and_b32_e32 v79, 0xffff0000, v59
	v_max_f32_e32 v41, v42, v41
	v_max_f32_e64 v42, |v79|, |v79|
	v_max_f32_e64 v43, |v81|, |v81|
	v_lshlrev_b32_e32 v76, 16, v61
	v_and_b32_e32 v75, 0xffff0000, v61
	v_max_f32_e32 v42, v43, v42
	v_max_f32_e64 v43, |v75|, |v75|
	v_max_f32_e64 v44, |v76|, |v76|
	v_lshlrev_b32_e32 v78, 16, v60
	v_and_b32_e32 v77, 0xffff0000, v60
	v_max_f32_e32 v43, v44, v43
	v_max3_f32 v43, |v78|, |v77|, v43
	v_lshlrev_b32_e32 v74, 16, v26
	v_and_b32_e32 v72, 0xffff0000, v26
	v_lshlrev_b32_e32 v68, 16, v29
	v_and_b32_e32 v67, 0xffff0000, v29
	v_max3_f32 v41, v41, v42, v43
	v_max_f32_e64 v26, |v72|, |v72|
	v_max_f32_e64 v42, |v74|, |v74|
	v_lshlrev_b32_e32 v73, 16, v27
	v_and_b32_e32 v71, 0xffff0000, v27
	v_lshlrev_b32_e32 v70, 16, v28
	v_and_b32_e32 v69, 0xffff0000, v28
	v_max_f32_e64 v28, |v67|, |v67|
	v_max_f32_e64 v29, |v68|, |v68|
	v_max_f32_e32 v26, v42, v26
	v_max_f32_e64 v27, |v71|, |v71|
	v_max_f32_e64 v42, |v73|, |v73|
	v_max_f32_e32 v28, v29, v28
	v_max_f32_e32 v27, v42, v27
	v_max3_f32 v28, |v70|, |v69|, v28
	v_lshlrev_b32_e32 v66, 16, v22
	v_and_b32_e32 v64, 0xffff0000, v22
	v_lshlrev_b32_e32 v60, 16, v25
	v_and_b32_e32 v59, 0xffff0000, v25
	v_max3_f32 v26, v26, v27, v28
	v_max_f32_e64 v22, |v64|, |v64|
	v_max_f32_e64 v27, |v66|, |v66|
	v_lshlrev_b32_e32 v65, 16, v23
	v_and_b32_e32 v63, 0xffff0000, v23
	v_lshlrev_b32_e32 v62, 16, v24
	v_and_b32_e32 v61, 0xffff0000, v24
	v_max_f32_e64 v24, |v59|, |v59|
	v_max_f32_e64 v25, |v60|, |v60|
	v_max_f32_e32 v22, v27, v22
	v_max_f32_e64 v23, |v63|, |v63|
	v_max_f32_e64 v27, |v65|, |v65|
	v_max_f32_e32 v24, v25, v24
	v_max_f32_e32 v23, v27, v23
	v_max3_f32 v24, |v62|, |v61|, v24
	v_lshlrev_b32_e32 v58, 16, v18
	v_and_b32_e32 v56, 0xffff0000, v18
	v_lshlrev_b32_e32 v52, 16, v21
	v_and_b32_e32 v51, 0xffff0000, v21
	v_max3_f32 v22, v22, v23, v24
	v_max_f32_e64 v18, |v56|, |v56|
	v_max_f32_e64 v23, |v58|, |v58|
	v_lshlrev_b32_e32 v57, 16, v19
	v_and_b32_e32 v55, 0xffff0000, v19
	v_lshlrev_b32_e32 v54, 16, v20
	v_and_b32_e32 v53, 0xffff0000, v20
	v_max_f32_e64 v20, |v51|, |v51|
	v_max_f32_e64 v21, |v52|, |v52|
	v_max_f32_e32 v18, v23, v18
	v_max_f32_e64 v19, |v55|, |v55|
	v_max_f32_e64 v23, |v57|, |v57|
	v_max_f32_e32 v20, v21, v20
	v_max_f32_e32 v19, v23, v19
	v_max3_f32 v20, |v54|, |v53|, v20
	s_waitcnt vmcnt(3)
	v_lshlrev_b32_e32 v50, 16, v14
	v_and_b32_e32 v48, 0xffff0000, v14
	v_lshlrev_b32_e32 v44, 16, v17
	v_and_b32_e32 v43, 0xffff0000, v17
	v_max3_f32 v18, v18, v19, v20
	v_max_f32_e64 v14, |v48|, |v48|
	v_max_f32_e64 v19, |v50|, |v50|
	v_lshlrev_b32_e32 v49, 16, v15
	v_and_b32_e32 v47, 0xffff0000, v15
	v_lshlrev_b32_e32 v46, 16, v16
	v_and_b32_e32 v45, 0xffff0000, v16
	v_max_f32_e64 v16, |v43|, |v43|
	v_max_f32_e64 v17, |v44|, |v44|
	v_max_f32_e32 v14, v19, v14
	v_max_f32_e64 v15, |v47|, |v47|
	v_max_f32_e64 v19, |v49|, |v49|
	v_max_f32_e32 v16, v17, v16
	v_max3_f32 v26, v41, 0, v26
	v_max_f32_e32 v15, v19, v15
	v_max3_f32 v16, |v46|, |v45|, v16
	s_waitcnt vmcnt(2)
	v_lshlrev_b32_e32 v42, 16, v10
	v_and_b32_e32 v29, 0xffff0000, v10
	v_lshlrev_b32_e32 v25, 16, v13
	v_and_b32_e32 v24, 0xffff0000, v13
	v_max3_f32 v18, v26, v22, v18
	v_max3_f32 v14, v14, v15, v16
	v_max_f32_e64 v10, |v29|, |v29|
	v_max_f32_e64 v15, |v42|, |v42|
	v_lshlrev_b32_e32 v41, 16, v11
	v_and_b32_e32 v28, 0xffff0000, v11
	v_lshlrev_b32_e32 v27, 16, v12
	v_and_b32_e32 v26, 0xffff0000, v12
	v_max_f32_e64 v12, |v24|, |v24|
	v_max_f32_e64 v13, |v25|, |v25|
	v_max_f32_e32 v10, v15, v10
	v_max_f32_e64 v11, |v28|, |v28|
	v_max_f32_e64 v15, |v41|, |v41|
	v_max_f32_e32 v12, v13, v12
	v_max_f32_e32 v11, v15, v11
	v_max3_f32 v12, |v27|, |v26|, v12
	v_max3_f32 v10, v10, v11, v12
	s_waitcnt vmcnt(1)
	v_lshlrev_b32_e32 v23, 16, v6
	v_and_b32_e32 v21, 0xffff0000, v6
	v_lshlrev_b32_e32 v17, 16, v9
	v_and_b32_e32 v16, 0xffff0000, v9
	v_max3_f32 v149, v18, v14, v10
	v_max_f32_e64 v6, |v21|, |v21|
	v_max_f32_e64 v10, |v23|, |v23|
	v_lshlrev_b32_e32 v22, 16, v7
	v_and_b32_e32 v20, 0xffff0000, v7
	v_lshlrev_b32_e32 v19, 16, v8
	v_and_b32_e32 v18, 0xffff0000, v8
	v_max_f32_e64 v8, |v16|, |v16|
	v_max_f32_e64 v9, |v17|, |v17|
	v_max_f32_e32 v6, v10, v6
	v_max_f32_e64 v7, |v20|, |v20|
	v_max_f32_e64 v10, |v22|, |v22|
	v_max_f32_e32 v8, v9, v8
	v_max_f32_e32 v7, v10, v7
	v_max3_f32 v8, |v19|, |v18|, v8
	v_max3_f32 v6, v6, v7, v8
	s_waitcnt vmcnt(0)
	v_lshlrev_b32_e32 v15, 16, v2
	v_and_b32_e32 v13, 0xffff0000, v2
	v_lshlrev_b32_e32 v9, 16, v5
	v_and_b32_e32 v8, 0xffff0000, v5
	v_max_f32_e64 v2, |v13|, |v13|
	v_max_f32_e64 v7, |v15|, |v15|
	v_lshlrev_b32_e32 v14, 16, v3
	v_and_b32_e32 v12, 0xffff0000, v3
	v_lshlrev_b32_e32 v11, 16, v4
	v_and_b32_e32 v10, 0xffff0000, v4
	v_max_f32_e64 v4, |v8|, |v8|
	v_max_f32_e64 v5, |v9|, |v9|
	v_max_f32_e32 v2, v7, v2
	v_max_f32_e64 v3, |v12|, |v12|
	v_max_f32_e64 v7, |v14|, |v14|
	v_max_f32_e32 v4, v5, v4
	v_max_f32_e32 v3, v7, v3
	v_max3_f32 v4, |v11|, |v10|, v4
	v_max3_f32 v2, v2, v3, v4
	v_max3_f32 v2, v149, v6, v2
	s_nop 1
	v_mov_b32_dpp v148, v147 quad_perm:[1,0,3,2] row_mask:0xf bank_mask:0xf
	s_nop 1
	v_mov_b32_dpp v3, v2 quad_perm:[1,0,3,2] row_mask:0xf bank_mask:0xf
	s_waitcnt lgkmcnt(0)
; __device__ __forceinline__ float bflo(unsigned w) { return __uint_as_float(w << 16); }
; __device__ __forceinline__ float bfhi(unsigned w) { return __uint_as_float(w & 0xffff0000u); }
; #pragma unroll
;     for (int j = 0; j < 8; ++j) mx = fmaxf(mx, fmaxf(fmaxf(fmaxf(fabsf(bflo(w[j].x)), fabsf(bfhi(w[j].x))), fmaxf(fabsf(bflo(w[j].y)), fabsf(bfhi(w[j].y)))), fmaxf(fmaxf(fabsf(bflo(w[j].z)), fabsf(bfhi(w[j].z))), fmaxf(fabsf(bflo(w[j].w)), fabsf(bfhi(w[j].w))))));
; #pragma unroll
;     for (int o = 1; o < 64; o <<= 1) mx = fmaxf(mx, __shfl_xor(mx, o));
;     return mx; }
; __device__ __forceinline__ void quant_store8(const u32x4 (&w)[8], float inv, signed char* dst, int lane) { u32x2* qp = (u32x2*)dst + lane;
; #pragma unroll
;     for (int j = 0; j < 8; ++j) { const unsigned ww[4] = {w[j].x, w[j].y, w[j].z, w[j].w}; unsigned o2[2];
; #pragma unroll
;         for (int h2 = 0; h2 < 2; ++h2) { const int q0 = (int)rintf(bflo(ww[2 * h2]) * inv), q1 = (int)rintf(bfhi(ww[2 * h2]) * inv), q2 = (int)rintf(bflo(ww[2 * h2 + 1]) * inv), q3 = (int)rintf(bfhi(ww[2 * h2 + 1]) * inv);
;             o2[h2] = (unsigned)(q0 & 255) | ((unsigned)(q1 & 255) << 8) | ((unsigned)(q2 & 255) << 16) | ((unsigned)(q3 & 255) << 24); }
;         u32x2 o; o.x = o2[0]; o.y = o2[1]; qp[64 * j] = o; } }
; __device__ __forceinline__ void quant_rows2(const bf16_t* s0, const bf16_t* s1, signed char* d0, signed char* d1, int lane, float& step0, float& step1) {
;     const u32x4* p0 = (const u32x4*)s0 + lane; const u32x4* p1 = (const u32x4*)s1 + lane; u32x4 w0[8], w1[8];
; #pragma unroll
;     for (int j = 0; j < 8; ++j) { w0[j] = p0[64 * j]; w1[j] = p1[64 * j]; }
;     step0 = fmaxf(absmax8(w0), 1e-30f) * (1.0f / 127.0f); step1 = fmaxf(absmax8(w1), 1e-30f) * (1.0f / 127.0f);
;     quant_store8(w0, 1.0f / step0, d0, lane); quant_store8(w1, 1.0f / step1, d1, lane);
	v_max_f32_e32 v4, v148, v148
	s_waitcnt lgkmcnt(0)
	v_max_f32_e32 v3, v3, v3
	v_max_f32_e32 v4, v147, v4
	v_max_f32_e32 v2, v2, v3
	s_nop 1
	v_mov_b32_dpp v5, v4 quad_perm:[2,3,0,1] row_mask:0xf bank_mask:0xf
	s_nop 1
	v_mov_b32_dpp v3, v2 quad_perm:[2,3,0,1] row_mask:0xf bank_mask:0xf
	s_waitcnt lgkmcnt(0)
	v_max_f32_e32 v5, v5, v5
	s_waitcnt lgkmcnt(0)
	v_max_f32_e32 v3, v3, v3
	v_max_f32_e32 v4, v4, v5
	v_max_f32_e32 v2, v2, v3
	s_nop 1
	v_mov_b32_dpp v5, v4 row_half_mirror row_mask:0xf bank_mask:0xf
	s_nop 1
	v_mov_b32_dpp v3, v2 row_half_mirror row_mask:0xf bank_mask:0xf
	s_waitcnt lgkmcnt(0)
	v_max_f32_e32 v5, v5, v5
	s_waitcnt lgkmcnt(0)
	v_max_f32_e32 v3, v3, v3
	v_max_f32_e32 v4, v4, v5
	v_max_f32_e32 v2, v2, v3
	s_nop 1
	v_mov_b32_dpp v5, v4 row_mirror row_mask:0xf bank_mask:0xf
	s_nop 1
	v_mov_b32_dpp v3, v2 row_mirror row_mask:0xf bank_mask:0xf
	s_waitcnt lgkmcnt(0)
	v_max_f32_e32 v5, v5, v5
	s_waitcnt lgkmcnt(0)
	v_max_f32_e32 v3, v3, v3
	v_max_f32_e32 v4, v4, v5
	v_max_f32_e32 v2, v2, v3
	s_waitcnt lgkmcnt(0)
	s_waitcnt lgkmcnt(0)
	v_mov_b32_e32 v5, v4
	s_nop 1
	v_permlane16_swap_b32_e32 v4, v5
	s_nop 0
	v_max_f32_e32 v4, v4, v5
	v_mov_b32_e32 v3, v2
	s_nop 1
	v_permlane16_swap_b32_e32 v3, v2
	s_nop 0
	v_max_f32_e32 v3, v3, v2
	ds_bpermute_b32 v5, v39, v4
	ds_bpermute_b32 v6, v39, v3
	s_waitcnt lgkmcnt(1)
	v_max3_f32 v2, v4, v5, s19
	s_waitcnt lgkmcnt(0)
	v_max3_f32 v3, v3, v6, s19
	v_pk_mul_f32 v[2:3], v[2:3], s[6:7] op_sel_hi:[1,0]
	s_nop 0
	v_div_scale_f32 v4, s[14:15], v2, v2, 1.0
	v_rcp_f32_e32 v5, v4
	s_nop 0
	v_fma_f32 v6, -v4, v5, 1.0
	v_fmac_f32_e32 v5, v6, v5
	v_div_scale_f32 v6, vcc, 1.0, v2, 1.0
	v_mul_f32_e32 v7, v6, v5
	v_fma_f32 v147, -v4, v7, v6
	v_fmac_f32_e32 v7, v147, v5
	v_fma_f32 v4, -v4, v7, v6
	v_div_fmas_f32 v4, v4, v5, v7
	v_div_fixup_f32 v147, v4, v2, 1.0
	v_mul_f32_e32 v7, v147, v84
	v_mul_f32_e32 v6, v147, v83
	v_rndne_f32_e32 v7, v7
	v_mul_f32_e32 v83, v147, v85
	v_rndne_f32_e32 v6, v6
	v_cvt_i32_f32_e32 v7, v7
	v_rndne_f32_e32 v83, v83
	v_mul_f32_e32 v84, v147, v86
	v_cvt_i32_f32_e32 v6, v6
	v_cvt_i32_f32_sdwa v83, v83 dst_sel:WORD_1 dst_unused:UNUSED_PAD src0_sel:DWORD
	v_rndne_f32_e32 v84, v84
	v_cvt_i32_f32_sdwa v84, v84 dst_sel:BYTE_3 dst_unused:UNUSED_PAD src0_sel:DWORD
	v_lshlrev_b32_e32 v7, 8, v7
	v_and_b32_e32 v83, 0xff0000, v83
	v_perm_b32 v6, v7, v6, s20
	v_mul_f32_e32 v7, v147, v88
	v_or3_b32 v84, v6, v84, v83
	v_mul_f32_e32 v6, v147, v87
	v_rndne_f32_e32 v7, v7
	v_mul_f32_e32 v83, v147, v89
	v_rndne_f32_e32 v6, v6
	v_cvt_i32_f32_e32 v7, v7
	v_rndne_f32_e32 v83, v83
	v_mul_f32_e32 v85, v147, v90
	v_cvt_i32_f32_e32 v6, v6
	v_cvt_i32_f32_sdwa v83, v83 dst_sel:WORD_1 dst_unused:UNUSED_PAD src0_sel:DWORD
	v_rndne_f32_e32 v85, v85
	v_cvt_i32_f32_sdwa v85, v85 dst_sel:BYTE_3 dst_unused:UNUSED_PAD src0_sel:DWORD
	v_lshlrev_b32_e32 v7, 8, v7
	v_lshl_add_u64 v[4:5], s[78:79], 0, v[32:33]
	v_and_b32_e32 v83, 0xff0000, v83
	v_perm_b32 v6, v7, v6, s20
	v_or3_b32 v85, v6, v85, v83
	v_add_co_u32_e32 v6, vcc, s21, v4
	v_mul_f32_e32 v83, v147, v91
	s_nop 0
	v_addc_co_u32_e32 v7, vcc, 0, v5, vcc
	v_add_co_u32_e32 v4, vcc, s22, v4
	v_rndne_f32_e32 v83, v83
	s_nop 0
	v_addc_co_u32_e32 v5, vcc, 0, v5, vcc
	global_store_dwordx2 v[4:5], v[84:85], off offset:-4096
	v_mul_f32_e32 v84, v147, v92
	v_rndne_f32_e32 v84, v84
	v_mul_f32_e32 v85, v147, v93
	v_cvt_i32_f32_e32 v84, v84
	v_rndne_f32_e32 v85, v85
	v_mul_f32_e32 v86, v147, v94
	v_cvt_i32_f32_e32 v83, v83
	v_cvt_i32_f32_sdwa v85, v85 dst_sel:WORD_1 dst_unused:UNUSED_PAD src0_sel:DWORD
	v_rndne_f32_e32 v86, v86
	v_cvt_i32_f32_sdwa v86, v86 dst_sel:BYTE_3 dst_unused:UNUSED_PAD src0_sel:DWORD
	v_lshlrev_b32_e32 v84, 8, v84
	v_and_b32_e32 v85, 0xff0000, v85
	v_perm_b32 v83, v84, v83, s20
	v_or3_b32 v84, v83, v86, v85
	v_mul_f32_e32 v85, v147, v96
	v_mul_f32_e32 v83, v147, v95
	v_rndne_f32_e32 v85, v85
	v_mul_f32_e32 v86, v147, v97
	v_rndne_f32_e32 v83, v83
	v_cvt_i32_f32_e32 v85, v85
	v_rndne_f32_e32 v86, v86
	v_mul_f32_e32 v87, v147, v98
	v_cvt_i32_f32_e32 v83, v83
	v_cvt_i32_f32_sdwa v86, v86 dst_sel:WORD_1 dst_unused:UNUSED_PAD src0_sel:DWORD
	v_rndne_f32_e32 v87, v87
	v_cvt_i32_f32_sdwa v87, v87 dst_sel:BYTE_3 dst_unused:UNUSED_PAD src0_sel:DWORD
	v_lshlrev_b32_e32 v85, 8, v85
	v_and_b32_e32 v86, 0xff0000, v86
	v_perm_b32 v83, v85, v83, s20
	v_or3_b32 v85, v83, v87, v86
	global_store_dwordx2 v[6:7], v[84:85], off offset:512
	v_mul_f32_e32 v84, v147, v100
	v_mul_f32_e32 v83, v147, v99
	v_rndne_f32_e32 v84, v84
	v_mul_f32_e32 v85, v147, v101
	v_rndne_f32_e32 v83, v83
	v_cvt_i32_f32_e32 v84, v84
	v_rndne_f32_e32 v85, v85
	v_mul_f32_e32 v86, v147, v102
	v_cvt_i32_f32_e32 v83, v83
	v_cvt_i32_f32_sdwa v85, v85 dst_sel:WORD_1 dst_unused:UNUSED_PAD src0_sel:DWORD
	v_rndne_f32_e32 v86, v86
	v_cvt_i32_f32_sdwa v86, v86 dst_sel:BYTE_3 dst_unused:UNUSED_PAD src0_sel:DWORD
	v_lshlrev_b32_e32 v84, 8, v84
	v_and_b32_e32 v85, 0xff0000, v85
	v_perm_b32 v83, v84, v83, s20
	v_or3_b32 v84, v83, v86, v85
	v_mul_f32_e32 v85, v147, v104
	v_mul_f32_e32 v83, v147, v103
	v_rndne_f32_e32 v85, v85
	v_mul_f32_e32 v86, v147, v105
	v_rndne_f32_e32 v83, v83
	v_cvt_i32_f32_e32 v85, v85
	v_rndne_f32_e32 v86, v86
	v_mul_f32_e32 v87, v147, v106
	v_cvt_i32_f32_e32 v83, v83
	v_cvt_i32_f32_sdwa v86, v86 dst_sel:WORD_1 dst_unused:UNUSED_PAD src0_sel:DWORD
	v_rndne_f32_e32 v87, v87
	v_cvt_i32_f32_sdwa v87, v87 dst_sel:BYTE_3 dst_unused:UNUSED_PAD src0_sel:DWORD
	v_lshlrev_b32_e32 v85, 8, v85
	v_and_b32_e32 v86, 0xff0000, v86
	v_perm_b32 v83, v85, v83, s20
	v_or3_b32 v85, v83, v87, v86
	global_store_dwordx2 v[6:7], v[84:85], off offset:1024
	v_mul_f32_e32 v84, v147, v108
	v_mul_f32_e32 v83, v147, v107
; __device__ __forceinline__ float bflo(unsigned w) { return __uint_as_float(w << 16); }
; __device__ __forceinline__ float bfhi(unsigned w) { return __uint_as_float(w & 0xffff0000u); }
; __device__ __forceinline__ void quant_store8(const u32x4 (&w)[8], float inv, signed char* dst, int lane) { u32x2* qp = (u32x2*)dst + lane;
; #pragma unroll
;     for (int j = 0; j < 8; ++j) { const unsigned ww[4] = {w[j].x, w[j].y, w[j].z, w[j].w}; unsigned o2[2];
; #pragma unroll
;         for (int h2 = 0; h2 < 2; ++h2) { const int q0 = (int)rintf(bflo(ww[2 * h2]) * inv), q1 = (int)rintf(bfhi(ww[2 * h2]) * inv), q2 = (int)rintf(bflo(ww[2 * h2 + 1]) * inv), q3 = (int)rintf(bfhi(ww[2 * h2 + 1]) * inv);
;             o2[h2] = (unsigned)(q0 & 255) | ((unsigned)(q1 & 255) << 8) | ((unsigned)(q2 & 255) << 16) | ((unsigned)(q3 & 255) << 24); }
;         u32x2 o; o.x = o2[0]; o.y = o2[1]; qp[64 * j] = o; } }
	v_rndne_f32_e32 v84, v84
	v_mul_f32_e32 v85, v147, v109
	v_rndne_f32_e32 v83, v83
	v_cvt_i32_f32_e32 v84, v84
	v_rndne_f32_e32 v85, v85
	v_mul_f32_e32 v86, v147, v110
	v_cvt_i32_f32_e32 v83, v83
	v_cvt_i32_f32_sdwa v85, v85 dst_sel:WORD_1 dst_unused:UNUSED_PAD src0_sel:DWORD
	v_rndne_f32_e32 v86, v86
	v_cvt_i32_f32_sdwa v86, v86 dst_sel:BYTE_3 dst_unused:UNUSED_PAD src0_sel:DWORD
	v_lshlrev_b32_e32 v84, 8, v84
	v_and_b32_e32 v85, 0xff0000, v85
	v_perm_b32 v83, v84, v83, s20
	v_or3_b32 v84, v83, v86, v85
	v_mul_f32_e32 v85, v147, v112
	v_mul_f32_e32 v83, v147, v111
	v_rndne_f32_e32 v85, v85
	v_mul_f32_e32 v86, v147, v113
	v_rndne_f32_e32 v83, v83
	v_cvt_i32_f32_e32 v85, v85
	v_rndne_f32_e32 v86, v86
	v_mul_f32_e32 v87, v147, v114
	v_cvt_i32_f32_e32 v83, v83
	v_cvt_i32_f32_sdwa v86, v86 dst_sel:WORD_1 dst_unused:UNUSED_PAD src0_sel:DWORD
	v_rndne_f32_e32 v87, v87
	v_cvt_i32_f32_sdwa v87, v87 dst_sel:BYTE_3 dst_unused:UNUSED_PAD src0_sel:DWORD
	v_lshlrev_b32_e32 v85, 8, v85
	v_and_b32_e32 v86, 0xff0000, v86
	v_perm_b32 v83, v85, v83, s20
	v_or3_b32 v85, v83, v87, v86
	global_store_dwordx2 v[6:7], v[84:85], off offset:1536
	v_mul_f32_e32 v84, v147, v116
	v_mul_f32_e32 v83, v147, v115
	v_rndne_f32_e32 v84, v84
	v_mul_f32_e32 v85, v147, v117
	v_rndne_f32_e32 v83, v83
	v_cvt_i32_f32_e32 v84, v84
	v_rndne_f32_e32 v85, v85
	v_mul_f32_e32 v86, v147, v118
	v_cvt_i32_f32_e32 v83, v83
	v_cvt_i32_f32_sdwa v85, v85 dst_sel:WORD_1 dst_unused:UNUSED_PAD src0_sel:DWORD
	v_rndne_f32_e32 v86, v86
	v_cvt_i32_f32_sdwa v86, v86 dst_sel:BYTE_3 dst_unused:UNUSED_PAD src0_sel:DWORD
	v_lshlrev_b32_e32 v84, 8, v84
	v_and_b32_e32 v85, 0xff0000, v85
	v_perm_b32 v83, v84, v83, s20
	v_or3_b32 v84, v83, v86, v85
	v_mul_f32_e32 v85, v147, v120
	v_mul_f32_e32 v83, v147, v119
	v_rndne_f32_e32 v85, v85
	v_mul_f32_e32 v86, v147, v121
	v_rndne_f32_e32 v83, v83
	v_cvt_i32_f32_e32 v85, v85
	v_rndne_f32_e32 v86, v86
	v_mul_f32_e32 v87, v147, v122
	v_cvt_i32_f32_e32 v83, v83
	v_cvt_i32_f32_sdwa v86, v86 dst_sel:WORD_1 dst_unused:UNUSED_PAD src0_sel:DWORD
	v_rndne_f32_e32 v87, v87
	v_cvt_i32_f32_sdwa v87, v87 dst_sel:BYTE_3 dst_unused:UNUSED_PAD src0_sel:DWORD
	v_lshlrev_b32_e32 v85, 8, v85
	v_and_b32_e32 v86, 0xff0000, v86
	v_perm_b32 v83, v85, v83, s20
	v_or3_b32 v85, v83, v87, v86
	global_store_dwordx2 v[6:7], v[84:85], off offset:2048
	v_mul_f32_e32 v84, v147, v124
	v_mul_f32_e32 v83, v147, v123
	v_rndne_f32_e32 v84, v84
	v_mul_f32_e32 v85, v147, v125
	v_rndne_f32_e32 v83, v83
	v_cvt_i32_f32_e32 v84, v84
	v_rndne_f32_e32 v85, v85
	v_mul_f32_e32 v86, v147, v126
	v_cvt_i32_f32_e32 v83, v83
	v_cvt_i32_f32_sdwa v85, v85 dst_sel:WORD_1 dst_unused:UNUSED_PAD src0_sel:DWORD
	v_rndne_f32_e32 v86, v86
	v_cvt_i32_f32_sdwa v86, v86 dst_sel:BYTE_3 dst_unused:UNUSED_PAD src0_sel:DWORD
	v_lshlrev_b32_e32 v84, 8, v84
	v_and_b32_e32 v85, 0xff0000, v85
	v_perm_b32 v83, v84, v83, s20
	v_or3_b32 v84, v83, v86, v85
	v_mul_f32_e32 v85, v147, v128
	v_mul_f32_e32 v83, v147, v127
	v_rndne_f32_e32 v85, v85
	v_mul_f32_e32 v86, v147, v129
	v_rndne_f32_e32 v83, v83
	v_cvt_i32_f32_e32 v85, v85
	v_rndne_f32_e32 v86, v86
	v_mul_f32_e32 v87, v147, v130
	v_cvt_i32_f32_e32 v83, v83
	v_cvt_i32_f32_sdwa v86, v86 dst_sel:WORD_1 dst_unused:UNUSED_PAD src0_sel:DWORD
	v_rndne_f32_e32 v87, v87
	v_cvt_i32_f32_sdwa v87, v87 dst_sel:BYTE_3 dst_unused:UNUSED_PAD src0_sel:DWORD
	v_lshlrev_b32_e32 v85, 8, v85
	v_and_b32_e32 v86, 0xff0000, v86
	v_perm_b32 v83, v85, v83, s20
	v_or3_b32 v85, v83, v87, v86
	global_store_dwordx2 v[6:7], v[84:85], off offset:2560
	v_mul_f32_e32 v84, v147, v132
	v_mul_f32_e32 v83, v147, v131
	v_rndne_f32_e32 v84, v84
	v_mul_f32_e32 v85, v147, v133
	v_rndne_f32_e32 v83, v83
	v_cvt_i32_f32_e32 v84, v84
	v_rndne_f32_e32 v85, v85
	v_mul_f32_e32 v86, v147, v134
	v_cvt_i32_f32_e32 v83, v83
	v_cvt_i32_f32_sdwa v85, v85 dst_sel:WORD_1 dst_unused:UNUSED_PAD src0_sel:DWORD
	v_rndne_f32_e32 v86, v86
	v_cvt_i32_f32_sdwa v86, v86 dst_sel:BYTE_3 dst_unused:UNUSED_PAD src0_sel:DWORD
	v_lshlrev_b32_e32 v84, 8, v84
	v_and_b32_e32 v85, 0xff0000, v85
	v_perm_b32 v83, v84, v83, s20
	v_or3_b32 v84, v83, v86, v85
	v_mul_f32_e32 v85, v147, v136
	v_mul_f32_e32 v83, v147, v135
	v_rndne_f32_e32 v85, v85
	v_mul_f32_e32 v86, v147, v137
	v_rndne_f32_e32 v83, v83
	v_cvt_i32_f32_e32 v85, v85
	v_rndne_f32_e32 v86, v86
	v_mul_f32_e32 v87, v147, v138
	v_cvt_i32_f32_e32 v83, v83
	v_cvt_i32_f32_sdwa v86, v86 dst_sel:WORD_1 dst_unused:UNUSED_PAD src0_sel:DWORD
	v_rndne_f32_e32 v87, v87
	v_cvt_i32_f32_sdwa v87, v87 dst_sel:BYTE_3 dst_unused:UNUSED_PAD src0_sel:DWORD
	v_lshlrev_b32_e32 v85, 8, v85
	v_and_b32_e32 v86, 0xff0000, v86
	v_perm_b32 v83, v85, v83, s20
	v_or3_b32 v85, v83, v87, v86
	global_store_dwordx2 v[6:7], v[84:85], off offset:3072
	v_mul_f32_e32 v84, v147, v140
	v_mul_f32_e32 v83, v147, v139
	v_rndne_f32_e32 v84, v84
	v_mul_f32_e32 v85, v147, v141
	v_rndne_f32_e32 v83, v83
	v_cvt_i32_f32_e32 v84, v84
	v_rndne_f32_e32 v85, v85
	v_mul_f32_e32 v86, v147, v142
	v_cvt_i32_f32_e32 v83, v83
	v_cvt_i32_f32_sdwa v85, v85 dst_sel:WORD_1 dst_unused:UNUSED_PAD src0_sel:DWORD
	v_rndne_f32_e32 v86, v86
	v_cvt_i32_f32_sdwa v86, v86 dst_sel:BYTE_3 dst_unused:UNUSED_PAD src0_sel:DWORD
	v_lshlrev_b32_e32 v84, 8, v84
	v_and_b32_e32 v85, 0xff0000, v85
	v_perm_b32 v83, v84, v83, s20
	v_or3_b32 v84, v83, v86, v85
	v_mul_f32_e32 v85, v147, v144
	v_mul_f32_e32 v83, v147, v143
	v_rndne_f32_e32 v85, v85
	v_mul_f32_e32 v86, v147, v145
	v_rndne_f32_e32 v83, v83
	v_cvt_i32_f32_e32 v85, v85
	v_rndne_f32_e32 v86, v86
	v_mul_f32_e32 v87, v147, v146
	v_cvt_i32_f32_e32 v83, v83
	v_cvt_i32_f32_sdwa v86, v86 dst_sel:WORD_1 dst_unused:UNUSED_PAD src0_sel:DWORD
; __device__ __forceinline__ float bflo(unsigned w) { return __uint_as_float(w << 16); }
; __device__ __forceinline__ float bfhi(unsigned w) { return __uint_as_float(w & 0xffff0000u); }
; __device__ __forceinline__ void quant_store8(const u32x4 (&w)[8], float inv, signed char* dst, int lane) { u32x2* qp = (u32x2*)dst + lane;
; #pragma unroll
;     for (int j = 0; j < 8; ++j) { const unsigned ww[4] = {w[j].x, w[j].y, w[j].z, w[j].w}; unsigned o2[2];
; #pragma unroll
;         for (int h2 = 0; h2 < 2; ++h2) { const int q0 = (int)rintf(bflo(ww[2 * h2]) * inv), q1 = (int)rintf(bfhi(ww[2 * h2]) * inv), q2 = (int)rintf(bflo(ww[2 * h2 + 1]) * inv), q3 = (int)rintf(bfhi(ww[2 * h2 + 1]) * inv);
;             o2[h2] = (unsigned)(q0 & 255) | ((unsigned)(q1 & 255) << 8) | ((unsigned)(q2 & 255) << 16) | ((unsigned)(q3 & 255) << 24); }
;         u32x2 o; o.x = o2[0]; o.y = o2[1]; qp[64 * j] = o; } }
; __device__ __forceinline__ void quant_rows2(const bf16_t* s0, const bf16_t* s1, signed char* d0, signed char* d1, int lane, float& step0, float& step1) {
;     ...
;     step0 = fmaxf(absmax8(w0), 1e-30f) * (1.0f / 127.0f); step1 = fmaxf(absmax8(w1), 1e-30f) * (1.0f / 127.0f);
;     quant_store8(w0, 1.0f / step0, d0, lane); quant_store8(w1, 1.0f / step1, d1, lane);
	v_rndne_f32_e32 v87, v87
	v_cvt_i32_f32_sdwa v87, v87 dst_sel:BYTE_3 dst_unused:UNUSED_PAD src0_sel:DWORD
	v_div_scale_f32 v88, s[14:15], v3, v3, 1.0
	v_rcp_f32_e32 v89, v88
	v_lshlrev_b32_e32 v85, 8, v85
	v_and_b32_e32 v86, 0xff0000, v86
	v_perm_b32 v83, v85, v83, s20
	v_or3_b32 v85, v83, v87, v86
	global_store_dwordx2 v[6:7], v[84:85], off offset:3584
	v_fma_f32 v6, -v88, v89, 1.0
	v_fmac_f32_e32 v89, v6, v89
	v_div_scale_f32 v6, vcc, 1.0, v3, 1.0
	v_mul_f32_e32 v7, v6, v89
	v_fma_f32 v83, -v88, v7, v6
	v_fmac_f32_e32 v7, v83, v89
	v_fma_f32 v6, -v88, v7, v6
	v_div_fmas_f32 v6, v6, v89, v7
	v_div_fixup_f32 v83, v6, v3, 1.0
	v_mul_f32_e32 v7, v83, v80
	v_mul_f32_e32 v6, v83, v82
	v_rndne_f32_e32 v7, v7
	v_rndne_f32_e32 v6, v6
	v_cvt_i32_f32_e32 v7, v7
	v_cvt_i32_f32_e32 v6, v6
	v_mul_f32_e32 v77, v83, v77
	v_mul_f32_e32 v80, v83, v81
	v_lshlrev_b32_e32 v7, 8, v7
	v_perm_b32 v6, v7, v6, s20
	v_mul_f32_e32 v7, v83, v78
	v_rndne_f32_e32 v77, v77
	v_mul_f32_e32 v76, v83, v76
	v_rndne_f32_e32 v80, v80
	v_mul_f32_e32 v79, v83, v79
	v_rndne_f32_e32 v7, v7
	v_cvt_i32_f32_e32 v77, v77
	v_rndne_f32_e32 v76, v76
	v_mul_f32_e32 v75, v83, v75
	v_cvt_i32_f32_sdwa v80, v80 dst_sel:WORD_1 dst_unused:UNUSED_PAD src0_sel:DWORD
	v_rndne_f32_e32 v79, v79
	v_cvt_i32_f32_e32 v7, v7
	v_cvt_i32_f32_sdwa v76, v76 dst_sel:WORD_1 dst_unused:UNUSED_PAD src0_sel:DWORD
	v_rndne_f32_e32 v75, v75
	v_cvt_i32_f32_sdwa v79, v79 dst_sel:BYTE_3 dst_unused:UNUSED_PAD src0_sel:DWORD
	v_cvt_i32_f32_sdwa v75, v75 dst_sel:BYTE_3 dst_unused:UNUSED_PAD src0_sel:DWORD
	v_lshlrev_b32_e32 v77, 8, v77
	v_and_b32_e32 v80, 0xff0000, v80
	v_and_b32_e32 v76, 0xff0000, v76
	v_perm_b32 v7, v77, v7, s20
	v_or3_b32 v6, v6, v79, v80
	v_or3_b32 v7, v7, v75, v76
	global_store_dwordx2 v[4:5], v[6:7], off
	v_mul_f32_e32 v7, v83, v72
	v_mul_f32_e32 v6, v83, v74
	v_rndne_f32_e32 v7, v7
	v_rndne_f32_e32 v6, v6
	v_cvt_i32_f32_e32 v7, v7
	v_cvt_i32_f32_e32 v6, v6
	v_mul_f32_e32 v69, v83, v69
	v_mul_f32_e32 v72, v83, v73
	v_lshlrev_b32_e32 v7, 8, v7
	v_perm_b32 v6, v7, v6, s20
	v_mul_f32_e32 v7, v83, v70
	v_rndne_f32_e32 v69, v69
	v_mul_f32_e32 v68, v83, v68
	v_rndne_f32_e32 v72, v72
	v_mul_f32_e32 v71, v83, v71
	v_rndne_f32_e32 v7, v7
	v_cvt_i32_f32_e32 v69, v69
	v_rndne_f32_e32 v68, v68
	v_mul_f32_e32 v67, v83, v67
	v_cvt_i32_f32_sdwa v72, v72 dst_sel:WORD_1 dst_unused:UNUSED_PAD src0_sel:DWORD
	v_rndne_f32_e32 v71, v71
	v_cvt_i32_f32_e32 v7, v7
	v_cvt_i32_f32_sdwa v68, v68 dst_sel:WORD_1 dst_unused:UNUSED_PAD src0_sel:DWORD
	v_rndne_f32_e32 v67, v67
	v_cvt_i32_f32_sdwa v71, v71 dst_sel:BYTE_3 dst_unused:UNUSED_PAD src0_sel:DWORD
	v_cvt_i32_f32_sdwa v67, v67 dst_sel:BYTE_3 dst_unused:UNUSED_PAD src0_sel:DWORD
	v_lshlrev_b32_e32 v69, 8, v69
	v_and_b32_e32 v72, 0xff0000, v72
	v_and_b32_e32 v68, 0xff0000, v68
	v_perm_b32 v7, v69, v7, s20
	v_or3_b32 v6, v6, v71, v72
	v_or3_b32 v7, v7, v67, v68
	global_store_dwordx2 v[4:5], v[6:7], off offset:512
	v_mul_f32_e32 v7, v83, v64
	v_mul_f32_e32 v6, v83, v66
	v_rndne_f32_e32 v7, v7
	v_rndne_f32_e32 v6, v6
	v_cvt_i32_f32_e32 v7, v7
	v_cvt_i32_f32_e32 v6, v6
	v_mul_f32_e32 v61, v83, v61
	v_mul_f32_e32 v64, v83, v65
	v_lshlrev_b32_e32 v7, 8, v7
	v_perm_b32 v6, v7, v6, s20
	v_mul_f32_e32 v7, v83, v62
	v_rndne_f32_e32 v61, v61
	v_mul_f32_e32 v60, v83, v60
	v_rndne_f32_e32 v64, v64
	v_mul_f32_e32 v63, v83, v63
	v_rndne_f32_e32 v7, v7
	v_cvt_i32_f32_e32 v61, v61
	v_rndne_f32_e32 v60, v60
	v_mul_f32_e32 v59, v83, v59
	v_cvt_i32_f32_sdwa v64, v64 dst_sel:WORD_1 dst_unused:UNUSED_PAD src0_sel:DWORD
	v_rndne_f32_e32 v63, v63
	v_cvt_i32_f32_e32 v7, v7
	v_cvt_i32_f32_sdwa v60, v60 dst_sel:WORD_1 dst_unused:UNUSED_PAD src0_sel:DWORD
	v_rndne_f32_e32 v59, v59
	v_cvt_i32_f32_sdwa v63, v63 dst_sel:BYTE_3 dst_unused:UNUSED_PAD src0_sel:DWORD
	v_cvt_i32_f32_sdwa v59, v59 dst_sel:BYTE_3 dst_unused:UNUSED_PAD src0_sel:DWORD
	v_lshlrev_b32_e32 v61, 8, v61
	v_and_b32_e32 v64, 0xff0000, v64
	v_and_b32_e32 v60, 0xff0000, v60
	v_perm_b32 v7, v61, v7, s20
	v_or3_b32 v6, v6, v63, v64
	v_or3_b32 v7, v7, v59, v60
	global_store_dwordx2 v[4:5], v[6:7], off offset:1024
	v_mul_f32_e32 v7, v83, v56
	v_mul_f32_e32 v6, v83, v58
	v_rndne_f32_e32 v7, v7
	v_rndne_f32_e32 v6, v6
	v_cvt_i32_f32_e32 v7, v7
	v_cvt_i32_f32_e32 v6, v6
	v_mul_f32_e32 v53, v83, v53
	v_mul_f32_e32 v56, v83, v57
	v_lshlrev_b32_e32 v7, 8, v7
	v_perm_b32 v6, v7, v6, s20
	v_mul_f32_e32 v7, v83, v54
	v_rndne_f32_e32 v53, v53
	v_mul_f32_e32 v52, v83, v52
	v_rndne_f32_e32 v56, v56
	v_mul_f32_e32 v55, v83, v55
	v_rndne_f32_e32 v7, v7
	v_cvt_i32_f32_e32 v53, v53
	v_rndne_f32_e32 v52, v52
	v_mul_f32_e32 v51, v83, v51
	v_cvt_i32_f32_sdwa v56, v56 dst_sel:WORD_1 dst_unused:UNUSED_PAD src0_sel:DWORD
	v_rndne_f32_e32 v55, v55
	v_cvt_i32_f32_e32 v7, v7
	v_cvt_i32_f32_sdwa v52, v52 dst_sel:WORD_1 dst_unused:UNUSED_PAD src0_sel:DWORD
	v_rndne_f32_e32 v51, v51
	v_cvt_i32_f32_sdwa v55, v55 dst_sel:BYTE_3 dst_unused:UNUSED_PAD src0_sel:DWORD
	v_cvt_i32_f32_sdwa v51, v51 dst_sel:BYTE_3 dst_unused:UNUSED_PAD src0_sel:DWORD
; __device__ __forceinline__ float bflo(unsigned w) { return __uint_as_float(w << 16); }
; __device__ __forceinline__ float bfhi(unsigned w) { return __uint_as_float(w & 0xffff0000u); }
; __device__ __forceinline__ void quant_store8(const u32x4 (&w)[8], float inv, signed char* dst, int lane) { u32x2* qp = (u32x2*)dst + lane;
; #pragma unroll
;     for (int j = 0; j < 8; ++j) { const unsigned ww[4] = {w[j].x, w[j].y, w[j].z, w[j].w}; unsigned o2[2];
; #pragma unroll
;         for (int h2 = 0; h2 < 2; ++h2) { const int q0 = (int)rintf(bflo(ww[2 * h2]) * inv), q1 = (int)rintf(bfhi(ww[2 * h2]) * inv), q2 = (int)rintf(bflo(ww[2 * h2 + 1]) * inv), q3 = (int)rintf(bfhi(ww[2 * h2 + 1]) * inv);
;             o2[h2] = (unsigned)(q0 & 255) | ((unsigned)(q1 & 255) << 8) | ((unsigned)(q2 & 255) << 16) | ((unsigned)(q3 & 255) << 24); }
;         u32x2 o; o.x = o2[0]; o.y = o2[1]; qp[64 * j] = o; } }
; __global__ void __launch_bounds__(NWAVES * 64, 2) fwd(Args args) {
;     ...
;             for (int p = 0; p < 4; ++p) { const int n = 64 * bx + 8 * F.wave + 2 * p; float s0, s1;
;                 quant_rows2(W_inT + (size_t)(IN_Q0 + n) * DM, W_inT + (size_t)(IN_Q0 + n + 1) * DM, W_inq + (size_t)n * DM, W_inq + (size_t)(n + 1) * DM, F.lane, s0, s1);
;                 if (F.lane == 0) { colq[n] = s0; colq[n + 1] = s1; } }
	v_lshlrev_b32_e32 v53, 8, v53
	v_and_b32_e32 v56, 0xff0000, v56
	v_and_b32_e32 v52, 0xff0000, v52
	v_perm_b32 v7, v53, v7, s20
	v_or3_b32 v6, v6, v55, v56
	v_or3_b32 v7, v7, v51, v52
	global_store_dwordx2 v[4:5], v[6:7], off offset:1536
	v_mul_f32_e32 v7, v83, v48
	v_mul_f32_e32 v6, v83, v50
	v_rndne_f32_e32 v7, v7
	v_rndne_f32_e32 v6, v6
	v_cvt_i32_f32_e32 v7, v7
	v_cvt_i32_f32_e32 v6, v6
	v_mul_f32_e32 v45, v83, v45
	v_mul_f32_e32 v48, v83, v49
	v_lshlrev_b32_e32 v7, 8, v7
	v_perm_b32 v6, v7, v6, s20
	v_mul_f32_e32 v7, v83, v46
	v_rndne_f32_e32 v45, v45
	v_mul_f32_e32 v44, v83, v44
	v_rndne_f32_e32 v48, v48
	v_mul_f32_e32 v47, v83, v47
	v_rndne_f32_e32 v7, v7
	v_cvt_i32_f32_e32 v45, v45
	v_rndne_f32_e32 v44, v44
	v_mul_f32_e32 v43, v83, v43
	v_cvt_i32_f32_sdwa v48, v48 dst_sel:WORD_1 dst_unused:UNUSED_PAD src0_sel:DWORD
	v_rndne_f32_e32 v47, v47
	v_cvt_i32_f32_e32 v7, v7
	v_cvt_i32_f32_sdwa v44, v44 dst_sel:WORD_1 dst_unused:UNUSED_PAD src0_sel:DWORD
	v_rndne_f32_e32 v43, v43
	v_cvt_i32_f32_sdwa v47, v47 dst_sel:BYTE_3 dst_unused:UNUSED_PAD src0_sel:DWORD
	v_cvt_i32_f32_sdwa v43, v43 dst_sel:BYTE_3 dst_unused:UNUSED_PAD src0_sel:DWORD
	v_lshlrev_b32_e32 v45, 8, v45
	v_and_b32_e32 v48, 0xff0000, v48
	v_and_b32_e32 v44, 0xff0000, v44
	v_perm_b32 v7, v45, v7, s20
	v_or3_b32 v6, v6, v47, v48
	v_or3_b32 v7, v7, v43, v44
	global_store_dwordx2 v[4:5], v[6:7], off offset:2048
	v_mul_f32_e32 v7, v83, v29
	v_mul_f32_e32 v6, v83, v42
	v_rndne_f32_e32 v7, v7
	v_rndne_f32_e32 v6, v6
	v_cvt_i32_f32_e32 v7, v7
	v_cvt_i32_f32_e32 v6, v6
	v_mul_f32_e32 v26, v83, v26
	v_mul_f32_e32 v29, v83, v41
	v_lshlrev_b32_e32 v7, 8, v7
	v_perm_b32 v6, v7, v6, s20
	v_mul_f32_e32 v7, v83, v27
	v_rndne_f32_e32 v26, v26
	v_mul_f32_e32 v25, v83, v25
	v_rndne_f32_e32 v29, v29
	v_mul_f32_e32 v28, v83, v28
	v_rndne_f32_e32 v7, v7
	v_cvt_i32_f32_e32 v26, v26
	v_rndne_f32_e32 v25, v25
	v_mul_f32_e32 v24, v83, v24
	v_cvt_i32_f32_sdwa v29, v29 dst_sel:WORD_1 dst_unused:UNUSED_PAD src0_sel:DWORD
	v_rndne_f32_e32 v28, v28
	v_cvt_i32_f32_e32 v7, v7
	v_cvt_i32_f32_sdwa v25, v25 dst_sel:WORD_1 dst_unused:UNUSED_PAD src0_sel:DWORD
	v_rndne_f32_e32 v24, v24
	v_cvt_i32_f32_sdwa v28, v28 dst_sel:BYTE_3 dst_unused:UNUSED_PAD src0_sel:DWORD
	v_cvt_i32_f32_sdwa v24, v24 dst_sel:BYTE_3 dst_unused:UNUSED_PAD src0_sel:DWORD
	v_lshlrev_b32_e32 v26, 8, v26
	v_and_b32_e32 v29, 0xff0000, v29
	v_and_b32_e32 v25, 0xff0000, v25
	v_perm_b32 v7, v26, v7, s20
	v_or3_b32 v6, v6, v28, v29
	v_or3_b32 v7, v7, v24, v25
	global_store_dwordx2 v[4:5], v[6:7], off offset:2560
	v_mul_f32_e32 v7, v83, v21
	v_mul_f32_e32 v6, v83, v23
	v_rndne_f32_e32 v7, v7
	v_rndne_f32_e32 v6, v6
	v_cvt_i32_f32_e32 v7, v7
	v_cvt_i32_f32_e32 v6, v6
	v_mul_f32_e32 v18, v83, v18
	v_mul_f32_e32 v21, v83, v22
	v_lshlrev_b32_e32 v7, 8, v7
	v_perm_b32 v6, v7, v6, s20
	v_mul_f32_e32 v7, v83, v19
	v_rndne_f32_e32 v18, v18
	v_mul_f32_e32 v17, v83, v17
	v_rndne_f32_e32 v21, v21
	v_mul_f32_e32 v20, v83, v20
	v_rndne_f32_e32 v7, v7
	v_cvt_i32_f32_e32 v18, v18
	v_rndne_f32_e32 v17, v17
	v_mul_f32_e32 v16, v83, v16
	v_cvt_i32_f32_sdwa v21, v21 dst_sel:WORD_1 dst_unused:UNUSED_PAD src0_sel:DWORD
	v_rndne_f32_e32 v20, v20
	v_cvt_i32_f32_e32 v7, v7
	v_cvt_i32_f32_sdwa v17, v17 dst_sel:WORD_1 dst_unused:UNUSED_PAD src0_sel:DWORD
	v_rndne_f32_e32 v16, v16
	v_cvt_i32_f32_sdwa v20, v20 dst_sel:BYTE_3 dst_unused:UNUSED_PAD src0_sel:DWORD
	v_cvt_i32_f32_sdwa v16, v16 dst_sel:BYTE_3 dst_unused:UNUSED_PAD src0_sel:DWORD
	v_lshlrev_b32_e32 v18, 8, v18
	v_and_b32_e32 v21, 0xff0000, v21
	v_and_b32_e32 v17, 0xff0000, v17
	v_perm_b32 v7, v18, v7, s20
	v_or3_b32 v6, v6, v20, v21
	v_or3_b32 v7, v7, v16, v17
	global_store_dwordx2 v[4:5], v[6:7], off offset:3072
	v_mul_f32_e32 v7, v83, v13
	v_mul_f32_e32 v6, v83, v15
	v_rndne_f32_e32 v7, v7
	v_rndne_f32_e32 v6, v6
	v_cvt_i32_f32_e32 v7, v7
	v_cvt_i32_f32_e32 v6, v6
	v_mul_f32_e32 v10, v83, v10
	v_mul_f32_e32 v13, v83, v14
	v_lshlrev_b32_e32 v7, 8, v7
	v_perm_b32 v6, v7, v6, s20
	v_mul_f32_e32 v7, v83, v11
	v_rndne_f32_e32 v10, v10
	v_mul_f32_e32 v9, v83, v9
	v_rndne_f32_e32 v13, v13
	v_mul_f32_e32 v12, v83, v12
	v_rndne_f32_e32 v7, v7
	v_cvt_i32_f32_e32 v10, v10
	v_rndne_f32_e32 v9, v9
	v_mul_f32_e32 v8, v83, v8
	v_cvt_i32_f32_sdwa v13, v13 dst_sel:WORD_1 dst_unused:UNUSED_PAD src0_sel:DWORD
	v_rndne_f32_e32 v12, v12
	v_cvt_i32_f32_e32 v7, v7
	v_cvt_i32_f32_sdwa v9, v9 dst_sel:WORD_1 dst_unused:UNUSED_PAD src0_sel:DWORD
	v_rndne_f32_e32 v8, v8
	v_cvt_i32_f32_sdwa v12, v12 dst_sel:BYTE_3 dst_unused:UNUSED_PAD src0_sel:DWORD
	v_cvt_i32_f32_sdwa v8, v8 dst_sel:BYTE_3 dst_unused:UNUSED_PAD src0_sel:DWORD
	v_lshlrev_b32_e32 v10, 8, v10
	v_and_b32_e32 v13, 0xff0000, v13
	v_and_b32_e32 v9, 0xff0000, v9
	v_perm_b32 v7, v10, v7, s20
	v_or3_b32 v6, v6, v12, v13
	v_or3_b32 v7, v7, v8, v9
	global_store_dwordx2 v[4:5], v[6:7], off offset:3584
	s_and_saveexec_b64 s[14:15], s[4:5]
	s_cbranch_execz .LBB0_63
	s_add_u32 s24, s78, s7
	s_addc_u32 s25, s79, s16
	global_store_dwordx2 v40, v[2:3], s[24:25]
	s_branch .LBB0_63

; #define in_x ARGP(0)
; __global__ void __launch_bounds__(NWAVES * 64, 2) fwd(Args args) {
;     ...
;           for (int j = 0; j < mcnt && m < T; ++j, m += mstep) {
;             const f32x4* xr = (const f32x4*)(in_x + (size_t)m * DM) + F.lane; f32x4 v[16]; float s2 = 0.f;
; #pragma unroll
;             for (int j2 = 0; j2 < 16; ++j2) { v[j2] = __builtin_nontemporal_load(xr + 64 * j2); s2 += (v[j2][0] * v[j2][0] + v[j2][1] * v[j2][1]) + (v[j2][2] * v[j2][2] + v[j2][3] * v[j2][3]); }
;             const float rs = 1.0f / sqrtf(wave_sum(s2) * (1.0f / DM) + EPS);
;             float mx = 0.f;
; #pragma unroll
;             for (int j2 = 0; j2 < 16; ++j2) mx = fmaxf(fmaxf(mx, fmaxf(fabsf(v[j2][0]), fabsf(v[j2][1]))), fmaxf(fabsf(v[j2][2]), fabsf(v[j2][3])));
; #pragma unroll
;             for (int o = 1; o < 64; o <<= 1) mx = fmaxf(mx, __shfl_xor(mx, o));
;             const float step = fmaxf(mx, 1e-30f) * (1.0f / 127.0f), inv = 1.0f / step;
.LBB0_73:
	flat_load_dwordx2 v[2:3], v[72:73] sc0 sc1
	s_waitcnt vmcnt(0) lgkmcnt(0)
	v_lshl_add_u64 v[6:7], v[2:3], 0, v[70:71]
	v_add_co_u32_e32 v2, vcc, 0xffffc400, v6
	s_nop 1
	v_addc_co_u32_e32 v3, vcc, -1, v7, vcc
	v_add_co_u32_e32 v8, vcc, 0xffffc800, v6
	flat_load_dwordx4 v[30:33], v[2:3] nt
	s_nop 0
	v_addc_co_u32_e32 v9, vcc, -1, v7, vcc
	v_add_co_u32_e32 v10, vcc, 0xffffcc00, v6
	flat_load_dwordx4 v[2:5], v[6:7] nt
	flat_load_dwordx4 v[62:65], v[8:9] nt
	v_addc_co_u32_e32 v11, vcc, -1, v7, vcc
	v_add_co_u32_e32 v8, vcc, 0xffffd000, v6
	flat_load_dwordx4 v[58:61], v[10:11] nt
	s_nop 0
	v_addc_co_u32_e32 v9, vcc, -1, v7, vcc
	flat_load_dwordx4 v[54:57], v[8:9] nt
	v_add_co_u32_e32 v8, vcc, 0xffffd400, v6
	s_waitcnt vmcnt(0) lgkmcnt(0)
	v_mul_f32_e32 v74, v31, v31
	v_addc_co_u32_e32 v9, vcc, -1, v7, vcc
	flat_load_dwordx4 v[50:53], v[8:9] nt
	v_add_co_u32_e32 v8, vcc, 0xffffd800, v6
	v_mul_f32_e32 v75, v33, v33
	s_nop 0
	v_addc_co_u32_e32 v9, vcc, -1, v7, vcc
	flat_load_dwordx4 v[46:49], v[8:9] nt
	v_add_co_u32_e32 v8, vcc, 0xffffdc00, v6
	v_fmac_f32_e32 v74, v30, v30
	s_nop 0
	v_addc_co_u32_e32 v9, vcc, -1, v7, vcc
	flat_load_dwordx4 v[42:45], v[8:9] nt
	v_add_co_u32_e32 v8, vcc, 0xffffe000, v6
	v_fmac_f32_e32 v75, v32, v32
	s_nop 0
	v_addc_co_u32_e32 v9, vcc, -1, v7, vcc
	flat_load_dwordx4 v[38:41], v[8:9] nt
	v_add_co_u32_e32 v8, vcc, 0xffffe400, v6
	v_mul_f32_e32 v86, v63, v63
	s_nop 0
	v_addc_co_u32_e32 v9, vcc, -1, v7, vcc
	flat_load_dwordx4 v[34:37], v[8:9] nt
	v_add_co_u32_e32 v8, vcc, 0xffffe800, v6
	v_mul_f32_e32 v87, v65, v65
	s_nop 0
	v_addc_co_u32_e32 v9, vcc, -1, v7, vcc
	flat_load_dwordx4 v[26:29], v[8:9] nt
	v_add_co_u32_e32 v8, vcc, 0xffffec00, v6
	v_add_f32_e32 v74, v74, v75
	s_nop 0
	v_addc_co_u32_e32 v9, vcc, -1, v7, vcc
	flat_load_dwordx4 v[22:25], v[8:9] nt
	v_add_co_u32_e32 v8, vcc, 0xfffff000, v6
	v_fmac_f32_e32 v86, v62, v62
	s_nop 0
	v_addc_co_u32_e32 v9, vcc, -1, v7, vcc
	flat_load_dwordx4 v[18:21], v[8:9] nt
	v_add_co_u32_e32 v8, vcc, 0xfffff400, v6
	v_fmac_f32_e32 v87, v64, v64
	s_nop 0
	v_addc_co_u32_e32 v9, vcc, -1, v7, vcc
	flat_load_dwordx4 v[14:17], v[8:9] nt
	v_add_co_u32_e32 v8, vcc, 0xfffff800, v6
	v_mul_f32_e32 v75, v59, v59
	s_nop 0
	v_addc_co_u32_e32 v9, vcc, -1, v7, vcc
	v_add_co_u32_e32 v6, vcc, 0xfffffc00, v6
	flat_load_dwordx4 v[10:13], v[8:9] nt
	s_nop 0
	v_addc_co_u32_e32 v7, vcc, -1, v7, vcc
	flat_load_dwordx4 v[6:9], v[6:7] nt
	v_mul_f32_e32 v88, v61, v61
	v_add_f32_e32 v86, v86, v87
	v_fmac_f32_e32 v75, v58, v58
	v_fmac_f32_e32 v88, v60, v60
	v_mul_f32_e32 v87, v55, v55
	v_mul_f32_e32 v89, v57, v57
	v_add_f32_e32 v74, v74, v86
	v_add_f32_e32 v75, v75, v88
	v_fmac_f32_e32 v87, v54, v54
	v_fmac_f32_e32 v89, v56, v56
	v_add_f32_e32 v74, v74, v75
	v_add_f32_e32 v75, v87, v89
	v_add_f32_e32 v74, v74, v75
	v_max_f32_e64 v90, |v64|, |v64|
	s_waitcnt vmcnt(0) lgkmcnt(0)
	v_mul_f32_e32 v86, v51, v51
	v_mul_f32_e32 v88, v53, v53
	v_fmac_f32_e32 v86, v50, v50
	v_fmac_f32_e32 v88, v52, v52
	v_add_f32_e32 v75, v86, v88
	v_add_f32_e32 v74, v74, v75
	v_mul_f32_e32 v87, v47, v47
	v_mul_f32_e32 v89, v49, v49
	v_fmac_f32_e32 v87, v46, v46
	v_fmac_f32_e32 v89, v48, v48
	v_add_f32_e32 v75, v87, v89
	v_add_f32_e32 v74, v74, v75
	v_mul_f32_e32 v86, v43, v43
	v_mul_f32_e32 v88, v45, v45
	v_fmac_f32_e32 v86, v42, v42
	v_fmac_f32_e32 v88, v44, v44
	v_add_f32_e32 v75, v86, v88
	v_add_f32_e32 v74, v74, v75
	v_mul_f32_e32 v87, v39, v39
	v_mul_f32_e32 v89, v41, v41
	v_fmac_f32_e32 v87, v38, v38
	v_fmac_f32_e32 v89, v40, v40
	v_add_f32_e32 v75, v87, v89
	v_add_f32_e32 v74, v74, v75
	v_mul_f32_e32 v86, v35, v35
	v_mul_f32_e32 v88, v37, v37
	v_fmac_f32_e32 v86, v34, v34
	v_fmac_f32_e32 v88, v36, v36
	v_add_f32_e32 v75, v86, v88
	v_add_f32_e32 v74, v74, v75
	v_mul_f32_e32 v87, v27, v27
	v_mul_f32_e32 v89, v29, v29
	v_fmac_f32_e32 v87, v26, v26
	v_fmac_f32_e32 v89, v28, v28
	v_add_f32_e32 v75, v87, v89
	v_add_f32_e32 v74, v74, v75
	v_mul_f32_e32 v86, v23, v23
	v_mul_f32_e32 v88, v25, v25
	v_fmac_f32_e32 v86, v22, v22
	v_fmac_f32_e32 v88, v24, v24
	v_add_f32_e32 v75, v86, v88
	v_add_f32_e32 v74, v74, v75
	v_mul_f32_e32 v87, v19, v19
	v_mul_f32_e32 v89, v21, v21
	v_fmac_f32_e32 v87, v18, v18
	v_fmac_f32_e32 v89, v20, v20
	v_add_f32_e32 v75, v87, v89
	v_add_f32_e32 v74, v74, v75
	v_mul_f32_e32 v86, v15, v15
	v_mul_f32_e32 v88, v17, v17
	v_fmac_f32_e32 v86, v14, v14
	v_fmac_f32_e32 v88, v16, v16
	v_add_f32_e32 v75, v86, v88
	v_add_f32_e32 v74, v74, v75
	v_mul_f32_e32 v87, v11, v11
	v_mul_f32_e32 v89, v13, v13
	v_fmac_f32_e32 v87, v10, v10
	v_fmac_f32_e32 v89, v12, v12
	v_mul_f32_e32 v86, v7, v7
	v_mul_f32_e32 v88, v9, v9
	v_add_f32_e32 v75, v87, v89
	v_fmac_f32_e32 v86, v6, v6
	v_fmac_f32_e32 v88, v8, v8
	v_add_f32_e32 v74, v74, v75
	v_add_f32_e32 v75, v86, v88
	v_max_f32_e64 v87, |v31|, |v31|
	v_max_f32_e64 v88, |v30|, |v30|
	v_max_f32_e32 v87, v88, v87
	v_max_f32_e64 v88, |v33|, |v33|
	v_max_f32_e64 v89, |v32|, |v32|
	v_max_f32_e32 v88, v89, v88
	v_max3_f32 v87, v87, 0, v88
	v_max_f32_e64 v88, |v63|, |v63|
	v_max_f32_e64 v89, |v62|, |v62|
	v_max_f32_e32 v88, v89, v88
	v_max_f32_e64 v89, |v65|, |v65|
	v_max_f32_e32 v89, v90, v89
	v_max3_f32 v87, v87, v88, v89
	v_max_f32_e64 v88, |v59|, |v59|
	v_max_f32_e64 v89, |v58|, |v58|
	v_max_f32_e32 v88, v89, v88
	v_max_f32_e64 v89, |v61|, |v61|
	v_max_f32_e64 v90, |v60|, |v60|
	v_max_f32_e32 v89, v90, v89
	v_max3_f32 v87, v87, v88, v89
	v_max_f32_e64 v88, |v55|, |v55|
	v_max_f32_e64 v89, |v54|, |v54|
	v_max_f32_e32 v88, v89, v88
	v_max_f32_e64 v89, |v57|, |v57|
	v_max_f32_e64 v90, |v56|, |v56|
	v_max_f32_e32 v89, v90, v89
	v_max3_f32 v87, v87, v88, v89
	v_max_f32_e64 v88, |v51|, |v51|
; #define in_x ARGP(0)
; __device__ __forceinline__ float wave_sum(float v) {
; #pragma unroll
;     for (int o = 1; o < 64; o <<= 1) v += __shfl_xor(v, o);
;     return v;
; }
; __global__ void __launch_bounds__(NWAVES * 64, 2) fwd(Args args) {
;     ...
;             const f32x4* xr = (const f32x4*)(in_x + (size_t)m * DM) + F.lane; f32x4 v[16]; float s2 = 0.f;
; #pragma unroll
;             for (int j2 = 0; j2 < 16; ++j2) { v[j2] = __builtin_nontemporal_load(xr + 64 * j2); s2 += (v[j2][0] * v[j2][0] + v[j2][1] * v[j2][1]) + (v[j2][2] * v[j2][2] + v[j2][3] * v[j2][3]); }
;             const float rs = 1.0f / sqrtf(wave_sum(s2) * (1.0f / DM) + EPS);
;             float mx = 0.f;
; #pragma unroll
;             for (int j2 = 0; j2 < 16; ++j2) mx = fmaxf(fmaxf(mx, fmaxf(fabsf(v[j2][0]), fabsf(v[j2][1]))), fmaxf(fabsf(v[j2][2]), fabsf(v[j2][3])));
; #pragma unroll
;             for (int o = 1; o < 64; o <<= 1) mx = fmaxf(mx, __shfl_xor(mx, o));
;             const float step = fmaxf(mx, 1e-30f) * (1.0f / 127.0f), inv = 1.0f / step;
;             if (F.lane == 0) { rstd_x[m] = rs; rowq[m] = rs * step; }
	v_max_f32_e64 v89, |v50|, |v50|
	v_max_f32_e32 v88, v89, v88
	v_max_f32_e64 v89, |v53|, |v53|
	v_max_f32_e64 v90, |v52|, |v52|
	v_max_f32_e32 v89, v90, v89
	v_max3_f32 v87, v87, v88, v89
	v_max_f32_e64 v88, |v47|, |v47|
	v_max_f32_e64 v89, |v46|, |v46|
	v_max_f32_e32 v88, v89, v88
	v_max_f32_e64 v89, |v49|, |v49|
	v_max_f32_e64 v90, |v48|, |v48|
	v_max_f32_e32 v89, v90, v89
	v_max3_f32 v87, v87, v88, v89
	v_max_f32_e64 v88, |v43|, |v43|
	v_max_f32_e64 v89, |v42|, |v42|
	v_max_f32_e32 v88, v89, v88
	v_max_f32_e64 v89, |v45|, |v45|
	v_max_f32_e64 v90, |v44|, |v44|
	v_max_f32_e32 v89, v90, v89
	v_max3_f32 v87, v87, v88, v89
	v_max_f32_e64 v88, |v39|, |v39|
	v_max_f32_e64 v89, |v38|, |v38|
	v_max_f32_e32 v88, v89, v88
	v_max_f32_e64 v89, |v41|, |v41|
	v_max_f32_e64 v90, |v40|, |v40|
	v_max_f32_e32 v89, v90, v89
	v_max3_f32 v87, v87, v88, v89
	v_max_f32_e64 v88, |v35|, |v35|
	v_max_f32_e64 v89, |v34|, |v34|
	v_max_f32_e32 v88, v89, v88
	v_max_f32_e64 v89, |v37|, |v37|
	v_max_f32_e64 v90, |v36|, |v36|
	v_max_f32_e32 v89, v90, v89
	v_max3_f32 v87, v87, v88, v89
	v_max_f32_e64 v88, |v27|, |v27|
	v_max_f32_e64 v89, |v26|, |v26|
	v_max_f32_e32 v88, v89, v88
	v_max_f32_e64 v89, |v29|, |v29|
	v_max_f32_e64 v90, |v28|, |v28|
	v_max_f32_e32 v89, v90, v89
	v_max3_f32 v87, v87, v88, v89
	v_max_f32_e64 v88, |v23|, |v23|
	v_max_f32_e64 v89, |v22|, |v22|
	v_max_f32_e32 v88, v89, v88
	v_max_f32_e64 v89, |v25|, |v25|
	v_max_f32_e64 v90, |v24|, |v24|
	v_max_f32_e32 v89, v90, v89
	v_max3_f32 v87, v87, v88, v89
	v_max_f32_e64 v88, |v19|, |v19|
	v_max_f32_e64 v89, |v18|, |v18|
	v_max_f32_e32 v88, v89, v88
	v_max_f32_e64 v89, |v21|, |v21|
	v_max_f32_e64 v90, |v20|, |v20|
	v_max_f32_e32 v89, v90, v89
	v_max3_f32 v87, v87, v88, v89
	v_max_f32_e64 v88, |v15|, |v15|
	v_max_f32_e64 v89, |v14|, |v14|
	v_max_f32_e32 v88, v89, v88
	v_max_f32_e64 v89, |v17|, |v17|
	v_max_f32_e64 v90, |v16|, |v16|
	v_max_f32_e32 v89, v90, v89
	v_max3_f32 v87, v87, v88, v89
	v_max_f32_e64 v88, |v11|, |v11|
	v_max_f32_e64 v89, |v10|, |v10|
	v_max_f32_e32 v88, v89, v88
	v_max_f32_e64 v89, |v13|, |v13|
	v_max_f32_e64 v90, |v12|, |v12|
	v_max_f32_e32 v89, v90, v89
	v_max3_f32 v87, v87, v88, v89
	v_max_f32_e64 v88, |v7|, |v7|
	v_max_f32_e64 v89, |v6|, |v6|
	v_max_f32_e32 v88, v89, v88
	v_max_f32_e64 v89, |v9|, |v9|
	v_max_f32_e64 v90, |v8|, |v8|
	v_max_f32_e32 v89, v90, v89
	v_max3_f32 v87, v87, v88, v89
	v_max_f32_e64 v88, |v3|, |v3|
	v_max_f32_e64 v89, |v2|, |v2|
	v_max_f32_e32 v88, v89, v88
	v_max_f32_e64 v89, |v5|, |v5|
	v_max_f32_e64 v90, |v4|, |v4|
	v_max_f32_e32 v89, v90, v89
	v_max3_f32 v87, v87, v88, v89
	s_nop 1
	v_mov_b32_dpp v88, v87 quad_perm:[1,0,3,2] row_mask:0xf bank_mask:0xf
	v_add_f32_e32 v74, v74, v75
	v_mul_f32_e32 v75, v3, v3
	v_mul_f32_e32 v86, v5, v5
	v_fmac_f32_e32 v75, v2, v2
	v_fmac_f32_e32 v86, v4, v4
	v_add_f32_e32 v75, v75, v86
	s_waitcnt lgkmcnt(0)
	v_max_f32_e32 v86, v88, v88
	v_add_f32_e32 v74, v74, v75
	v_max_f32_e32 v86, v87, v86
	s_nop 1
	v_mov_b32_dpp v75, v74 quad_perm:[1,0,3,2] row_mask:0xf bank_mask:0xf
	s_nop 1
	v_mov_b32_dpp v87, v86 quad_perm:[2,3,0,1] row_mask:0xf bank_mask:0xf
	s_waitcnt lgkmcnt(0)
	v_add_f32_e32 v74, v74, v75
	s_waitcnt lgkmcnt(0)
	v_max_f32_e32 v87, v87, v87
	s_nop 1
	v_mov_b32_dpp v75, v74 quad_perm:[2,3,0,1] row_mask:0xf bank_mask:0xf
	v_max_f32_e32 v86, v86, v87
	s_nop 1
	v_mov_b32_dpp v87, v86 row_half_mirror row_mask:0xf bank_mask:0xf
	s_waitcnt lgkmcnt(0)
	v_add_f32_e32 v74, v74, v75
	s_nop 1
	v_mov_b32_dpp v75, v74 row_half_mirror row_mask:0xf bank_mask:0xf
	s_waitcnt lgkmcnt(0)
	v_max_f32_e32 v87, v87, v87
	v_max_f32_e32 v86, v86, v87
	s_nop 1
	v_mov_b32_dpp v87, v86 row_mirror row_mask:0xf bank_mask:0xf
	s_waitcnt lgkmcnt(0)
	v_add_f32_e32 v74, v74, v75
	s_nop 1
	v_mov_b32_dpp v75, v74 row_mirror row_mask:0xf bank_mask:0xf
	s_waitcnt lgkmcnt(0)
	v_max_f32_e32 v87, v87, v87
	v_max_f32_e32 v86, v86, v87
	s_waitcnt lgkmcnt(0)
	v_add_f32_e32 v74, v74, v75
	s_waitcnt lgkmcnt(0)
	v_mov_b32_e32 v87, v86
	s_nop 1
	v_permlane16_swap_b32_e32 v87, v86
	s_nop 0
	v_max_f32_e32 v87, v87, v86
	ds_bpermute_b32 v88, v81, v87
	s_waitcnt lgkmcnt(1)
	v_mov_b32_e32 v75, v74
	s_nop 1
	v_permlane16_swap_b32_e32 v75, v74
	s_nop 0
	v_add_f32_e32 v75, v75, v74
	ds_bpermute_b32 v86, v81, v75
	s_waitcnt lgkmcnt(1)
	v_max3_f32 v74, v87, v88, s22
	v_mul_f32_e32 v74, 0x3c010204, v74
	s_and_saveexec_b64 s[16:17], s[4:5]
	s_cbranch_execz .LBB0_72
	s_waitcnt lgkmcnt(0)
	v_add_f32_e32 v75, v75, v86
	v_fmamk_f32 v75, v75, 0x39800000, v82
	v_mul_f32_e32 v86, 0x4f800000, v75
	v_cmp_gt_f32_e32 vcc, s23, v75
	s_nop 1
	v_cndmask_b32_e32 v75, v75, v86, vcc
	v_sqrt_f32_e32 v86, v75
	s_nop 0
	v_add_u32_e32 v87, -1, v86
	v_fma_f32 v89, -v87, v86, v75
	v_add_u32_e32 v88, 1, v86
	v_cmp_ge_f32_e64 s[6:7], 0, v89
	s_nop 1
	v_cndmask_b32_e64 v87, v86, v87, s[6:7]
	v_fma_f32 v86, -v88, v86, v75
	v_cmp_lt_f32_e64 s[6:7], 0, v86
	s_nop 1
	v_cndmask_b32_e64 v86, v87, v88, s[6:7]
	v_mul_f32_e32 v87, 0x37800000, v86
	v_cndmask_b32_e32 v86, v86, v87, vcc
	v_cmp_class_f32_e32 vcc, v75, v83
	s_nop 1
	v_cndmask_b32_e32 v75, v86, v75, vcc
	v_div_scale_f32 v86, s[6:7], v75, v75, 1.0
	v_rcp_f32_e32 v87, v86
	s_add_u32 s6, s78, s10
	s_addc_u32 s7, s79, s11
	v_fma_f32 v88, -v86, v87, 1.0
	v_fmac_f32_e32 v87, v88, v87
	v_div_scale_f32 v88, vcc, 1.0, v75, 1.0
	v_mul_f32_e32 v89, v88, v87
	v_fma_f32 v90, -v86, v89, v88
	v_fmac_f32_e32 v89, v90, v87
	v_fma_f32 v86, -v86, v89, v88
	v_div_fmas_f32 v86, v86, v87, v89
	v_div_fixup_f32 v75, v86, v75, 1.0
	v_mul_f32_e32 v86, v75, v74
	global_store_dword v84, v75, s[6:7]
	global_store_dword v85, v86, s[6:7]
	s_branch .LBB0_72

; #define in_mem ARGP(1)
; __global__ void __launch_bounds__(NWAVES * 64, 2) fwd(Args args) {
;     ...
;         for (int m = gw; m < TM; m += NGW) {
;             const f32x4* xr = (const f32x4*)(in_mem + (size_t)m * DM) + F.lane; f32x4 v[16]; float s2 = 0.f;
; #pragma unroll
;             for (int j = 0; j < 16; ++j) { v[j] = xr[64 * j]; s2 += (v[j][0] * v[j][0] + v[j][1] * v[j][1]) + (v[j][2] * v[j][2] + v[j][3] * v[j][3]); }
;             const float rs = 1.0f / sqrtf(wave_sum(s2) * (1.0f / DM) + EPS);
.LBB0_77:
	flat_load_dwordx2 v[2:3], v[56:57] offset:8 sc0 sc1
	s_waitcnt vmcnt(0)
	v_add_co_u32_e32 v58, vcc, s3, v52
	s_add_i32 s14, s14, s68
	s_nop 0
	v_addc_co_u32_e32 v59, vcc, -1, v53, vcc
	s_cmpk_gt_i32 s14, 0x3ff
	s_waitcnt lgkmcnt(0)
	v_lshl_add_u64 v[6:7], v[2:3], 0, v[54:55]
	v_add_co_u32_e32 v8, vcc, 0xffffc400, v6
	v_lshl_add_u64 v[54:55], v[54:55], 0, s[8:9]
	s_nop 0
	v_addc_co_u32_e32 v9, vcc, -1, v7, vcc
	v_add_co_u32_e32 v10, vcc, 0xffffc800, v6
	s_nop 1
	v_addc_co_u32_e32 v11, vcc, -1, v7, vcc
	v_add_co_u32_e32 v12, vcc, 0xffffcc00, v6
	flat_load_dwordx4 v[68:71], v[8:9]
	flat_load_dwordx4 v[2:5], v[6:7]
	flat_load_dwordx4 v[72:75], v[10:11]
	v_addc_co_u32_e32 v13, vcc, -1, v7, vcc
	v_add_co_u32_e32 v8, vcc, 0xffffd000, v6
	flat_load_dwordx4 v[76:79], v[12:13]
	s_nop 0
	v_addc_co_u32_e32 v9, vcc, -1, v7, vcc
	v_add_co_u32_e32 v10, vcc, 0xffffd400, v6
	s_waitcnt vmcnt(0) lgkmcnt(0)
	v_mul_f32_e32 v90, v73, v73
	v_addc_co_u32_e32 v11, vcc, -1, v7, vcc
	v_add_co_u32_e32 v12, vcc, 0xffffd800, v6
	flat_load_dwordx4 v[80:83], v[8:9]
	flat_load_dwordx4 v[46:49], v[10:11]
	v_addc_co_u32_e32 v13, vcc, -1, v7, vcc
	v_add_co_u32_e32 v8, vcc, 0xffffdc00, v6
	v_mul_f32_e32 v91, v75, v75
	s_nop 0
	v_addc_co_u32_e32 v9, vcc, -1, v7, vcc
	v_add_co_u32_e32 v10, vcc, 0xffffe000, v6
	flat_load_dwordx4 v[42:45], v[12:13]
	flat_load_dwordx4 v[38:41], v[8:9]
	v_addc_co_u32_e32 v11, vcc, -1, v7, vcc
	v_add_co_u32_e32 v8, vcc, 0xffffe400, v6
	v_fmac_f32_e32 v90, v72, v72
	s_nop 0
	v_addc_co_u32_e32 v9, vcc, -1, v7, vcc
	v_add_co_u32_e32 v12, vcc, 0xffffe800, v6
	flat_load_dwordx4 v[34:37], v[10:11]
	flat_load_dwordx4 v[30:33], v[8:9]
	v_addc_co_u32_e32 v13, vcc, -1, v7, vcc
	v_add_co_u32_e32 v8, vcc, 0xffffec00, v6
	v_fmac_f32_e32 v91, v74, v74
	s_nop 0
	v_addc_co_u32_e32 v9, vcc, -1, v7, vcc
	v_add_co_u32_e32 v10, vcc, 0xfffff000, v6
	flat_load_dwordx4 v[26:29], v[12:13]
	flat_load_dwordx4 v[22:25], v[8:9]
	v_addc_co_u32_e32 v11, vcc, -1, v7, vcc
	v_add_co_u32_e32 v8, vcc, 0xfffff400, v6
	v_mul_f32_e32 v92, v79, v79
	s_nop 0
	v_addc_co_u32_e32 v9, vcc, -1, v7, vcc
	v_add_co_u32_e32 v84, vcc, 0xfffff800, v6
	flat_load_dwordx4 v[18:21], v[10:11]
	flat_load_dwordx4 v[14:17], v[8:9]
	v_addc_co_u32_e32 v85, vcc, -1, v7, vcc
	v_add_co_u32_e32 v86, vcc, 0xfffffc00, v6
	v_fmac_f32_e32 v92, v78, v78
	s_nop 0
	v_addc_co_u32_e32 v87, vcc, -1, v7, vcc
	flat_load_dwordx4 v[10:13], v[84:85]
	flat_load_dwordx4 v[6:9], v[86:87]
	flat_load_dwordx2 v[88:89], v[56:57] offset:72 sc0 sc1
	s_waitcnt vmcnt(0)
	v_mul_f32_e32 v84, v69, v69
	v_mul_f32_e32 v85, v71, v71
	v_mul_f32_e32 v86, v3, v3
	v_mul_f32_e32 v87, v5, v5
	v_fmac_f32_e32 v84, v68, v68
	v_fmac_f32_e32 v85, v70, v70
	v_fmac_f32_e32 v86, v2, v2
	v_fmac_f32_e32 v87, v4, v4
	v_add_f32_e32 v84, v84, v85
	v_mul_f32_e32 v85, v77, v77
	v_add_f32_e32 v93, v86, v87
	v_add_f32_e32 v86, v90, v91
	v_fmac_f32_e32 v85, v76, v76
	v_add_f32_e32 v84, v84, v86
	v_add_f32_e32 v85, v85, v92
	v_add_f32_e32 v84, v84, v85
	s_waitcnt lgkmcnt(0)
	v_mul_f32_e32 v87, v81, v81
	v_mul_f32_e32 v90, v83, v83
	v_fmac_f32_e32 v87, v80, v80
	v_fmac_f32_e32 v90, v82, v82
	v_mul_f32_e32 v86, v47, v47
	v_mul_f32_e32 v91, v49, v49
	v_add_f32_e32 v85, v87, v90
	v_fmac_f32_e32 v86, v46, v46
	v_fmac_f32_e32 v91, v48, v48
	v_add_f32_e32 v84, v84, v85
	v_mul_f32_e32 v87, v43, v43
	v_mul_f32_e32 v90, v45, v45
	v_add_f32_e32 v85, v86, v91
	v_fmac_f32_e32 v87, v42, v42
	v_fmac_f32_e32 v90, v44, v44
	v_mul_f32_e32 v86, v39, v39
	v_mul_f32_e32 v91, v41, v41
	v_add_f32_e32 v84, v84, v85
	v_add_f32_e32 v85, v87, v90
	v_fmac_f32_e32 v86, v38, v38
	v_fmac_f32_e32 v91, v40, v40
	v_mul_f32_e32 v87, v35, v35
	v_mul_f32_e32 v90, v37, v37
	v_add_f32_e32 v84, v84, v85
	v_add_f32_e32 v85, v86, v91
	v_fmac_f32_e32 v87, v34, v34
	v_fmac_f32_e32 v90, v36, v36
	v_mul_f32_e32 v86, v31, v31
	v_mul_f32_e32 v91, v33, v33
	v_add_f32_e32 v84, v84, v85
	v_add_f32_e32 v85, v87, v90
	v_fmac_f32_e32 v86, v30, v30
	v_fmac_f32_e32 v91, v32, v32
	v_mul_f32_e32 v87, v27, v27
	v_mul_f32_e32 v90, v29, v29
	v_add_f32_e32 v84, v84, v85
	v_add_f32_e32 v85, v86, v91
	v_fmac_f32_e32 v87, v26, v26
	v_fmac_f32_e32 v90, v28, v28
	v_mul_f32_e32 v86, v23, v23
	v_mul_f32_e32 v91, v25, v25
	v_add_f32_e32 v84, v84, v85
	v_add_f32_e32 v85, v87, v90
	v_fmac_f32_e32 v86, v22, v22
	v_fmac_f32_e32 v91, v24, v24
	v_mul_f32_e32 v87, v19, v19
	v_mul_f32_e32 v90, v21, v21
	v_add_f32_e32 v84, v84, v85
	v_add_f32_e32 v85, v86, v91
	v_fmac_f32_e32 v87, v18, v18
	v_fmac_f32_e32 v90, v20, v20
	v_mul_f32_e32 v86, v15, v15
	v_mul_f32_e32 v91, v17, v17
	v_add_f32_e32 v84, v84, v85
	v_add_f32_e32 v85, v87, v90
	v_fmac_f32_e32 v86, v14, v14
	v_fmac_f32_e32 v91, v16, v16
	v_mul_f32_e32 v87, v11, v11
	v_mul_f32_e32 v90, v13, v13
	v_add_f32_e32 v92, v84, v85
	v_add_f32_e32 v86, v86, v91
	v_fmac_f32_e32 v87, v10, v10
	v_fmac_f32_e32 v90, v12, v12
	v_lshl_add_u64 v[84:85], v[88:89], 0, v[50:51]
	v_add_f32_e32 v88, v92, v86
	v_add_f32_e32 v89, v87, v90
	flat_load_dwordx4 v[84:87], v[84:85]
	v_mul_f32_e32 v91, v7, v7
	v_mul_f32_e32 v94, v9, v9
	v_fmac_f32_e32 v91, v6, v6
	v_fmac_f32_e32 v94, v8, v8
	v_add_f32_e32 v88, v88, v89
	v_add_f32_e32 v89, v91, v94
	v_add_f32_e32 v88, v88, v89
	v_add_f32_e32 v88, v88, v93
	s_nop 1
	v_mov_b32_dpp v89, v88 quad_perm:[1,0,3,2] row_mask:0xf bank_mask:0xf
	s_waitcnt lgkmcnt(0)
	v_add_f32_e32 v88, v88, v89
	s_nop 1
	v_mov_b32_dpp v89, v88 quad_perm:[2,3,0,1] row_mask:0xf bank_mask:0xf
	s_waitcnt lgkmcnt(0)
	v_add_f32_e32 v88, v88, v89
	s_nop 1
	v_mov_b32_dpp v89, v88 row_half_mirror row_mask:0xf bank_mask:0xf
	s_waitcnt lgkmcnt(0)
; __device__ __forceinline__ unsigned cvt_pk_bf16(float lo, float hi) { unsigned r; asm volatile("v_cvt_pk_bf16_f32 %0, %1, %2" : "=v"(r) : "v"(lo), "v"(hi)); return r; }
; #define in_mem ARGP(1)
; #define g_mem ARGP(9)
; __device__ __forceinline__ float wave_sum(float v) {
; #pragma unroll
;     for (int o = 1; o < 64; o <<= 1) v += __shfl_xor(v, o);
;     return v;
; }
; __global__ void __launch_bounds__(NWAVES * 64, 2) fwd(Args args) {
;     ...
;         for (int m = gw; m < TM; m += NGW) {
;             const f32x4* xr = (const f32x4*)(in_mem + (size_t)m * DM) + F.lane; f32x4 v[16]; float s2 = 0.f;
; #pragma unroll
;             for (int j = 0; j < 16; ++j) { v[j] = xr[64 * j]; s2 += (v[j][0] * v[j][0] + v[j][1] * v[j][1]) + (v[j][2] * v[j][2] + v[j][3] * v[j][3]); }
;             const float rs = 1.0f / sqrtf(wave_sum(s2) * (1.0f / DM) + EPS);
;             u32x2* o8 = (u32x2*)(memn + (size_t)m * DM) + F.lane;
; #pragma unroll
;             for (int j = 0; j < 16; ++j) { const f32x4 g = *((const f32x4*)g_mem + F.lane + 64 * j); u32x2 w; w.x = cvt_pk_bf16(v[j][0] * rs * g[0], v[j][1] * rs * g[1]); w.y = cvt_pk_bf16(v[j][2] * rs * g[2], v[j][3] * rs * g[3]); o8[64 * j] = w; }
	v_add_f32_e32 v88, v88, v89
	s_nop 1
	v_mov_b32_dpp v89, v88 row_mirror row_mask:0xf bank_mask:0xf
	s_waitcnt lgkmcnt(0)
	v_add_f32_e32 v88, v88, v89
	s_waitcnt lgkmcnt(0)
	v_mov_b32_e32 v89, v88
	s_nop 1
	v_permlane16_swap_b32_e32 v88, v89
	s_nop 0
	v_add_f32_e32 v88, v88, v89
	s_waitcnt lgkmcnt(0)
	v_mov_b32_e32 v89, v88
	s_nop 1
	v_permlane32_swap_b32_e32 v88, v89
	s_nop 0
	v_add_f32_e32 v88, v88, v89
	v_fmamk_f32 v88, v88, 0x39800000, v66
	v_mul_f32_e32 v89, 0x4f800000, v88
	v_cmp_gt_f32_e32 vcc, s10, v88
	s_nop 1
	v_cndmask_b32_e32 v88, v88, v89, vcc
	v_sqrt_f32_e32 v89, v88
	s_nop 0
	v_add_u32_e32 v90, -1, v89
	v_add_u32_e32 v91, 1, v89
	v_fma_f32 v92, -v90, v89, v88
	v_fma_f32 v93, -v91, v89, v88
	v_cmp_ge_f32_e64 s[4:5], 0, v92
	s_nop 1
	v_cndmask_b32_e64 v89, v89, v90, s[4:5]
	v_cmp_lt_f32_e64 s[4:5], 0, v93
	s_nop 1
	v_cndmask_b32_e64 v89, v89, v91, s[4:5]
	v_mul_f32_e32 v90, 0x37800000, v89
	v_cndmask_b32_e32 v89, v89, v90, vcc
	v_cmp_class_f32_e32 vcc, v88, v67
	s_nop 1
	v_cndmask_b32_e32 v88, v89, v88, vcc
	v_div_scale_f32 v89, s[4:5], v88, v88, 1.0
	v_rcp_f32_e32 v91, v89
	v_div_scale_f32 v90, vcc, 1.0, v88, 1.0
	v_fma_f32 v92, -v89, v91, 1.0
	v_fmac_f32_e32 v91, v92, v91
	v_mul_f32_e32 v92, v90, v91
	v_fma_f32 v93, -v89, v92, v90
	v_fmac_f32_e32 v92, v93, v91
	v_fma_f32 v89, -v89, v92, v90
	v_div_fmas_f32 v89, v89, v91, v92
	v_div_fixup_f32 v88, v89, v88, 1.0
	v_mul_f32_e32 v68, v88, v68
	v_mul_f32_e32 v69, v88, v69
	v_mul_f32_e32 v70, v88, v70
	v_mul_f32_e32 v71, v88, v71
	v_mul_f32_e32 v89, v88, v46
	v_mul_f32_e32 v90, v88, v47
	s_waitcnt vmcnt(0)
	v_mul_f32_e32 v46, v84, v68
	v_mul_f32_e32 v47, v85, v69
	v_mul_f32_e32 v91, v88, v48
	v_mul_f32_e32 v92, v88, v49
	v_mul_f32_e32 v48, v86, v70
	v_mul_f32_e32 v49, v87, v71
	v_cvt_pk_bf16_f32 v46, v46, v47
	v_cvt_pk_bf16_f32 v47, v48, v49
	global_store_dwordx2 v[58:59], v[46:47], off offset:-3584
	flat_load_dwordx2 v[46:47], v[56:57] offset:72 sc0 sc1
	s_waitcnt vmcnt(0)
	v_mul_f32_e32 v72, v88, v72
	v_mul_f32_e32 v73, v88, v73
	v_mul_f32_e32 v74, v88, v74
	v_mul_f32_e32 v75, v88, v75
	v_mul_f32_e32 v76, v88, v76
	v_mul_f32_e32 v77, v88, v77
	v_mul_f32_e32 v78, v88, v78
	v_mul_f32_e32 v79, v88, v79
	v_mul_f32_e32 v80, v88, v80
	v_mul_f32_e32 v81, v88, v81
	v_mul_f32_e32 v82, v88, v82
	v_mul_f32_e32 v83, v88, v83
	v_mul_f32_e32 v42, v88, v42
	v_mul_f32_e32 v43, v88, v43
	v_mul_f32_e32 v44, v88, v44
	v_mul_f32_e32 v45, v88, v45
	v_mul_f32_e32 v38, v88, v38
	v_mul_f32_e32 v39, v88, v39
	v_mul_f32_e32 v40, v88, v40
	v_mul_f32_e32 v41, v88, v41
	v_mul_f32_e32 v34, v88, v34
	v_mul_f32_e32 v35, v88, v35
	v_mul_f32_e32 v36, v88, v36
	v_mul_f32_e32 v37, v88, v37
	v_mul_f32_e32 v30, v88, v30
	v_mul_f32_e32 v31, v88, v31
	v_mul_f32_e32 v32, v88, v32
	v_mul_f32_e32 v33, v88, v33
	v_mul_f32_e32 v26, v88, v26
	v_mul_f32_e32 v27, v88, v27
	v_mul_f32_e32 v28, v88, v28
	v_mul_f32_e32 v29, v88, v29
	v_mul_f32_e32 v22, v88, v22
	v_mul_f32_e32 v23, v88, v23
	v_mul_f32_e32 v24, v88, v24
	v_mul_f32_e32 v25, v88, v25
	v_mul_f32_e32 v18, v88, v18
	v_mul_f32_e32 v19, v88, v19
	v_mul_f32_e32 v20, v88, v20
	v_mul_f32_e32 v21, v88, v21
	v_mul_f32_e32 v14, v88, v14
	v_mul_f32_e32 v15, v88, v15
	v_mul_f32_e32 v16, v88, v16
	v_mul_f32_e32 v17, v88, v17
	v_mul_f32_e32 v10, v88, v10
	v_mul_f32_e32 v11, v88, v11
	v_mul_f32_e32 v12, v88, v12
	v_mul_f32_e32 v13, v88, v13
	v_mul_f32_e32 v6, v88, v6
	v_mul_f32_e32 v7, v88, v7
	v_mul_f32_e32 v8, v88, v8
	v_mul_f32_e32 v9, v88, v9
	v_mul_f32_e32 v2, v88, v2
	v_mul_f32_e32 v3, v88, v3
	v_mul_f32_e32 v4, v88, v4
	v_mul_f32_e32 v5, v88, v5
	s_waitcnt lgkmcnt(0)
	v_lshl_add_u64 v[46:47], v[46:47], 0, v[50:51]
	flat_load_dwordx4 v[46:49], v[46:47] offset:1024
	s_waitcnt vmcnt(0) lgkmcnt(0)
	v_mul_f32_e32 v46, v46, v72
	v_mul_f32_e32 v47, v47, v73
	v_mul_f32_e32 v48, v48, v74
	v_mul_f32_e32 v49, v49, v75
	v_cvt_pk_bf16_f32 v46, v46, v47
	v_cvt_pk_bf16_f32 v47, v48, v49
	global_store_dwordx2 v[58:59], v[46:47], off offset:-3072
	flat_load_dwordx2 v[46:47], v[56:57] offset:72 sc0 sc1
	s_waitcnt vmcnt(0) lgkmcnt(0)
	v_lshl_add_u64 v[46:47], v[46:47], 0, v[50:51]
	flat_load_dwordx4 v[46:49], v[46:47] offset:2048
	s_waitcnt vmcnt(0) lgkmcnt(0)
	v_mul_f32_e32 v46, v46, v76
	v_mul_f32_e32 v47, v47, v77
	v_mul_f32_e32 v48, v48, v78
	v_mul_f32_e32 v49, v49, v79
	v_cvt_pk_bf16_f32 v46, v46, v47
	v_cvt_pk_bf16_f32 v47, v48, v49
	global_store_dwordx2 v[58:59], v[46:47], off offset:-2560
	flat_load_dwordx2 v[46:47], v[56:57] offset:72 sc0 sc1
	s_waitcnt vmcnt(0) lgkmcnt(0)
	v_lshl_add_u64 v[46:47], v[46:47], 0, v[50:51]
	flat_load_dwordx4 v[46:49], v[46:47] offset:3072
	s_waitcnt vmcnt(0) lgkmcnt(0)
	v_mul_f32_e32 v46, v46, v80
	v_mul_f32_e32 v47, v47, v81
	v_mul_f32_e32 v48, v48, v82
	v_mul_f32_e32 v49, v49, v83
	v_cvt_pk_bf16_f32 v46, v46, v47
	v_cvt_pk_bf16_f32 v47, v48, v49
	global_store_dwordx2 v[58:59], v[46:47], off offset:-2048
	flat_load_dwordx2 v[46:47], v[56:57] offset:72 sc0 sc1
	s_waitcnt vmcnt(0) lgkmcnt(0)
	v_lshl_add_u64 v[46:47], v[46:47], 0, v[50:51]
	v_add_co_u32_e32 v46, vcc, s11, v46
	s_nop 1
	v_addc_co_u32_e32 v47, vcc, 0, v47, vcc
	flat_load_dwordx4 v[46:49], v[46:47]
	s_waitcnt vmcnt(0) lgkmcnt(0)
	v_mul_f32_e32 v46, v46, v89
	v_mul_f32_e32 v47, v47, v90
	v_mul_f32_e32 v48, v48, v91
	v_mul_f32_e32 v49, v49, v92
	v_cvt_pk_bf16_f32 v46, v46, v47
	v_cvt_pk_bf16_f32 v47, v48, v49
	global_store_dwordx2 v[58:59], v[46:47], off offset:-1536
	flat_load_dwordx2 v[46:47], v[56:57] offset:72 sc0 sc1
	s_waitcnt vmcnt(0) lgkmcnt(0)
	v_lshl_add_u64 v[46:47], v[46:47], 0, v[50:51]
	v_add_co_u32_e32 v46, vcc, s11, v46
	s_nop 1
	v_addc_co_u32_e32 v47, vcc, 0, v47, vcc
	flat_load_dwordx4 v[46:49], v[46:47] offset:1024
	s_waitcnt vmcnt(0) lgkmcnt(0)
; __device__ __forceinline__ unsigned cvt_pk_bf16(float lo, float hi) { unsigned r; asm volatile("v_cvt_pk_bf16_f32 %0, %1, %2" : "=v"(r) : "v"(lo), "v"(hi)); return r; }
; #define g_mem ARGP(9)
; __global__ void __launch_bounds__(NWAVES * 64, 2) fwd(Args args) {
;     ...
;             u32x2* o8 = (u32x2*)(memn + (size_t)m * DM) + F.lane;
; #pragma unroll
;             for (int j = 0; j < 16; ++j) { const f32x4 g = *((const f32x4*)g_mem + F.lane + 64 * j); u32x2 w; w.x = cvt_pk_bf16(v[j][0] * rs * g[0], v[j][1] * rs * g[1]); w.y = cvt_pk_bf16(v[j][2] * rs * g[2], v[j][3] * rs * g[3]); o8[64 * j] = w; }
	v_mul_f32_e32 v42, v46, v42
	v_mul_f32_e32 v43, v47, v43
	v_mul_f32_e32 v44, v48, v44
	v_mul_f32_e32 v45, v49, v45
	v_cvt_pk_bf16_f32 v42, v42, v43
	v_cvt_pk_bf16_f32 v43, v44, v45
	global_store_dwordx2 v[58:59], v[42:43], off offset:-1024
	flat_load_dwordx2 v[42:43], v[56:57] offset:72 sc0 sc1
	s_waitcnt vmcnt(0) lgkmcnt(0)
	v_lshl_add_u64 v[42:43], v[42:43], 0, v[50:51]
	v_add_co_u32_e32 v42, vcc, s11, v42
	s_nop 1
	v_addc_co_u32_e32 v43, vcc, 0, v43, vcc
	flat_load_dwordx4 v[42:45], v[42:43] offset:2048
	s_waitcnt vmcnt(0) lgkmcnt(0)
	v_mul_f32_e32 v38, v42, v38
	v_mul_f32_e32 v39, v43, v39
	v_mul_f32_e32 v40, v44, v40
	v_mul_f32_e32 v41, v45, v41
	v_cvt_pk_bf16_f32 v38, v38, v39
	v_cvt_pk_bf16_f32 v39, v40, v41
	global_store_dwordx2 v[58:59], v[38:39], off offset:-512
	flat_load_dwordx2 v[38:39], v[56:57] offset:72 sc0 sc1
	s_waitcnt vmcnt(0) lgkmcnt(0)
	v_lshl_add_u64 v[38:39], v[38:39], 0, v[50:51]
	v_add_co_u32_e32 v38, vcc, s11, v38
	s_nop 1
	v_addc_co_u32_e32 v39, vcc, 0, v39, vcc
	flat_load_dwordx4 v[38:41], v[38:39] offset:3072
	s_waitcnt vmcnt(0) lgkmcnt(0)
	v_mul_f32_e32 v34, v38, v34
	v_mul_f32_e32 v35, v39, v35
	v_mul_f32_e32 v36, v40, v36
	v_mul_f32_e32 v37, v41, v37
	v_cvt_pk_bf16_f32 v34, v34, v35
	v_cvt_pk_bf16_f32 v35, v36, v37
	global_store_dwordx2 v[52:53], v[34:35], off offset:-4096
	flat_load_dwordx2 v[34:35], v[56:57] offset:72 sc0 sc1
	s_waitcnt vmcnt(0) lgkmcnt(0)
	v_lshl_add_u64 v[34:35], v[34:35], 0, v[50:51]
	v_add_co_u32_e32 v34, vcc, s12, v34
	s_nop 1
	v_addc_co_u32_e32 v35, vcc, 0, v35, vcc
	flat_load_dwordx4 v[34:37], v[34:35]
	s_waitcnt vmcnt(0) lgkmcnt(0)
	v_mul_f32_e32 v30, v34, v30
	v_mul_f32_e32 v31, v35, v31
	v_mul_f32_e32 v32, v36, v32
	v_mul_f32_e32 v33, v37, v33
	v_cvt_pk_bf16_f32 v30, v30, v31
	v_cvt_pk_bf16_f32 v31, v32, v33
	global_store_dwordx2 v[52:53], v[30:31], off offset:-3584
	flat_load_dwordx2 v[30:31], v[56:57] offset:72 sc0 sc1
	s_waitcnt vmcnt(0) lgkmcnt(0)
	v_lshl_add_u64 v[30:31], v[30:31], 0, v[50:51]
	v_add_co_u32_e32 v30, vcc, s12, v30
	s_nop 1
	v_addc_co_u32_e32 v31, vcc, 0, v31, vcc
	flat_load_dwordx4 v[30:33], v[30:31] offset:1024
	s_waitcnt vmcnt(0) lgkmcnt(0)
	v_mul_f32_e32 v26, v30, v26
	v_mul_f32_e32 v27, v31, v27
	v_mul_f32_e32 v28, v32, v28
	v_mul_f32_e32 v29, v33, v29
	v_cvt_pk_bf16_f32 v26, v26, v27
	v_cvt_pk_bf16_f32 v27, v28, v29
	global_store_dwordx2 v[52:53], v[26:27], off offset:-3072
	flat_load_dwordx2 v[26:27], v[56:57] offset:72 sc0 sc1
	s_waitcnt vmcnt(0) lgkmcnt(0)
	v_lshl_add_u64 v[26:27], v[26:27], 0, v[50:51]
	v_add_co_u32_e32 v26, vcc, s12, v26
	s_nop 1
	v_addc_co_u32_e32 v27, vcc, 0, v27, vcc
	flat_load_dwordx4 v[26:29], v[26:27] offset:2048
	s_waitcnt vmcnt(0) lgkmcnt(0)
	v_mul_f32_e32 v22, v26, v22
	v_mul_f32_e32 v23, v27, v23
	v_mul_f32_e32 v24, v28, v24
	v_mul_f32_e32 v25, v29, v25
	v_cvt_pk_bf16_f32 v22, v22, v23
	v_cvt_pk_bf16_f32 v23, v24, v25
	global_store_dwordx2 v[52:53], v[22:23], off offset:-2560
	flat_load_dwordx2 v[22:23], v[56:57] offset:72 sc0 sc1
	s_waitcnt vmcnt(0) lgkmcnt(0)
	v_lshl_add_u64 v[22:23], v[22:23], 0, v[50:51]
	v_add_co_u32_e32 v22, vcc, s12, v22
	s_nop 1
	v_addc_co_u32_e32 v23, vcc, 0, v23, vcc
	flat_load_dwordx4 v[22:25], v[22:23] offset:3072
	s_waitcnt vmcnt(0) lgkmcnt(0)
	v_mul_f32_e32 v18, v22, v18
	v_mul_f32_e32 v19, v23, v19
	v_mul_f32_e32 v20, v24, v20
	v_mul_f32_e32 v21, v25, v21
	v_cvt_pk_bf16_f32 v18, v18, v19
	v_cvt_pk_bf16_f32 v19, v20, v21
	global_store_dwordx2 v[52:53], v[18:19], off offset:-2048
	flat_load_dwordx2 v[18:19], v[56:57] offset:72 sc0 sc1
	s_waitcnt vmcnt(0) lgkmcnt(0)
	v_lshl_add_u64 v[18:19], v[18:19], 0, v[50:51]
	v_add_co_u32_e32 v18, vcc, s13, v18
	s_nop 1
	v_addc_co_u32_e32 v19, vcc, 0, v19, vcc
	flat_load_dwordx4 v[18:21], v[18:19]
	s_waitcnt vmcnt(0) lgkmcnt(0)
	v_mul_f32_e32 v14, v18, v14
	v_mul_f32_e32 v15, v19, v15
	v_mul_f32_e32 v16, v20, v16
	v_mul_f32_e32 v17, v21, v17
	v_cvt_pk_bf16_f32 v14, v14, v15
	v_cvt_pk_bf16_f32 v15, v16, v17
	global_store_dwordx2 v[52:53], v[14:15], off offset:-1536
	flat_load_dwordx2 v[14:15], v[56:57] offset:72 sc0 sc1
	s_waitcnt vmcnt(0) lgkmcnt(0)
	v_lshl_add_u64 v[14:15], v[14:15], 0, v[50:51]
	v_add_co_u32_e32 v14, vcc, s13, v14
	s_nop 1
	v_addc_co_u32_e32 v15, vcc, 0, v15, vcc
	flat_load_dwordx4 v[14:17], v[14:15] offset:1024
	s_waitcnt vmcnt(0) lgkmcnt(0)
	v_mul_f32_e32 v10, v14, v10
	v_mul_f32_e32 v11, v15, v11
	v_mul_f32_e32 v12, v16, v12
	v_mul_f32_e32 v13, v17, v13
	v_cvt_pk_bf16_f32 v10, v10, v11
	v_cvt_pk_bf16_f32 v11, v12, v13
	global_store_dwordx2 v[52:53], v[10:11], off offset:-1024
	flat_load_dwordx2 v[10:11], v[56:57] offset:72 sc0 sc1
	s_waitcnt vmcnt(0) lgkmcnt(0)
	v_lshl_add_u64 v[10:11], v[10:11], 0, v[50:51]
	v_add_co_u32_e32 v10, vcc, s13, v10
	s_nop 1
	v_addc_co_u32_e32 v11, vcc, 0, v11, vcc
	flat_load_dwordx4 v[10:13], v[10:11] offset:2048
	s_waitcnt vmcnt(0) lgkmcnt(0)
	v_mul_f32_e32 v6, v10, v6
	v_mul_f32_e32 v7, v11, v7
	v_mul_f32_e32 v8, v12, v8
	v_mul_f32_e32 v9, v13, v9
	v_cvt_pk_bf16_f32 v6, v6, v7
	v_cvt_pk_bf16_f32 v7, v8, v9
	global_store_dwordx2 v[52:53], v[6:7], off offset:-512
	flat_load_dwordx2 v[6:7], v[56:57] offset:72 sc0 sc1
	s_waitcnt vmcnt(0) lgkmcnt(0)
	v_lshl_add_u64 v[6:7], v[6:7], 0, v[50:51]
	v_add_co_u32_e32 v6, vcc, s13, v6
	s_nop 1
	v_addc_co_u32_e32 v7, vcc, 0, v7, vcc
	flat_load_dwordx4 v[6:9], v[6:7] offset:3072
	s_waitcnt vmcnt(0) lgkmcnt(0)
	v_mul_f32_e32 v2, v6, v2
	v_mul_f32_e32 v3, v7, v3
	v_mul_f32_e32 v4, v8, v4
	v_mul_f32_e32 v5, v9, v5
	v_cvt_pk_bf16_f32 v2, v2, v3
	v_cvt_pk_bf16_f32 v3, v4, v5
	global_store_dwordx2 v[52:53], v[2:3], off
	v_lshl_add_u64 v[52:53], v[52:53], 0, s[6:7]
	s_cbranch_scc0 .LBB0_77

; __device__ __forceinline__ float bflo(unsigned w) { return __uint_as_float(w << 16); }
; __device__ __forceinline__ float bfhi(unsigned w) { return __uint_as_float(w & 0xffff0000u); }
; #pragma unroll
;     for (int j = 0; j < 8; ++j) mx = fmaxf(mx, fmaxf(fmaxf(fmaxf(fabsf(bflo(w[j].x)), fabsf(bfhi(w[j].x))), fmaxf(fabsf(bflo(w[j].y)), fabsf(bfhi(w[j].y)))), fmaxf(fmaxf(fabsf(bflo(w[j].z)), fabsf(bfhi(w[j].z))), fmaxf(fabsf(bflo(w[j].w)), fabsf(bfhi(w[j].w))))));
; #pragma unroll
;     for (int o = 1; o < 64; o <<= 1) mx = fmaxf(mx, __shfl_xor(mx, o));
;     return mx; }
; __device__ __forceinline__ void quant_store8(const u32x4 (&w)[8], float inv, signed char* dst, int lane) { u32x2* qp = (u32x2*)dst + lane;
; #pragma unroll
;     for (int j = 0; j < 8; ++j) { const unsigned ww[4] = {w[j].x, w[j].y, w[j].z, w[j].w}; unsigned o2[2];
; #pragma unroll
;         for (int h2 = 0; h2 < 2; ++h2) { const int q0 = (int)rintf(bflo(ww[2 * h2]) * inv), q1 = (int)rintf(bfhi(ww[2 * h2]) * inv), q2 = (int)rintf(bflo(ww[2 * h2 + 1]) * inv), q3 = (int)rintf(bfhi(ww[2 * h2 + 1]) * inv);
;             o2[h2] = (unsigned)(q0 & 255) | ((unsigned)(q1 & 255) << 8) | ((unsigned)(q2 & 255) << 16) | ((unsigned)(q3 & 255) << 24); }
;         u32x2 o; o.x = o2[0]; o.y = o2[1]; qp[64 * j] = o; } }
; __device__ __forceinline__ void quant_rows2(const bf16_t* s0, const bf16_t* s1, signed char* d0, signed char* d1, int lane, float& step0, float& step1) {
;     const u32x4* p0 = (const u32x4*)s0 + lane; const u32x4* p1 = (const u32x4*)s1 + lane; u32x4 w0[8], w1[8];
; #pragma unroll
;     for (int j = 0; j < 8; ++j) { w0[j] = p0[64 * j]; w1[j] = p1[64 * j]; }
;     step0 = fmaxf(absmax8(w0), 1e-30f) * (1.0f / 127.0f); step1 = fmaxf(absmax8(w1), 1e-30f) * (1.0f / 127.0f);
.LBB0_160:
	v_lshl_add_u64 v[2:3], s[78:79], 0, v[30:31]
	v_add_co_u32_e32 v4, vcc, 0x10800000, v2
	s_nop 1
	v_addc_co_u32_e32 v5, vcc, 0, v3, vcc
	global_load_dwordx4 v[42:45], v[4:5], off
	global_load_dwordx4 v[46:49], v[4:5], off offset:1024
	global_load_dwordx4 v[50:53], v[4:5], off offset:2048
	global_load_dwordx4 v[54:57], v[4:5], off offset:3072
	v_add_co_u32_e32 v6, vcc, 0x10802000, v2
	s_waitcnt vmcnt(3)
	v_lshlrev_b32_e32 v83, 16, v42
	v_addc_co_u32_e32 v7, vcc, 0, v3, vcc
	v_add_co_u32_e32 v4, vcc, s13, v2
	global_load_dwordx4 v[58:61], v[6:7], off
	global_load_dwordx4 v[26:29], v[6:7], off offset:1024
	global_load_dwordx4 v[22:25], v[6:7], off offset:2048
	global_load_dwordx4 v[18:21], v[6:7], off offset:3072
	v_addc_co_u32_e32 v5, vcc, 0, v3, vcc
	v_add_co_u32_e32 v2, vcc, s22, v2
	v_and_b32_e32 v84, 0xffff0000, v42
	s_nop 0
	v_addc_co_u32_e32 v3, vcc, 0, v3, vcc
	global_load_dwordx4 v[62:65], v[4:5], off
	global_load_dwordx4 v[66:69], v[4:5], off offset:1024
	global_load_dwordx4 v[70:73], v[4:5], off offset:2048
	global_load_dwordx4 v[74:77], v[4:5], off offset:3072
	global_load_dwordx4 v[14:17], v[2:3], off
	global_load_dwordx4 v[10:13], v[2:3], off offset:1024
	global_load_dwordx4 v[6:9], v[2:3], off offset:2048
	s_nop 0
	global_load_dwordx4 v[2:5], v[2:3], off offset:3072
	v_lshlrev_b32_e32 v85, 16, v43
	v_and_b32_e32 v86, 0xffff0000, v43
	v_lshlrev_b32_e32 v89, 16, v45
	v_and_b32_e32 v90, 0xffff0000, v45
	s_waitcnt vmcnt(14)
	v_lshlrev_b32_e32 v97, 16, v49
	v_and_b32_e32 v98, 0xffff0000, v49
	v_lshlrev_b32_e32 v87, 16, v44
	v_and_b32_e32 v88, 0xffff0000, v44
	v_lshlrev_b32_e32 v91, 16, v46
	v_and_b32_e32 v92, 0xffff0000, v46
	v_lshlrev_b32_e32 v93, 16, v47
	v_and_b32_e32 v94, 0xffff0000, v47
	s_waitcnt vmcnt(13)
	v_lshlrev_b32_e32 v101, 16, v51
	v_and_b32_e32 v102, 0xffff0000, v51
	v_lshlrev_b32_e32 v103, 16, v52
	v_and_b32_e32 v104, 0xffff0000, v52
	v_max_f32_e64 v41, |v84|, |v84|
	v_max_f32_e64 v42, |v83|, |v83|
	v_max_f32_e64 v43, |v86|, |v86|
	v_max_f32_e64 v44, |v85|, |v85|
	v_max_f32_e64 v45, |v90|, |v90|
	v_max_f32_e64 v46, |v89|, |v89|
	v_max_f32_e64 v51, |v98|, |v98|
	v_max_f32_e64 v52, |v97|, |v97|
	v_lshlrev_b32_e32 v95, 16, v48
	v_and_b32_e32 v96, 0xffff0000, v48
	v_lshlrev_b32_e32 v99, 16, v50
	v_and_b32_e32 v100, 0xffff0000, v50
	v_max_f32_e64 v47, |v92|, |v92|
	v_max_f32_e64 v48, |v91|, |v91|
	v_max_f32_e64 v49, |v94|, |v94|
	v_max_f32_e64 v50, |v93|, |v93|
	v_max_f32_e32 v41, v42, v41
	v_max_f32_e32 v42, v44, v43
	v_max_f32_e32 v43, v46, v45
	v_max_f32_e32 v46, v52, v51
	v_max_f32_e32 v44, v48, v47
	v_max_f32_e32 v45, v50, v49
	v_max3_f32 v43, |v87|, |v88|, v43
	v_max3_f32 v46, |v95|, |v96|, v46
	v_lshlrev_b32_e32 v105, 16, v53
	v_max3_f32 v41, v41, v42, v43
	v_max3_f32 v42, v44, v45, v46
	v_and_b32_e32 v106, 0xffff0000, v53
	v_max3_f32 v41, v41, 0, v42
	v_max_f32_e64 v42, |v106|, |v106|
	v_max_f32_e64 v43, |v105|, |v105|
	s_waitcnt vmcnt(12)
	v_lshlrev_b32_e32 v107, 16, v54
	v_and_b32_e32 v108, 0xffff0000, v54
	v_max_f32_e32 v42, v43, v42
	v_max_f32_e64 v43, |v108|, |v108|
	v_max_f32_e64 v44, |v107|, |v107|
	v_lshlrev_b32_e32 v109, 16, v55
	v_and_b32_e32 v110, 0xffff0000, v55
	v_max_f32_e32 v43, v44, v43
	v_max_f32_e64 v44, |v110|, |v110|
	v_max_f32_e64 v45, |v109|, |v109|
	v_lshlrev_b32_e32 v113, 16, v57
	v_and_b32_e32 v114, 0xffff0000, v57
	v_max_f32_e32 v44, v45, v44
	v_max_f32_e64 v45, |v114|, |v114|
	v_max_f32_e64 v46, |v113|, |v113|
	v_max_f32_e64 v78, |v100|, |v100|
	v_max_f32_e64 v79, |v99|, |v99|
	v_max_f32_e64 v80, |v102|, |v102|
	v_max_f32_e64 v81, |v101|, |v101|
	v_lshlrev_b32_e32 v111, 16, v56
	v_and_b32_e32 v112, 0xffff0000, v56
	v_max_f32_e32 v45, v46, v45
	v_max_f32_e32 v47, v79, v78
	v_max_f32_e32 v48, v81, v80
	v_max3_f32 v42, |v103|, |v104|, v42
	v_max3_f32 v45, |v111|, |v112|, v45
	v_max3_f32 v42, v47, v48, v42
	v_max3_f32 v43, v43, v44, v45
	s_waitcnt vmcnt(7)
	v_lshlrev_b32_e32 v115, 16, v62
	v_and_b32_e32 v116, 0xffff0000, v62
	v_max3_f32 v41, v41, v42, v43
	v_max_f32_e64 v42, |v116|, |v116|
	v_max_f32_e64 v43, |v115|, |v115|
	v_lshlrev_b32_e32 v117, 16, v63
	v_and_b32_e32 v118, 0xffff0000, v63
	v_max_f32_e32 v42, v43, v42
	v_max_f32_e64 v43, |v118|, |v118|
	v_max_f32_e64 v44, |v117|, |v117|
	v_lshlrev_b32_e32 v121, 16, v65
	v_and_b32_e32 v122, 0xffff0000, v65
	v_max_f32_e32 v43, v44, v43
	v_max_f32_e64 v44, |v122|, |v122|
	v_max_f32_e64 v45, |v121|, |v121|
	v_lshlrev_b32_e32 v119, 16, v64
	v_and_b32_e32 v120, 0xffff0000, v64
	v_max_f32_e32 v44, v45, v44
	v_max3_f32 v44, |v119|, |v120|, v44
	s_waitcnt vmcnt(6)
	v_lshlrev_b32_e32 v123, 16, v66
	v_and_b32_e32 v124, 0xffff0000, v66
	v_max3_f32 v42, v42, v43, v44
	v_max_f32_e64 v43, |v124|, |v124|
	v_max_f32_e64 v44, |v123|, |v123|
	v_lshlrev_b32_e32 v125, 16, v67
	v_and_b32_e32 v126, 0xffff0000, v67
	v_max_f32_e32 v43, v44, v43
	v_max_f32_e64 v44, |v126|, |v126|
	v_max_f32_e64 v45, |v125|, |v125|
	v_lshlrev_b32_e32 v129, 16, v69
	v_and_b32_e32 v130, 0xffff0000, v69
	v_max_f32_e32 v44, v45, v44
	v_max_f32_e64 v45, |v130|, |v130|
	v_max_f32_e64 v46, |v129|, |v129|
	v_lshlrev_b32_e32 v127, 16, v68
	v_and_b32_e32 v128, 0xffff0000, v68
	v_max_f32_e32 v45, v46, v45
	v_max3_f32 v45, |v127|, |v128|, v45
	v_max3_f32 v43, v43, v44, v45
	s_waitcnt vmcnt(5)
	v_lshlrev_b32_e32 v131, 16, v70
	v_and_b32_e32 v132, 0xffff0000, v70
	v_max3_f32 v41, v41, v42, v43
	v_max_f32_e64 v42, |v132|, |v132|
	v_max_f32_e64 v43, |v131|, |v131|
	v_lshlrev_b32_e32 v133, 16, v71
	v_and_b32_e32 v137, 0xffff0000, v71
	v_max_f32_e32 v42, v43, v42
	v_max_f32_e64 v43, |v137|, |v137|
	v_max_f32_e64 v44, |v133|, |v133|
	v_lshlrev_b32_e32 v140, 16, v73
	v_and_b32_e32 v141, 0xffff0000, v73
	v_max_f32_e32 v43, v44, v43
	v_max_f32_e64 v44, |v141|, |v141|
	v_max_f32_e64 v45, |v140|, |v140|
	v_lshlrev_b32_e32 v138, 16, v72
	v_and_b32_e32 v139, 0xffff0000, v72
	v_max_f32_e32 v44, v45, v44
	v_max3_f32 v44, |v138|, |v139|, v44
	s_waitcnt vmcnt(4)
; __device__ __forceinline__ float bflo(unsigned w) { return __uint_as_float(w << 16); }
; __device__ __forceinline__ float bfhi(unsigned w) { return __uint_as_float(w & 0xffff0000u); }
; #pragma unroll
;     for (int j = 0; j < 8; ++j) mx = fmaxf(mx, fmaxf(fmaxf(fmaxf(fabsf(bflo(w[j].x)), fabsf(bfhi(w[j].x))), fmaxf(fabsf(bflo(w[j].y)), fabsf(bfhi(w[j].y)))), fmaxf(fmaxf(fabsf(bflo(w[j].z)), fabsf(bfhi(w[j].z))), fmaxf(fabsf(bflo(w[j].w)), fabsf(bfhi(w[j].w))))));
; #pragma unroll
;     for (int o = 1; o < 64; o <<= 1) mx = fmaxf(mx, __shfl_xor(mx, o));
;     return mx; }
	v_lshlrev_b32_e32 v142, 16, v74
	v_and_b32_e32 v143, 0xffff0000, v74
	v_max3_f32 v42, v42, v43, v44
	v_max_f32_e64 v43, |v143|, |v143|
	v_max_f32_e64 v44, |v142|, |v142|
	v_lshlrev_b32_e32 v144, 16, v75
	v_and_b32_e32 v145, 0xffff0000, v75
	v_max_f32_e32 v43, v44, v43
	v_max_f32_e64 v44, |v145|, |v145|
	v_max_f32_e64 v45, |v144|, |v144|
	v_lshlrev_b32_e32 v148, 16, v77
	v_and_b32_e32 v149, 0xffff0000, v77
	v_max_f32_e32 v44, v45, v44
	v_max_f32_e64 v45, |v149|, |v149|
	v_max_f32_e64 v46, |v148|, |v148|
	v_lshlrev_b32_e32 v146, 16, v76
	v_and_b32_e32 v147, 0xffff0000, v76
	v_max_f32_e32 v45, v46, v45
	v_max3_f32 v45, |v146|, |v147|, v45
	v_max3_f32 v43, v43, v44, v45
	v_lshlrev_b32_e32 v82, 16, v58
	v_and_b32_e32 v80, 0xffff0000, v58
	v_max3_f32 v156, v41, v42, v43
	v_max_f32_e64 v41, |v80|, |v80|
	v_max_f32_e64 v42, |v82|, |v82|
	v_lshlrev_b32_e32 v81, 16, v59
	v_and_b32_e32 v79, 0xffff0000, v59
	v_max_f32_e32 v41, v42, v41
	v_max_f32_e64 v42, |v79|, |v79|
	v_max_f32_e64 v43, |v81|, |v81|
	v_lshlrev_b32_e32 v76, 16, v61
	v_and_b32_e32 v75, 0xffff0000, v61
	v_max_f32_e32 v42, v43, v42
	v_max_f32_e64 v43, |v75|, |v75|
	v_max_f32_e64 v44, |v76|, |v76|
	v_lshlrev_b32_e32 v78, 16, v60
	v_and_b32_e32 v77, 0xffff0000, v60
	v_max_f32_e32 v43, v44, v43
	v_max3_f32 v43, |v78|, |v77|, v43
	v_lshlrev_b32_e32 v74, 16, v26
	v_and_b32_e32 v72, 0xffff0000, v26
	v_lshlrev_b32_e32 v68, 16, v29
	v_and_b32_e32 v67, 0xffff0000, v29
	v_max3_f32 v41, v41, v42, v43
	v_max_f32_e64 v26, |v72|, |v72|
	v_max_f32_e64 v42, |v74|, |v74|
	v_lshlrev_b32_e32 v73, 16, v27
	v_and_b32_e32 v71, 0xffff0000, v27
	v_lshlrev_b32_e32 v70, 16, v28
	v_and_b32_e32 v69, 0xffff0000, v28
	v_max_f32_e64 v28, |v67|, |v67|
	v_max_f32_e64 v29, |v68|, |v68|
	v_max_f32_e32 v26, v42, v26
	v_max_f32_e64 v27, |v71|, |v71|
	v_max_f32_e64 v42, |v73|, |v73|
	v_max_f32_e32 v28, v29, v28
	v_max_f32_e32 v27, v42, v27
	v_max3_f32 v28, |v70|, |v69|, v28
	v_lshlrev_b32_e32 v66, 16, v22
	v_and_b32_e32 v64, 0xffff0000, v22
	v_lshlrev_b32_e32 v60, 16, v25
	v_and_b32_e32 v59, 0xffff0000, v25
	v_max3_f32 v26, v26, v27, v28
	v_max_f32_e64 v22, |v64|, |v64|
	v_max_f32_e64 v27, |v66|, |v66|
	v_lshlrev_b32_e32 v65, 16, v23
	v_and_b32_e32 v63, 0xffff0000, v23
	v_lshlrev_b32_e32 v62, 16, v24
	v_and_b32_e32 v61, 0xffff0000, v24
	v_max_f32_e64 v24, |v59|, |v59|
	v_max_f32_e64 v25, |v60|, |v60|
	v_max_f32_e32 v22, v27, v22
	v_max_f32_e64 v23, |v63|, |v63|
	v_max_f32_e64 v27, |v65|, |v65|
	v_max_f32_e32 v24, v25, v24
	v_max_f32_e32 v23, v27, v23
	v_max3_f32 v24, |v62|, |v61|, v24
	v_lshlrev_b32_e32 v58, 16, v18
	v_and_b32_e32 v56, 0xffff0000, v18
	v_lshlrev_b32_e32 v52, 16, v21
	v_and_b32_e32 v51, 0xffff0000, v21
	v_max3_f32 v22, v22, v23, v24
	v_max_f32_e64 v18, |v56|, |v56|
	v_max_f32_e64 v23, |v58|, |v58|
	v_lshlrev_b32_e32 v57, 16, v19
	v_and_b32_e32 v55, 0xffff0000, v19
	v_lshlrev_b32_e32 v54, 16, v20
	v_and_b32_e32 v53, 0xffff0000, v20
	v_max_f32_e64 v20, |v51|, |v51|
	v_max_f32_e64 v21, |v52|, |v52|
	v_max_f32_e32 v18, v23, v18
	v_max_f32_e64 v19, |v55|, |v55|
	v_max_f32_e64 v23, |v57|, |v57|
	v_max_f32_e32 v20, v21, v20
	v_max_f32_e32 v19, v23, v19
	v_max3_f32 v20, |v54|, |v53|, v20
	s_waitcnt vmcnt(3)
	v_lshlrev_b32_e32 v50, 16, v14
	v_and_b32_e32 v48, 0xffff0000, v14
	v_lshlrev_b32_e32 v44, 16, v17
	v_and_b32_e32 v43, 0xffff0000, v17
	v_max3_f32 v18, v18, v19, v20
	v_max_f32_e64 v14, |v48|, |v48|
	v_max_f32_e64 v19, |v50|, |v50|
	v_lshlrev_b32_e32 v49, 16, v15
	v_and_b32_e32 v47, 0xffff0000, v15
	v_lshlrev_b32_e32 v46, 16, v16
	v_and_b32_e32 v45, 0xffff0000, v16
	v_max_f32_e64 v16, |v43|, |v43|
	v_max_f32_e64 v17, |v44|, |v44|
	v_max_f32_e32 v14, v19, v14
	v_max_f32_e64 v15, |v47|, |v47|
	v_max_f32_e64 v19, |v49|, |v49|
	v_max_f32_e32 v16, v17, v16
	v_max3_f32 v26, v41, 0, v26
	v_max_f32_e32 v15, v19, v15
	v_max3_f32 v16, |v46|, |v45|, v16
	s_waitcnt vmcnt(2)
	v_lshlrev_b32_e32 v42, 16, v10
	v_and_b32_e32 v29, 0xffff0000, v10
	v_lshlrev_b32_e32 v25, 16, v13
	v_and_b32_e32 v24, 0xffff0000, v13
	v_max3_f32 v18, v26, v22, v18
	v_max3_f32 v14, v14, v15, v16
	v_max_f32_e64 v10, |v29|, |v29|
	v_max_f32_e64 v15, |v42|, |v42|
	v_lshlrev_b32_e32 v41, 16, v11
	v_and_b32_e32 v28, 0xffff0000, v11
	v_lshlrev_b32_e32 v27, 16, v12
	v_and_b32_e32 v26, 0xffff0000, v12
	v_max_f32_e64 v12, |v24|, |v24|
	v_max_f32_e64 v13, |v25|, |v25|
	v_max_f32_e32 v10, v15, v10
	v_max_f32_e64 v11, |v28|, |v28|
	v_max_f32_e64 v15, |v41|, |v41|
	v_max_f32_e32 v12, v13, v12
	v_max_f32_e32 v11, v15, v11
	v_max3_f32 v12, |v27|, |v26|, v12
	v_max3_f32 v10, v10, v11, v12
	s_waitcnt vmcnt(1)
	v_lshlrev_b32_e32 v23, 16, v6
	v_and_b32_e32 v21, 0xffff0000, v6
	v_lshlrev_b32_e32 v17, 16, v9
	v_and_b32_e32 v16, 0xffff0000, v9
	v_max3_f32 v158, v18, v14, v10
	v_max_f32_e64 v6, |v21|, |v21|
	v_max_f32_e64 v10, |v23|, |v23|
	v_lshlrev_b32_e32 v22, 16, v7
	v_and_b32_e32 v20, 0xffff0000, v7
	v_lshlrev_b32_e32 v19, 16, v8
	v_and_b32_e32 v18, 0xffff0000, v8
	v_max_f32_e64 v8, |v16|, |v16|
	v_max_f32_e64 v9, |v17|, |v17|
	v_max_f32_e32 v6, v10, v6
	v_max_f32_e64 v7, |v20|, |v20|
	v_max_f32_e64 v10, |v22|, |v22|
	v_max_f32_e32 v8, v9, v8
	v_max_f32_e32 v7, v10, v7
	v_max3_f32 v8, |v19|, |v18|, v8
	v_max3_f32 v6, v6, v7, v8
	s_waitcnt vmcnt(0)
	v_lshlrev_b32_e32 v15, 16, v2
	v_and_b32_e32 v13, 0xffff0000, v2
	v_lshlrev_b32_e32 v9, 16, v5
	v_and_b32_e32 v8, 0xffff0000, v5
	v_max_f32_e64 v2, |v13|, |v13|
	v_max_f32_e64 v7, |v15|, |v15|
	v_lshlrev_b32_e32 v14, 16, v3
	v_and_b32_e32 v12, 0xffff0000, v3
	v_lshlrev_b32_e32 v11, 16, v4
	v_and_b32_e32 v10, 0xffff0000, v4
	v_max_f32_e64 v4, |v8|, |v8|
	v_max_f32_e64 v5, |v9|, |v9|
	v_max_f32_e32 v2, v7, v2
	v_max_f32_e64 v3, |v12|, |v12|
	v_max_f32_e64 v7, |v14|, |v14|
	v_max_f32_e32 v4, v5, v4
	v_max_f32_e32 v3, v7, v3
	v_max3_f32 v4, |v11|, |v10|, v4
	v_max3_f32 v2, v2, v3, v4
	v_max3_f32 v2, v158, v6, v2
	s_nop 1
	v_mov_b32_dpp v157, v156 quad_perm:[1,0,3,2] row_mask:0xf bank_mask:0xf
	s_nop 1
	v_mov_b32_dpp v3, v2 quad_perm:[1,0,3,2] row_mask:0xf bank_mask:0xf
	s_waitcnt lgkmcnt(0)
; __device__ __forceinline__ float bflo(unsigned w) { return __uint_as_float(w << 16); }
; __device__ __forceinline__ float bfhi(unsigned w) { return __uint_as_float(w & 0xffff0000u); }
; #pragma unroll
;     for (int j = 0; j < 8; ++j) mx = fmaxf(mx, fmaxf(fmaxf(fmaxf(fabsf(bflo(w[j].x)), fabsf(bfhi(w[j].x))), fmaxf(fabsf(bflo(w[j].y)), fabsf(bfhi(w[j].y)))), fmaxf(fmaxf(fabsf(bflo(w[j].z)), fabsf(bfhi(w[j].z))), fmaxf(fabsf(bflo(w[j].w)), fabsf(bfhi(w[j].w))))));
; #pragma unroll
;     for (int o = 1; o < 64; o <<= 1) mx = fmaxf(mx, __shfl_xor(mx, o));
;     return mx; }
; __device__ __forceinline__ void quant_store8(const u32x4 (&w)[8], float inv, signed char* dst, int lane) { u32x2* qp = (u32x2*)dst + lane;
; #pragma unroll
;     for (int j = 0; j < 8; ++j) { const unsigned ww[4] = {w[j].x, w[j].y, w[j].z, w[j].w}; unsigned o2[2];
; #pragma unroll
;         for (int h2 = 0; h2 < 2; ++h2) { const int q0 = (int)rintf(bflo(ww[2 * h2]) * inv), q1 = (int)rintf(bfhi(ww[2 * h2]) * inv), q2 = (int)rintf(bflo(ww[2 * h2 + 1]) * inv), q3 = (int)rintf(bfhi(ww[2 * h2 + 1]) * inv);
;             o2[h2] = (unsigned)(q0 & 255) | ((unsigned)(q1 & 255) << 8) | ((unsigned)(q2 & 255) << 16) | ((unsigned)(q3 & 255) << 24); }
;         u32x2 o; o.x = o2[0]; o.y = o2[1]; qp[64 * j] = o; } }
; __device__ __forceinline__ void quant_rows2(const bf16_t* s0, const bf16_t* s1, signed char* d0, signed char* d1, int lane, float& step0, float& step1) {
;     const u32x4* p0 = (const u32x4*)s0 + lane; const u32x4* p1 = (const u32x4*)s1 + lane; u32x4 w0[8], w1[8];
; #pragma unroll
;     for (int j = 0; j < 8; ++j) { w0[j] = p0[64 * j]; w1[j] = p1[64 * j]; }
;     step0 = fmaxf(absmax8(w0), 1e-30f) * (1.0f / 127.0f); step1 = fmaxf(absmax8(w1), 1e-30f) * (1.0f / 127.0f);
;     quant_store8(w0, 1.0f / step0, d0, lane); quant_store8(w1, 1.0f / step1, d1, lane);
	v_max_f32_e32 v4, v157, v157
	s_waitcnt lgkmcnt(0)
	v_max_f32_e32 v3, v3, v3
	v_max_f32_e32 v4, v156, v4
	v_max_f32_e32 v2, v2, v3
	s_nop 1
	v_mov_b32_dpp v5, v4 quad_perm:[2,3,0,1] row_mask:0xf bank_mask:0xf
	s_nop 1
	v_mov_b32_dpp v3, v2 quad_perm:[2,3,0,1] row_mask:0xf bank_mask:0xf
	s_waitcnt lgkmcnt(0)
	v_max_f32_e32 v5, v5, v5
	s_waitcnt lgkmcnt(0)
	v_max_f32_e32 v3, v3, v3
	v_max_f32_e32 v4, v4, v5
	v_max_f32_e32 v2, v2, v3
	s_nop 1
	v_mov_b32_dpp v5, v4 row_half_mirror row_mask:0xf bank_mask:0xf
	s_nop 1
	v_mov_b32_dpp v3, v2 row_half_mirror row_mask:0xf bank_mask:0xf
	s_waitcnt lgkmcnt(0)
	v_max_f32_e32 v5, v5, v5
	s_waitcnt lgkmcnt(0)
	v_max_f32_e32 v3, v3, v3
	v_max_f32_e32 v4, v4, v5
	v_max_f32_e32 v2, v2, v3
	s_nop 1
	v_mov_b32_dpp v5, v4 row_mirror row_mask:0xf bank_mask:0xf
	s_nop 1
	v_mov_b32_dpp v3, v2 row_mirror row_mask:0xf bank_mask:0xf
	s_waitcnt lgkmcnt(0)
	v_max_f32_e32 v5, v5, v5
	s_waitcnt lgkmcnt(0)
	v_max_f32_e32 v3, v3, v3
	v_max_f32_e32 v4, v4, v5
	v_max_f32_e32 v2, v2, v3
	s_waitcnt lgkmcnt(0)
	s_waitcnt lgkmcnt(0)
	v_mov_b32_e32 v5, v4
	s_nop 1
	v_permlane16_swap_b32_e32 v4, v5
	s_nop 0
	v_max_f32_e32 v4, v4, v5
	v_mov_b32_e32 v3, v2
	s_nop 1
	v_permlane16_swap_b32_e32 v3, v2
	s_nop 0
	v_max_f32_e32 v3, v3, v2
	ds_bpermute_b32 v5, v39, v4
	ds_bpermute_b32 v6, v39, v3
	s_waitcnt lgkmcnt(1)
	v_max3_f32 v2, v4, v5, s23
	s_waitcnt lgkmcnt(0)
	v_max3_f32 v3, v3, v6, s23
	v_pk_mul_f32 v[2:3], v[2:3], s[6:7] op_sel_hi:[1,0]
	s_nop 0
	v_div_scale_f32 v4, s[10:11], v2, v2, 1.0
	v_rcp_f32_e32 v5, v4
	s_nop 0
	v_fma_f32 v6, -v4, v5, 1.0
	v_fmac_f32_e32 v5, v6, v5
	v_div_scale_f32 v6, vcc, 1.0, v2, 1.0
	v_mul_f32_e32 v7, v6, v5
	v_fma_f32 v156, -v4, v7, v6
	v_fmac_f32_e32 v7, v156, v5
	v_fma_f32 v4, -v4, v7, v6
	v_div_fmas_f32 v4, v4, v5, v7
	v_div_fixup_f32 v156, v4, v2, 1.0
	v_mul_f32_e32 v7, v156, v84
	v_mul_f32_e32 v6, v156, v83
	v_rndne_f32_e32 v7, v7
	v_mul_f32_e32 v83, v156, v85
	v_rndne_f32_e32 v6, v6
	v_cvt_i32_f32_e32 v7, v7
	v_rndne_f32_e32 v83, v83
	v_mul_f32_e32 v84, v156, v86
	v_cvt_i32_f32_e32 v6, v6
	v_cvt_i32_f32_sdwa v83, v83 dst_sel:WORD_1 dst_unused:UNUSED_PAD src0_sel:DWORD
	v_rndne_f32_e32 v84, v84
	v_cvt_i32_f32_sdwa v84, v84 dst_sel:BYTE_3 dst_unused:UNUSED_PAD src0_sel:DWORD
	v_lshlrev_b32_e32 v7, 8, v7
	v_and_b32_e32 v83, 0xff0000, v83
	v_perm_b32 v6, v7, v6, s26
	v_mul_f32_e32 v7, v156, v88
	v_or3_b32 v84, v6, v84, v83
	v_mul_f32_e32 v6, v156, v87
	v_rndne_f32_e32 v7, v7
	v_mul_f32_e32 v83, v156, v89
	v_rndne_f32_e32 v6, v6
	v_cvt_i32_f32_e32 v7, v7
	v_rndne_f32_e32 v83, v83
	v_mul_f32_e32 v85, v156, v90
	v_cvt_i32_f32_e32 v6, v6
	v_cvt_i32_f32_sdwa v83, v83 dst_sel:WORD_1 dst_unused:UNUSED_PAD src0_sel:DWORD
	v_rndne_f32_e32 v85, v85
	v_cvt_i32_f32_sdwa v85, v85 dst_sel:BYTE_3 dst_unused:UNUSED_PAD src0_sel:DWORD
	v_lshlrev_b32_e32 v7, 8, v7
	v_lshl_add_u64 v[4:5], v[32:33], 0, s[0:1]
	v_and_b32_e32 v83, 0xff0000, v83
	v_perm_b32 v6, v7, v6, s26
	v_or3_b32 v85, v6, v85, v83
	v_add_co_u32_e32 v6, vcc, s27, v4
	v_mul_f32_e32 v83, v156, v91
	s_nop 0
	v_addc_co_u32_e32 v7, vcc, 0, v5, vcc
	v_add_co_u32_e32 v4, vcc, s28, v4
	v_rndne_f32_e32 v83, v83
	s_nop 0
	v_addc_co_u32_e32 v5, vcc, 0, v5, vcc
	global_store_dwordx2 v[4:5], v[84:85], off offset:-4096
	v_mul_f32_e32 v84, v156, v92
	v_rndne_f32_e32 v84, v84
	v_mul_f32_e32 v85, v156, v93
	v_cvt_i32_f32_e32 v84, v84
	v_rndne_f32_e32 v85, v85
	v_mul_f32_e32 v86, v156, v94
	v_cvt_i32_f32_e32 v83, v83
	v_cvt_i32_f32_sdwa v85, v85 dst_sel:WORD_1 dst_unused:UNUSED_PAD src0_sel:DWORD
	v_rndne_f32_e32 v86, v86
	v_cvt_i32_f32_sdwa v86, v86 dst_sel:BYTE_3 dst_unused:UNUSED_PAD src0_sel:DWORD
	v_lshlrev_b32_e32 v84, 8, v84
	v_and_b32_e32 v85, 0xff0000, v85
	v_perm_b32 v83, v84, v83, s26
	v_or3_b32 v84, v83, v86, v85
	v_mul_f32_e32 v85, v156, v96
	v_mul_f32_e32 v83, v156, v95
	v_rndne_f32_e32 v85, v85
	v_mul_f32_e32 v86, v156, v97
	v_rndne_f32_e32 v83, v83
	v_cvt_i32_f32_e32 v85, v85
	v_rndne_f32_e32 v86, v86
	v_mul_f32_e32 v87, v156, v98
	v_cvt_i32_f32_e32 v83, v83
	v_cvt_i32_f32_sdwa v86, v86 dst_sel:WORD_1 dst_unused:UNUSED_PAD src0_sel:DWORD
	v_rndne_f32_e32 v87, v87
	v_cvt_i32_f32_sdwa v87, v87 dst_sel:BYTE_3 dst_unused:UNUSED_PAD src0_sel:DWORD
	v_lshlrev_b32_e32 v85, 8, v85
	v_and_b32_e32 v86, 0xff0000, v86
	v_perm_b32 v83, v85, v83, s26
	v_or3_b32 v85, v83, v87, v86
	global_store_dwordx2 v[6:7], v[84:85], off offset:512
	v_mul_f32_e32 v84, v156, v100
	v_mul_f32_e32 v83, v156, v99
	v_rndne_f32_e32 v84, v84
	v_mul_f32_e32 v85, v156, v101
	v_rndne_f32_e32 v83, v83
	v_cvt_i32_f32_e32 v84, v84
	v_rndne_f32_e32 v85, v85
	v_mul_f32_e32 v86, v156, v102
	v_cvt_i32_f32_e32 v83, v83
	v_cvt_i32_f32_sdwa v85, v85 dst_sel:WORD_1 dst_unused:UNUSED_PAD src0_sel:DWORD
	v_rndne_f32_e32 v86, v86
	v_cvt_i32_f32_sdwa v86, v86 dst_sel:BYTE_3 dst_unused:UNUSED_PAD src0_sel:DWORD
	v_lshlrev_b32_e32 v84, 8, v84
	v_and_b32_e32 v85, 0xff0000, v85
	v_perm_b32 v83, v84, v83, s26
	v_or3_b32 v84, v83, v86, v85
	v_mul_f32_e32 v85, v156, v104
	v_mul_f32_e32 v83, v156, v103
	v_rndne_f32_e32 v85, v85
	v_mul_f32_e32 v86, v156, v105
	v_rndne_f32_e32 v83, v83
	v_cvt_i32_f32_e32 v85, v85
	v_rndne_f32_e32 v86, v86
	v_mul_f32_e32 v87, v156, v106
	v_cvt_i32_f32_e32 v83, v83
	v_cvt_i32_f32_sdwa v86, v86 dst_sel:WORD_1 dst_unused:UNUSED_PAD src0_sel:DWORD
	v_rndne_f32_e32 v87, v87
	v_cvt_i32_f32_sdwa v87, v87 dst_sel:BYTE_3 dst_unused:UNUSED_PAD src0_sel:DWORD
	v_lshlrev_b32_e32 v85, 8, v85
	v_and_b32_e32 v86, 0xff0000, v86
	v_perm_b32 v83, v85, v83, s26
	v_or3_b32 v85, v83, v87, v86
	global_store_dwordx2 v[6:7], v[84:85], off offset:1024
	v_mul_f32_e32 v84, v156, v108
	v_mul_f32_e32 v83, v156, v107
; __device__ __forceinline__ float bflo(unsigned w) { return __uint_as_float(w << 16); }
; __device__ __forceinline__ float bfhi(unsigned w) { return __uint_as_float(w & 0xffff0000u); }
; __device__ __forceinline__ void quant_store8(const u32x4 (&w)[8], float inv, signed char* dst, int lane) { u32x2* qp = (u32x2*)dst + lane;
; #pragma unroll
;     for (int j = 0; j < 8; ++j) { const unsigned ww[4] = {w[j].x, w[j].y, w[j].z, w[j].w}; unsigned o2[2];
; #pragma unroll
;         for (int h2 = 0; h2 < 2; ++h2) { const int q0 = (int)rintf(bflo(ww[2 * h2]) * inv), q1 = (int)rintf(bfhi(ww[2 * h2]) * inv), q2 = (int)rintf(bflo(ww[2 * h2 + 1]) * inv), q3 = (int)rintf(bfhi(ww[2 * h2 + 1]) * inv);
;             o2[h2] = (unsigned)(q0 & 255) | ((unsigned)(q1 & 255) << 8) | ((unsigned)(q2 & 255) << 16) | ((unsigned)(q3 & 255) << 24); }
;         u32x2 o; o.x = o2[0]; o.y = o2[1]; qp[64 * j] = o; } }
	v_rndne_f32_e32 v84, v84
	v_mul_f32_e32 v85, v156, v109
	v_rndne_f32_e32 v83, v83
	v_cvt_i32_f32_e32 v84, v84
	v_rndne_f32_e32 v85, v85
	v_mul_f32_e32 v86, v156, v110
	v_cvt_i32_f32_e32 v83, v83
	v_cvt_i32_f32_sdwa v85, v85 dst_sel:WORD_1 dst_unused:UNUSED_PAD src0_sel:DWORD
	v_rndne_f32_e32 v86, v86
	v_cvt_i32_f32_sdwa v86, v86 dst_sel:BYTE_3 dst_unused:UNUSED_PAD src0_sel:DWORD
	v_lshlrev_b32_e32 v84, 8, v84
	v_and_b32_e32 v85, 0xff0000, v85
	v_perm_b32 v83, v84, v83, s26
	v_or3_b32 v84, v83, v86, v85
	v_mul_f32_e32 v85, v156, v112
	v_mul_f32_e32 v83, v156, v111
	v_rndne_f32_e32 v85, v85
	v_mul_f32_e32 v86, v156, v113
	v_rndne_f32_e32 v83, v83
	v_cvt_i32_f32_e32 v85, v85
	v_rndne_f32_e32 v86, v86
	v_mul_f32_e32 v87, v156, v114
	v_cvt_i32_f32_e32 v83, v83
	v_cvt_i32_f32_sdwa v86, v86 dst_sel:WORD_1 dst_unused:UNUSED_PAD src0_sel:DWORD
	v_rndne_f32_e32 v87, v87
	v_cvt_i32_f32_sdwa v87, v87 dst_sel:BYTE_3 dst_unused:UNUSED_PAD src0_sel:DWORD
	v_lshlrev_b32_e32 v85, 8, v85
	v_and_b32_e32 v86, 0xff0000, v86
	v_perm_b32 v83, v85, v83, s26
	v_or3_b32 v85, v83, v87, v86
	global_store_dwordx2 v[6:7], v[84:85], off offset:1536
	v_mul_f32_e32 v84, v156, v116
	v_mul_f32_e32 v83, v156, v115
	v_rndne_f32_e32 v84, v84
	v_mul_f32_e32 v85, v156, v117
	v_rndne_f32_e32 v83, v83
	v_cvt_i32_f32_e32 v84, v84
	v_rndne_f32_e32 v85, v85
	v_mul_f32_e32 v86, v156, v118
	v_cvt_i32_f32_e32 v83, v83
	v_cvt_i32_f32_sdwa v85, v85 dst_sel:WORD_1 dst_unused:UNUSED_PAD src0_sel:DWORD
	v_rndne_f32_e32 v86, v86
	v_cvt_i32_f32_sdwa v86, v86 dst_sel:BYTE_3 dst_unused:UNUSED_PAD src0_sel:DWORD
	v_lshlrev_b32_e32 v84, 8, v84
	v_and_b32_e32 v85, 0xff0000, v85
	v_perm_b32 v83, v84, v83, s26
	v_or3_b32 v84, v83, v86, v85
	v_mul_f32_e32 v85, v156, v120
	v_mul_f32_e32 v83, v156, v119
	v_rndne_f32_e32 v85, v85
	v_mul_f32_e32 v86, v156, v121
	v_rndne_f32_e32 v83, v83
	v_cvt_i32_f32_e32 v85, v85
	v_rndne_f32_e32 v86, v86
	v_mul_f32_e32 v87, v156, v122
	v_cvt_i32_f32_e32 v83, v83
	v_cvt_i32_f32_sdwa v86, v86 dst_sel:WORD_1 dst_unused:UNUSED_PAD src0_sel:DWORD
	v_rndne_f32_e32 v87, v87
	v_cvt_i32_f32_sdwa v87, v87 dst_sel:BYTE_3 dst_unused:UNUSED_PAD src0_sel:DWORD
	v_lshlrev_b32_e32 v85, 8, v85
	v_and_b32_e32 v86, 0xff0000, v86
	v_perm_b32 v83, v85, v83, s26
	v_or3_b32 v85, v83, v87, v86
	global_store_dwordx2 v[6:7], v[84:85], off offset:2048
	v_mul_f32_e32 v84, v156, v124
	v_mul_f32_e32 v83, v156, v123
	v_rndne_f32_e32 v84, v84
	v_mul_f32_e32 v85, v156, v125
	v_rndne_f32_e32 v83, v83
	v_cvt_i32_f32_e32 v84, v84
	v_rndne_f32_e32 v85, v85
	v_mul_f32_e32 v86, v156, v126
	v_cvt_i32_f32_e32 v83, v83
	v_cvt_i32_f32_sdwa v85, v85 dst_sel:WORD_1 dst_unused:UNUSED_PAD src0_sel:DWORD
	v_rndne_f32_e32 v86, v86
	v_cvt_i32_f32_sdwa v86, v86 dst_sel:BYTE_3 dst_unused:UNUSED_PAD src0_sel:DWORD
	v_lshlrev_b32_e32 v84, 8, v84
	v_and_b32_e32 v85, 0xff0000, v85
	v_perm_b32 v83, v84, v83, s26
	v_or3_b32 v84, v83, v86, v85
	v_mul_f32_e32 v85, v156, v128
	v_mul_f32_e32 v83, v156, v127
	v_rndne_f32_e32 v85, v85
	v_mul_f32_e32 v86, v156, v129
	v_rndne_f32_e32 v83, v83
	v_cvt_i32_f32_e32 v85, v85
	v_rndne_f32_e32 v86, v86
	v_mul_f32_e32 v87, v156, v130
	v_cvt_i32_f32_e32 v83, v83
	v_cvt_i32_f32_sdwa v86, v86 dst_sel:WORD_1 dst_unused:UNUSED_PAD src0_sel:DWORD
	v_rndne_f32_e32 v87, v87
	v_cvt_i32_f32_sdwa v87, v87 dst_sel:BYTE_3 dst_unused:UNUSED_PAD src0_sel:DWORD
	v_lshlrev_b32_e32 v85, 8, v85
	v_and_b32_e32 v86, 0xff0000, v86
	v_perm_b32 v83, v85, v83, s26
	v_or3_b32 v85, v83, v87, v86
	global_store_dwordx2 v[6:7], v[84:85], off offset:2560
	v_mul_f32_e32 v84, v156, v132
	v_mul_f32_e32 v83, v156, v131
	v_rndne_f32_e32 v84, v84
	v_mul_f32_e32 v85, v156, v133
	v_rndne_f32_e32 v83, v83
	v_cvt_i32_f32_e32 v84, v84
	v_rndne_f32_e32 v85, v85
	v_mul_f32_e32 v86, v156, v137
	v_cvt_i32_f32_e32 v83, v83
	v_cvt_i32_f32_sdwa v85, v85 dst_sel:WORD_1 dst_unused:UNUSED_PAD src0_sel:DWORD
	v_rndne_f32_e32 v86, v86
	v_cvt_i32_f32_sdwa v86, v86 dst_sel:BYTE_3 dst_unused:UNUSED_PAD src0_sel:DWORD
	v_lshlrev_b32_e32 v84, 8, v84
	v_and_b32_e32 v85, 0xff0000, v85
	v_perm_b32 v83, v84, v83, s26
	v_or3_b32 v84, v83, v86, v85
	v_mul_f32_e32 v85, v156, v139
	v_mul_f32_e32 v83, v156, v138
	v_rndne_f32_e32 v85, v85
	v_mul_f32_e32 v86, v156, v140
	v_rndne_f32_e32 v83, v83
	v_cvt_i32_f32_e32 v85, v85
	v_rndne_f32_e32 v86, v86
	v_mul_f32_e32 v87, v156, v141
	v_cvt_i32_f32_e32 v83, v83
	v_cvt_i32_f32_sdwa v86, v86 dst_sel:WORD_1 dst_unused:UNUSED_PAD src0_sel:DWORD
	v_rndne_f32_e32 v87, v87
	v_cvt_i32_f32_sdwa v87, v87 dst_sel:BYTE_3 dst_unused:UNUSED_PAD src0_sel:DWORD
	v_lshlrev_b32_e32 v85, 8, v85
	v_and_b32_e32 v86, 0xff0000, v86
	v_perm_b32 v83, v85, v83, s26
	v_or3_b32 v85, v83, v87, v86
	global_store_dwordx2 v[6:7], v[84:85], off offset:3072
	v_mul_f32_e32 v84, v156, v143
	v_mul_f32_e32 v83, v156, v142
	v_rndne_f32_e32 v84, v84
	v_mul_f32_e32 v85, v156, v144
	v_rndne_f32_e32 v83, v83
	v_cvt_i32_f32_e32 v84, v84
	v_rndne_f32_e32 v85, v85
	v_mul_f32_e32 v86, v156, v145
	v_cvt_i32_f32_e32 v83, v83
	v_cvt_i32_f32_sdwa v85, v85 dst_sel:WORD_1 dst_unused:UNUSED_PAD src0_sel:DWORD
	v_rndne_f32_e32 v86, v86
	v_cvt_i32_f32_sdwa v86, v86 dst_sel:BYTE_3 dst_unused:UNUSED_PAD src0_sel:DWORD
	v_lshlrev_b32_e32 v84, 8, v84
	v_and_b32_e32 v85, 0xff0000, v85
	v_perm_b32 v83, v84, v83, s26
	v_or3_b32 v84, v83, v86, v85
	v_mul_f32_e32 v85, v156, v147
	v_mul_f32_e32 v83, v156, v146
	v_rndne_f32_e32 v85, v85
	v_mul_f32_e32 v86, v156, v148
	v_rndne_f32_e32 v83, v83
	v_cvt_i32_f32_e32 v85, v85
	v_rndne_f32_e32 v86, v86
	v_mul_f32_e32 v87, v156, v149
	v_cvt_i32_f32_e32 v83, v83
	v_cvt_i32_f32_sdwa v86, v86 dst_sel:WORD_1 dst_unused:UNUSED_PAD src0_sel:DWORD
; __device__ __forceinline__ float bflo(unsigned w) { return __uint_as_float(w << 16); }
; __device__ __forceinline__ float bfhi(unsigned w) { return __uint_as_float(w & 0xffff0000u); }
; __device__ __forceinline__ void quant_store8(const u32x4 (&w)[8], float inv, signed char* dst, int lane) { u32x2* qp = (u32x2*)dst + lane;
; #pragma unroll
;     for (int j = 0; j < 8; ++j) { const unsigned ww[4] = {w[j].x, w[j].y, w[j].z, w[j].w}; unsigned o2[2];
; #pragma unroll
;         for (int h2 = 0; h2 < 2; ++h2) { const int q0 = (int)rintf(bflo(ww[2 * h2]) * inv), q1 = (int)rintf(bfhi(ww[2 * h2]) * inv), q2 = (int)rintf(bflo(ww[2 * h2 + 1]) * inv), q3 = (int)rintf(bfhi(ww[2 * h2 + 1]) * inv);
;             o2[h2] = (unsigned)(q0 & 255) | ((unsigned)(q1 & 255) << 8) | ((unsigned)(q2 & 255) << 16) | ((unsigned)(q3 & 255) << 24); }
;         u32x2 o; o.x = o2[0]; o.y = o2[1]; qp[64 * j] = o; } }
; __device__ __forceinline__ void quant_rows2(const bf16_t* s0, const bf16_t* s1, signed char* d0, signed char* d1, int lane, float& step0, float& step1) {
;     ...
;     step0 = fmaxf(absmax8(w0), 1e-30f) * (1.0f / 127.0f); step1 = fmaxf(absmax8(w1), 1e-30f) * (1.0f / 127.0f);
;     quant_store8(w0, 1.0f / step0, d0, lane); quant_store8(w1, 1.0f / step1, d1, lane);
	v_rndne_f32_e32 v87, v87
	v_cvt_i32_f32_sdwa v87, v87 dst_sel:BYTE_3 dst_unused:UNUSED_PAD src0_sel:DWORD
	v_div_scale_f32 v88, s[10:11], v3, v3, 1.0
	v_rcp_f32_e32 v89, v88
	v_lshlrev_b32_e32 v85, 8, v85
	v_and_b32_e32 v86, 0xff0000, v86
	v_perm_b32 v83, v85, v83, s26
	v_or3_b32 v85, v83, v87, v86
	global_store_dwordx2 v[6:7], v[84:85], off offset:3584
	v_fma_f32 v6, -v88, v89, 1.0
	v_fmac_f32_e32 v89, v6, v89
	v_div_scale_f32 v6, vcc, 1.0, v3, 1.0
	v_mul_f32_e32 v7, v6, v89
	v_fma_f32 v83, -v88, v7, v6
	v_fmac_f32_e32 v7, v83, v89
	v_fma_f32 v6, -v88, v7, v6
	v_div_fmas_f32 v6, v6, v89, v7
	v_div_fixup_f32 v83, v6, v3, 1.0
	v_mul_f32_e32 v7, v83, v80
	v_mul_f32_e32 v6, v83, v82
	v_rndne_f32_e32 v7, v7
	v_rndne_f32_e32 v6, v6
	v_cvt_i32_f32_e32 v7, v7
	v_cvt_i32_f32_e32 v6, v6
	v_mul_f32_e32 v77, v83, v77
	v_mul_f32_e32 v80, v83, v81
	v_lshlrev_b32_e32 v7, 8, v7
	v_perm_b32 v6, v7, v6, s26
	v_mul_f32_e32 v7, v83, v78
	v_rndne_f32_e32 v77, v77
	v_mul_f32_e32 v76, v83, v76
	v_rndne_f32_e32 v80, v80
	v_mul_f32_e32 v79, v83, v79
	v_rndne_f32_e32 v7, v7
	v_cvt_i32_f32_e32 v77, v77
	v_rndne_f32_e32 v76, v76
	v_mul_f32_e32 v75, v83, v75
	v_cvt_i32_f32_sdwa v80, v80 dst_sel:WORD_1 dst_unused:UNUSED_PAD src0_sel:DWORD
	v_rndne_f32_e32 v79, v79
	v_cvt_i32_f32_e32 v7, v7
	v_cvt_i32_f32_sdwa v76, v76 dst_sel:WORD_1 dst_unused:UNUSED_PAD src0_sel:DWORD
	v_rndne_f32_e32 v75, v75
	v_cvt_i32_f32_sdwa v79, v79 dst_sel:BYTE_3 dst_unused:UNUSED_PAD src0_sel:DWORD
	v_cvt_i32_f32_sdwa v75, v75 dst_sel:BYTE_3 dst_unused:UNUSED_PAD src0_sel:DWORD
	v_lshlrev_b32_e32 v77, 8, v77
	v_and_b32_e32 v80, 0xff0000, v80
	v_and_b32_e32 v76, 0xff0000, v76
	v_perm_b32 v7, v77, v7, s26
	v_or3_b32 v6, v6, v79, v80
	v_or3_b32 v7, v7, v75, v76
	global_store_dwordx2 v[4:5], v[6:7], off
	v_mul_f32_e32 v7, v83, v72
	v_mul_f32_e32 v6, v83, v74
	v_rndne_f32_e32 v7, v7
	v_rndne_f32_e32 v6, v6
	v_cvt_i32_f32_e32 v7, v7
	v_cvt_i32_f32_e32 v6, v6
	v_mul_f32_e32 v69, v83, v69
	v_mul_f32_e32 v72, v83, v73
	v_lshlrev_b32_e32 v7, 8, v7
	v_perm_b32 v6, v7, v6, s26
	v_mul_f32_e32 v7, v83, v70
	v_rndne_f32_e32 v69, v69
	v_mul_f32_e32 v68, v83, v68
	v_rndne_f32_e32 v72, v72
	v_mul_f32_e32 v71, v83, v71
	v_rndne_f32_e32 v7, v7
	v_cvt_i32_f32_e32 v69, v69
	v_rndne_f32_e32 v68, v68
	v_mul_f32_e32 v67, v83, v67
	v_cvt_i32_f32_sdwa v72, v72 dst_sel:WORD_1 dst_unused:UNUSED_PAD src0_sel:DWORD
	v_rndne_f32_e32 v71, v71
	v_cvt_i32_f32_e32 v7, v7
	v_cvt_i32_f32_sdwa v68, v68 dst_sel:WORD_1 dst_unused:UNUSED_PAD src0_sel:DWORD
	v_rndne_f32_e32 v67, v67
	v_cvt_i32_f32_sdwa v71, v71 dst_sel:BYTE_3 dst_unused:UNUSED_PAD src0_sel:DWORD
	v_cvt_i32_f32_sdwa v67, v67 dst_sel:BYTE_3 dst_unused:UNUSED_PAD src0_sel:DWORD
	v_lshlrev_b32_e32 v69, 8, v69
	v_and_b32_e32 v72, 0xff0000, v72
	v_and_b32_e32 v68, 0xff0000, v68
	v_perm_b32 v7, v69, v7, s26
	v_or3_b32 v6, v6, v71, v72
	v_or3_b32 v7, v7, v67, v68
	global_store_dwordx2 v[4:5], v[6:7], off offset:512
	v_mul_f32_e32 v7, v83, v64
	v_mul_f32_e32 v6, v83, v66
	v_rndne_f32_e32 v7, v7
	v_rndne_f32_e32 v6, v6
	v_cvt_i32_f32_e32 v7, v7
	v_cvt_i32_f32_e32 v6, v6
	v_mul_f32_e32 v61, v83, v61
	v_mul_f32_e32 v64, v83, v65
	v_lshlrev_b32_e32 v7, 8, v7
	v_perm_b32 v6, v7, v6, s26
	v_mul_f32_e32 v7, v83, v62
	v_rndne_f32_e32 v61, v61
	v_mul_f32_e32 v60, v83, v60
	v_rndne_f32_e32 v64, v64
	v_mul_f32_e32 v63, v83, v63
	v_rndne_f32_e32 v7, v7
	v_cvt_i32_f32_e32 v61, v61
	v_rndne_f32_e32 v60, v60
	v_mul_f32_e32 v59, v83, v59
	v_cvt_i32_f32_sdwa v64, v64 dst_sel:WORD_1 dst_unused:UNUSED_PAD src0_sel:DWORD
	v_rndne_f32_e32 v63, v63
	v_cvt_i32_f32_e32 v7, v7
	v_cvt_i32_f32_sdwa v60, v60 dst_sel:WORD_1 dst_unused:UNUSED_PAD src0_sel:DWORD
	v_rndne_f32_e32 v59, v59
	v_cvt_i32_f32_sdwa v63, v63 dst_sel:BYTE_3 dst_unused:UNUSED_PAD src0_sel:DWORD
	v_cvt_i32_f32_sdwa v59, v59 dst_sel:BYTE_3 dst_unused:UNUSED_PAD src0_sel:DWORD
	v_lshlrev_b32_e32 v61, 8, v61
	v_and_b32_e32 v64, 0xff0000, v64
	v_and_b32_e32 v60, 0xff0000, v60
	v_perm_b32 v7, v61, v7, s26
	v_or3_b32 v6, v6, v63, v64
	v_or3_b32 v7, v7, v59, v60
	global_store_dwordx2 v[4:5], v[6:7], off offset:1024
	v_mul_f32_e32 v7, v83, v56
	v_mul_f32_e32 v6, v83, v58
	v_rndne_f32_e32 v7, v7
	v_rndne_f32_e32 v6, v6
	v_cvt_i32_f32_e32 v7, v7
	v_cvt_i32_f32_e32 v6, v6
	v_mul_f32_e32 v53, v83, v53
	v_mul_f32_e32 v56, v83, v57
	v_lshlrev_b32_e32 v7, 8, v7
	v_perm_b32 v6, v7, v6, s26
	v_mul_f32_e32 v7, v83, v54
	v_rndne_f32_e32 v53, v53
	v_mul_f32_e32 v52, v83, v52
	v_rndne_f32_e32 v56, v56
	v_mul_f32_e32 v55, v83, v55
	v_rndne_f32_e32 v7, v7
	v_cvt_i32_f32_e32 v53, v53
	v_rndne_f32_e32 v52, v52
	v_mul_f32_e32 v51, v83, v51
	v_cvt_i32_f32_sdwa v56, v56 dst_sel:WORD_1 dst_unused:UNUSED_PAD src0_sel:DWORD
	v_rndne_f32_e32 v55, v55
	v_cvt_i32_f32_e32 v7, v7
	v_cvt_i32_f32_sdwa v52, v52 dst_sel:WORD_1 dst_unused:UNUSED_PAD src0_sel:DWORD
	v_rndne_f32_e32 v51, v51
	v_cvt_i32_f32_sdwa v55, v55 dst_sel:BYTE_3 dst_unused:UNUSED_PAD src0_sel:DWORD
	v_cvt_i32_f32_sdwa v51, v51 dst_sel:BYTE_3 dst_unused:UNUSED_PAD src0_sel:DWORD
; __device__ __forceinline__ float bflo(unsigned w) { return __uint_as_float(w << 16); }
; __device__ __forceinline__ float bfhi(unsigned w) { return __uint_as_float(w & 0xffff0000u); }
; __device__ __forceinline__ void quant_store8(const u32x4 (&w)[8], float inv, signed char* dst, int lane) { u32x2* qp = (u32x2*)dst + lane;
; #pragma unroll
;     for (int j = 0; j < 8; ++j) { const unsigned ww[4] = {w[j].x, w[j].y, w[j].z, w[j].w}; unsigned o2[2];
; #pragma unroll
;         for (int h2 = 0; h2 < 2; ++h2) { const int q0 = (int)rintf(bflo(ww[2 * h2]) * inv), q1 = (int)rintf(bfhi(ww[2 * h2]) * inv), q2 = (int)rintf(bflo(ww[2 * h2 + 1]) * inv), q3 = (int)rintf(bfhi(ww[2 * h2 + 1]) * inv);
;             o2[h2] = (unsigned)(q0 & 255) | ((unsigned)(q1 & 255) << 8) | ((unsigned)(q2 & 255) << 16) | ((unsigned)(q3 & 255) << 24); }
;         u32x2 o; o.x = o2[0]; o.y = o2[1]; qp[64 * j] = o; } }
	v_lshlrev_b32_e32 v53, 8, v53
	v_and_b32_e32 v56, 0xff0000, v56
	v_and_b32_e32 v52, 0xff0000, v52
	v_perm_b32 v7, v53, v7, s26
	v_or3_b32 v6, v6, v55, v56
	v_or3_b32 v7, v7, v51, v52
	global_store_dwordx2 v[4:5], v[6:7], off offset:1536
	v_mul_f32_e32 v7, v83, v48
	v_mul_f32_e32 v6, v83, v50
	v_rndne_f32_e32 v7, v7
	v_rndne_f32_e32 v6, v6
	v_cvt_i32_f32_e32 v7, v7
	v_cvt_i32_f32_e32 v6, v6
	v_mul_f32_e32 v45, v83, v45
	v_mul_f32_e32 v48, v83, v49
	v_lshlrev_b32_e32 v7, 8, v7
	v_perm_b32 v6, v7, v6, s26
	v_mul_f32_e32 v7, v83, v46
	v_rndne_f32_e32 v45, v45
	v_mul_f32_e32 v44, v83, v44
	v_rndne_f32_e32 v48, v48
	v_mul_f32_e32 v47, v83, v47
	v_rndne_f32_e32 v7, v7
	v_cvt_i32_f32_e32 v45, v45
	v_rndne_f32_e32 v44, v44
	v_mul_f32_e32 v43, v83, v43
	v_cvt_i32_f32_sdwa v48, v48 dst_sel:WORD_1 dst_unused:UNUSED_PAD src0_sel:DWORD
	v_rndne_f32_e32 v47, v47
	v_cvt_i32_f32_e32 v7, v7
	v_cvt_i32_f32_sdwa v44, v44 dst_sel:WORD_1 dst_unused:UNUSED_PAD src0_sel:DWORD
	v_rndne_f32_e32 v43, v43
	v_cvt_i32_f32_sdwa v47, v47 dst_sel:BYTE_3 dst_unused:UNUSED_PAD src0_sel:DWORD
	v_cvt_i32_f32_sdwa v43, v43 dst_sel:BYTE_3 dst_unused:UNUSED_PAD src0_sel:DWORD
	v_lshlrev_b32_e32 v45, 8, v45
	v_and_b32_e32 v48, 0xff0000, v48
	v_and_b32_e32 v44, 0xff0000, v44
	v_perm_b32 v7, v45, v7, s26
	v_or3_b32 v6, v6, v47, v48
	v_or3_b32 v7, v7, v43, v44
	global_store_dwordx2 v[4:5], v[6:7], off offset:2048
	v_mul_f32_e32 v7, v83, v29
	v_mul_f32_e32 v6, v83, v42
	v_rndne_f32_e32 v7, v7
	v_rndne_f32_e32 v6, v6
	v_cvt_i32_f32_e32 v7, v7
	v_cvt_i32_f32_e32 v6, v6
	v_mul_f32_e32 v26, v83, v26
	v_mul_f32_e32 v29, v83, v41
	v_lshlrev_b32_e32 v7, 8, v7
	v_perm_b32 v6, v7, v6, s26
	v_mul_f32_e32 v7, v83, v27
	v_rndne_f32_e32 v26, v26
	v_mul_f32_e32 v25, v83, v25
	v_rndne_f32_e32 v29, v29
	v_mul_f32_e32 v28, v83, v28
	v_rndne_f32_e32 v7, v7
	v_cvt_i32_f32_e32 v26, v26
	v_rndne_f32_e32 v25, v25
	v_mul_f32_e32 v24, v83, v24
	v_cvt_i32_f32_sdwa v29, v29 dst_sel:WORD_1 dst_unused:UNUSED_PAD src0_sel:DWORD
	v_rndne_f32_e32 v28, v28
	v_cvt_i32_f32_e32 v7, v7
	v_cvt_i32_f32_sdwa v25, v25 dst_sel:WORD_1 dst_unused:UNUSED_PAD src0_sel:DWORD
	v_rndne_f32_e32 v24, v24
	v_cvt_i32_f32_sdwa v28, v28 dst_sel:BYTE_3 dst_unused:UNUSED_PAD src0_sel:DWORD
	v_cvt_i32_f32_sdwa v24, v24 dst_sel:BYTE_3 dst_unused:UNUSED_PAD src0_sel:DWORD
	v_lshlrev_b32_e32 v26, 8, v26
	v_and_b32_e32 v29, 0xff0000, v29
	v_and_b32_e32 v25, 0xff0000, v25
	v_perm_b32 v7, v26, v7, s26
	v_or3_b32 v6, v6, v28, v29
	v_or3_b32 v7, v7, v24, v25
	global_store_dwordx2 v[4:5], v[6:7], off offset:2560
	v_mul_f32_e32 v7, v83, v21
	v_mul_f32_e32 v6, v83, v23
	v_rndne_f32_e32 v7, v7
	v_rndne_f32_e32 v6, v6
	v_cvt_i32_f32_e32 v7, v7
	v_cvt_i32_f32_e32 v6, v6
	v_mul_f32_e32 v18, v83, v18
	v_mul_f32_e32 v21, v83, v22
	v_lshlrev_b32_e32 v7, 8, v7
	v_perm_b32 v6, v7, v6, s26
	v_mul_f32_e32 v7, v83, v19
	v_rndne_f32_e32 v18, v18
	v_mul_f32_e32 v17, v83, v17
	v_rndne_f32_e32 v21, v21
	v_mul_f32_e32 v20, v83, v20
	v_rndne_f32_e32 v7, v7
	v_cvt_i32_f32_e32 v18, v18
	v_rndne_f32_e32 v17, v17
	v_mul_f32_e32 v16, v83, v16
	v_cvt_i32_f32_sdwa v21, v21 dst_sel:WORD_1 dst_unused:UNUSED_PAD src0_sel:DWORD
	v_rndne_f32_e32 v20, v20
	v_cvt_i32_f32_e32 v7, v7
	v_cvt_i32_f32_sdwa v17, v17 dst_sel:WORD_1 dst_unused:UNUSED_PAD src0_sel:DWORD
	v_rndne_f32_e32 v16, v16
	v_cvt_i32_f32_sdwa v20, v20 dst_sel:BYTE_3 dst_unused:UNUSED_PAD src0_sel:DWORD
	v_cvt_i32_f32_sdwa v16, v16 dst_sel:BYTE_3 dst_unused:UNUSED_PAD src0_sel:DWORD
	v_lshlrev_b32_e32 v18, 8, v18
	v_and_b32_e32 v21, 0xff0000, v21
	v_and_b32_e32 v17, 0xff0000, v17
	v_perm_b32 v7, v18, v7, s26
	v_or3_b32 v6, v6, v20, v21
	v_or3_b32 v7, v7, v16, v17
	global_store_dwordx2 v[4:5], v[6:7], off offset:3072
	v_mul_f32_e32 v7, v83, v13
	v_mul_f32_e32 v6, v83, v15
	v_rndne_f32_e32 v7, v7
	v_rndne_f32_e32 v6, v6
	v_cvt_i32_f32_e32 v7, v7
	v_cvt_i32_f32_e32 v6, v6
	v_mul_f32_e32 v10, v83, v10
	v_mul_f32_e32 v13, v83, v14
	v_lshlrev_b32_e32 v7, 8, v7
	v_perm_b32 v6, v7, v6, s26
	v_mul_f32_e32 v7, v83, v11
	v_rndne_f32_e32 v10, v10
	v_mul_f32_e32 v9, v83, v9
	v_rndne_f32_e32 v13, v13
	v_mul_f32_e32 v12, v83, v12
	v_rndne_f32_e32 v7, v7
	v_cvt_i32_f32_e32 v10, v10
	v_rndne_f32_e32 v9, v9
	v_mul_f32_e32 v8, v83, v8
	v_cvt_i32_f32_sdwa v13, v13 dst_sel:WORD_1 dst_unused:UNUSED_PAD src0_sel:DWORD
	v_rndne_f32_e32 v12, v12
	v_cvt_i32_f32_e32 v7, v7
	v_cvt_i32_f32_sdwa v9, v9 dst_sel:WORD_1 dst_unused:UNUSED_PAD src0_sel:DWORD
	v_rndne_f32_e32 v8, v8
	v_cvt_i32_f32_sdwa v12, v12 dst_sel:BYTE_3 dst_unused:UNUSED_PAD src0_sel:DWORD
	v_cvt_i32_f32_sdwa v8, v8 dst_sel:BYTE_3 dst_unused:UNUSED_PAD src0_sel:DWORD
	v_lshlrev_b32_e32 v10, 8, v10
	v_and_b32_e32 v13, 0xff0000, v13
	v_and_b32_e32 v9, 0xff0000, v9
	v_perm_b32 v7, v10, v7, s26
	v_or3_b32 v6, v6, v12, v13
	v_or3_b32 v7, v7, v8, v9
	global_store_dwordx2 v[4:5], v[6:7], off offset:3584
	s_and_saveexec_b64 s[10:11], s[4:5]
	s_cbranch_execz .LBB0_159
	s_add_u32 s30, s78, s7
	s_addc_u32 s31, s79, s12
	global_store_dwordx2 v40, v[2:3], s[30:31]
	s_branch .LBB0_159

; __device__ __forceinline__ float bflo(unsigned w) { return __uint_as_float(w << 16); }
; __device__ __forceinline__ float bfhi(unsigned w) { return __uint_as_float(w & 0xffff0000u); }
; #pragma unroll
;     for (int j = 0; j < 8; ++j) mx = fmaxf(mx, fmaxf(fmaxf(fmaxf(fabsf(bflo(w[j].x)), fabsf(bfhi(w[j].x))), fmaxf(fabsf(bflo(w[j].y)), fabsf(bfhi(w[j].y)))), fmaxf(fmaxf(fabsf(bflo(w[j].z)), fabsf(bfhi(w[j].z))), fmaxf(fabsf(bflo(w[j].w)), fabsf(bfhi(w[j].w))))));
; #pragma unroll
;     for (int o = 1; o < 64; o <<= 1) mx = fmaxf(mx, __shfl_xor(mx, o));
;     return mx; }
; __device__ __forceinline__ void quant_store8(const u32x4 (&w)[8], float inv, signed char* dst, int lane) { u32x2* qp = (u32x2*)dst + lane;
; #pragma unroll
;     for (int j = 0; j < 8; ++j) { const unsigned ww[4] = {w[j].x, w[j].y, w[j].z, w[j].w}; unsigned o2[2];
; #pragma unroll
;         for (int h2 = 0; h2 < 2; ++h2) { const int q0 = (int)rintf(bflo(ww[2 * h2]) * inv), q1 = (int)rintf(bfhi(ww[2 * h2]) * inv), q2 = (int)rintf(bflo(ww[2 * h2 + 1]) * inv), q3 = (int)rintf(bfhi(ww[2 * h2 + 1]) * inv);
;             o2[h2] = (unsigned)(q0 & 255) | ((unsigned)(q1 & 255) << 8) | ((unsigned)(q2 & 255) << 16) | ((unsigned)(q3 & 255) << 24); }
;         u32x2 o; o.x = o2[0]; o.y = o2[1]; qp[64 * j] = o; } }
; __device__ __forceinline__ void quant_rows2(const bf16_t* s0, const bf16_t* s1, signed char* d0, signed char* d1, int lane, float& step0, float& step1) {
;     const u32x4* p0 = (const u32x4*)s0 + lane; const u32x4* p1 = (const u32x4*)s1 + lane; u32x4 w0[8], w1[8];
; #pragma unroll
;     for (int j = 0; j < 8; ++j) { w0[j] = p0[64 * j]; w1[j] = p1[64 * j]; }
;     step0 = fmaxf(absmax8(w0), 1e-30f) * (1.0f / 127.0f); step1 = fmaxf(absmax8(w1), 1e-30f) * (1.0f / 127.0f);
.LBB0_272:
	v_lshl_add_u64 v[2:3], s[78:79], 0, v[30:31]
	v_add_co_u32_e32 v4, vcc, 0x10800000, v2
	s_nop 1
	v_addc_co_u32_e32 v5, vcc, 0, v3, vcc
	global_load_dwordx4 v[42:45], v[4:5], off
	global_load_dwordx4 v[46:49], v[4:5], off offset:1024
	global_load_dwordx4 v[50:53], v[4:5], off offset:2048
	global_load_dwordx4 v[54:57], v[4:5], off offset:3072
	v_add_co_u32_e32 v6, vcc, 0x10802000, v2
	s_waitcnt vmcnt(3)
	v_lshlrev_b32_e32 v83, 16, v42
	v_addc_co_u32_e32 v7, vcc, 0, v3, vcc
	v_add_co_u32_e32 v4, vcc, s23, v2
	global_load_dwordx4 v[58:61], v[6:7], off
	global_load_dwordx4 v[26:29], v[6:7], off offset:1024
	global_load_dwordx4 v[22:25], v[6:7], off offset:2048
	global_load_dwordx4 v[18:21], v[6:7], off offset:3072
	v_addc_co_u32_e32 v5, vcc, 0, v3, vcc
	v_add_co_u32_e32 v2, vcc, s24, v2
	v_and_b32_e32 v84, 0xffff0000, v42
	s_nop 0
	v_addc_co_u32_e32 v3, vcc, 0, v3, vcc
	global_load_dwordx4 v[62:65], v[4:5], off
	global_load_dwordx4 v[66:69], v[4:5], off offset:1024
	global_load_dwordx4 v[70:73], v[4:5], off offset:2048
	global_load_dwordx4 v[74:77], v[4:5], off offset:3072
	global_load_dwordx4 v[14:17], v[2:3], off
	global_load_dwordx4 v[10:13], v[2:3], off offset:1024
	global_load_dwordx4 v[6:9], v[2:3], off offset:2048
	s_nop 0
	global_load_dwordx4 v[2:5], v[2:3], off offset:3072
	v_lshlrev_b32_e32 v85, 16, v43
	v_and_b32_e32 v86, 0xffff0000, v43
	v_lshlrev_b32_e32 v89, 16, v45
	v_and_b32_e32 v90, 0xffff0000, v45
	s_waitcnt vmcnt(14)
	v_lshlrev_b32_e32 v97, 16, v49
	v_and_b32_e32 v98, 0xffff0000, v49
	v_lshlrev_b32_e32 v87, 16, v44
	v_and_b32_e32 v88, 0xffff0000, v44
	v_lshlrev_b32_e32 v91, 16, v46
	v_and_b32_e32 v92, 0xffff0000, v46
	v_lshlrev_b32_e32 v93, 16, v47
	v_and_b32_e32 v94, 0xffff0000, v47
	s_waitcnt vmcnt(13)
	v_lshlrev_b32_e32 v101, 16, v51
	v_and_b32_e32 v102, 0xffff0000, v51
	v_lshlrev_b32_e32 v103, 16, v52
	v_and_b32_e32 v104, 0xffff0000, v52
	v_max_f32_e64 v41, |v84|, |v84|
	v_max_f32_e64 v42, |v83|, |v83|
	v_max_f32_e64 v43, |v86|, |v86|
	v_max_f32_e64 v44, |v85|, |v85|
	v_max_f32_e64 v45, |v90|, |v90|
	v_max_f32_e64 v46, |v89|, |v89|
	v_max_f32_e64 v51, |v98|, |v98|
	v_max_f32_e64 v52, |v97|, |v97|
	v_lshlrev_b32_e32 v95, 16, v48
	v_and_b32_e32 v96, 0xffff0000, v48
	v_lshlrev_b32_e32 v99, 16, v50
	v_and_b32_e32 v100, 0xffff0000, v50
	v_max_f32_e64 v47, |v92|, |v92|
	v_max_f32_e64 v48, |v91|, |v91|
	v_max_f32_e64 v49, |v94|, |v94|
	v_max_f32_e64 v50, |v93|, |v93|
	v_max_f32_e32 v41, v42, v41
	v_max_f32_e32 v42, v44, v43
	v_max_f32_e32 v43, v46, v45
	v_max_f32_e32 v46, v52, v51
	v_max_f32_e32 v44, v48, v47
	v_max_f32_e32 v45, v50, v49
	v_max3_f32 v43, |v87|, |v88|, v43
	v_max3_f32 v46, |v95|, |v96|, v46
	v_lshlrev_b32_e32 v105, 16, v53
	v_max3_f32 v41, v41, v42, v43
	v_max3_f32 v42, v44, v45, v46
	v_and_b32_e32 v106, 0xffff0000, v53
	v_max3_f32 v41, v41, 0, v42
	v_max_f32_e64 v42, |v106|, |v106|
	v_max_f32_e64 v43, |v105|, |v105|
	s_waitcnt vmcnt(12)
	v_lshlrev_b32_e32 v107, 16, v54
	v_and_b32_e32 v108, 0xffff0000, v54
	v_max_f32_e32 v42, v43, v42
	v_max_f32_e64 v43, |v108|, |v108|
	v_max_f32_e64 v44, |v107|, |v107|
	v_lshlrev_b32_e32 v109, 16, v55
	v_and_b32_e32 v110, 0xffff0000, v55
	v_max_f32_e32 v43, v44, v43
	v_max_f32_e64 v44, |v110|, |v110|
	v_max_f32_e64 v45, |v109|, |v109|
	v_lshlrev_b32_e32 v113, 16, v57
	v_and_b32_e32 v114, 0xffff0000, v57
	v_max_f32_e32 v44, v45, v44
	v_max_f32_e64 v45, |v114|, |v114|
	v_max_f32_e64 v46, |v113|, |v113|
	v_max_f32_e64 v78, |v100|, |v100|
	v_max_f32_e64 v79, |v99|, |v99|
	v_max_f32_e64 v80, |v102|, |v102|
	v_max_f32_e64 v81, |v101|, |v101|
	v_lshlrev_b32_e32 v111, 16, v56
	v_and_b32_e32 v112, 0xffff0000, v56
	v_max_f32_e32 v45, v46, v45
	v_max_f32_e32 v47, v79, v78
	v_max_f32_e32 v48, v81, v80
	v_max3_f32 v42, |v103|, |v104|, v42
	v_max3_f32 v45, |v111|, |v112|, v45
	v_max3_f32 v42, v47, v48, v42
	v_max3_f32 v43, v43, v44, v45
	s_waitcnt vmcnt(7)
	v_lshlrev_b32_e32 v115, 16, v62
	v_and_b32_e32 v116, 0xffff0000, v62
	v_max3_f32 v41, v41, v42, v43
	v_max_f32_e64 v42, |v116|, |v116|
	v_max_f32_e64 v43, |v115|, |v115|
	v_lshlrev_b32_e32 v117, 16, v63
	v_and_b32_e32 v118, 0xffff0000, v63
	v_max_f32_e32 v42, v43, v42
	v_max_f32_e64 v43, |v118|, |v118|
	v_max_f32_e64 v44, |v117|, |v117|
	v_lshlrev_b32_e32 v121, 16, v65
	v_and_b32_e32 v122, 0xffff0000, v65
	v_max_f32_e32 v43, v44, v43
	v_max_f32_e64 v44, |v122|, |v122|
	v_max_f32_e64 v45, |v121|, |v121|
	v_lshlrev_b32_e32 v119, 16, v64
	v_and_b32_e32 v120, 0xffff0000, v64
	v_max_f32_e32 v44, v45, v44
	v_max3_f32 v44, |v119|, |v120|, v44
	s_waitcnt vmcnt(6)
	v_lshlrev_b32_e32 v123, 16, v66
	v_and_b32_e32 v124, 0xffff0000, v66
	v_max3_f32 v42, v42, v43, v44
	v_max_f32_e64 v43, |v124|, |v124|
	v_max_f32_e64 v44, |v123|, |v123|
	v_lshlrev_b32_e32 v125, 16, v67
	v_and_b32_e32 v126, 0xffff0000, v67
	v_max_f32_e32 v43, v44, v43
	v_max_f32_e64 v44, |v126|, |v126|
	v_max_f32_e64 v45, |v125|, |v125|
	v_lshlrev_b32_e32 v129, 16, v69
	v_and_b32_e32 v130, 0xffff0000, v69
	v_max_f32_e32 v44, v45, v44
	v_max_f32_e64 v45, |v130|, |v130|
	v_max_f32_e64 v46, |v129|, |v129|
	v_lshlrev_b32_e32 v127, 16, v68
	v_and_b32_e32 v128, 0xffff0000, v68
	v_max_f32_e32 v45, v46, v45
	v_max3_f32 v45, |v127|, |v128|, v45
	v_max3_f32 v43, v43, v44, v45
	s_waitcnt vmcnt(5)
	v_lshlrev_b32_e32 v131, 16, v70
	v_and_b32_e32 v132, 0xffff0000, v70
	v_max3_f32 v41, v41, v42, v43
	v_max_f32_e64 v42, |v132|, |v132|
	v_max_f32_e64 v43, |v131|, |v131|
	v_lshlrev_b32_e32 v133, 16, v71
	v_and_b32_e32 v137, 0xffff0000, v71
	v_max_f32_e32 v42, v43, v42
	v_max_f32_e64 v43, |v137|, |v137|
	v_max_f32_e64 v44, |v133|, |v133|
	v_lshlrev_b32_e32 v140, 16, v73
	v_and_b32_e32 v141, 0xffff0000, v73
	v_max_f32_e32 v43, v44, v43
	v_max_f32_e64 v44, |v141|, |v141|
	v_max_f32_e64 v45, |v140|, |v140|
	v_lshlrev_b32_e32 v138, 16, v72
	v_and_b32_e32 v139, 0xffff0000, v72
	v_max_f32_e32 v44, v45, v44
	v_max3_f32 v44, |v138|, |v139|, v44
	s_waitcnt vmcnt(4)
; __device__ __forceinline__ float bflo(unsigned w) { return __uint_as_float(w << 16); }
; __device__ __forceinline__ float bfhi(unsigned w) { return __uint_as_float(w & 0xffff0000u); }
; #pragma unroll
;     for (int j = 0; j < 8; ++j) mx = fmaxf(mx, fmaxf(fmaxf(fmaxf(fabsf(bflo(w[j].x)), fabsf(bfhi(w[j].x))), fmaxf(fabsf(bflo(w[j].y)), fabsf(bfhi(w[j].y)))), fmaxf(fmaxf(fabsf(bflo(w[j].z)), fabsf(bfhi(w[j].z))), fmaxf(fabsf(bflo(w[j].w)), fabsf(bfhi(w[j].w))))));
; #pragma unroll
;     for (int o = 1; o < 64; o <<= 1) mx = fmaxf(mx, __shfl_xor(mx, o));
;     return mx; }
	v_lshlrev_b32_e32 v142, 16, v74
	v_and_b32_e32 v143, 0xffff0000, v74
	v_max3_f32 v42, v42, v43, v44
	v_max_f32_e64 v43, |v143|, |v143|
	v_max_f32_e64 v44, |v142|, |v142|
	v_lshlrev_b32_e32 v144, 16, v75
	v_and_b32_e32 v145, 0xffff0000, v75
	v_max_f32_e32 v43, v44, v43
	v_max_f32_e64 v44, |v145|, |v145|
	v_max_f32_e64 v45, |v144|, |v144|
	v_lshlrev_b32_e32 v148, 16, v77
	v_and_b32_e32 v149, 0xffff0000, v77
	v_max_f32_e32 v44, v45, v44
	v_max_f32_e64 v45, |v149|, |v149|
	v_max_f32_e64 v46, |v148|, |v148|
	v_lshlrev_b32_e32 v146, 16, v76
	v_and_b32_e32 v147, 0xffff0000, v76
	v_max_f32_e32 v45, v46, v45
	v_max3_f32 v45, |v146|, |v147|, v45
	v_max3_f32 v43, v43, v44, v45
	v_lshlrev_b32_e32 v82, 16, v58
	v_and_b32_e32 v80, 0xffff0000, v58
	v_max3_f32 v157, v41, v42, v43
	v_max_f32_e64 v41, |v80|, |v80|
	v_max_f32_e64 v42, |v82|, |v82|
	v_lshlrev_b32_e32 v81, 16, v59
	v_and_b32_e32 v79, 0xffff0000, v59
	v_max_f32_e32 v41, v42, v41
	v_max_f32_e64 v42, |v79|, |v79|
	v_max_f32_e64 v43, |v81|, |v81|
	v_lshlrev_b32_e32 v76, 16, v61
	v_and_b32_e32 v75, 0xffff0000, v61
	v_max_f32_e32 v42, v43, v42
	v_max_f32_e64 v43, |v75|, |v75|
	v_max_f32_e64 v44, |v76|, |v76|
	v_lshlrev_b32_e32 v78, 16, v60
	v_and_b32_e32 v77, 0xffff0000, v60
	v_max_f32_e32 v43, v44, v43
	v_max3_f32 v43, |v78|, |v77|, v43
	v_lshlrev_b32_e32 v74, 16, v26
	v_and_b32_e32 v72, 0xffff0000, v26
	v_lshlrev_b32_e32 v68, 16, v29
	v_and_b32_e32 v67, 0xffff0000, v29
	v_max3_f32 v41, v41, v42, v43
	v_max_f32_e64 v26, |v72|, |v72|
	v_max_f32_e64 v42, |v74|, |v74|
	v_lshlrev_b32_e32 v73, 16, v27
	v_and_b32_e32 v71, 0xffff0000, v27
	v_lshlrev_b32_e32 v70, 16, v28
	v_and_b32_e32 v69, 0xffff0000, v28
	v_max_f32_e64 v28, |v67|, |v67|
	v_max_f32_e64 v29, |v68|, |v68|
	v_max_f32_e32 v26, v42, v26
	v_max_f32_e64 v27, |v71|, |v71|
	v_max_f32_e64 v42, |v73|, |v73|
	v_max_f32_e32 v28, v29, v28
	v_max_f32_e32 v27, v42, v27
	v_max3_f32 v28, |v70|, |v69|, v28
	v_lshlrev_b32_e32 v66, 16, v22
	v_and_b32_e32 v64, 0xffff0000, v22
	v_lshlrev_b32_e32 v60, 16, v25
	v_and_b32_e32 v59, 0xffff0000, v25
	v_max3_f32 v26, v26, v27, v28
	v_max_f32_e64 v22, |v64|, |v64|
	v_max_f32_e64 v27, |v66|, |v66|
	v_lshlrev_b32_e32 v65, 16, v23
	v_and_b32_e32 v63, 0xffff0000, v23
	v_lshlrev_b32_e32 v62, 16, v24
	v_and_b32_e32 v61, 0xffff0000, v24
	v_max_f32_e64 v24, |v59|, |v59|
	v_max_f32_e64 v25, |v60|, |v60|
	v_max_f32_e32 v22, v27, v22
	v_max_f32_e64 v23, |v63|, |v63|
	v_max_f32_e64 v27, |v65|, |v65|
	v_max_f32_e32 v24, v25, v24
	v_max_f32_e32 v23, v27, v23
	v_max3_f32 v24, |v62|, |v61|, v24
	v_lshlrev_b32_e32 v58, 16, v18
	v_and_b32_e32 v56, 0xffff0000, v18
	v_lshlrev_b32_e32 v52, 16, v21
	v_and_b32_e32 v51, 0xffff0000, v21
	v_max3_f32 v22, v22, v23, v24
	v_max_f32_e64 v18, |v56|, |v56|
	v_max_f32_e64 v23, |v58|, |v58|
	v_lshlrev_b32_e32 v57, 16, v19
	v_and_b32_e32 v55, 0xffff0000, v19
	v_lshlrev_b32_e32 v54, 16, v20
	v_and_b32_e32 v53, 0xffff0000, v20
	v_max_f32_e64 v20, |v51|, |v51|
	v_max_f32_e64 v21, |v52|, |v52|
	v_max_f32_e32 v18, v23, v18
	v_max_f32_e64 v19, |v55|, |v55|
	v_max_f32_e64 v23, |v57|, |v57|
	v_max_f32_e32 v20, v21, v20
	v_max_f32_e32 v19, v23, v19
	v_max3_f32 v20, |v54|, |v53|, v20
	s_waitcnt vmcnt(3)
	v_lshlrev_b32_e32 v50, 16, v14
	v_and_b32_e32 v48, 0xffff0000, v14
	v_lshlrev_b32_e32 v44, 16, v17
	v_and_b32_e32 v43, 0xffff0000, v17
	v_max3_f32 v18, v18, v19, v20
	v_max_f32_e64 v14, |v48|, |v48|
	v_max_f32_e64 v19, |v50|, |v50|
	v_lshlrev_b32_e32 v49, 16, v15
	v_and_b32_e32 v47, 0xffff0000, v15
	v_lshlrev_b32_e32 v46, 16, v16
	v_and_b32_e32 v45, 0xffff0000, v16
	v_max_f32_e64 v16, |v43|, |v43|
	v_max_f32_e64 v17, |v44|, |v44|
	v_max_f32_e32 v14, v19, v14
	v_max_f32_e64 v15, |v47|, |v47|
	v_max_f32_e64 v19, |v49|, |v49|
	v_max_f32_e32 v16, v17, v16
	v_max3_f32 v26, v41, 0, v26
	v_max_f32_e32 v15, v19, v15
	v_max3_f32 v16, |v46|, |v45|, v16
	s_waitcnt vmcnt(2)
	v_lshlrev_b32_e32 v42, 16, v10
	v_and_b32_e32 v29, 0xffff0000, v10
	v_lshlrev_b32_e32 v25, 16, v13
	v_and_b32_e32 v24, 0xffff0000, v13
	v_max3_f32 v18, v26, v22, v18
	v_max3_f32 v14, v14, v15, v16
	v_max_f32_e64 v10, |v29|, |v29|
	v_max_f32_e64 v15, |v42|, |v42|
	v_lshlrev_b32_e32 v41, 16, v11
	v_and_b32_e32 v28, 0xffff0000, v11
	v_lshlrev_b32_e32 v27, 16, v12
	v_and_b32_e32 v26, 0xffff0000, v12
	v_max_f32_e64 v12, |v24|, |v24|
	v_max_f32_e64 v13, |v25|, |v25|
	v_max_f32_e32 v10, v15, v10
	v_max_f32_e64 v11, |v28|, |v28|
	v_max_f32_e64 v15, |v41|, |v41|
	v_max_f32_e32 v12, v13, v12
	v_max_f32_e32 v11, v15, v11
	v_max3_f32 v12, |v27|, |v26|, v12
	v_max3_f32 v10, v10, v11, v12
	s_waitcnt vmcnt(1)
	v_lshlrev_b32_e32 v23, 16, v6
	v_and_b32_e32 v21, 0xffff0000, v6
	v_lshlrev_b32_e32 v17, 16, v9
	v_and_b32_e32 v16, 0xffff0000, v9
	v_max3_f32 v160, v18, v14, v10
	v_max_f32_e64 v6, |v21|, |v21|
	v_max_f32_e64 v10, |v23|, |v23|
	v_lshlrev_b32_e32 v22, 16, v7
	v_and_b32_e32 v20, 0xffff0000, v7
	v_lshlrev_b32_e32 v19, 16, v8
	v_and_b32_e32 v18, 0xffff0000, v8
	v_max_f32_e64 v8, |v16|, |v16|
	v_max_f32_e64 v9, |v17|, |v17|
	v_max_f32_e32 v6, v10, v6
	v_max_f32_e64 v7, |v20|, |v20|
	v_max_f32_e64 v10, |v22|, |v22|
	v_max_f32_e32 v8, v9, v8
	v_max_f32_e32 v7, v10, v7
	v_max3_f32 v8, |v19|, |v18|, v8
	v_max3_f32 v6, v6, v7, v8
	s_waitcnt vmcnt(0)
	v_lshlrev_b32_e32 v15, 16, v2
	v_and_b32_e32 v13, 0xffff0000, v2
	v_lshlrev_b32_e32 v9, 16, v5
	v_and_b32_e32 v8, 0xffff0000, v5
	v_max_f32_e64 v2, |v13|, |v13|
	v_max_f32_e64 v7, |v15|, |v15|
	v_lshlrev_b32_e32 v14, 16, v3
	v_and_b32_e32 v12, 0xffff0000, v3
	v_lshlrev_b32_e32 v11, 16, v4
	v_and_b32_e32 v10, 0xffff0000, v4
	v_max_f32_e64 v4, |v8|, |v8|
	v_max_f32_e64 v5, |v9|, |v9|
	v_max_f32_e32 v2, v7, v2
	v_max_f32_e64 v3, |v12|, |v12|
	v_max_f32_e64 v7, |v14|, |v14|
	v_max_f32_e32 v4, v5, v4
	v_max_f32_e32 v3, v7, v3
	v_max3_f32 v4, |v11|, |v10|, v4
	v_max3_f32 v2, v2, v3, v4
	v_max3_f32 v2, v160, v6, v2
	s_nop 1
	v_mov_b32_dpp v158, v157 quad_perm:[1,0,3,2] row_mask:0xf bank_mask:0xf
	s_nop 1
	v_mov_b32_dpp v3, v2 quad_perm:[1,0,3,2] row_mask:0xf bank_mask:0xf
	s_waitcnt lgkmcnt(0)
; __device__ __forceinline__ float bflo(unsigned w) { return __uint_as_float(w << 16); }
; __device__ __forceinline__ float bfhi(unsigned w) { return __uint_as_float(w & 0xffff0000u); }
; #pragma unroll
;     for (int j = 0; j < 8; ++j) mx = fmaxf(mx, fmaxf(fmaxf(fmaxf(fabsf(bflo(w[j].x)), fabsf(bfhi(w[j].x))), fmaxf(fabsf(bflo(w[j].y)), fabsf(bfhi(w[j].y)))), fmaxf(fmaxf(fabsf(bflo(w[j].z)), fabsf(bfhi(w[j].z))), fmaxf(fabsf(bflo(w[j].w)), fabsf(bfhi(w[j].w))))));
; #pragma unroll
;     for (int o = 1; o < 64; o <<= 1) mx = fmaxf(mx, __shfl_xor(mx, o));
;     return mx; }
; __device__ __forceinline__ void quant_store8(const u32x4 (&w)[8], float inv, signed char* dst, int lane) { u32x2* qp = (u32x2*)dst + lane;
; #pragma unroll
;     for (int j = 0; j < 8; ++j) { const unsigned ww[4] = {w[j].x, w[j].y, w[j].z, w[j].w}; unsigned o2[2];
; #pragma unroll
;         for (int h2 = 0; h2 < 2; ++h2) { const int q0 = (int)rintf(bflo(ww[2 * h2]) * inv), q1 = (int)rintf(bfhi(ww[2 * h2]) * inv), q2 = (int)rintf(bflo(ww[2 * h2 + 1]) * inv), q3 = (int)rintf(bfhi(ww[2 * h2 + 1]) * inv);
;             o2[h2] = (unsigned)(q0 & 255) | ((unsigned)(q1 & 255) << 8) | ((unsigned)(q2 & 255) << 16) | ((unsigned)(q3 & 255) << 24); }
;         u32x2 o; o.x = o2[0]; o.y = o2[1]; qp[64 * j] = o; } }
; __device__ __forceinline__ void quant_rows2(const bf16_t* s0, const bf16_t* s1, signed char* d0, signed char* d1, int lane, float& step0, float& step1) {
;     const u32x4* p0 = (const u32x4*)s0 + lane; const u32x4* p1 = (const u32x4*)s1 + lane; u32x4 w0[8], w1[8];
; #pragma unroll
;     for (int j = 0; j < 8; ++j) { w0[j] = p0[64 * j]; w1[j] = p1[64 * j]; }
;     step0 = fmaxf(absmax8(w0), 1e-30f) * (1.0f / 127.0f); step1 = fmaxf(absmax8(w1), 1e-30f) * (1.0f / 127.0f);
;     quant_store8(w0, 1.0f / step0, d0, lane); quant_store8(w1, 1.0f / step1, d1, lane);
	v_max_f32_e32 v4, v158, v158
	s_waitcnt lgkmcnt(0)
	v_max_f32_e32 v3, v3, v3
	v_max_f32_e32 v4, v157, v4
	v_max_f32_e32 v2, v2, v3
	s_nop 1
	v_mov_b32_dpp v5, v4 quad_perm:[2,3,0,1] row_mask:0xf bank_mask:0xf
	s_nop 1
	v_mov_b32_dpp v3, v2 quad_perm:[2,3,0,1] row_mask:0xf bank_mask:0xf
	s_waitcnt lgkmcnt(0)
	v_max_f32_e32 v5, v5, v5
	s_waitcnt lgkmcnt(0)
	v_max_f32_e32 v3, v3, v3
	v_max_f32_e32 v4, v4, v5
	v_max_f32_e32 v2, v2, v3
	s_nop 1
	v_mov_b32_dpp v5, v4 row_half_mirror row_mask:0xf bank_mask:0xf
	s_nop 1
	v_mov_b32_dpp v3, v2 row_half_mirror row_mask:0xf bank_mask:0xf
	s_waitcnt lgkmcnt(0)
	v_max_f32_e32 v5, v5, v5
	s_waitcnt lgkmcnt(0)
	v_max_f32_e32 v3, v3, v3
	v_max_f32_e32 v4, v4, v5
	v_max_f32_e32 v2, v2, v3
	s_nop 1
	v_mov_b32_dpp v5, v4 row_mirror row_mask:0xf bank_mask:0xf
	s_nop 1
	v_mov_b32_dpp v3, v2 row_mirror row_mask:0xf bank_mask:0xf
	s_waitcnt lgkmcnt(0)
	v_max_f32_e32 v5, v5, v5
	s_waitcnt lgkmcnt(0)
	v_max_f32_e32 v3, v3, v3
	v_max_f32_e32 v4, v4, v5
	v_max_f32_e32 v2, v2, v3
	s_waitcnt lgkmcnt(0)
	s_waitcnt lgkmcnt(0)
	v_mov_b32_e32 v5, v4
	s_nop 1
	v_permlane16_swap_b32_e32 v4, v5
	s_nop 0
	v_max_f32_e32 v4, v4, v5
	v_mov_b32_e32 v3, v2
	s_nop 1
	v_permlane16_swap_b32_e32 v3, v2
	s_nop 0
	v_max_f32_e32 v3, v3, v2
	ds_bpermute_b32 v5, v39, v4
	ds_bpermute_b32 v6, v39, v3
	s_waitcnt lgkmcnt(1)
	v_max3_f32 v2, v4, v5, s25
	s_waitcnt lgkmcnt(0)
	v_max3_f32 v3, v3, v6, s25
	v_pk_mul_f32 v[2:3], v[2:3], s[8:9] op_sel_hi:[1,0]
	s_nop 0
	v_div_scale_f32 v4, s[12:13], v2, v2, 1.0
	v_rcp_f32_e32 v5, v4
	s_nop 0
	v_fma_f32 v6, -v4, v5, 1.0
	v_fmac_f32_e32 v5, v6, v5
	v_div_scale_f32 v6, vcc, 1.0, v2, 1.0
	v_mul_f32_e32 v7, v6, v5
	v_fma_f32 v157, -v4, v7, v6
	v_fmac_f32_e32 v7, v157, v5
	v_fma_f32 v4, -v4, v7, v6
	v_div_fmas_f32 v4, v4, v5, v7
	v_div_fixup_f32 v157, v4, v2, 1.0
	v_mul_f32_e32 v7, v157, v84
	v_mul_f32_e32 v6, v157, v83
	v_rndne_f32_e32 v7, v7
	v_mul_f32_e32 v83, v157, v85
	v_rndne_f32_e32 v6, v6
	v_cvt_i32_f32_e32 v7, v7
	v_rndne_f32_e32 v83, v83
	v_mul_f32_e32 v84, v157, v86
	v_cvt_i32_f32_e32 v6, v6
	v_cvt_i32_f32_sdwa v83, v83 dst_sel:WORD_1 dst_unused:UNUSED_PAD src0_sel:DWORD
	v_rndne_f32_e32 v84, v84
	v_cvt_i32_f32_sdwa v84, v84 dst_sel:BYTE_3 dst_unused:UNUSED_PAD src0_sel:DWORD
	v_lshlrev_b32_e32 v7, 8, v7
	v_and_b32_e32 v83, 0xff0000, v83
	v_perm_b32 v6, v7, v6, s28
	v_mul_f32_e32 v7, v157, v88
	v_or3_b32 v84, v6, v84, v83
	v_mul_f32_e32 v6, v157, v87
	v_rndne_f32_e32 v7, v7
	v_mul_f32_e32 v83, v157, v89
	v_rndne_f32_e32 v6, v6
	v_cvt_i32_f32_e32 v7, v7
	v_rndne_f32_e32 v83, v83
	v_mul_f32_e32 v85, v157, v90
	v_cvt_i32_f32_e32 v6, v6
	v_cvt_i32_f32_sdwa v83, v83 dst_sel:WORD_1 dst_unused:UNUSED_PAD src0_sel:DWORD
	v_rndne_f32_e32 v85, v85
	v_cvt_i32_f32_sdwa v85, v85 dst_sel:BYTE_3 dst_unused:UNUSED_PAD src0_sel:DWORD
	v_lshlrev_b32_e32 v7, 8, v7
	v_lshl_add_u64 v[4:5], v[32:33], 0, s[0:1]
	v_and_b32_e32 v83, 0xff0000, v83
	v_perm_b32 v6, v7, v6, s28
	v_or3_b32 v85, v6, v85, v83
	v_add_co_u32_e32 v6, vcc, s29, v4
	v_mul_f32_e32 v83, v157, v91
	s_nop 0
	v_addc_co_u32_e32 v7, vcc, 0, v5, vcc
	v_add_co_u32_e32 v4, vcc, s30, v4
	v_rndne_f32_e32 v83, v83
	s_nop 0
	v_addc_co_u32_e32 v5, vcc, 0, v5, vcc
	global_store_dwordx2 v[4:5], v[84:85], off offset:-4096
	v_mul_f32_e32 v84, v157, v92
	v_rndne_f32_e32 v84, v84
	v_mul_f32_e32 v85, v157, v93
	v_cvt_i32_f32_e32 v84, v84
	v_rndne_f32_e32 v85, v85
	v_mul_f32_e32 v86, v157, v94
	v_cvt_i32_f32_e32 v83, v83
	v_cvt_i32_f32_sdwa v85, v85 dst_sel:WORD_1 dst_unused:UNUSED_PAD src0_sel:DWORD
	v_rndne_f32_e32 v86, v86
	v_cvt_i32_f32_sdwa v86, v86 dst_sel:BYTE_3 dst_unused:UNUSED_PAD src0_sel:DWORD
	v_lshlrev_b32_e32 v84, 8, v84
	v_and_b32_e32 v85, 0xff0000, v85
	v_perm_b32 v83, v84, v83, s28
	v_or3_b32 v84, v83, v86, v85
	v_mul_f32_e32 v85, v157, v96
	v_mul_f32_e32 v83, v157, v95
	v_rndne_f32_e32 v85, v85
	v_mul_f32_e32 v86, v157, v97
	v_rndne_f32_e32 v83, v83
	v_cvt_i32_f32_e32 v85, v85
	v_rndne_f32_e32 v86, v86
	v_mul_f32_e32 v87, v157, v98
	v_cvt_i32_f32_e32 v83, v83
	v_cvt_i32_f32_sdwa v86, v86 dst_sel:WORD_1 dst_unused:UNUSED_PAD src0_sel:DWORD
	v_rndne_f32_e32 v87, v87
	v_cvt_i32_f32_sdwa v87, v87 dst_sel:BYTE_3 dst_unused:UNUSED_PAD src0_sel:DWORD
	v_lshlrev_b32_e32 v85, 8, v85
	v_and_b32_e32 v86, 0xff0000, v86
	v_perm_b32 v83, v85, v83, s28
	v_or3_b32 v85, v83, v87, v86
	global_store_dwordx2 v[6:7], v[84:85], off offset:512
	v_mul_f32_e32 v84, v157, v100
	v_mul_f32_e32 v83, v157, v99
	v_rndne_f32_e32 v84, v84
	v_mul_f32_e32 v85, v157, v101
	v_rndne_f32_e32 v83, v83
	v_cvt_i32_f32_e32 v84, v84
	v_rndne_f32_e32 v85, v85
	v_mul_f32_e32 v86, v157, v102
	v_cvt_i32_f32_e32 v83, v83
	v_cvt_i32_f32_sdwa v85, v85 dst_sel:WORD_1 dst_unused:UNUSED_PAD src0_sel:DWORD
	v_rndne_f32_e32 v86, v86
	v_cvt_i32_f32_sdwa v86, v86 dst_sel:BYTE_3 dst_unused:UNUSED_PAD src0_sel:DWORD
	v_lshlrev_b32_e32 v84, 8, v84
	v_and_b32_e32 v85, 0xff0000, v85
	v_perm_b32 v83, v84, v83, s28
	v_or3_b32 v84, v83, v86, v85
	v_mul_f32_e32 v85, v157, v104
	v_mul_f32_e32 v83, v157, v103
	v_rndne_f32_e32 v85, v85
	v_mul_f32_e32 v86, v157, v105
	v_rndne_f32_e32 v83, v83
	v_cvt_i32_f32_e32 v85, v85
	v_rndne_f32_e32 v86, v86
	v_mul_f32_e32 v87, v157, v106
	v_cvt_i32_f32_e32 v83, v83
	v_cvt_i32_f32_sdwa v86, v86 dst_sel:WORD_1 dst_unused:UNUSED_PAD src0_sel:DWORD
	v_rndne_f32_e32 v87, v87
	v_cvt_i32_f32_sdwa v87, v87 dst_sel:BYTE_3 dst_unused:UNUSED_PAD src0_sel:DWORD
	v_lshlrev_b32_e32 v85, 8, v85
	v_and_b32_e32 v86, 0xff0000, v86
	v_perm_b32 v83, v85, v83, s28
	v_or3_b32 v85, v83, v87, v86
	global_store_dwordx2 v[6:7], v[84:85], off offset:1024
	v_mul_f32_e32 v84, v157, v108
	v_mul_f32_e32 v83, v157, v107
; __device__ __forceinline__ float bflo(unsigned w) { return __uint_as_float(w << 16); }
; __device__ __forceinline__ float bfhi(unsigned w) { return __uint_as_float(w & 0xffff0000u); }
; __device__ __forceinline__ void quant_store8(const u32x4 (&w)[8], float inv, signed char* dst, int lane) { u32x2* qp = (u32x2*)dst + lane;
; #pragma unroll
;     for (int j = 0; j < 8; ++j) { const unsigned ww[4] = {w[j].x, w[j].y, w[j].z, w[j].w}; unsigned o2[2];
; #pragma unroll
;         for (int h2 = 0; h2 < 2; ++h2) { const int q0 = (int)rintf(bflo(ww[2 * h2]) * inv), q1 = (int)rintf(bfhi(ww[2 * h2]) * inv), q2 = (int)rintf(bflo(ww[2 * h2 + 1]) * inv), q3 = (int)rintf(bfhi(ww[2 * h2 + 1]) * inv);
;             o2[h2] = (unsigned)(q0 & 255) | ((unsigned)(q1 & 255) << 8) | ((unsigned)(q2 & 255) << 16) | ((unsigned)(q3 & 255) << 24); }
;         u32x2 o; o.x = o2[0]; o.y = o2[1]; qp[64 * j] = o; } }
	v_rndne_f32_e32 v84, v84
	v_mul_f32_e32 v85, v157, v109
	v_rndne_f32_e32 v83, v83
	v_cvt_i32_f32_e32 v84, v84
	v_rndne_f32_e32 v85, v85
	v_mul_f32_e32 v86, v157, v110
	v_cvt_i32_f32_e32 v83, v83
	v_cvt_i32_f32_sdwa v85, v85 dst_sel:WORD_1 dst_unused:UNUSED_PAD src0_sel:DWORD
	v_rndne_f32_e32 v86, v86
	v_cvt_i32_f32_sdwa v86, v86 dst_sel:BYTE_3 dst_unused:UNUSED_PAD src0_sel:DWORD
	v_lshlrev_b32_e32 v84, 8, v84
	v_and_b32_e32 v85, 0xff0000, v85
	v_perm_b32 v83, v84, v83, s28
	v_or3_b32 v84, v83, v86, v85
	v_mul_f32_e32 v85, v157, v112
	v_mul_f32_e32 v83, v157, v111
	v_rndne_f32_e32 v85, v85
	v_mul_f32_e32 v86, v157, v113
	v_rndne_f32_e32 v83, v83
	v_cvt_i32_f32_e32 v85, v85
	v_rndne_f32_e32 v86, v86
	v_mul_f32_e32 v87, v157, v114
	v_cvt_i32_f32_e32 v83, v83
	v_cvt_i32_f32_sdwa v86, v86 dst_sel:WORD_1 dst_unused:UNUSED_PAD src0_sel:DWORD
	v_rndne_f32_e32 v87, v87
	v_cvt_i32_f32_sdwa v87, v87 dst_sel:BYTE_3 dst_unused:UNUSED_PAD src0_sel:DWORD
	v_lshlrev_b32_e32 v85, 8, v85
	v_and_b32_e32 v86, 0xff0000, v86
	v_perm_b32 v83, v85, v83, s28
	v_or3_b32 v85, v83, v87, v86
	global_store_dwordx2 v[6:7], v[84:85], off offset:1536
	v_mul_f32_e32 v84, v157, v116
	v_mul_f32_e32 v83, v157, v115
	v_rndne_f32_e32 v84, v84
	v_mul_f32_e32 v85, v157, v117
	v_rndne_f32_e32 v83, v83
	v_cvt_i32_f32_e32 v84, v84
	v_rndne_f32_e32 v85, v85
	v_mul_f32_e32 v86, v157, v118
	v_cvt_i32_f32_e32 v83, v83
	v_cvt_i32_f32_sdwa v85, v85 dst_sel:WORD_1 dst_unused:UNUSED_PAD src0_sel:DWORD
	v_rndne_f32_e32 v86, v86
	v_cvt_i32_f32_sdwa v86, v86 dst_sel:BYTE_3 dst_unused:UNUSED_PAD src0_sel:DWORD
	v_lshlrev_b32_e32 v84, 8, v84
	v_and_b32_e32 v85, 0xff0000, v85
	v_perm_b32 v83, v84, v83, s28
	v_or3_b32 v84, v83, v86, v85
	v_mul_f32_e32 v85, v157, v120
	v_mul_f32_e32 v83, v157, v119
	v_rndne_f32_e32 v85, v85
	v_mul_f32_e32 v86, v157, v121
	v_rndne_f32_e32 v83, v83
	v_cvt_i32_f32_e32 v85, v85
	v_rndne_f32_e32 v86, v86
	v_mul_f32_e32 v87, v157, v122
	v_cvt_i32_f32_e32 v83, v83
	v_cvt_i32_f32_sdwa v86, v86 dst_sel:WORD_1 dst_unused:UNUSED_PAD src0_sel:DWORD
	v_rndne_f32_e32 v87, v87
	v_cvt_i32_f32_sdwa v87, v87 dst_sel:BYTE_3 dst_unused:UNUSED_PAD src0_sel:DWORD
	v_lshlrev_b32_e32 v85, 8, v85
	v_and_b32_e32 v86, 0xff0000, v86
	v_perm_b32 v83, v85, v83, s28
	v_or3_b32 v85, v83, v87, v86
	global_store_dwordx2 v[6:7], v[84:85], off offset:2048
	v_mul_f32_e32 v84, v157, v124
	v_mul_f32_e32 v83, v157, v123
	v_rndne_f32_e32 v84, v84
	v_mul_f32_e32 v85, v157, v125
	v_rndne_f32_e32 v83, v83
	v_cvt_i32_f32_e32 v84, v84
	v_rndne_f32_e32 v85, v85
	v_mul_f32_e32 v86, v157, v126
	v_cvt_i32_f32_e32 v83, v83
	v_cvt_i32_f32_sdwa v85, v85 dst_sel:WORD_1 dst_unused:UNUSED_PAD src0_sel:DWORD
	v_rndne_f32_e32 v86, v86
	v_cvt_i32_f32_sdwa v86, v86 dst_sel:BYTE_3 dst_unused:UNUSED_PAD src0_sel:DWORD
	v_lshlrev_b32_e32 v84, 8, v84
	v_and_b32_e32 v85, 0xff0000, v85
	v_perm_b32 v83, v84, v83, s28
	v_or3_b32 v84, v83, v86, v85
	v_mul_f32_e32 v85, v157, v128
	v_mul_f32_e32 v83, v157, v127
	v_rndne_f32_e32 v85, v85
	v_mul_f32_e32 v86, v157, v129
	v_rndne_f32_e32 v83, v83
	v_cvt_i32_f32_e32 v85, v85
	v_rndne_f32_e32 v86, v86
	v_mul_f32_e32 v87, v157, v130
	v_cvt_i32_f32_e32 v83, v83
	v_cvt_i32_f32_sdwa v86, v86 dst_sel:WORD_1 dst_unused:UNUSED_PAD src0_sel:DWORD
	v_rndne_f32_e32 v87, v87
	v_cvt_i32_f32_sdwa v87, v87 dst_sel:BYTE_3 dst_unused:UNUSED_PAD src0_sel:DWORD
	v_lshlrev_b32_e32 v85, 8, v85
	v_and_b32_e32 v86, 0xff0000, v86
	v_perm_b32 v83, v85, v83, s28
	v_or3_b32 v85, v83, v87, v86
	global_store_dwordx2 v[6:7], v[84:85], off offset:2560
	v_mul_f32_e32 v84, v157, v132
	v_mul_f32_e32 v83, v157, v131
	v_rndne_f32_e32 v84, v84
	v_mul_f32_e32 v85, v157, v133
	v_rndne_f32_e32 v83, v83
	v_cvt_i32_f32_e32 v84, v84
	v_rndne_f32_e32 v85, v85
	v_mul_f32_e32 v86, v157, v137
	v_cvt_i32_f32_e32 v83, v83
	v_cvt_i32_f32_sdwa v85, v85 dst_sel:WORD_1 dst_unused:UNUSED_PAD src0_sel:DWORD
	v_rndne_f32_e32 v86, v86
	v_cvt_i32_f32_sdwa v86, v86 dst_sel:BYTE_3 dst_unused:UNUSED_PAD src0_sel:DWORD
	v_lshlrev_b32_e32 v84, 8, v84
	v_and_b32_e32 v85, 0xff0000, v85
	v_perm_b32 v83, v84, v83, s28
	v_or3_b32 v84, v83, v86, v85
	v_mul_f32_e32 v85, v157, v139
	v_mul_f32_e32 v83, v157, v138
	v_rndne_f32_e32 v85, v85
	v_mul_f32_e32 v86, v157, v140
	v_rndne_f32_e32 v83, v83
	v_cvt_i32_f32_e32 v85, v85
	v_rndne_f32_e32 v86, v86
	v_mul_f32_e32 v87, v157, v141
	v_cvt_i32_f32_e32 v83, v83
	v_cvt_i32_f32_sdwa v86, v86 dst_sel:WORD_1 dst_unused:UNUSED_PAD src0_sel:DWORD
	v_rndne_f32_e32 v87, v87
	v_cvt_i32_f32_sdwa v87, v87 dst_sel:BYTE_3 dst_unused:UNUSED_PAD src0_sel:DWORD
	v_lshlrev_b32_e32 v85, 8, v85
	v_and_b32_e32 v86, 0xff0000, v86
	v_perm_b32 v83, v85, v83, s28
	v_or3_b32 v85, v83, v87, v86
	global_store_dwordx2 v[6:7], v[84:85], off offset:3072
	v_mul_f32_e32 v84, v157, v143
	v_mul_f32_e32 v83, v157, v142
	v_rndne_f32_e32 v84, v84
	v_mul_f32_e32 v85, v157, v144
	v_rndne_f32_e32 v83, v83
	v_cvt_i32_f32_e32 v84, v84
	v_rndne_f32_e32 v85, v85
	v_mul_f32_e32 v86, v157, v145
	v_cvt_i32_f32_e32 v83, v83
	v_cvt_i32_f32_sdwa v85, v85 dst_sel:WORD_1 dst_unused:UNUSED_PAD src0_sel:DWORD
	v_rndne_f32_e32 v86, v86
	v_cvt_i32_f32_sdwa v86, v86 dst_sel:BYTE_3 dst_unused:UNUSED_PAD src0_sel:DWORD
	v_lshlrev_b32_e32 v84, 8, v84
	v_and_b32_e32 v85, 0xff0000, v85
	v_perm_b32 v83, v84, v83, s28
	v_or3_b32 v84, v83, v86, v85
	v_mul_f32_e32 v85, v157, v147
	v_mul_f32_e32 v83, v157, v146
	v_rndne_f32_e32 v85, v85
	v_mul_f32_e32 v86, v157, v148
	v_rndne_f32_e32 v83, v83
	v_cvt_i32_f32_e32 v85, v85
	v_rndne_f32_e32 v86, v86
	v_mul_f32_e32 v87, v157, v149
	v_cvt_i32_f32_e32 v83, v83
	v_cvt_i32_f32_sdwa v86, v86 dst_sel:WORD_1 dst_unused:UNUSED_PAD src0_sel:DWORD
; __device__ __forceinline__ float bflo(unsigned w) { return __uint_as_float(w << 16); }
; __device__ __forceinline__ float bfhi(unsigned w) { return __uint_as_float(w & 0xffff0000u); }
; __device__ __forceinline__ void quant_store8(const u32x4 (&w)[8], float inv, signed char* dst, int lane) { u32x2* qp = (u32x2*)dst + lane;
; #pragma unroll
;     for (int j = 0; j < 8; ++j) { const unsigned ww[4] = {w[j].x, w[j].y, w[j].z, w[j].w}; unsigned o2[2];
; #pragma unroll
;         for (int h2 = 0; h2 < 2; ++h2) { const int q0 = (int)rintf(bflo(ww[2 * h2]) * inv), q1 = (int)rintf(bfhi(ww[2 * h2]) * inv), q2 = (int)rintf(bflo(ww[2 * h2 + 1]) * inv), q3 = (int)rintf(bfhi(ww[2 * h2 + 1]) * inv);
;             o2[h2] = (unsigned)(q0 & 255) | ((unsigned)(q1 & 255) << 8) | ((unsigned)(q2 & 255) << 16) | ((unsigned)(q3 & 255) << 24); }
;         u32x2 o; o.x = o2[0]; o.y = o2[1]; qp[64 * j] = o; } }
; __device__ __forceinline__ void quant_rows2(const bf16_t* s0, const bf16_t* s1, signed char* d0, signed char* d1, int lane, float& step0, float& step1) {
;     const u32x4* p0 = (const u32x4*)s0 + lane; const u32x4* p1 = (const u32x4*)s1 + lane; u32x4 w0[8], w1[8];
; #pragma unroll
;     for (int j = 0; j < 8; ++j) { w0[j] = p0[64 * j]; w1[j] = p1[64 * j]; }
;     step0 = fmaxf(absmax8(w0), 1e-30f) * (1.0f / 127.0f); step1 = fmaxf(absmax8(w1), 1e-30f) * (1.0f / 127.0f);
;     quant_store8(w0, 1.0f / step0, d0, lane); quant_store8(w1, 1.0f / step1, d1, lane);
	v_rndne_f32_e32 v87, v87
	v_cvt_i32_f32_sdwa v87, v87 dst_sel:BYTE_3 dst_unused:UNUSED_PAD src0_sel:DWORD
	v_div_scale_f32 v88, s[12:13], v3, v3, 1.0
	v_rcp_f32_e32 v89, v88
	v_lshlrev_b32_e32 v85, 8, v85
	v_and_b32_e32 v86, 0xff0000, v86
	v_perm_b32 v83, v85, v83, s28
	v_or3_b32 v85, v83, v87, v86
	global_store_dwordx2 v[6:7], v[84:85], off offset:3584
	v_fma_f32 v6, -v88, v89, 1.0
	v_fmac_f32_e32 v89, v6, v89
	v_div_scale_f32 v6, vcc, 1.0, v3, 1.0
	v_mul_f32_e32 v7, v6, v89
	v_fma_f32 v83, -v88, v7, v6
	v_fmac_f32_e32 v7, v83, v89
	v_fma_f32 v6, -v88, v7, v6
	v_div_fmas_f32 v6, v6, v89, v7
	v_div_fixup_f32 v83, v6, v3, 1.0
	v_mul_f32_e32 v7, v83, v80
	v_mul_f32_e32 v6, v83, v82
	v_rndne_f32_e32 v7, v7
	v_rndne_f32_e32 v6, v6
	v_cvt_i32_f32_e32 v7, v7
	v_cvt_i32_f32_e32 v6, v6
	v_mul_f32_e32 v77, v83, v77
	v_mul_f32_e32 v80, v83, v81
	v_lshlrev_b32_e32 v7, 8, v7
	v_perm_b32 v6, v7, v6, s28
	v_mul_f32_e32 v7, v83, v78
	v_rndne_f32_e32 v77, v77
	v_mul_f32_e32 v76, v83, v76
	v_rndne_f32_e32 v80, v80
	v_mul_f32_e32 v79, v83, v79
	v_rndne_f32_e32 v7, v7
	v_cvt_i32_f32_e32 v77, v77
	v_rndne_f32_e32 v76, v76
	v_mul_f32_e32 v75, v83, v75
	v_cvt_i32_f32_sdwa v80, v80 dst_sel:WORD_1 dst_unused:UNUSED_PAD src0_sel:DWORD
	v_rndne_f32_e32 v79, v79
	v_cvt_i32_f32_e32 v7, v7
	v_cvt_i32_f32_sdwa v76, v76 dst_sel:WORD_1 dst_unused:UNUSED_PAD src0_sel:DWORD
	v_rndne_f32_e32 v75, v75
	v_cvt_i32_f32_sdwa v79, v79 dst_sel:BYTE_3 dst_unused:UNUSED_PAD src0_sel:DWORD
	v_cvt_i32_f32_sdwa v75, v75 dst_sel:BYTE_3 dst_unused:UNUSED_PAD src0_sel:DWORD
	v_lshlrev_b32_e32 v77, 8, v77
	v_and_b32_e32 v80, 0xff0000, v80
	v_and_b32_e32 v76, 0xff0000, v76
	v_perm_b32 v7, v77, v7, s28
	v_or3_b32 v6, v6, v79, v80
	v_or3_b32 v7, v7, v75, v76
	global_store_dwordx2 v[4:5], v[6:7], off
	v_mul_f32_e32 v7, v83, v72
	v_mul_f32_e32 v6, v83, v74
	v_rndne_f32_e32 v7, v7
	v_rndne_f32_e32 v6, v6
	v_cvt_i32_f32_e32 v7, v7
	v_cvt_i32_f32_e32 v6, v6
	v_mul_f32_e32 v69, v83, v69
	v_mul_f32_e32 v72, v83, v73
	v_lshlrev_b32_e32 v7, 8, v7
	v_perm_b32 v6, v7, v6, s28
	v_mul_f32_e32 v7, v83, v70
	v_rndne_f32_e32 v69, v69
	v_mul_f32_e32 v68, v83, v68
	v_rndne_f32_e32 v72, v72
	v_mul_f32_e32 v71, v83, v71
	v_rndne_f32_e32 v7, v7
	v_cvt_i32_f32_e32 v69, v69
	v_rndne_f32_e32 v68, v68
	v_mul_f32_e32 v67, v83, v67
	v_cvt_i32_f32_sdwa v72, v72 dst_sel:WORD_1 dst_unused:UNUSED_PAD src0_sel:DWORD
	v_rndne_f32_e32 v71, v71
	v_cvt_i32_f32_e32 v7, v7
	v_cvt_i32_f32_sdwa v68, v68 dst_sel:WORD_1 dst_unused:UNUSED_PAD src0_sel:DWORD
	v_rndne_f32_e32 v67, v67
	v_cvt_i32_f32_sdwa v71, v71 dst_sel:BYTE_3 dst_unused:UNUSED_PAD src0_sel:DWORD
	v_cvt_i32_f32_sdwa v67, v67 dst_sel:BYTE_3 dst_unused:UNUSED_PAD src0_sel:DWORD
	v_lshlrev_b32_e32 v69, 8, v69
	v_and_b32_e32 v72, 0xff0000, v72
	v_and_b32_e32 v68, 0xff0000, v68
	v_perm_b32 v7, v69, v7, s28
	v_or3_b32 v6, v6, v71, v72
	v_or3_b32 v7, v7, v67, v68
	global_store_dwordx2 v[4:5], v[6:7], off offset:512
	v_mul_f32_e32 v7, v83, v64
	v_mul_f32_e32 v6, v83, v66
	v_rndne_f32_e32 v7, v7
	v_rndne_f32_e32 v6, v6
	v_cvt_i32_f32_e32 v7, v7
	v_cvt_i32_f32_e32 v6, v6
	v_mul_f32_e32 v61, v83, v61
	v_mul_f32_e32 v64, v83, v65
	v_lshlrev_b32_e32 v7, 8, v7
	v_perm_b32 v6, v7, v6, s28
	v_mul_f32_e32 v7, v83, v62
	v_rndne_f32_e32 v61, v61
	v_mul_f32_e32 v60, v83, v60
	v_rndne_f32_e32 v64, v64
	v_mul_f32_e32 v63, v83, v63
	v_rndne_f32_e32 v7, v7
	v_cvt_i32_f32_e32 v61, v61
	v_rndne_f32_e32 v60, v60
	v_mul_f32_e32 v59, v83, v59
	v_cvt_i32_f32_sdwa v64, v64 dst_sel:WORD_1 dst_unused:UNUSED_PAD src0_sel:DWORD
	v_rndne_f32_e32 v63, v63
	v_cvt_i32_f32_e32 v7, v7
	v_cvt_i32_f32_sdwa v60, v60 dst_sel:WORD_1 dst_unused:UNUSED_PAD src0_sel:DWORD
	v_rndne_f32_e32 v59, v59
	v_cvt_i32_f32_sdwa v63, v63 dst_sel:BYTE_3 dst_unused:UNUSED_PAD src0_sel:DWORD
	v_cvt_i32_f32_sdwa v59, v59 dst_sel:BYTE_3 dst_unused:UNUSED_PAD src0_sel:DWORD
	v_lshlrev_b32_e32 v61, 8, v61
	v_and_b32_e32 v64, 0xff0000, v64
	v_and_b32_e32 v60, 0xff0000, v60
	v_perm_b32 v7, v61, v7, s28
	v_or3_b32 v6, v6, v63, v64
	v_or3_b32 v7, v7, v59, v60
	global_store_dwordx2 v[4:5], v[6:7], off offset:1024
	v_mul_f32_e32 v7, v83, v56
	v_mul_f32_e32 v6, v83, v58
	v_rndne_f32_e32 v7, v7
	v_rndne_f32_e32 v6, v6
	v_cvt_i32_f32_e32 v7, v7
	v_cvt_i32_f32_e32 v6, v6
	v_mul_f32_e32 v53, v83, v53
	v_mul_f32_e32 v56, v83, v57
	v_lshlrev_b32_e32 v7, 8, v7
	v_perm_b32 v6, v7, v6, s28
	v_mul_f32_e32 v7, v83, v54
	v_rndne_f32_e32 v53, v53
	v_mul_f32_e32 v52, v83, v52
	v_rndne_f32_e32 v56, v56
	v_mul_f32_e32 v55, v83, v55
	v_rndne_f32_e32 v7, v7
	v_cvt_i32_f32_e32 v53, v53
	v_rndne_f32_e32 v52, v52
	v_mul_f32_e32 v51, v83, v51
	v_cvt_i32_f32_sdwa v56, v56 dst_sel:WORD_1 dst_unused:UNUSED_PAD src0_sel:DWORD
	v_rndne_f32_e32 v55, v55
	v_cvt_i32_f32_e32 v7, v7
	v_cvt_i32_f32_sdwa v52, v52 dst_sel:WORD_1 dst_unused:UNUSED_PAD src0_sel:DWORD
	v_rndne_f32_e32 v51, v51
	v_cvt_i32_f32_sdwa v55, v55 dst_sel:BYTE_3 dst_unused:UNUSED_PAD src0_sel:DWORD
	v_cvt_i32_f32_sdwa v51, v51 dst_sel:BYTE_3 dst_unused:UNUSED_PAD src0_sel:DWORD
; __device__ __forceinline__ float bflo(unsigned w) { return __uint_as_float(w << 16); }
; __device__ __forceinline__ float bfhi(unsigned w) { return __uint_as_float(w & 0xffff0000u); }
; __device__ __forceinline__ void quant_store8(const u32x4 (&w)[8], float inv, signed char* dst, int lane) { u32x2* qp = (u32x2*)dst + lane;
; #pragma unroll
;     for (int j = 0; j < 8; ++j) { const unsigned ww[4] = {w[j].x, w[j].y, w[j].z, w[j].w}; unsigned o2[2];
; #pragma unroll
;         for (int h2 = 0; h2 < 2; ++h2) { const int q0 = (int)rintf(bflo(ww[2 * h2]) * inv), q1 = (int)rintf(bfhi(ww[2 * h2]) * inv), q2 = (int)rintf(bflo(ww[2 * h2 + 1]) * inv), q3 = (int)rintf(bfhi(ww[2 * h2 + 1]) * inv);
;             o2[h2] = (unsigned)(q0 & 255) | ((unsigned)(q1 & 255) << 8) | ((unsigned)(q2 & 255) << 16) | ((unsigned)(q3 & 255) << 24); }
;         u32x2 o; o.x = o2[0]; o.y = o2[1]; qp[64 * j] = o; } }
; __global__ void __launch_bounds__(NWAVES * 64, 2) fwd(Args args) {
;     ...
;             for (int p = 0; p < 4; ++p) { const int n = 64 * bx + 8 * F.wave + 2 * p; float s0, s1;
;                 quant_rows2(W_inT + (size_t)(IN_Q0 + n) * DM, W_inT + (size_t)(IN_Q0 + n + 1) * DM, W_inq + (size_t)n * DM, W_inq + (size_t)(n + 1) * DM, F.lane, s0, s1);
;                 if (F.lane == 0) { colq[n] = s0; colq[n + 1] = s1; } }
	v_lshlrev_b32_e32 v53, 8, v53
	v_and_b32_e32 v56, 0xff0000, v56
	v_and_b32_e32 v52, 0xff0000, v52
	v_perm_b32 v7, v53, v7, s28
	v_or3_b32 v6, v6, v55, v56
	v_or3_b32 v7, v7, v51, v52
	global_store_dwordx2 v[4:5], v[6:7], off offset:1536
	v_mul_f32_e32 v7, v83, v48
	v_mul_f32_e32 v6, v83, v50
	v_rndne_f32_e32 v7, v7
	v_rndne_f32_e32 v6, v6
	v_cvt_i32_f32_e32 v7, v7
	v_cvt_i32_f32_e32 v6, v6
	v_mul_f32_e32 v45, v83, v45
	v_mul_f32_e32 v48, v83, v49
	v_lshlrev_b32_e32 v7, 8, v7
	v_perm_b32 v6, v7, v6, s28
	v_mul_f32_e32 v7, v83, v46
	v_rndne_f32_e32 v45, v45
	v_mul_f32_e32 v44, v83, v44
	v_rndne_f32_e32 v48, v48
	v_mul_f32_e32 v47, v83, v47
	v_rndne_f32_e32 v7, v7
	v_cvt_i32_f32_e32 v45, v45
	v_rndne_f32_e32 v44, v44
	v_mul_f32_e32 v43, v83, v43
	v_cvt_i32_f32_sdwa v48, v48 dst_sel:WORD_1 dst_unused:UNUSED_PAD src0_sel:DWORD
	v_rndne_f32_e32 v47, v47
	v_cvt_i32_f32_e32 v7, v7
	v_cvt_i32_f32_sdwa v44, v44 dst_sel:WORD_1 dst_unused:UNUSED_PAD src0_sel:DWORD
	v_rndne_f32_e32 v43, v43
	v_cvt_i32_f32_sdwa v47, v47 dst_sel:BYTE_3 dst_unused:UNUSED_PAD src0_sel:DWORD
	v_cvt_i32_f32_sdwa v43, v43 dst_sel:BYTE_3 dst_unused:UNUSED_PAD src0_sel:DWORD
	v_lshlrev_b32_e32 v45, 8, v45
	v_and_b32_e32 v48, 0xff0000, v48
	v_and_b32_e32 v44, 0xff0000, v44
	v_perm_b32 v7, v45, v7, s28
	v_or3_b32 v6, v6, v47, v48
	v_or3_b32 v7, v7, v43, v44
	global_store_dwordx2 v[4:5], v[6:7], off offset:2048
	v_mul_f32_e32 v7, v83, v29
	v_mul_f32_e32 v6, v83, v42
	v_rndne_f32_e32 v7, v7
	v_rndne_f32_e32 v6, v6
	v_cvt_i32_f32_e32 v7, v7
	v_cvt_i32_f32_e32 v6, v6
	v_mul_f32_e32 v26, v83, v26
	v_mul_f32_e32 v29, v83, v41
	v_lshlrev_b32_e32 v7, 8, v7
	v_perm_b32 v6, v7, v6, s28
	v_mul_f32_e32 v7, v83, v27
	v_rndne_f32_e32 v26, v26
	v_mul_f32_e32 v25, v83, v25
	v_rndne_f32_e32 v29, v29
	v_mul_f32_e32 v28, v83, v28
	v_rndne_f32_e32 v7, v7
	v_cvt_i32_f32_e32 v26, v26
	v_rndne_f32_e32 v25, v25
	v_mul_f32_e32 v24, v83, v24
	v_cvt_i32_f32_sdwa v29, v29 dst_sel:WORD_1 dst_unused:UNUSED_PAD src0_sel:DWORD
	v_rndne_f32_e32 v28, v28
	v_cvt_i32_f32_e32 v7, v7
	v_cvt_i32_f32_sdwa v25, v25 dst_sel:WORD_1 dst_unused:UNUSED_PAD src0_sel:DWORD
	v_rndne_f32_e32 v24, v24
	v_cvt_i32_f32_sdwa v28, v28 dst_sel:BYTE_3 dst_unused:UNUSED_PAD src0_sel:DWORD
	v_cvt_i32_f32_sdwa v24, v24 dst_sel:BYTE_3 dst_unused:UNUSED_PAD src0_sel:DWORD
	v_lshlrev_b32_e32 v26, 8, v26
	v_and_b32_e32 v29, 0xff0000, v29
	v_and_b32_e32 v25, 0xff0000, v25
	v_perm_b32 v7, v26, v7, s28
	v_or3_b32 v6, v6, v28, v29
	v_or3_b32 v7, v7, v24, v25
	global_store_dwordx2 v[4:5], v[6:7], off offset:2560
	v_mul_f32_e32 v7, v83, v21
	v_mul_f32_e32 v6, v83, v23
	v_rndne_f32_e32 v7, v7
	v_rndne_f32_e32 v6, v6
	v_cvt_i32_f32_e32 v7, v7
	v_cvt_i32_f32_e32 v6, v6
	v_mul_f32_e32 v18, v83, v18
	v_mul_f32_e32 v21, v83, v22
	v_lshlrev_b32_e32 v7, 8, v7
	v_perm_b32 v6, v7, v6, s28
	v_mul_f32_e32 v7, v83, v19
	v_rndne_f32_e32 v18, v18
	v_mul_f32_e32 v17, v83, v17
	v_rndne_f32_e32 v21, v21
	v_mul_f32_e32 v20, v83, v20
	v_rndne_f32_e32 v7, v7
	v_cvt_i32_f32_e32 v18, v18
	v_rndne_f32_e32 v17, v17
	v_mul_f32_e32 v16, v83, v16
	v_cvt_i32_f32_sdwa v21, v21 dst_sel:WORD_1 dst_unused:UNUSED_PAD src0_sel:DWORD
	v_rndne_f32_e32 v20, v20
	v_cvt_i32_f32_e32 v7, v7
	v_cvt_i32_f32_sdwa v17, v17 dst_sel:WORD_1 dst_unused:UNUSED_PAD src0_sel:DWORD
	v_rndne_f32_e32 v16, v16
	v_cvt_i32_f32_sdwa v20, v20 dst_sel:BYTE_3 dst_unused:UNUSED_PAD src0_sel:DWORD
	v_cvt_i32_f32_sdwa v16, v16 dst_sel:BYTE_3 dst_unused:UNUSED_PAD src0_sel:DWORD
	v_lshlrev_b32_e32 v18, 8, v18
	v_and_b32_e32 v21, 0xff0000, v21
	v_and_b32_e32 v17, 0xff0000, v17
	v_perm_b32 v7, v18, v7, s28
	v_or3_b32 v6, v6, v20, v21
	v_or3_b32 v7, v7, v16, v17
	global_store_dwordx2 v[4:5], v[6:7], off offset:3072
	v_mul_f32_e32 v7, v83, v13
	v_mul_f32_e32 v6, v83, v15
	v_rndne_f32_e32 v7, v7
	v_rndne_f32_e32 v6, v6
	v_cvt_i32_f32_e32 v7, v7
	v_cvt_i32_f32_e32 v6, v6
	v_mul_f32_e32 v10, v83, v10
	v_mul_f32_e32 v13, v83, v14
	v_lshlrev_b32_e32 v7, 8, v7
	v_perm_b32 v6, v7, v6, s28
	v_mul_f32_e32 v7, v83, v11
	v_rndne_f32_e32 v10, v10
	v_mul_f32_e32 v9, v83, v9
	v_rndne_f32_e32 v13, v13
	v_mul_f32_e32 v12, v83, v12
	v_rndne_f32_e32 v7, v7
	v_cvt_i32_f32_e32 v10, v10
	v_rndne_f32_e32 v9, v9
	v_mul_f32_e32 v8, v83, v8
	v_cvt_i32_f32_sdwa v13, v13 dst_sel:WORD_1 dst_unused:UNUSED_PAD src0_sel:DWORD
	v_rndne_f32_e32 v12, v12
	v_cvt_i32_f32_e32 v7, v7
	v_cvt_i32_f32_sdwa v9, v9 dst_sel:WORD_1 dst_unused:UNUSED_PAD src0_sel:DWORD
	v_rndne_f32_e32 v8, v8
	v_cvt_i32_f32_sdwa v12, v12 dst_sel:BYTE_3 dst_unused:UNUSED_PAD src0_sel:DWORD
	v_cvt_i32_f32_sdwa v8, v8 dst_sel:BYTE_3 dst_unused:UNUSED_PAD src0_sel:DWORD
	v_lshlrev_b32_e32 v10, 8, v10
	v_and_b32_e32 v13, 0xff0000, v13
	v_and_b32_e32 v9, 0xff0000, v9
	v_perm_b32 v7, v10, v7, s28
	v_or3_b32 v6, v6, v12, v13
	v_or3_b32 v7, v7, v8, v9
	global_store_dwordx2 v[4:5], v[6:7], off offset:3584
	s_and_saveexec_b64 s[12:13], s[6:7]
	s_cbranch_execz .LBB0_271
	s_add_u32 s34, s78, s9
	s_addc_u32 s35, s79, s22
	global_store_dwordx2 v40, v[2:3], s[34:35]
	s_branch .LBB0_271

; #define LAS __attribute__((address_space(3)))
; __device__ __forceinline__ void gc_unit(LAS unsigned char* lds, int unit, const bf16_t* proj, const bf16_t* dSt, const float* gnorm, bf16_t* omix, int tid, int wave, int lane) {
;     ...
;     bf16x8 sfr[8];
;     { const bf16_t* sp = dSt + ((size_t)unit * 256 + 32 * wave + (lane & 31)) * 128 + (lane >> 5) * 8;
; #pragma unroll
;       for (int ks = 0; ks < 8; ++ks) sfr[ks] = *(const bf16x8*)(sp + ks * 16); }
;     { const int t = tid >> 3, c0 = (tid & 7) * 16; const bf16_t* qp = proj + (row0 + t) * PROJ_LD + C_GQ + h * 128 + c0;
;       const u32x4 q0 = *(const u32x4*)qp, q1 = *(const u32x4*)(qp + 8), k0 = *(const u32x4*)(qp + (C_GK - C_GQ)), k1 = *(const u32x4*)(qp + (C_GK - C_GQ) + 8);
;       u32x4 vr[4]; load_v(vr, proj + row0 * PROJ_LD + C_GV + h * 256, tid);
;     ...
; #pragma unroll
;       for (int ss = 0; ss < 4; ++ss) { const bf16x8 a0 = *(const LAS bf16x8*)(lds + L_AT + r * 144 + ss * 32 + hh * 16), a1 = *(const LAS bf16x8*)(lds + L_AT + (32 + r) * 144 + ss * 32 + hh * 16);
;           o0 = __builtin_amdgcn_mfma_f32_32x32x16_bf16(a0, vf[ss], o0, 0, 0, 0); o1 = __builtin_amdgcn_mfma_f32_32x32x16_bf16(a1, vf[ss], o1, 0, 0, 0); } }
;     {
; #pragma unroll
;       for (int ks = 0; ks < 8; ++ks) { const bf16x8 bb = sfr[ks];
;           const bf16x8 a0 = *(const LAS bf16x8*)(lds + L_QD + r * 272 + ks * 32 + hh * 16), a1 = *(const LAS bf16x8*)(lds + L_QD + (32 + r) * 272 + ks * 32 + hh * 16);
;           o0 = __builtin_amdgcn_mfma_f32_32x32x16_bf16(a0, bb, o0, 0, 0, 0); o1 = __builtin_amdgcn_mfma_f32_32x32x16_bf16(a1, bb, o1, 0, 0, 0); } }
;     __syncthreads();
;     ...
;         const u32x2 gw2 = *((const u32x2*)(proj + (row0 + c) * PROJ_LD + C_GOUT + h * 256) + lane);
.LBB0_1008:
	ds_read_b128 v[2:5], v105
	ds_read_b128 v[114:117], v105 offset:32
	ds_read_b128 v[22:25], v106
	ds_read_b128 v[118:121], v106 offset:32
	s_lshl_b32 s38, s38, 1
	s_add_u32 s50, s48, s33
	s_waitcnt lgkmcnt(3)
	v_mfma_f32_32x32x16_bf16 v[2:17], v[2:5], v[18:21], 0
	s_addc_u32 s51, s49, 0
	s_mul_i32 s40, s51, 0x3000
	s_mul_hi_u32 s41, s50, 0x3000
	s_add_i32 s41, s41, s40
	s_mul_i32 s40, s50, 0x3000
	s_add_u32 s40, s90, s40
	s_addc_u32 s41, s91, s41
	s_waitcnt lgkmcnt(1)
	v_mfma_f32_32x32x16_bf16 v[18:33], v[22:25], v[18:21], 0
	v_lshlrev_b32_e32 v78, 4, v182
	s_add_u32 s40, s40, s38
	s_addc_u32 s41, s41, 0
	v_lshlrev_b32_e32 v122, 3, v182
	v_add_u32_e32 v122, 0x2000, v122
	v_mov_b32_e32 v123, 0
	v_mov_b32_e32 v124, 0x3000
	v_mov_b32_e32 v125, 0
	v_lshl_add_u64 v[122:123], s[40:41], 0, v[122:123]
	global_load_dwordx2 v[126:127], v[122:123], off
	v_lshl_add_u64 v[122:123], v[122:123], 0, v[124:125]
	global_load_dwordx2 v[128:129], v[122:123], off
	v_lshl_add_u64 v[122:123], v[122:123], 0, v[124:125]
	global_load_dwordx2 v[130:131], v[122:123], off
	v_lshl_add_u64 v[122:123], v[122:123], 0, v[124:125]
	global_load_dwordx2 v[132:133], v[122:123], off
	v_lshl_add_u64 v[122:123], v[122:123], 0, v[124:125]
	global_load_dwordx2 v[134:135], v[122:123], off
	v_lshl_add_u64 v[122:123], v[122:123], 0, v[124:125]
	global_load_dwordx2 v[136:137], v[122:123], off
	v_lshl_add_u64 v[122:123], v[122:123], 0, v[124:125]
	global_load_dwordx2 v[138:139], v[122:123], off
	v_lshl_add_u64 v[122:123], v[122:123], 0, v[124:125]
	global_load_dwordx2 v[140:141], v[122:123], off
	v_lshl_add_u64 v[84:85], v[84:85], 0, s[44:45]
	s_add_i32 vcc_lo, s94, s88
	s_add_i32 vcc_hi, s61, s62
	s_cmpk_lt_i32 vcc_lo, 0x800
	s_cselect_b32 vcc_lo, vcc_lo, s94
	s_cselect_b32 vcc_hi, vcc_hi, s61
	s_and_b32 vcc_hi, vcc_hi, 0xfc0
	s_ashr_i32 s40, vcc_lo, 9
	s_lshl_b32 s40, s40, 12
	s_or_b32 s40, s40, vcc_hi
	s_mul_i32 s40, s40, 0x3000
	s_bfe_u32 vcc_hi, vcc_lo, 0x30006
	s_lshl_b32 vcc_hi, vcc_hi, 8
	s_add_u32 s40, s40, vcc_hi
	s_mov_b32 s41, 0
	v_lshl_add_u64 v[248:249], v[176:177], 0, s[40:41]
	s_add_u32 s40, s40, vcc_hi
	s_nop 0
	v_lshl_add_u64 v[250:251], v[178:179], 0, s[40:41]
	global_load_dwordx4 v[188:191], v[248:249], off
	global_load_dwordx4 v[184:187], v[248:249], off offset:16
	global_load_dwordx4 v[196:199], v[248:249], off offset:2048
	global_load_dwordx4 v[192:195], v[248:249], off offset:2064
	global_load_dwordx4 v[200:203], v[250:251], off
	global_load_dwordx4 v[208:211], v[250:251], off offset:16
	global_load_dwordx4 v[204:207], v[250:251], off offset:32
	global_load_dwordx4 v[212:215], v[250:251], off offset:48
	global_load_dwordx4 v[220:223], v[84:85], off offset:-224
	global_load_dwordx4 v[216:219], v[84:85], off offset:-192
	global_load_dwordx4 v[244:247], v[84:85], off offset:-160
	global_load_dwordx4 v[240:243], v[84:85], off offset:-128
	global_load_dwordx4 v[236:239], v[84:85], off offset:-96
	global_load_dwordx4 v[232:235], v[84:85], off offset:-64
	global_load_dwordx4 v[228:231], v[84:85], off offset:-32
	global_load_dwordx4 v[224:227], v[84:85], off
	v_mfma_f32_32x32x16_bf16 v[2:17], v[114:117], v[74:77], v[2:17]
	s_waitcnt lgkmcnt(0)
	v_mfma_f32_32x32x16_bf16 v[18:33], v[118:121], v[74:77], v[18:33]
	ds_read_b128 v[74:77], v105 offset:64
	ds_read_b128 v[114:117], v105 offset:96
	s_waitcnt lgkmcnt(1)
	v_mfma_f32_32x32x16_bf16 v[2:17], v[74:77], v[70:73], v[2:17]
	ds_read_b128 v[74:77], v106 offset:64
	ds_read_b128 v[118:121], v106 offset:96
	s_waitcnt lgkmcnt(1)
	v_mfma_f32_32x32x16_bf16 v[18:33], v[74:77], v[70:73], v[18:33]
	v_mfma_f32_32x32x16_bf16 v[2:17], v[114:117], v[66:69], v[2:17]
	s_waitcnt lgkmcnt(0)
	v_mfma_f32_32x32x16_bf16 v[18:33], v[118:121], v[66:69], v[18:33]
	ds_read_b128 v[66:69], v107 offset:4096
	ds_read_b128 v[70:73], v107 offset:4128
	s_waitcnt lgkmcnt(1)
	v_mfma_f32_32x32x16_bf16 v[2:17], v[66:69], v[38:41], v[2:17]
	ds_read_b128 v[66:69], v108 offset:4096
	ds_read_b128 v[74:77], v108 offset:4128
	s_waitcnt lgkmcnt(1)
	v_mfma_f32_32x32x16_bf16 v[18:33], v[66:69], v[38:41], v[18:33]
	v_mfma_f32_32x32x16_bf16 v[2:17], v[70:73], v[34:37], v[2:17]
	s_waitcnt lgkmcnt(0)
	v_mfma_f32_32x32x16_bf16 v[18:33], v[74:77], v[34:37], v[18:33]
	ds_read_b128 v[34:37], v107 offset:4160
	ds_read_b128 v[38:41], v107 offset:4192
	s_waitcnt lgkmcnt(1)
	v_mfma_f32_32x32x16_bf16 v[2:17], v[34:37], v[62:65], v[2:17]
	ds_read_b128 v[34:37], v108 offset:4160
	ds_read_b128 v[66:69], v108 offset:4192
	s_waitcnt lgkmcnt(1)
	v_mfma_f32_32x32x16_bf16 v[18:33], v[34:37], v[62:65], v[18:33]
	v_mfma_f32_32x32x16_bf16 v[2:17], v[38:41], v[58:61], v[2:17]
	ds_read_b128 v[34:37], v107 offset:4224
	ds_read_b128 v[38:41], v107 offset:4256
	s_waitcnt lgkmcnt(2)
	v_mfma_f32_32x32x16_bf16 v[18:33], v[66:69], v[58:61], v[18:33]
	s_waitcnt lgkmcnt(1)
	v_mfma_f32_32x32x16_bf16 v[2:17], v[34:37], v[54:57], v[2:17]
	ds_read_b128 v[34:37], v108 offset:4224
	ds_read_b128 v[58:61], v108 offset:4256
	s_waitcnt lgkmcnt(1)
	v_mfma_f32_32x32x16_bf16 v[18:33], v[34:37], v[54:57], v[18:33]
	v_mfma_f32_32x32x16_bf16 v[2:17], v[38:41], v[50:53], v[2:17]
	ds_read_b128 v[34:37], v107 offset:4288
	ds_read_b128 v[38:41], v107 offset:4320
	s_waitcnt lgkmcnt(2)
	v_mfma_f32_32x32x16_bf16 v[18:33], v[58:61], v[50:53], v[18:33]
	s_waitcnt lgkmcnt(1)
	v_mfma_f32_32x32x16_bf16 v[2:17], v[34:37], v[46:49], v[2:17]
	ds_read_b128 v[34:37], v108 offset:4288
	ds_read_b128 v[50:53], v108 offset:4320
	s_waitcnt lgkmcnt(0)
	s_barrier
; #define LAS __attribute__((address_space(3)))
; __device__ __forceinline__ int crow(int r, int hi) { return (r & 3) + 8 * (r >> 2) + 4 * hi; }
; __device__ __forceinline__ int crow(int r, int hi) { return (r & 3) + 8 * (r >> 2) + 4 * hi; }
; __device__ __forceinline__ void gc_unit(LAS unsigned char* lds, int unit, const bf16_t* proj, const bf16_t* dSt, const float* gnorm, bf16_t* omix, int tid, int wave, int lane) {
;     ...
;     __syncthreads();
; #pragma unroll
;     for (int i = 0; i < 16; ++i) { const int c = crow(i, hh); *(LAS float*)(lds + L_OT + c * 1040 + (32 * wave + r) * 4) = o0[i]; *(LAS float*)(lds + L_OT + (32 + c) * 1040 + (32 * wave + r) * 4) = o1[i]; }
;     __syncthreads();
;     const f32x4 g = *((const f32x4*)gnorm + lane);
; #pragma unroll
;     for (int rr = 0; rr < 8; ++rr) { const int c = 8 * wave + rr; const f32x4 v = *(const LAS f32x4*)(lds + L_OT + c * 1040 + lane * 16);
;         float ss = (v[0] * v[0] + v[1] * v[1]) + (v[2] * v[2] + v[3] * v[3]);
; #pragma unroll
;         for (int o = 1; o < 64; o <<= 1) ss += __shfl_xor(ss, o);
;         const float rs = 1.0f / sqrtf(ss * (1.0f / 256.0f) + EPS);
	v_mfma_f32_32x32x16_bf16 v[18:33], v[34:37], v[46:49], v[18:33]
	v_mfma_f32_32x32x16_bf16 v[2:17], v[38:41], v[42:45], v[2:17]
	v_mfma_f32_32x32x16_bf16 v[18:33], v[50:53], v[42:45], v[18:33]
	s_nop 10
	ds_write_b32 v109, v2 offset:4096
	v_add_u32_e32 v2, s52, v98
	ds_write_b32 v109, v18 offset:37376
	ds_write_b32 v109, v3 offset:5136
	ds_write_b32 v109, v19 offset:38416
	ds_write_b32 v109, v4 offset:6176
	ds_write_b32 v109, v20 offset:39456
	ds_write_b32 v109, v5 offset:7216
	ds_write_b32 v109, v21 offset:40496
	ds_write_b32 v109, v6 offset:12416
	ds_write_b32 v109, v22 offset:45696
	ds_write_b32 v109, v7 offset:13456
	ds_write_b32 v109, v23 offset:46736
	ds_write_b32 v109, v8 offset:14496
	ds_write_b32 v109, v24 offset:47776
	ds_write_b32 v109, v9 offset:15536
	ds_write_b32 v109, v25 offset:48816
	ds_write_b32 v109, v10 offset:20736
	ds_write_b32 v109, v26 offset:54016
	ds_write_b32 v109, v11 offset:21776
	ds_write_b32 v109, v27 offset:55056
	ds_write_b32 v109, v12 offset:22816
	ds_write_b32 v109, v28 offset:56096
	ds_write_b32 v109, v13 offset:23856
	ds_write_b32 v109, v29 offset:57136
	ds_write_b32 v109, v14 offset:29056
	ds_write_b32 v109, v30 offset:62336
	ds_write_b32 v109, v15 offset:30096
	ds_write_b32 v109, v31 offset:63376
	ds_write_b32 v109, v16 offset:31136
	ds_write_b32 v109, v32 offset:64416
	ds_write_b32 v109, v17 offset:32176
	ds_write_b32 v109, v33 offset:65456
	s_waitcnt lgkmcnt(0)
	s_barrier
	ds_read_b128 v[14:17], v2 offset:4096
	v_and_b32_e32 v2, 64, v112
	v_add_u32_e32 v6, 64, v2
	s_waitcnt lgkmcnt(0)
	v_mul_f32_e32 v2, v15, v15
	v_mul_f32_e32 v3, v17, v17
	v_fmac_f32_e32 v2, v14, v14
	v_fmac_f32_e32 v3, v16, v16
	v_add_f32_e32 v4, v2, v3
	v_xor_b32_e32 v2, 1, v112
	v_cmp_lt_i32_e32 vcc, v2, v6
	s_nop 1
	v_cndmask_b32_e32 v2, v112, v2, vcc
	v_lshlrev_b32_e32 v8, 2, v2
	s_nop 1
	v_mov_b32_dpp v5, v4 quad_perm:[1,0,3,2] row_mask:0xf bank_mask:0xf
	v_lshl_add_u64 v[2:3], v[96:97], 0, v[78:79]
	v_lshlrev_b32_e32 v78, 3, v182
	s_waitcnt lgkmcnt(0)
	v_add_f32_e32 v7, v4, v5
	v_xor_b32_e32 v4, 2, v112
	v_cmp_lt_i32_e32 vcc, v4, v6
	s_nop 1
	v_cndmask_b32_e32 v4, v112, v4, vcc
	v_lshlrev_b32_e32 v9, 2, v4
	v_lshl_add_u64 v[4:5], s[40:41], 0, v[78:79]
	v_add_co_u32_e32 v4, vcc, s66, v4
	s_nop 1
	v_mov_b32_dpp v10, v7 quad_perm:[2,3,0,1] row_mask:0xf bank_mask:0xf
	s_nop 0
	v_addc_co_u32_e32 v5, vcc, 0, v5, vcc
	v_xor_b32_e32 v4, 4, v112
	v_cmp_lt_i32_e32 vcc, v4, v6
	s_waitcnt lgkmcnt(0)
	v_add_f32_e32 v7, v7, v10
	v_cndmask_b32_e32 v4, v112, v4, vcc
	v_lshlrev_b32_e32 v10, 2, v4
	s_nop 1
	v_mov_b32_dpp v11, v7 row_half_mirror row_mask:0xf bank_mask:0xf
	s_waitcnt lgkmcnt(0)
	v_add_f32_e32 v7, v7, v11
	v_xor_b32_e32 v11, 8, v112
	v_cmp_lt_i32_e32 vcc, v11, v6
	s_nop 1
	v_cndmask_b32_e32 v11, v112, v11, vcc
	v_lshlrev_b32_e32 v11, 2, v11
	s_nop 1
	v_mov_b32_dpp v12, v7 row_mirror row_mask:0xf bank_mask:0xf
	s_waitcnt lgkmcnt(0)
	v_add_f32_e32 v7, v7, v12
	v_xor_b32_e32 v12, 16, v112
	v_cmp_lt_i32_e32 vcc, v12, v6
	s_nop 1
	v_cndmask_b32_e32 v12, v112, v12, vcc
	v_lshlrev_b32_e32 v12, 2, v12
	s_waitcnt lgkmcnt(0)
	v_mov_b32_e32 v13, v7
	s_nop 1
	v_permlane16_swap_b32_e32 v7, v13
	s_nop 0
	v_add_f32_e32 v7, v7, v13
	v_xor_b32_e32 v13, 32, v112
	v_cmp_lt_i32_e32 vcc, v13, v6
	s_nop 1
	v_cndmask_b32_e32 v6, v112, v13, vcc
	v_lshlrev_b32_e32 v13, 2, v6
	s_waitcnt lgkmcnt(0)
	v_mov_b32_e32 v6, v7
	s_nop 1
	v_permlane32_swap_b32_e32 v6, v7
	s_nop 0
	v_add_f32_e32 v6, v6, v7
	v_fmamk_f32 v6, v6, 0x3b800000, v110
	v_mul_f32_e32 v7, 0x4f800000, v6
	v_cmp_gt_f32_e32 vcc, s65, v6
	s_nop 1
	v_cndmask_b32_e32 v6, v6, v7, vcc
	v_sqrt_f32_e32 v7, v6
	s_nop 0
	v_add_u32_e32 v20, -1, v7
	v_fma_f32 v21, -v20, v7, v6
	v_cmp_ge_f32_e64 s[40:41], 0, v21
	v_add_u32_e32 v21, 1, v7
	s_nop 0
	v_cndmask_b32_e64 v20, v7, v20, s[40:41]
	v_fma_f32 v7, -v21, v7, v6
	v_cmp_lt_f32_e64 s[40:41], 0, v7
	s_nop 1
	v_cndmask_b32_e64 v7, v20, v21, s[40:41]
	v_mul_f32_e32 v20, 0x37800000, v7
	v_cndmask_b32_e32 v7, v7, v20, vcc
	v_cmp_class_f32_e32 vcc, v6, v111
	s_nop 1
	v_cndmask_b32_e32 v20, v7, v6, vcc
	v_div_scale_f32 v21, s[40:41], v20, v20, 1.0
	v_rcp_f32_e32 v22, v21
	v_lshl_add_u64 v[6:7], v[82:83], 0, s[38:39]
	v_fma_f32 v23, -v21, v22, 1.0
	v_fmac_f32_e32 v22, v23, v22
	v_div_scale_f32 v23, vcc, 1.0, v20, 1.0
	v_mul_f32_e32 v24, v23, v22
	v_fma_f32 v25, -v21, v24, v23
	v_fmac_f32_e32 v24, v25, v22
	v_fma_f32 v21, -v21, v24, v23
	v_div_fmas_f32 v21, v21, v22, v24
	s_waitcnt vmcnt(16)
; #define LAS __attribute__((address_space(3)))
; __device__ __forceinline__ unsigned cvt_pk_bf16(float lo, float hi) { unsigned r; asm volatile("v_cvt_pk_bf16_f32 %0, %1, %2" : "=v"(r) : "v"(lo), "v"(hi)); return r; }
; __device__ __forceinline__ float bflo(unsigned w) { return __uint_as_float(w << 16); }
; __device__ __forceinline__ float bfhi(unsigned w) { return __uint_as_float(w & 0xffff0000u); }
; __device__ __forceinline__ void gc_unit(LAS unsigned char* lds, int unit, const bf16_t* proj, const bf16_t* dSt, const float* gnorm, bf16_t* omix, int tid, int wave, int lane) {
;     ...
;     for (int rr = 0; rr < 8; ++rr) { const int c = 8 * wave + rr; const f32x4 v = *(const LAS f32x4*)(lds + L_OT + c * 1040 + lane * 16);
;         float ss = (v[0] * v[0] + v[1] * v[1]) + (v[2] * v[2] + v[3] * v[3]);
; #pragma unroll
;         for (int o = 1; o < 64; o <<= 1) ss += __shfl_xor(ss, o);
;         const float rs = 1.0f / sqrtf(ss * (1.0f / 256.0f) + EPS);
;         const u32x2 gw2 = *((const u32x2*)(proj + (row0 + c) * PROJ_LD + C_GOUT + h * 256) + lane);
;         const float z0 = bflo(gw2.x), z1 = bfhi(gw2.x), z2 = bflo(gw2.y), z3 = bfhi(gw2.y);
;         const float p0 = v[0] * rs * g[0] * (z0 / (1.0f + __expf(-z0))), p1 = v[1] * rs * g[1] * (z1 / (1.0f + __expf(-z1)));
;         const float p2 = v[2] * rs * g[2] * (z2 / (1.0f + __expf(-z2))), p3 = v[3] * rs * g[3] * (z3 / (1.0f + __expf(-z3)));
;         u32x2 w; w.x = cvt_pk_bf16(p0, p1); w.y = cvt_pk_bf16(p2, p3); *((u32x2*)(omix + (row0 + c) * DM + h * 256) + lane) = w; }
	v_mov_b32_e32 v2, v172
	v_mov_b32_e32 v3, v173
	v_mov_b32_e32 v4, v174
	v_mov_b32_e32 v5, v175
	v_mov_b32_e32 v18, v126
	v_mov_b32_e32 v19, v127
	v_lshlrev_b32_e32 v22, 16, v18
	v_mul_f32_e32 v23, 0xbfb8aa3b, v22
	v_exp_f32_e32 v23, v23
	v_div_fixup_f32 v20, v21, v20, 1.0
	v_and_b32_e32 v18, 0xffff0000, v18
	v_mul_f32_e32 v14, v14, v20
	v_add_f32_e32 v21, 1.0, v23
	v_div_scale_f32 v23, s[40:41], v21, v21, v22
	v_rcp_f32_e32 v24, v23
	v_mul_f32_e32 v14, v2, v14
	v_lshlrev_b32_e32 v25, 16, v19
	v_mul_f32_e32 v15, v15, v20
	v_fma_f32 v26, -v23, v24, 1.0
	v_fmac_f32_e32 v24, v26, v24
	v_div_scale_f32 v26, vcc, v22, v21, v22
	v_mul_f32_e32 v27, v26, v24
	v_fma_f32 v28, -v23, v27, v26
	v_fmac_f32_e32 v27, v28, v24
	v_fma_f32 v23, -v23, v27, v26
	v_mul_f32_e32 v26, 0xbfb8aa3b, v18
	v_exp_f32_e32 v26, v26
	v_div_fmas_f32 v23, v23, v24, v27
	v_div_fixup_f32 v21, v23, v21, v22
	v_mul_f32_e32 v14, v21, v14
	v_add_f32_e32 v22, 1.0, v26
	v_div_scale_f32 v23, s[40:41], v22, v22, v18
	v_rcp_f32_e32 v24, v23
	v_mul_f32_e32 v15, v3, v15
	v_and_b32_e32 v19, 0xffff0000, v19
	v_mul_f32_e32 v16, v16, v20
	v_fma_f32 v21, -v23, v24, 1.0
	v_fmac_f32_e32 v24, v21, v24
	v_div_scale_f32 v21, vcc, v18, v22, v18
	v_mul_f32_e32 v26, v21, v24
	v_fma_f32 v27, -v23, v26, v21
	v_fmac_f32_e32 v26, v27, v24
	v_fma_f32 v21, -v23, v26, v21
	v_mul_f32_e32 v23, 0xbfb8aa3b, v25
	v_exp_f32_e32 v23, v23
	v_div_fmas_f32 v21, v21, v24, v26
	v_div_fixup_f32 v18, v21, v22, v18
	v_mul_f32_e32 v15, v18, v15
	v_add_f32_e32 v21, 1.0, v23
	v_div_scale_f32 v22, s[40:41], v21, v21, v25
	v_rcp_f32_e32 v23, v22
	v_mul_f32_e32 v16, v4, v16
	v_mul_f32_e32 v17, v17, v20
	v_mul_f32_e32 v17, v5, v17
	v_fma_f32 v18, -v22, v23, 1.0
	v_fmac_f32_e32 v23, v18, v23
	v_div_scale_f32 v18, vcc, v25, v21, v25
	v_mul_f32_e32 v24, v18, v23
	v_fma_f32 v26, -v22, v24, v18
	v_fmac_f32_e32 v24, v26, v23
	v_fma_f32 v18, -v22, v24, v18
	v_mul_f32_e32 v22, 0xbfb8aa3b, v19
	v_exp_f32_e32 v22, v22
	v_div_fmas_f32 v18, v18, v23, v24
	v_div_fixup_f32 v18, v18, v21, v25
	v_mul_f32_e32 v16, v18, v16
	v_add_f32_e32 v21, 1.0, v22
	v_div_scale_f32 v22, s[40:41], v21, v21, v19
	v_rcp_f32_e32 v23, v22
	s_lshl_b64 s[40:41], s[50:51], 13
	s_add_u32 s50, s48, s53
	s_addc_u32 s51, s49, 0
	v_fma_f32 v18, -v22, v23, 1.0
	v_fmac_f32_e32 v23, v18, v23
	v_div_scale_f32 v18, vcc, v19, v21, v19
	v_mul_f32_e32 v20, v18, v23
	v_fma_f32 v24, -v22, v20, v18
	v_fmac_f32_e32 v20, v24, v23
	v_fma_f32 v18, -v22, v20, v18
	v_div_fmas_f32 v18, v18, v23, v20
	v_div_fixup_f32 v18, v18, v21, v19
	v_mul_f32_e32 v17, v18, v17
	v_cvt_pk_bf16_f32 v14, v14, v15
	v_cvt_pk_bf16_f32 v15, v16, v17
	v_lshl_add_u64 v[16:17], v[6:7], 0, s[40:41]
	s_mul_i32 s40, s51, 0x3000
	s_mul_hi_u32 s41, s50, 0x3000
	s_add_i32 s41, s41, s40
	s_mul_i32 s40, s50, 0x3000
	s_add_u32 s40, s90, s40
	s_addc_u32 s41, s91, s41
	s_add_u32 s40, s40, s38
	s_addc_u32 s41, s41, 0
	v_lshl_add_u64 v[20:21], s[40:41], 0, v[78:79]
	v_add_co_u32_e32 v20, vcc, s66, v20
	global_store_dwordx2 v[16:17], v[14:15], off
	s_nop 0
	v_addc_co_u32_e32 v21, vcc, 0, v21, vcc
	v_add_u32_e32 v14, s54, v98
	ds_read_b128 v[16:19], v14 offset:4096
	s_waitcnt lgkmcnt(0)
	v_mul_f32_e32 v15, v17, v17
	v_mul_f32_e32 v22, v19, v19
	v_fmac_f32_e32 v15, v16, v16
	v_fmac_f32_e32 v22, v18, v18
	v_add_f32_e32 v15, v15, v22
	s_nop 1
	v_add_f32_dpp v15, v15, v15 quad_perm:[1,0,3,2] row_mask:0xf bank_mask:0xf
	s_nop 1
	v_add_f32_dpp v15, v15, v15 quad_perm:[2,3,0,1] row_mask:0xf bank_mask:0xf
	s_nop 1
	v_add_f32_dpp v15, v15, v15 row_half_mirror row_mask:0xf bank_mask:0xf
	s_nop 1
	v_add_f32_dpp v15, v15, v15 row_mirror row_mask:0xf bank_mask:0xf
	v_mov_b32_e32 v22, v15
	s_nop 1
	v_permlane16_swap_b32_e32 v15, v22
	s_nop 0
	v_add_f32_e32 v15, v15, v22
	v_mov_b32_e32 v22, v15
	s_nop 1
	v_permlane32_swap_b32_e32 v15, v22
	s_nop 0
	v_add_f32_e32 v15, v15, v22
	v_fmamk_f32 v15, v15, 0x3b800000, v110
	v_mul_f32_e32 v22, 0x4f800000, v15
	v_cmp_gt_f32_e32 vcc, s65, v15
	s_nop 1
	v_cndmask_b32_e32 v15, v15, v22, vcc
	v_sqrt_f32_e32 v22, v15
	s_nop 0
	v_add_u32_e32 v23, -1, v22
	v_fma_f32 v24, -v23, v22, v15
	v_cmp_ge_f32_e64 s[40:41], 0, v24
	v_add_u32_e32 v24, 1, v22
	s_nop 0
	v_cndmask_b32_e64 v23, v22, v23, s[40:41]
	v_fma_f32 v22, -v24, v22, v15
	v_cmp_lt_f32_e64 s[40:41], 0, v22
	s_nop 1
	v_cndmask_b32_e64 v22, v23, v24, s[40:41]
	v_mul_f32_e32 v23, 0x37800000, v22
	v_cndmask_b32_e32 v22, v22, v23, vcc
	v_cmp_class_f32_e32 vcc, v15, v111
	s_nop 1
	v_cndmask_b32_e32 v15, v22, v15, vcc
	v_div_scale_f32 v22, s[40:41], v15, v15, 1.0
	v_rcp_f32_e32 v23, v22
	s_nop 0
	v_fma_f32 v24, -v22, v23, 1.0
	v_fmac_f32_e32 v23, v24, v23
	v_div_scale_f32 v24, vcc, 1.0, v15, 1.0
	v_mul_f32_e32 v25, v24, v23
	v_fma_f32 v26, -v22, v25, v24
	v_fmac_f32_e32 v25, v26, v23
	v_fma_f32 v22, -v22, v25, v24
	v_div_fmas_f32 v22, v22, v23, v25
	v_mov_b32_e32 v20, v128
	v_mov_b32_e32 v21, v129
	v_lshlrev_b32_e32 v23, 16, v20
	v_mul_f32_e32 v24, 0xbfb8aa3b, v23
	v_exp_f32_e32 v24, v24
	v_and_b32_e32 v20, 0xffff0000, v20
	v_div_fixup_f32 v15, v22, v15, 1.0
	v_mul_f32_e32 v16, v16, v15
	v_add_f32_e32 v24, 1.0, v24
	v_div_scale_f32 v25, s[40:41], v24, v24, v23
	v_rcp_f32_e32 v26, v25
	v_mul_f32_e32 v16, v2, v16
	v_lshlrev_b32_e32 v22, 16, v21
	v_mul_f32_e32 v17, v17, v15
	v_fma_f32 v27, -v25, v26, 1.0
	v_fmac_f32_e32 v26, v27, v26
	v_div_scale_f32 v27, vcc, v23, v24, v23
	v_mul_f32_e32 v28, v27, v26
	v_fma_f32 v29, -v25, v28, v27
	v_fmac_f32_e32 v28, v29, v26
	v_fma_f32 v25, -v25, v28, v27
	v_mul_f32_e32 v27, 0xbfb8aa3b, v20
	v_exp_f32_e32 v27, v27
	v_div_fmas_f32 v25, v25, v26, v28
	v_div_fixup_f32 v23, v25, v24, v23
	v_mul_f32_e32 v16, v23, v16
; #define LAS __attribute__((address_space(3)))
; __device__ __forceinline__ unsigned cvt_pk_bf16(float lo, float hi) { unsigned r; asm volatile("v_cvt_pk_bf16_f32 %0, %1, %2" : "=v"(r) : "v"(lo), "v"(hi)); return r; }
; __device__ __forceinline__ float bflo(unsigned w) { return __uint_as_float(w << 16); }
; __device__ __forceinline__ float bfhi(unsigned w) { return __uint_as_float(w & 0xffff0000u); }
; __device__ __forceinline__ void gc_unit(LAS unsigned char* lds, int unit, const bf16_t* proj, const bf16_t* dSt, const float* gnorm, bf16_t* omix, int tid, int wave, int lane) {
;     ...
;     for (int rr = 0; rr < 8; ++rr) { const int c = 8 * wave + rr; const f32x4 v = *(const LAS f32x4*)(lds + L_OT + c * 1040 + lane * 16);
;         float ss = (v[0] * v[0] + v[1] * v[1]) + (v[2] * v[2] + v[3] * v[3]);
; #pragma unroll
;         for (int o = 1; o < 64; o <<= 1) ss += __shfl_xor(ss, o);
;         const float rs = 1.0f / sqrtf(ss * (1.0f / 256.0f) + EPS);
;         const u32x2 gw2 = *((const u32x2*)(proj + (row0 + c) * PROJ_LD + C_GOUT + h * 256) + lane);
;         const float z0 = bflo(gw2.x), z1 = bfhi(gw2.x), z2 = bflo(gw2.y), z3 = bfhi(gw2.y);
;         const float p0 = v[0] * rs * g[0] * (z0 / (1.0f + __expf(-z0))), p1 = v[1] * rs * g[1] * (z1 / (1.0f + __expf(-z1)));
;         const float p2 = v[2] * rs * g[2] * (z2 / (1.0f + __expf(-z2))), p3 = v[3] * rs * g[3] * (z3 / (1.0f + __expf(-z3)));
;         u32x2 w; w.x = cvt_pk_bf16(p0, p1); w.y = cvt_pk_bf16(p2, p3); *((u32x2*)(omix + (row0 + c) * DM + h * 256) + lane) = w; }
	v_add_f32_e32 v24, 1.0, v27
	v_div_scale_f32 v25, s[40:41], v24, v24, v20
	v_rcp_f32_e32 v26, v25
	v_mul_f32_e32 v17, v3, v17
	v_and_b32_e32 v21, 0xffff0000, v21
	v_mul_f32_e32 v18, v18, v15
	v_fma_f32 v23, -v25, v26, 1.0
	v_fmac_f32_e32 v26, v23, v26
	v_div_scale_f32 v23, vcc, v20, v24, v20
	v_mul_f32_e32 v27, v23, v26
	v_fma_f32 v28, -v25, v27, v23
	v_fmac_f32_e32 v27, v28, v26
	v_fma_f32 v23, -v25, v27, v23
	v_mul_f32_e32 v25, 0xbfb8aa3b, v22
	v_exp_f32_e32 v25, v25
	v_div_fmas_f32 v23, v23, v26, v27
	v_div_fixup_f32 v20, v23, v24, v20
	v_mul_f32_e32 v17, v20, v17
	v_add_f32_e32 v23, 1.0, v25
	v_div_scale_f32 v24, s[40:41], v23, v23, v22
	v_rcp_f32_e32 v25, v24
	v_mul_f32_e32 v15, v19, v15
	v_mul_f32_e32 v18, v4, v18
	v_mul_f32_e32 v15, v5, v15
	v_fma_f32 v20, -v24, v25, 1.0
	v_fmac_f32_e32 v25, v20, v25
	v_div_scale_f32 v20, vcc, v22, v23, v22
	v_mul_f32_e32 v26, v20, v25
	v_fma_f32 v27, -v24, v26, v20
	v_fmac_f32_e32 v26, v27, v25
	v_fma_f32 v20, -v24, v26, v20
	v_mul_f32_e32 v24, 0xbfb8aa3b, v21
	v_exp_f32_e32 v24, v24
	v_div_fmas_f32 v20, v20, v25, v26
	v_div_fixup_f32 v20, v20, v23, v22
	v_mul_f32_e32 v18, v20, v18
	v_add_f32_e32 v22, 1.0, v24
	v_div_scale_f32 v23, s[40:41], v22, v22, v21
	v_rcp_f32_e32 v24, v23
	s_lshl_b64 s[40:41], s[50:51], 13
	s_add_u32 s50, s48, s55
	s_addc_u32 s51, s49, 0
	v_fma_f32 v19, -v23, v24, 1.0
	v_fmac_f32_e32 v24, v19, v24
	v_div_scale_f32 v19, vcc, v21, v22, v21
	v_mul_f32_e32 v20, v19, v24
	v_fma_f32 v25, -v23, v20, v19
	v_fmac_f32_e32 v20, v25, v24
	v_fma_f32 v19, -v23, v20, v19
	v_div_fmas_f32 v19, v19, v24, v20
	v_div_fixup_f32 v19, v19, v22, v21
	v_mul_f32_e32 v15, v19, v15
	v_cvt_pk_bf16_f32 v16, v16, v17
	v_cvt_pk_bf16_f32 v17, v18, v15
	v_lshl_add_u64 v[18:19], v[6:7], 0, s[40:41]
	s_mul_i32 s40, s51, 0x3000
	s_mul_hi_u32 s41, s50, 0x3000
	s_add_i32 s41, s41, s40
	s_mul_i32 s40, s50, 0x3000
	s_add_u32 s40, s90, s40
	s_addc_u32 s41, s91, s41
	s_add_u32 s40, s40, s38
	s_addc_u32 s41, s41, 0
	v_lshl_add_u64 v[20:21], s[40:41], 0, v[78:79]
	v_add_co_u32_e32 v20, vcc, s66, v20
	global_store_dwordx2 v[18:19], v[16:17], off
	s_nop 0
	v_addc_co_u32_e32 v21, vcc, 0, v21, vcc
	ds_read_b128 v[16:19], v14 offset:5136
	s_waitcnt lgkmcnt(0)
	v_mul_f32_e32 v15, v17, v17
	v_mul_f32_e32 v22, v19, v19
	v_fmac_f32_e32 v15, v16, v16
	v_fmac_f32_e32 v22, v18, v18
	v_add_f32_e32 v15, v15, v22
	s_nop 1
	v_add_f32_dpp v15, v15, v15 quad_perm:[1,0,3,2] row_mask:0xf bank_mask:0xf
	s_nop 1
	v_add_f32_dpp v15, v15, v15 quad_perm:[2,3,0,1] row_mask:0xf bank_mask:0xf
	s_nop 1
	v_add_f32_dpp v15, v15, v15 row_half_mirror row_mask:0xf bank_mask:0xf
	s_nop 1
	v_add_f32_dpp v15, v15, v15 row_mirror row_mask:0xf bank_mask:0xf
	v_mov_b32_e32 v22, v15
	s_nop 1
	v_permlane16_swap_b32_e32 v15, v22
	s_nop 0
	v_add_f32_e32 v15, v15, v22
	v_mov_b32_e32 v22, v15
	s_nop 1
	v_permlane32_swap_b32_e32 v15, v22
	s_nop 0
	v_add_f32_e32 v15, v15, v22
	v_fmamk_f32 v15, v15, 0x3b800000, v110
	v_mul_f32_e32 v22, 0x4f800000, v15
	v_cmp_gt_f32_e32 vcc, s65, v15
	s_nop 1
	v_cndmask_b32_e32 v15, v15, v22, vcc
	v_sqrt_f32_e32 v22, v15
	s_nop 0
	v_add_u32_e32 v23, -1, v22
	v_fma_f32 v24, -v23, v22, v15
	v_cmp_ge_f32_e64 s[40:41], 0, v24
	v_add_u32_e32 v24, 1, v22
	s_nop 0
	v_cndmask_b32_e64 v23, v22, v23, s[40:41]
	v_fma_f32 v22, -v24, v22, v15
	v_cmp_lt_f32_e64 s[40:41], 0, v22
	s_nop 1
	v_cndmask_b32_e64 v22, v23, v24, s[40:41]
	v_mul_f32_e32 v23, 0x37800000, v22
	v_cndmask_b32_e32 v22, v22, v23, vcc
	v_cmp_class_f32_e32 vcc, v15, v111
	s_nop 1
	v_cndmask_b32_e32 v15, v22, v15, vcc
	v_div_scale_f32 v22, s[40:41], v15, v15, 1.0
	v_rcp_f32_e32 v23, v22
	s_nop 0
	v_fma_f32 v24, -v22, v23, 1.0
	v_fmac_f32_e32 v23, v24, v23
	v_div_scale_f32 v24, vcc, 1.0, v15, 1.0
	v_mul_f32_e32 v25, v24, v23
	v_fma_f32 v26, -v22, v25, v24
	v_fmac_f32_e32 v25, v26, v23
	v_fma_f32 v22, -v22, v25, v24
	v_div_fmas_f32 v22, v22, v23, v25
	v_mov_b32_e32 v20, v130
	v_mov_b32_e32 v21, v131
	v_lshlrev_b32_e32 v23, 16, v20
	v_mul_f32_e32 v24, 0xbfb8aa3b, v23
	v_exp_f32_e32 v24, v24
	v_and_b32_e32 v20, 0xffff0000, v20
	v_div_fixup_f32 v15, v22, v15, 1.0
	v_mul_f32_e32 v16, v16, v15
	v_add_f32_e32 v24, 1.0, v24
	v_div_scale_f32 v25, s[40:41], v24, v24, v23
	v_rcp_f32_e32 v26, v25
	v_mul_f32_e32 v16, v2, v16
	v_lshlrev_b32_e32 v22, 16, v21
	v_mul_f32_e32 v17, v17, v15
	v_fma_f32 v27, -v25, v26, 1.0
	v_fmac_f32_e32 v26, v27, v26
	v_div_scale_f32 v27, vcc, v23, v24, v23
	v_mul_f32_e32 v28, v27, v26
	v_fma_f32 v29, -v25, v28, v27
	v_fmac_f32_e32 v28, v29, v26
	v_fma_f32 v25, -v25, v28, v27
	v_mul_f32_e32 v27, 0xbfb8aa3b, v20
	v_exp_f32_e32 v27, v27
	v_div_fmas_f32 v25, v25, v26, v28
	v_div_fixup_f32 v23, v25, v24, v23
	v_mul_f32_e32 v16, v23, v16
	v_add_f32_e32 v24, 1.0, v27
	v_div_scale_f32 v25, s[40:41], v24, v24, v20
	v_rcp_f32_e32 v26, v25
	v_mul_f32_e32 v17, v3, v17
	v_and_b32_e32 v21, 0xffff0000, v21
	v_mul_f32_e32 v18, v18, v15
	v_fma_f32 v23, -v25, v26, 1.0
	v_fmac_f32_e32 v26, v23, v26
	v_div_scale_f32 v23, vcc, v20, v24, v20
	v_mul_f32_e32 v27, v23, v26
	v_fma_f32 v28, -v25, v27, v23
	v_fmac_f32_e32 v27, v28, v26
	v_fma_f32 v23, -v25, v27, v23
	v_mul_f32_e32 v25, 0xbfb8aa3b, v22
	v_exp_f32_e32 v25, v25
	v_div_fmas_f32 v23, v23, v26, v27
	v_div_fixup_f32 v20, v23, v24, v20
	v_mul_f32_e32 v17, v20, v17
	v_add_f32_e32 v23, 1.0, v25
	v_div_scale_f32 v24, s[40:41], v23, v23, v22
	v_rcp_f32_e32 v25, v24
	v_mul_f32_e32 v15, v19, v15
	v_mul_f32_e32 v18, v4, v18
	v_mul_f32_e32 v15, v5, v15
	v_fma_f32 v20, -v24, v25, 1.0
	v_fmac_f32_e32 v25, v20, v25
	v_div_scale_f32 v20, vcc, v22, v23, v22
	v_mul_f32_e32 v26, v20, v25
	v_fma_f32 v27, -v24, v26, v20
	v_fmac_f32_e32 v26, v27, v25
	v_fma_f32 v20, -v24, v26, v20
	v_mul_f32_e32 v24, 0xbfb8aa3b, v21
	v_exp_f32_e32 v24, v24
	v_div_fmas_f32 v20, v20, v25, v26
	v_div_fixup_f32 v20, v20, v23, v22
	v_mul_f32_e32 v18, v20, v18
	v_add_f32_e32 v22, 1.0, v24
	v_div_scale_f32 v23, s[40:41], v22, v22, v21
	v_rcp_f32_e32 v24, v23
	s_lshl_b64 s[40:41], s[50:51], 13
	s_add_u32 s50, s48, s56
	s_addc_u32 s51, s49, 0
	v_fma_f32 v19, -v23, v24, 1.0
	v_fmac_f32_e32 v24, v19, v24
	v_div_scale_f32 v19, vcc, v21, v22, v21
	v_mul_f32_e32 v20, v19, v24
	v_fma_f32 v25, -v23, v20, v19
	v_fmac_f32_e32 v20, v25, v24
	v_fma_f32 v19, -v23, v20, v19
	v_div_fmas_f32 v19, v19, v24, v20
	v_div_fixup_f32 v19, v19, v22, v21
	v_mul_f32_e32 v15, v19, v15
	v_cvt_pk_bf16_f32 v16, v16, v17
	v_cvt_pk_bf16_f32 v17, v18, v15
	v_lshl_add_u64 v[18:19], v[6:7], 0, s[40:41]
	s_mul_i32 s40, s51, 0x3000
	s_mul_hi_u32 s41, s50, 0x3000
	s_add_i32 s41, s41, s40
	s_mul_i32 s40, s50, 0x3000
	s_add_u32 s40, s90, s40
	s_addc_u32 s41, s91, s41
	s_add_u32 s40, s40, s38
	s_addc_u32 s41, s41, 0
	v_lshl_add_u64 v[20:21], s[40:41], 0, v[78:79]
	v_add_co_u32_e32 v20, vcc, s66, v20
	global_store_dwordx2 v[18:19], v[16:17], off
	s_nop 0
	v_addc_co_u32_e32 v21, vcc, 0, v21, vcc
	ds_read_b128 v[16:19], v14 offset:6176
	s_waitcnt lgkmcnt(0)
; #define LAS __attribute__((address_space(3)))
; __device__ __forceinline__ unsigned cvt_pk_bf16(float lo, float hi) { unsigned r; asm volatile("v_cvt_pk_bf16_f32 %0, %1, %2" : "=v"(r) : "v"(lo), "v"(hi)); return r; }
; __device__ __forceinline__ float bflo(unsigned w) { return __uint_as_float(w << 16); }
; __device__ __forceinline__ float bfhi(unsigned w) { return __uint_as_float(w & 0xffff0000u); }
; __device__ __forceinline__ void gc_unit(LAS unsigned char* lds, int unit, const bf16_t* proj, const bf16_t* dSt, const float* gnorm, bf16_t* omix, int tid, int wave, int lane) {
;     ...
;     for (int rr = 0; rr < 8; ++rr) { const int c = 8 * wave + rr; const f32x4 v = *(const LAS f32x4*)(lds + L_OT + c * 1040 + lane * 16);
;         float ss = (v[0] * v[0] + v[1] * v[1]) + (v[2] * v[2] + v[3] * v[3]);
; #pragma unroll
;         for (int o = 1; o < 64; o <<= 1) ss += __shfl_xor(ss, o);
;         const float rs = 1.0f / sqrtf(ss * (1.0f / 256.0f) + EPS);
;         const u32x2 gw2 = *((const u32x2*)(proj + (row0 + c) * PROJ_LD + C_GOUT + h * 256) + lane);
;         const float z0 = bflo(gw2.x), z1 = bfhi(gw2.x), z2 = bflo(gw2.y), z3 = bfhi(gw2.y);
;         const float p0 = v[0] * rs * g[0] * (z0 / (1.0f + __expf(-z0))), p1 = v[1] * rs * g[1] * (z1 / (1.0f + __expf(-z1)));
;         const float p2 = v[2] * rs * g[2] * (z2 / (1.0f + __expf(-z2))), p3 = v[3] * rs * g[3] * (z3 / (1.0f + __expf(-z3)));
;         u32x2 w; w.x = cvt_pk_bf16(p0, p1); w.y = cvt_pk_bf16(p2, p3); *((u32x2*)(omix + (row0 + c) * DM + h * 256) + lane) = w; }
	v_mul_f32_e32 v15, v17, v17
	v_mul_f32_e32 v22, v19, v19
	v_fmac_f32_e32 v15, v16, v16
	v_fmac_f32_e32 v22, v18, v18
	v_add_f32_e32 v15, v15, v22
	s_nop 1
	v_add_f32_dpp v15, v15, v15 quad_perm:[1,0,3,2] row_mask:0xf bank_mask:0xf
	s_nop 1
	v_add_f32_dpp v15, v15, v15 quad_perm:[2,3,0,1] row_mask:0xf bank_mask:0xf
	s_nop 1
	v_add_f32_dpp v15, v15, v15 row_half_mirror row_mask:0xf bank_mask:0xf
	s_nop 1
	v_add_f32_dpp v15, v15, v15 row_mirror row_mask:0xf bank_mask:0xf
	v_mov_b32_e32 v22, v15
	s_nop 1
	v_permlane16_swap_b32_e32 v15, v22
	s_nop 0
	v_add_f32_e32 v15, v15, v22
	v_mov_b32_e32 v22, v15
	s_nop 1
	v_permlane32_swap_b32_e32 v15, v22
	s_nop 0
	v_add_f32_e32 v15, v15, v22
	v_fmamk_f32 v15, v15, 0x3b800000, v110
	v_mul_f32_e32 v22, 0x4f800000, v15
	v_cmp_gt_f32_e32 vcc, s65, v15
	s_nop 1
	v_cndmask_b32_e32 v15, v15, v22, vcc
	v_sqrt_f32_e32 v22, v15
	s_nop 0
	v_add_u32_e32 v23, -1, v22
	v_fma_f32 v24, -v23, v22, v15
	v_cmp_ge_f32_e64 s[40:41], 0, v24
	v_add_u32_e32 v24, 1, v22
	s_nop 0
	v_cndmask_b32_e64 v23, v22, v23, s[40:41]
	v_fma_f32 v22, -v24, v22, v15
	v_cmp_lt_f32_e64 s[40:41], 0, v22
	s_nop 1
	v_cndmask_b32_e64 v22, v23, v24, s[40:41]
	v_mul_f32_e32 v23, 0x37800000, v22
	v_cndmask_b32_e32 v22, v22, v23, vcc
	v_cmp_class_f32_e32 vcc, v15, v111
	s_nop 1
	v_cndmask_b32_e32 v15, v22, v15, vcc
	v_div_scale_f32 v22, s[40:41], v15, v15, 1.0
	v_rcp_f32_e32 v23, v22
	s_nop 0
	v_fma_f32 v24, -v22, v23, 1.0
	v_fmac_f32_e32 v23, v24, v23
	v_div_scale_f32 v24, vcc, 1.0, v15, 1.0
	v_mul_f32_e32 v25, v24, v23
	v_fma_f32 v26, -v22, v25, v24
	v_fmac_f32_e32 v25, v26, v23
	v_fma_f32 v22, -v22, v25, v24
	v_div_fmas_f32 v22, v22, v23, v25
	v_mov_b32_e32 v20, v132
	v_mov_b32_e32 v21, v133
	v_lshlrev_b32_e32 v23, 16, v20
	v_mul_f32_e32 v24, 0xbfb8aa3b, v23
	v_exp_f32_e32 v24, v24
	v_and_b32_e32 v20, 0xffff0000, v20
	v_div_fixup_f32 v15, v22, v15, 1.0
	v_mul_f32_e32 v16, v16, v15
	v_add_f32_e32 v24, 1.0, v24
	v_div_scale_f32 v25, s[40:41], v24, v24, v23
	v_rcp_f32_e32 v26, v25
	v_mul_f32_e32 v16, v2, v16
	v_lshlrev_b32_e32 v22, 16, v21
	v_mul_f32_e32 v17, v17, v15
	v_fma_f32 v27, -v25, v26, 1.0
	v_fmac_f32_e32 v26, v27, v26
	v_div_scale_f32 v27, vcc, v23, v24, v23
	v_mul_f32_e32 v28, v27, v26
	v_fma_f32 v29, -v25, v28, v27
	v_fmac_f32_e32 v28, v29, v26
	v_fma_f32 v25, -v25, v28, v27
	v_mul_f32_e32 v27, 0xbfb8aa3b, v20
	v_exp_f32_e32 v27, v27
	v_div_fmas_f32 v25, v25, v26, v28
	v_div_fixup_f32 v23, v25, v24, v23
	v_mul_f32_e32 v16, v23, v16
	v_add_f32_e32 v24, 1.0, v27
	v_div_scale_f32 v25, s[40:41], v24, v24, v20
	v_rcp_f32_e32 v26, v25
	v_mul_f32_e32 v17, v3, v17
	v_and_b32_e32 v21, 0xffff0000, v21
	v_mul_f32_e32 v18, v18, v15
	v_fma_f32 v23, -v25, v26, 1.0
	v_fmac_f32_e32 v26, v23, v26
	v_div_scale_f32 v23, vcc, v20, v24, v20
	v_mul_f32_e32 v27, v23, v26
	v_fma_f32 v28, -v25, v27, v23
	v_fmac_f32_e32 v27, v28, v26
	v_fma_f32 v23, -v25, v27, v23
	v_mul_f32_e32 v25, 0xbfb8aa3b, v22
	v_exp_f32_e32 v25, v25
	v_div_fmas_f32 v23, v23, v26, v27
	v_div_fixup_f32 v20, v23, v24, v20
	v_mul_f32_e32 v17, v20, v17
	v_add_f32_e32 v23, 1.0, v25
	v_div_scale_f32 v24, s[40:41], v23, v23, v22
	v_rcp_f32_e32 v25, v24
	v_mul_f32_e32 v15, v19, v15
	v_mul_f32_e32 v18, v4, v18
	v_mul_f32_e32 v15, v5, v15
	v_fma_f32 v20, -v24, v25, 1.0
	v_fmac_f32_e32 v25, v20, v25
	v_div_scale_f32 v20, vcc, v22, v23, v22
	v_mul_f32_e32 v26, v20, v25
	v_fma_f32 v27, -v24, v26, v20
	v_fmac_f32_e32 v26, v27, v25
	v_fma_f32 v20, -v24, v26, v20
	v_mul_f32_e32 v24, 0xbfb8aa3b, v21
	v_exp_f32_e32 v24, v24
	v_div_fmas_f32 v20, v20, v25, v26
	v_div_fixup_f32 v20, v20, v23, v22
	v_mul_f32_e32 v18, v20, v18
	v_add_f32_e32 v22, 1.0, v24
	v_div_scale_f32 v23, s[40:41], v22, v22, v21
	v_rcp_f32_e32 v24, v23
	s_lshl_b64 s[40:41], s[50:51], 13
	s_add_u32 s50, s48, s57
	s_addc_u32 s51, s49, 0
	v_fma_f32 v19, -v23, v24, 1.0
	v_fmac_f32_e32 v24, v19, v24
	v_div_scale_f32 v19, vcc, v21, v22, v21
	v_mul_f32_e32 v20, v19, v24
	v_fma_f32 v25, -v23, v20, v19
	v_fmac_f32_e32 v20, v25, v24
	v_fma_f32 v19, -v23, v20, v19
	v_div_fmas_f32 v19, v19, v24, v20
	v_div_fixup_f32 v19, v19, v22, v21
	v_mul_f32_e32 v15, v19, v15
	v_cvt_pk_bf16_f32 v16, v16, v17
	v_cvt_pk_bf16_f32 v17, v18, v15
	v_lshl_add_u64 v[18:19], v[6:7], 0, s[40:41]
	s_mul_i32 s40, s51, 0x3000
	s_mul_hi_u32 s41, s50, 0x3000
	s_add_i32 s41, s41, s40
	s_mul_i32 s40, s50, 0x3000
	s_add_u32 s40, s90, s40
	s_addc_u32 s41, s91, s41
	s_add_u32 s40, s40, s38
	s_addc_u32 s41, s41, 0
	v_lshl_add_u64 v[20:21], s[40:41], 0, v[78:79]
	v_add_co_u32_e32 v20, vcc, s66, v20
	global_store_dwordx2 v[18:19], v[16:17], off
	s_nop 0
	v_addc_co_u32_e32 v21, vcc, 0, v21, vcc
	ds_read_b128 v[16:19], v14 offset:7216
	s_waitcnt lgkmcnt(0)
; #define LAS __attribute__((address_space(3)))
; __device__ __forceinline__ unsigned cvt_pk_bf16(float lo, float hi) { unsigned r; asm volatile("v_cvt_pk_bf16_f32 %0, %1, %2" : "=v"(r) : "v"(lo), "v"(hi)); return r; }
; __device__ __forceinline__ float bflo(unsigned w) { return __uint_as_float(w << 16); }
; __device__ __forceinline__ float bfhi(unsigned w) { return __uint_as_float(w & 0xffff0000u); }
; __device__ __forceinline__ void gc_unit(LAS unsigned char* lds, int unit, const bf16_t* proj, const bf16_t* dSt, const float* gnorm, bf16_t* omix, int tid, int wave, int lane) {
;     ...
;     for (int rr = 0; rr < 8; ++rr) { const int c = 8 * wave + rr; const f32x4 v = *(const LAS f32x4*)(lds + L_OT + c * 1040 + lane * 16);
;         float ss = (v[0] * v[0] + v[1] * v[1]) + (v[2] * v[2] + v[3] * v[3]);
; #pragma unroll
;         for (int o = 1; o < 64; o <<= 1) ss += __shfl_xor(ss, o);
;         const float rs = 1.0f / sqrtf(ss * (1.0f / 256.0f) + EPS);
;         const u32x2 gw2 = *((const u32x2*)(proj + (row0 + c) * PROJ_LD + C_GOUT + h * 256) + lane);
;         const float z0 = bflo(gw2.x), z1 = bfhi(gw2.x), z2 = bflo(gw2.y), z3 = bfhi(gw2.y);
;         const float p0 = v[0] * rs * g[0] * (z0 / (1.0f + __expf(-z0))), p1 = v[1] * rs * g[1] * (z1 / (1.0f + __expf(-z1)));
;         const float p2 = v[2] * rs * g[2] * (z2 / (1.0f + __expf(-z2))), p3 = v[3] * rs * g[3] * (z3 / (1.0f + __expf(-z3)));
;         u32x2 w; w.x = cvt_pk_bf16(p0, p1); w.y = cvt_pk_bf16(p2, p3); *((u32x2*)(omix + (row0 + c) * DM + h * 256) + lane) = w; }
	v_mul_f32_e32 v15, v17, v17
	v_mul_f32_e32 v22, v19, v19
	v_fmac_f32_e32 v15, v16, v16
	v_fmac_f32_e32 v22, v18, v18
	v_add_f32_e32 v15, v15, v22
	s_nop 1
	v_add_f32_dpp v15, v15, v15 quad_perm:[1,0,3,2] row_mask:0xf bank_mask:0xf
	s_nop 1
	v_add_f32_dpp v15, v15, v15 quad_perm:[2,3,0,1] row_mask:0xf bank_mask:0xf
	s_nop 1
	v_add_f32_dpp v15, v15, v15 row_half_mirror row_mask:0xf bank_mask:0xf
	s_nop 1
	v_add_f32_dpp v15, v15, v15 row_mirror row_mask:0xf bank_mask:0xf
	v_mov_b32_e32 v22, v15
	s_nop 1
	v_permlane16_swap_b32_e32 v15, v22
	s_nop 0
	v_add_f32_e32 v15, v15, v22
	v_mov_b32_e32 v22, v15
	s_nop 1
	v_permlane32_swap_b32_e32 v15, v22
	s_nop 0
	v_add_f32_e32 v15, v15, v22
	v_fmamk_f32 v15, v15, 0x3b800000, v110
	v_mul_f32_e32 v22, 0x4f800000, v15
	v_cmp_gt_f32_e32 vcc, s65, v15
	s_nop 1
	v_cndmask_b32_e32 v15, v15, v22, vcc
	v_sqrt_f32_e32 v22, v15
	s_nop 0
	v_add_u32_e32 v23, -1, v22
	v_fma_f32 v24, -v23, v22, v15
	v_cmp_ge_f32_e64 s[40:41], 0, v24
	v_add_u32_e32 v24, 1, v22
	s_nop 0
	v_cndmask_b32_e64 v23, v22, v23, s[40:41]
	v_fma_f32 v22, -v24, v22, v15
	v_cmp_lt_f32_e64 s[40:41], 0, v22
	s_nop 1
	v_cndmask_b32_e64 v22, v23, v24, s[40:41]
	v_mul_f32_e32 v23, 0x37800000, v22
	v_cndmask_b32_e32 v22, v22, v23, vcc
	v_cmp_class_f32_e32 vcc, v15, v111
	s_nop 1
	v_cndmask_b32_e32 v15, v22, v15, vcc
	v_div_scale_f32 v22, s[40:41], v15, v15, 1.0
	v_rcp_f32_e32 v23, v22
	s_nop 0
	v_fma_f32 v24, -v22, v23, 1.0
	v_fmac_f32_e32 v23, v24, v23
	v_div_scale_f32 v24, vcc, 1.0, v15, 1.0
	v_mul_f32_e32 v25, v24, v23
	v_fma_f32 v26, -v22, v25, v24
	v_fmac_f32_e32 v25, v26, v23
	v_fma_f32 v22, -v22, v25, v24
	v_div_fmas_f32 v22, v22, v23, v25
	v_mov_b32_e32 v20, v134
	v_mov_b32_e32 v21, v135
	v_lshlrev_b32_e32 v23, 16, v20
	v_mul_f32_e32 v24, 0xbfb8aa3b, v23
	v_exp_f32_e32 v24, v24
	v_and_b32_e32 v20, 0xffff0000, v20
	v_div_fixup_f32 v15, v22, v15, 1.0
	v_mul_f32_e32 v16, v16, v15
	v_add_f32_e32 v24, 1.0, v24
	v_div_scale_f32 v25, s[40:41], v24, v24, v23
	v_rcp_f32_e32 v26, v25
	v_mul_f32_e32 v16, v2, v16
	v_lshlrev_b32_e32 v22, 16, v21
	v_mul_f32_e32 v17, v17, v15
	v_fma_f32 v27, -v25, v26, 1.0
	v_fmac_f32_e32 v26, v27, v26
	v_div_scale_f32 v27, vcc, v23, v24, v23
	v_mul_f32_e32 v28, v27, v26
	v_fma_f32 v29, -v25, v28, v27
	v_fmac_f32_e32 v28, v29, v26
	v_fma_f32 v25, -v25, v28, v27
	v_mul_f32_e32 v27, 0xbfb8aa3b, v20
	v_exp_f32_e32 v27, v27
	v_div_fmas_f32 v25, v25, v26, v28
	v_div_fixup_f32 v23, v25, v24, v23
	v_mul_f32_e32 v16, v23, v16
	v_add_f32_e32 v24, 1.0, v27
	v_div_scale_f32 v25, s[40:41], v24, v24, v20
	v_rcp_f32_e32 v26, v25
	v_mul_f32_e32 v17, v3, v17
	v_and_b32_e32 v21, 0xffff0000, v21
	v_mul_f32_e32 v18, v18, v15
	v_fma_f32 v23, -v25, v26, 1.0
	v_fmac_f32_e32 v26, v23, v26
	v_div_scale_f32 v23, vcc, v20, v24, v20
	v_mul_f32_e32 v27, v23, v26
	v_fma_f32 v28, -v25, v27, v23
	v_fmac_f32_e32 v27, v28, v26
	v_fma_f32 v23, -v25, v27, v23
	v_mul_f32_e32 v25, 0xbfb8aa3b, v22
	v_exp_f32_e32 v25, v25
	v_div_fmas_f32 v23, v23, v26, v27
	v_div_fixup_f32 v20, v23, v24, v20
	v_mul_f32_e32 v17, v20, v17
	v_add_f32_e32 v23, 1.0, v25
	v_div_scale_f32 v24, s[40:41], v23, v23, v22
	v_rcp_f32_e32 v25, v24
	v_mul_f32_e32 v15, v19, v15
	v_mul_f32_e32 v18, v4, v18
	v_mul_f32_e32 v15, v5, v15
	v_fma_f32 v20, -v24, v25, 1.0
	v_fmac_f32_e32 v25, v20, v25
	v_div_scale_f32 v20, vcc, v22, v23, v22
	v_mul_f32_e32 v26, v20, v25
	v_fma_f32 v27, -v24, v26, v20
	v_fmac_f32_e32 v26, v27, v25
	v_fma_f32 v20, -v24, v26, v20
	v_mul_f32_e32 v24, 0xbfb8aa3b, v21
	v_exp_f32_e32 v24, v24
	v_div_fmas_f32 v20, v20, v25, v26
	v_div_fixup_f32 v20, v20, v23, v22
	v_mul_f32_e32 v18, v20, v18
	v_add_f32_e32 v22, 1.0, v24
	v_div_scale_f32 v23, s[40:41], v22, v22, v21
	v_rcp_f32_e32 v24, v23
	s_lshl_b64 s[40:41], s[50:51], 13
	s_add_u32 s50, s48, s58
	s_addc_u32 s51, s49, 0
	v_fma_f32 v19, -v23, v24, 1.0
	v_fmac_f32_e32 v24, v19, v24
	v_div_scale_f32 v19, vcc, v21, v22, v21
	v_mul_f32_e32 v20, v19, v24
	v_fma_f32 v25, -v23, v20, v19
	v_fmac_f32_e32 v20, v25, v24
	v_fma_f32 v19, -v23, v20, v19
	v_div_fmas_f32 v19, v19, v24, v20
	v_div_fixup_f32 v19, v19, v22, v21
	v_mul_f32_e32 v15, v19, v15
	v_cvt_pk_bf16_f32 v16, v16, v17
	v_cvt_pk_bf16_f32 v17, v18, v15
	v_lshl_add_u64 v[18:19], v[6:7], 0, s[40:41]
	s_mul_i32 s40, s51, 0x3000
	s_mul_hi_u32 s41, s50, 0x3000
	s_add_i32 s41, s41, s40
	s_mul_i32 s40, s50, 0x3000
	s_add_u32 s40, s90, s40
	s_addc_u32 s41, s91, s41
	s_add_u32 s40, s40, s38
	s_addc_u32 s41, s41, 0
	v_lshl_add_u64 v[20:21], s[40:41], 0, v[78:79]
	v_add_co_u32_e32 v20, vcc, s66, v20
	global_store_dwordx2 v[18:19], v[16:17], off
	s_nop 0
	v_addc_co_u32_e32 v21, vcc, 0, v21, vcc
	ds_read_b128 v[16:19], v14 offset:8256
	s_waitcnt lgkmcnt(0)
; #define LAS __attribute__((address_space(3)))
; __device__ __forceinline__ unsigned cvt_pk_bf16(float lo, float hi) { unsigned r; asm volatile("v_cvt_pk_bf16_f32 %0, %1, %2" : "=v"(r) : "v"(lo), "v"(hi)); return r; }
; __device__ __forceinline__ float bflo(unsigned w) { return __uint_as_float(w << 16); }
; __device__ __forceinline__ float bfhi(unsigned w) { return __uint_as_float(w & 0xffff0000u); }
; __device__ __forceinline__ void gc_unit(LAS unsigned char* lds, int unit, const bf16_t* proj, const bf16_t* dSt, const float* gnorm, bf16_t* omix, int tid, int wave, int lane) {
;     ...
;     for (int rr = 0; rr < 8; ++rr) { const int c = 8 * wave + rr; const f32x4 v = *(const LAS f32x4*)(lds + L_OT + c * 1040 + lane * 16);
;         float ss = (v[0] * v[0] + v[1] * v[1]) + (v[2] * v[2] + v[3] * v[3]);
; #pragma unroll
;         for (int o = 1; o < 64; o <<= 1) ss += __shfl_xor(ss, o);
;         const float rs = 1.0f / sqrtf(ss * (1.0f / 256.0f) + EPS);
;         const u32x2 gw2 = *((const u32x2*)(proj + (row0 + c) * PROJ_LD + C_GOUT + h * 256) + lane);
;         const float z0 = bflo(gw2.x), z1 = bfhi(gw2.x), z2 = bflo(gw2.y), z3 = bfhi(gw2.y);
;         const float p0 = v[0] * rs * g[0] * (z0 / (1.0f + __expf(-z0))), p1 = v[1] * rs * g[1] * (z1 / (1.0f + __expf(-z1)));
;         const float p2 = v[2] * rs * g[2] * (z2 / (1.0f + __expf(-z2))), p3 = v[3] * rs * g[3] * (z3 / (1.0f + __expf(-z3)));
;         u32x2 w; w.x = cvt_pk_bf16(p0, p1); w.y = cvt_pk_bf16(p2, p3); *((u32x2*)(omix + (row0 + c) * DM + h * 256) + lane) = w; }
	v_mul_f32_e32 v15, v17, v17
	v_mul_f32_e32 v22, v19, v19
	v_fmac_f32_e32 v15, v16, v16
	v_fmac_f32_e32 v22, v18, v18
	v_add_f32_e32 v15, v15, v22
	s_nop 1
	v_add_f32_dpp v15, v15, v15 quad_perm:[1,0,3,2] row_mask:0xf bank_mask:0xf
	s_nop 1
	v_add_f32_dpp v15, v15, v15 quad_perm:[2,3,0,1] row_mask:0xf bank_mask:0xf
	s_nop 1
	v_add_f32_dpp v15, v15, v15 row_half_mirror row_mask:0xf bank_mask:0xf
	s_nop 1
	v_add_f32_dpp v15, v15, v15 row_mirror row_mask:0xf bank_mask:0xf
	v_mov_b32_e32 v22, v15
	s_nop 1
	v_permlane16_swap_b32_e32 v15, v22
	s_nop 0
	v_add_f32_e32 v15, v15, v22
	v_mov_b32_e32 v22, v15
	s_nop 1
	v_permlane32_swap_b32_e32 v15, v22
	s_nop 0
	v_add_f32_e32 v15, v15, v22
	v_fmamk_f32 v15, v15, 0x3b800000, v110
	v_mul_f32_e32 v22, 0x4f800000, v15
	v_cmp_gt_f32_e32 vcc, s65, v15
	s_nop 1
	v_cndmask_b32_e32 v15, v15, v22, vcc
	v_sqrt_f32_e32 v22, v15
	s_nop 0
	v_add_u32_e32 v23, -1, v22
	v_fma_f32 v24, -v23, v22, v15
	v_cmp_ge_f32_e64 s[40:41], 0, v24
	v_add_u32_e32 v24, 1, v22
	s_nop 0
	v_cndmask_b32_e64 v23, v22, v23, s[40:41]
	v_fma_f32 v22, -v24, v22, v15
	v_cmp_lt_f32_e64 s[40:41], 0, v22
	s_nop 1
	v_cndmask_b32_e64 v22, v23, v24, s[40:41]
	v_mul_f32_e32 v23, 0x37800000, v22
	v_cndmask_b32_e32 v22, v22, v23, vcc
	v_cmp_class_f32_e32 vcc, v15, v111
	s_nop 1
	v_cndmask_b32_e32 v15, v22, v15, vcc
	v_div_scale_f32 v22, s[40:41], v15, v15, 1.0
	v_rcp_f32_e32 v23, v22
	s_nop 0
	v_fma_f32 v24, -v22, v23, 1.0
	v_fmac_f32_e32 v23, v24, v23
	v_div_scale_f32 v24, vcc, 1.0, v15, 1.0
	v_mul_f32_e32 v25, v24, v23
	v_fma_f32 v26, -v22, v25, v24
	v_fmac_f32_e32 v25, v26, v23
	v_fma_f32 v22, -v22, v25, v24
	v_div_fmas_f32 v22, v22, v23, v25
	v_mov_b32_e32 v20, v136
	v_mov_b32_e32 v21, v137
	v_lshlrev_b32_e32 v23, 16, v20
	v_mul_f32_e32 v24, 0xbfb8aa3b, v23
	v_exp_f32_e32 v24, v24
	v_and_b32_e32 v20, 0xffff0000, v20
	v_div_fixup_f32 v15, v22, v15, 1.0
	v_mul_f32_e32 v16, v16, v15
	v_add_f32_e32 v24, 1.0, v24
	v_div_scale_f32 v25, s[40:41], v24, v24, v23
	v_rcp_f32_e32 v26, v25
	v_mul_f32_e32 v16, v2, v16
	v_lshlrev_b32_e32 v22, 16, v21
	v_mul_f32_e32 v17, v17, v15
	v_fma_f32 v27, -v25, v26, 1.0
	v_fmac_f32_e32 v26, v27, v26
	v_div_scale_f32 v27, vcc, v23, v24, v23
	v_mul_f32_e32 v28, v27, v26
	v_fma_f32 v29, -v25, v28, v27
	v_fmac_f32_e32 v28, v29, v26
	v_fma_f32 v25, -v25, v28, v27
	v_mul_f32_e32 v27, 0xbfb8aa3b, v20
	v_exp_f32_e32 v27, v27
	v_div_fmas_f32 v25, v25, v26, v28
	v_div_fixup_f32 v23, v25, v24, v23
	v_mul_f32_e32 v16, v23, v16
	v_add_f32_e32 v24, 1.0, v27
	v_div_scale_f32 v25, s[40:41], v24, v24, v20
	v_rcp_f32_e32 v26, v25
	v_mul_f32_e32 v17, v3, v17
	v_and_b32_e32 v21, 0xffff0000, v21
	v_mul_f32_e32 v18, v18, v15
	v_fma_f32 v23, -v25, v26, 1.0
	v_fmac_f32_e32 v26, v23, v26
	v_div_scale_f32 v23, vcc, v20, v24, v20
	v_mul_f32_e32 v27, v23, v26
	v_fma_f32 v28, -v25, v27, v23
	v_fmac_f32_e32 v27, v28, v26
	v_fma_f32 v23, -v25, v27, v23
	v_mul_f32_e32 v25, 0xbfb8aa3b, v22
	v_exp_f32_e32 v25, v25
	v_div_fmas_f32 v23, v23, v26, v27
	v_div_fixup_f32 v20, v23, v24, v20
	v_mul_f32_e32 v17, v20, v17
	v_add_f32_e32 v23, 1.0, v25
	v_div_scale_f32 v24, s[40:41], v23, v23, v22
	v_rcp_f32_e32 v25, v24
	v_mul_f32_e32 v15, v19, v15
	v_mul_f32_e32 v18, v4, v18
	v_mul_f32_e32 v15, v5, v15
	v_fma_f32 v20, -v24, v25, 1.0
	v_fmac_f32_e32 v25, v20, v25
	v_div_scale_f32 v20, vcc, v22, v23, v22
	v_mul_f32_e32 v26, v20, v25
	v_fma_f32 v27, -v24, v26, v20
	v_fmac_f32_e32 v26, v27, v25
	v_fma_f32 v20, -v24, v26, v20
	v_mul_f32_e32 v24, 0xbfb8aa3b, v21
	v_exp_f32_e32 v24, v24
	v_div_fmas_f32 v20, v20, v25, v26
	v_div_fixup_f32 v20, v20, v23, v22
	v_mul_f32_e32 v18, v20, v18
	v_add_f32_e32 v22, 1.0, v24
	v_div_scale_f32 v23, s[40:41], v22, v22, v21
	v_rcp_f32_e32 v24, v23
	s_lshl_b64 s[40:41], s[50:51], 13
	s_add_u32 s50, s48, s59
	s_addc_u32 s51, s49, 0
	v_fma_f32 v19, -v23, v24, 1.0
	v_fmac_f32_e32 v24, v19, v24
	v_div_scale_f32 v19, vcc, v21, v22, v21
	v_mul_f32_e32 v20, v19, v24
	v_fma_f32 v25, -v23, v20, v19
	v_fmac_f32_e32 v20, v25, v24
	v_fma_f32 v19, -v23, v20, v19
	v_div_fmas_f32 v19, v19, v24, v20
	v_div_fixup_f32 v19, v19, v22, v21
	v_mul_f32_e32 v15, v19, v15
	v_cvt_pk_bf16_f32 v16, v16, v17
	v_cvt_pk_bf16_f32 v17, v18, v15
	v_lshl_add_u64 v[18:19], v[6:7], 0, s[40:41]
	s_mul_i32 s40, s51, 0x3000
	s_mul_hi_u32 s41, s50, 0x3000
	s_add_i32 s41, s41, s40
	s_mul_i32 s40, s50, 0x3000
	s_add_u32 s40, s90, s40
	s_addc_u32 s41, s91, s41
	s_add_u32 s40, s40, s38
	s_addc_u32 s41, s41, 0
	v_lshl_add_u64 v[20:21], s[40:41], 0, v[78:79]
	v_add_co_u32_e32 v20, vcc, s66, v20
	global_store_dwordx2 v[18:19], v[16:17], off
	s_nop 0
	v_addc_co_u32_e32 v21, vcc, 0, v21, vcc
	ds_read_b128 v[16:19], v14 offset:9296
	s_waitcnt lgkmcnt(0)
; #define LAS __attribute__((address_space(3)))
; __device__ __forceinline__ unsigned cvt_pk_bf16(float lo, float hi) { unsigned r; asm volatile("v_cvt_pk_bf16_f32 %0, %1, %2" : "=v"(r) : "v"(lo), "v"(hi)); return r; }
; __device__ __forceinline__ float bflo(unsigned w) { return __uint_as_float(w << 16); }
; __device__ __forceinline__ float bfhi(unsigned w) { return __uint_as_float(w & 0xffff0000u); }
; __device__ __forceinline__ void gc_unit(LAS unsigned char* lds, int unit, const bf16_t* proj, const bf16_t* dSt, const float* gnorm, bf16_t* omix, int tid, int wave, int lane) {
;     ...
;     for (int rr = 0; rr < 8; ++rr) { const int c = 8 * wave + rr; const f32x4 v = *(const LAS f32x4*)(lds + L_OT + c * 1040 + lane * 16);
;         float ss = (v[0] * v[0] + v[1] * v[1]) + (v[2] * v[2] + v[3] * v[3]);
; #pragma unroll
;         for (int o = 1; o < 64; o <<= 1) ss += __shfl_xor(ss, o);
;         const float rs = 1.0f / sqrtf(ss * (1.0f / 256.0f) + EPS);
;         const u32x2 gw2 = *((const u32x2*)(proj + (row0 + c) * PROJ_LD + C_GOUT + h * 256) + lane);
;         const float z0 = bflo(gw2.x), z1 = bfhi(gw2.x), z2 = bflo(gw2.y), z3 = bfhi(gw2.y);
;         const float p0 = v[0] * rs * g[0] * (z0 / (1.0f + __expf(-z0))), p1 = v[1] * rs * g[1] * (z1 / (1.0f + __expf(-z1)));
;         const float p2 = v[2] * rs * g[2] * (z2 / (1.0f + __expf(-z2))), p3 = v[3] * rs * g[3] * (z3 / (1.0f + __expf(-z3)));
;         u32x2 w; w.x = cvt_pk_bf16(p0, p1); w.y = cvt_pk_bf16(p2, p3); *((u32x2*)(omix + (row0 + c) * DM + h * 256) + lane) = w; }
	v_mul_f32_e32 v15, v17, v17
	v_mul_f32_e32 v22, v19, v19
	v_fmac_f32_e32 v15, v16, v16
	v_fmac_f32_e32 v22, v18, v18
	v_add_f32_e32 v15, v15, v22
	s_nop 1
	v_add_f32_dpp v15, v15, v15 quad_perm:[1,0,3,2] row_mask:0xf bank_mask:0xf
	s_nop 1
	v_add_f32_dpp v15, v15, v15 quad_perm:[2,3,0,1] row_mask:0xf bank_mask:0xf
	s_nop 1
	v_add_f32_dpp v15, v15, v15 row_half_mirror row_mask:0xf bank_mask:0xf
	s_nop 1
	v_add_f32_dpp v15, v15, v15 row_mirror row_mask:0xf bank_mask:0xf
	v_mov_b32_e32 v22, v15
	s_nop 1
	v_permlane16_swap_b32_e32 v15, v22
	s_nop 0
	v_add_f32_e32 v15, v15, v22
	v_mov_b32_e32 v22, v15
	s_nop 1
	v_permlane32_swap_b32_e32 v15, v22
	s_nop 0
	v_add_f32_e32 v15, v15, v22
	v_fmamk_f32 v15, v15, 0x3b800000, v110
	v_mul_f32_e32 v22, 0x4f800000, v15
	v_cmp_gt_f32_e32 vcc, s65, v15
	s_nop 1
	v_cndmask_b32_e32 v15, v15, v22, vcc
	v_sqrt_f32_e32 v22, v15
	s_nop 0
	v_add_u32_e32 v23, -1, v22
	v_fma_f32 v24, -v23, v22, v15
	v_cmp_ge_f32_e64 s[40:41], 0, v24
	v_add_u32_e32 v24, 1, v22
	s_nop 0
	v_cndmask_b32_e64 v23, v22, v23, s[40:41]
	v_fma_f32 v22, -v24, v22, v15
	v_cmp_lt_f32_e64 s[40:41], 0, v22
	s_nop 1
	v_cndmask_b32_e64 v22, v23, v24, s[40:41]
	v_mul_f32_e32 v23, 0x37800000, v22
	v_cndmask_b32_e32 v22, v22, v23, vcc
	v_cmp_class_f32_e32 vcc, v15, v111
	s_nop 1
	v_cndmask_b32_e32 v15, v22, v15, vcc
	v_div_scale_f32 v22, s[40:41], v15, v15, 1.0
	v_rcp_f32_e32 v23, v22
	s_nop 0
	v_fma_f32 v24, -v22, v23, 1.0
	v_fmac_f32_e32 v23, v24, v23
	v_div_scale_f32 v24, vcc, 1.0, v15, 1.0
	v_mul_f32_e32 v25, v24, v23
	v_fma_f32 v26, -v22, v25, v24
	v_fmac_f32_e32 v25, v26, v23
	v_fma_f32 v22, -v22, v25, v24
	v_div_fmas_f32 v22, v22, v23, v25
	v_mov_b32_e32 v20, v138
	v_mov_b32_e32 v21, v139
	v_lshlrev_b32_e32 v23, 16, v20
	v_mul_f32_e32 v24, 0xbfb8aa3b, v23
	v_exp_f32_e32 v24, v24
	v_and_b32_e32 v20, 0xffff0000, v20
	v_div_fixup_f32 v15, v22, v15, 1.0
	v_mul_f32_e32 v16, v16, v15
	v_add_f32_e32 v24, 1.0, v24
	v_div_scale_f32 v25, s[40:41], v24, v24, v23
	v_rcp_f32_e32 v26, v25
	v_mul_f32_e32 v16, v2, v16
	v_lshlrev_b32_e32 v22, 16, v21
	v_mul_f32_e32 v17, v17, v15
	v_fma_f32 v27, -v25, v26, 1.0
	v_fmac_f32_e32 v26, v27, v26
	v_div_scale_f32 v27, vcc, v23, v24, v23
	v_mul_f32_e32 v28, v27, v26
	v_fma_f32 v29, -v25, v28, v27
	v_fmac_f32_e32 v28, v29, v26
	v_fma_f32 v25, -v25, v28, v27
	v_mul_f32_e32 v27, 0xbfb8aa3b, v20
	v_exp_f32_e32 v27, v27
	v_div_fmas_f32 v25, v25, v26, v28
	v_div_fixup_f32 v23, v25, v24, v23
	v_mul_f32_e32 v16, v23, v16
	v_add_f32_e32 v24, 1.0, v27
	v_div_scale_f32 v25, s[40:41], v24, v24, v20
	v_rcp_f32_e32 v26, v25
	v_mul_f32_e32 v17, v3, v17
	v_and_b32_e32 v21, 0xffff0000, v21
	v_mul_f32_e32 v18, v18, v15
	v_fma_f32 v23, -v25, v26, 1.0
	v_fmac_f32_e32 v26, v23, v26
	v_div_scale_f32 v23, vcc, v20, v24, v20
	v_mul_f32_e32 v27, v23, v26
	v_fma_f32 v28, -v25, v27, v23
	v_fmac_f32_e32 v27, v28, v26
	v_fma_f32 v23, -v25, v27, v23
	v_mul_f32_e32 v25, 0xbfb8aa3b, v22
	v_exp_f32_e32 v25, v25
	v_div_fmas_f32 v23, v23, v26, v27
	v_div_fixup_f32 v20, v23, v24, v20
	v_mul_f32_e32 v17, v20, v17
	v_add_f32_e32 v23, 1.0, v25
	v_div_scale_f32 v24, s[40:41], v23, v23, v22
	v_rcp_f32_e32 v25, v24
	v_mul_f32_e32 v15, v19, v15
	v_mul_f32_e32 v18, v4, v18
	v_mul_f32_e32 v15, v5, v15
	v_fma_f32 v20, -v24, v25, 1.0
	v_fmac_f32_e32 v25, v20, v25
	v_div_scale_f32 v20, vcc, v22, v23, v22
	v_mul_f32_e32 v26, v20, v25
	v_fma_f32 v27, -v24, v26, v20
	v_fmac_f32_e32 v26, v27, v25
	v_fma_f32 v20, -v24, v26, v20
	v_mul_f32_e32 v24, 0xbfb8aa3b, v21
	v_exp_f32_e32 v24, v24
	v_div_fmas_f32 v20, v20, v25, v26
	v_div_fixup_f32 v20, v20, v23, v22
	v_mul_f32_e32 v18, v20, v18
	v_add_f32_e32 v22, 1.0, v24
	v_div_scale_f32 v23, s[40:41], v22, v22, v21
	v_rcp_f32_e32 v24, v23
	s_lshl_b64 s[40:41], s[50:51], 13
	s_add_u32 s48, s48, s60
	s_addc_u32 s49, s49, 0
	v_fma_f32 v19, -v23, v24, 1.0
	v_fmac_f32_e32 v24, v19, v24
	v_div_scale_f32 v19, vcc, v21, v22, v21
	v_mul_f32_e32 v20, v19, v24
	v_fma_f32 v25, -v23, v20, v19
	v_fmac_f32_e32 v20, v25, v24
	v_fma_f32 v19, -v23, v20, v19
	v_div_fmas_f32 v19, v19, v24, v20
	v_div_fixup_f32 v19, v19, v22, v21
	v_mul_f32_e32 v15, v19, v15
	v_cvt_pk_bf16_f32 v16, v16, v17
	v_cvt_pk_bf16_f32 v17, v18, v15
	v_lshl_add_u64 v[18:19], v[6:7], 0, s[40:41]
	s_mul_i32 s40, s49, 0x3000
	s_mul_hi_u32 s41, s48, 0x3000
	s_add_i32 s41, s41, s40
	s_mul_i32 s40, s48, 0x3000
	s_add_u32 s40, s90, s40
	s_addc_u32 s41, s91, s41
	s_add_u32 s40, s40, s38
	s_addc_u32 s41, s41, 0
	global_store_dwordx2 v[18:19], v[16:17], off
	v_lshl_add_u64 v[18:19], s[40:41], 0, v[78:79]
	v_add_co_u32_e32 v18, vcc, s66, v18
	ds_read_b128 v[14:17], v14 offset:10336
	s_nop 0
	v_addc_co_u32_e32 v19, vcc, 0, v19, vcc
	s_add_i32 s94, s94, s88
	s_waitcnt lgkmcnt(0)
; #define LAS __attribute__((address_space(3)))
; __device__ __forceinline__ unsigned cvt_pk_bf16(float lo, float hi) { unsigned r; asm volatile("v_cvt_pk_bf16_f32 %0, %1, %2" : "=v"(r) : "v"(lo), "v"(hi)); return r; }
; __device__ __forceinline__ float bflo(unsigned w) { return __uint_as_float(w << 16); }
; __device__ __forceinline__ float bfhi(unsigned w) { return __uint_as_float(w & 0xffff0000u); }
; __device__ __forceinline__ void gc_unit(LAS unsigned char* lds, int unit, const bf16_t* proj, const bf16_t* dSt, const float* gnorm, bf16_t* omix, int tid, int wave, int lane) {
;     ...
;     for (int rr = 0; rr < 8; ++rr) { const int c = 8 * wave + rr; const f32x4 v = *(const LAS f32x4*)(lds + L_OT + c * 1040 + lane * 16);
;         float ss = (v[0] * v[0] + v[1] * v[1]) + (v[2] * v[2] + v[3] * v[3]);
; #pragma unroll
;         for (int o = 1; o < 64; o <<= 1) ss += __shfl_xor(ss, o);
;         const float rs = 1.0f / sqrtf(ss * (1.0f / 256.0f) + EPS);
;         const u32x2 gw2 = *((const u32x2*)(proj + (row0 + c) * PROJ_LD + C_GOUT + h * 256) + lane);
;         const float z0 = bflo(gw2.x), z1 = bfhi(gw2.x), z2 = bflo(gw2.y), z3 = bfhi(gw2.y);
;         const float p0 = v[0] * rs * g[0] * (z0 / (1.0f + __expf(-z0))), p1 = v[1] * rs * g[1] * (z1 / (1.0f + __expf(-z1)));
;         const float p2 = v[2] * rs * g[2] * (z2 / (1.0f + __expf(-z2))), p3 = v[3] * rs * g[3] * (z3 / (1.0f + __expf(-z3)));
;         u32x2 w; w.x = cvt_pk_bf16(p0, p1); w.y = cvt_pk_bf16(p2, p3); *((u32x2*)(omix + (row0 + c) * DM + h * 256) + lane) = w; }
;     __syncthreads();
	v_mul_f32_e32 v20, v15, v15
	v_mul_f32_e32 v21, v17, v17
	v_fmac_f32_e32 v20, v14, v14
	v_fmac_f32_e32 v21, v16, v16
	v_add_f32_e32 v20, v20, v21
	ds_bpermute_b32 v8, v8, v20
	s_add_i32 s61, s61, s62
	s_waitcnt lgkmcnt(0)
	v_add_f32_e32 v8, v20, v8
	ds_bpermute_b32 v9, v9, v8
	s_waitcnt lgkmcnt(0)
	v_add_f32_e32 v8, v8, v9
	ds_bpermute_b32 v9, v10, v8
	s_waitcnt lgkmcnt(0)
	v_add_f32_e32 v8, v8, v9
	ds_bpermute_b32 v9, v11, v8
	s_waitcnt lgkmcnt(0)
	v_add_f32_e32 v8, v8, v9
	s_waitcnt lgkmcnt(0)
	v_mov_b32_e32 v9, v8
	s_nop 1
	v_permlane16_swap_b32_e32 v8, v9
	s_nop 0
	v_add_f32_e32 v8, v8, v9
	s_waitcnt lgkmcnt(0)
	v_mov_b32_e32 v9, v8
	s_nop 1
	v_permlane32_swap_b32_e32 v8, v9
	s_nop 0
	v_add_f32_e32 v8, v8, v9
	v_fmamk_f32 v8, v8, 0x3b800000, v110
	v_mul_f32_e32 v9, 0x4f800000, v8
	v_cmp_gt_f32_e32 vcc, s65, v8
	s_nop 1
	v_cndmask_b32_e32 v8, v8, v9, vcc
	v_sqrt_f32_e32 v9, v8
	s_nop 0
	v_add_u32_e32 v10, -1, v9
	v_fma_f32 v11, -v10, v9, v8
	v_cmp_ge_f32_e64 s[40:41], 0, v11
	v_add_u32_e32 v11, 1, v9
	s_nop 0
	v_cndmask_b32_e64 v10, v9, v10, s[40:41]
	v_fma_f32 v9, -v11, v9, v8
	v_cmp_lt_f32_e64 s[40:41], 0, v9
	s_nop 1
	v_cndmask_b32_e64 v9, v10, v11, s[40:41]
	v_mul_f32_e32 v10, 0x37800000, v9
	v_cndmask_b32_e32 v9, v9, v10, vcc
	v_cmp_class_f32_e32 vcc, v8, v111
	s_nop 1
	v_cndmask_b32_e32 v8, v9, v8, vcc
	v_div_scale_f32 v9, s[40:41], v8, v8, 1.0
	v_rcp_f32_e32 v10, v9
	s_nop 0
	v_fma_f32 v11, -v9, v10, 1.0
	v_fmac_f32_e32 v10, v11, v10
	v_div_scale_f32 v11, vcc, 1.0, v8, 1.0
	v_mul_f32_e32 v12, v11, v10
	v_fma_f32 v13, -v9, v12, v11
	v_fmac_f32_e32 v12, v13, v10
	v_fma_f32 v9, -v9, v12, v11
	v_div_fmas_f32 v9, v9, v10, v12
	v_mov_b32_e32 v18, v140
	v_mov_b32_e32 v19, v141
	v_lshlrev_b32_e32 v10, 16, v18
	v_mul_f32_e32 v11, 0xbfb8aa3b, v10
	v_exp_f32_e32 v11, v11
	v_div_fixup_f32 v8, v9, v8, 1.0
	v_and_b32_e32 v9, 0xffff0000, v18
	v_mul_f32_e32 v14, v14, v8
	v_add_f32_e32 v11, 1.0, v11
	v_div_scale_f32 v13, s[40:41], v11, v11, v10
	v_rcp_f32_e32 v18, v13
	v_mul_f32_e32 v2, v2, v14
	v_lshlrev_b32_e32 v12, 16, v19
	v_and_b32_e32 v19, 0xffff0000, v19
	v_fma_f32 v14, -v13, v18, 1.0
	v_fmac_f32_e32 v18, v14, v18
	v_div_scale_f32 v14, vcc, v10, v11, v10
	v_mul_f32_e32 v20, v14, v18
	v_fma_f32 v21, -v13, v20, v14
	v_fmac_f32_e32 v20, v21, v18
	v_fma_f32 v13, -v13, v20, v14
	v_mul_f32_e32 v14, 0xbfb8aa3b, v9
	v_exp_f32_e32 v14, v14
	v_div_fmas_f32 v13, v13, v18, v20
	v_div_fixup_f32 v10, v13, v11, v10
	v_mul_f32_e32 v2, v10, v2
	v_add_f32_e32 v11, 1.0, v14
	v_div_scale_f32 v13, s[40:41], v11, v11, v9
	v_rcp_f32_e32 v14, v13
	v_mul_f32_e32 v10, v15, v8
	v_mul_f32_e32 v3, v3, v10
	v_fma_f32 v10, -v13, v14, 1.0
	v_fmac_f32_e32 v14, v10, v14
	v_div_scale_f32 v10, vcc, v9, v11, v9
	v_mul_f32_e32 v15, v10, v14
	v_fma_f32 v18, -v13, v15, v10
	v_fmac_f32_e32 v15, v18, v14
	v_fma_f32 v10, -v13, v15, v10
	v_mul_f32_e32 v13, 0xbfb8aa3b, v12
	v_exp_f32_e32 v13, v13
	v_div_fmas_f32 v10, v10, v14, v15
	v_div_fixup_f32 v9, v10, v11, v9
	v_mul_f32_e32 v3, v9, v3
	v_add_f32_e32 v10, 1.0, v13
	v_div_scale_f32 v11, s[40:41], v10, v10, v12
	v_rcp_f32_e32 v13, v11
	v_mul_f32_e32 v9, v16, v8
	v_mul_f32_e32 v4, v4, v9
	v_mul_f32_e32 v8, v17, v8
	v_fma_f32 v9, -v11, v13, 1.0
	v_fmac_f32_e32 v13, v9, v13
	v_div_scale_f32 v9, vcc, v12, v10, v12
	v_mul_f32_e32 v14, v9, v13
	v_fma_f32 v15, -v11, v14, v9
	v_fmac_f32_e32 v14, v15, v13
	v_fma_f32 v9, -v11, v14, v9
	v_mul_f32_e32 v11, 0xbfb8aa3b, v19
	v_exp_f32_e32 v11, v11
	v_div_fmas_f32 v9, v9, v13, v14
	v_div_fixup_f32 v9, v9, v10, v12
	v_mul_f32_e32 v5, v5, v8
	v_add_f32_e32 v10, 1.0, v11
	v_div_scale_f32 v11, s[40:41], v10, v10, v19
	v_rcp_f32_e32 v12, v11
	v_mul_f32_e32 v4, v9, v4
	s_lshl_b64 s[40:41], s[48:49], 13
	v_cvt_pk_bf16_f32 v2, v2, v3
	v_fma_f32 v8, -v11, v12, 1.0
	v_fmac_f32_e32 v12, v8, v12
	v_div_scale_f32 v8, vcc, v19, v10, v19
	v_mul_f32_e32 v9, v8, v12
	v_fma_f32 v13, -v11, v9, v8
	v_fmac_f32_e32 v9, v13, v12
	v_fma_f32 v8, -v11, v9, v8
	v_div_fmas_f32 v8, v8, v12, v9
	v_div_fixup_f32 v8, v8, v10, v19
	v_mul_f32_e32 v5, v8, v5
	v_cvt_pk_bf16_f32 v3, v4, v5
	v_lshl_add_u64 v[4:5], v[6:7], 0, s[40:41]
	s_cmpk_lt_i32 s94, 0x800
	global_store_dwordx2 v[4:5], v[2:3], off
	s_barrier
	s_cbranch_scc0 .LBB0_1022

; __device__ __forceinline__ unsigned cvt_pk_bf16(float lo, float hi) { unsigned r; asm volatile("v_cvt_pk_bf16_f32 %0, %1, %2" : "=v"(r) : "v"(lo), "v"(hi)); return r; }
; __device__ __forceinline__ float bflo(unsigned w) { return __uint_as_float(w << 16); }
; __device__ __forceinline__ float bfhi(unsigned w) { return __uint_as_float(w & 0xffff0000u); }
;     __device__ __forceinline__ void operator()(const f32x4 (&acc)[2][2][4][2], const Unit& u, int wr, int wc, int fr, int fq) const {
;         const int row0 = u.pm * BM + wr * 64 + fr, col0 = u.pn * BM + wc * 32 + 8 * fq;
; #pragma unroll
;         for (int ai = 0; ai < 2; ++ai) {
;             u32x4 bw[4][2];
; #pragma unroll
;             for (int m = 0; m < 4; ++m)
; #pragma unroll
;                 for (int bj = 0; bj < 2; ++bj) bw[m][bj] = *(const u32x4*)((const bf16_t*)base + (size_t)(row0 + ai * HALF + m * 16) * DM + col0 + bj * HALF);
; #pragma unroll
;             for (int m = 0; m < 4; ++m) { const int row = row0 + ai * HALF + m * 16; const size_t off = (size_t)row * DM + col0; float ss = 0.f;
; #pragma unroll
;                 for (int bj = 0; bj < 2; ++bj) { const u32x4 w = bw[m][bj];
;                     const f32x4 b0 = {bflo(w.x), bfhi(w.x), bflo(w.y), bfhi(w.y)}, b1 = {bflo(w.z), bfhi(w.z), bflo(w.w), bfhi(w.w)};
;                     const f32x4 o0 = b0 + acc[ai][bj][m][0], o1 = b1 + acc[ai][bj][m][1];
;                     ss += ((o0[0] * o0[0] + o0[1] * o0[1]) + (o0[2] * o0[2] + o0[3] * o0[3])) + ((o1[0] * o1[0] + o1[1] * o1[1]) + (o1[2] * o1[2] + o1[3] * o1[3]));
;                     u32x4 w2; w2.x = cvt_pk_bf16(o0[0], o0[1]); w2.y = cvt_pk_bf16(o0[2], o0[3]); w2.z = cvt_pk_bf16(o1[0], o1[1]); w2.w = cvt_pk_bf16(o1[2], o1[3]);
;                     *(u32x4*)(hout + off + bj * HALF) = w2; }
;                 ss += __shfl_xor(ss, 16); ss += __shfl_xor(ss, 32);
;                 if (fq == 0) part[(size_t)row * 64 + u.pn * 4 + wc] = ss; }
.LBB0_1099:
	v_lshl_or_b32 v170, s8, 8, v191
	v_lshl_add_u32 v174, s26, 8, v183
	v_ashrrev_i32_e32 v171, 31, v170
	v_lshlrev_b64 v[206:207], 1, v[170:171]
	v_ashrrev_i32_e32 v175, 31, v174
	v_lshl_add_u64 v[172:173], s[74:75], 0, v[206:207]
	v_lshlrev_b64 v[196:197], 13, v[174:175]
	v_lshl_add_u64 v[130:131], v[172:173], 0, v[196:197]
	global_load_dwordx4 v[198:201], v[130:131], off
	global_load_dwordx4 v[202:205], v[130:131], off offset:256
	v_or_b32_e32 v186, 16, v174
	v_or_b32_e32 v180, 32, v174
	v_or_b32_e32 v176, 48, v174
	v_ashrrev_i32_e32 v187, 31, v186
	v_ashrrev_i32_e32 v181, 31, v180
	v_ashrrev_i32_e32 v177, 31, v176
	v_lshlrev_b64 v[188:189], 13, v[186:187]
	v_lshlrev_b64 v[184:185], 13, v[180:181]
	v_lshlrev_b64 v[178:179], 13, v[176:177]
	v_lshl_add_u64 v[130:131], v[172:173], 0, v[188:189]
	v_lshl_add_u64 v[132:133], v[172:173], 0, v[184:185]
	v_lshl_add_u64 v[208:209], v[172:173], 0, v[178:179]
	global_load_dwordx4 v[150:153], v[130:131], off
	global_load_dwordx4 v[146:149], v[130:131], off offset:256
	global_load_dwordx4 v[142:145], v[132:133], off
	global_load_dwordx4 v[138:141], v[132:133], off offset:256
	global_load_dwordx4 v[134:137], v[208:209], off
	s_nop 0
	global_load_dwordx4 v[130:133], v[208:209], off offset:256
	v_add_u32_e32 v218, 0x80, v174
	v_ashrrev_i32_e32 v219, 31, v218
	v_lshlrev_b64 v[218:219], 13, v[218:219]
	v_lshl_add_u64 v[218:219], v[172:173], 0, v[218:219]
	global_load_dwordx4 v[220:223], v[218:219], off
	global_load_dwordx4 v[224:227], v[218:219], off offset:256
	v_add_co_u32_e32 v218, vcc, 0x20000, v218
	s_nop 1
	v_addc_co_u32_e32 v219, vcc, 0, v219, vcc
	global_load_dwordx4 v[228:231], v[218:219], off
	global_load_dwordx4 v[232:235], v[218:219], off offset:256
	v_add_co_u32_e32 v218, vcc, 0x20000, v218
	s_nop 1
	v_addc_co_u32_e32 v219, vcc, 0, v219, vcc
	global_load_dwordx4 v[236:239], v[218:219], off
	global_load_dwordx4 v[240:243], v[218:219], off offset:256
	v_add_co_u32_e32 v218, vcc, 0x20000, v218
	s_nop 1
	v_addc_co_u32_e32 v219, vcc, 0, v219, vcc
	global_load_dwordx4 v[244:247], v[218:219], off
	global_load_dwordx4 v[248:251], v[218:219], off offset:256
	v_and_b32_e32 v209, 64, v195
	v_xor_b32_e32 v208, 16, v195
	v_add_u32_e32 v209, 64, v209
	v_xor_b32_e32 v210, 32, v195
	v_cmp_lt_i32_e32 vcc, v208, v209
	s_lshl_b32 s26, s8, 2
	s_ashr_i32 s27, s26, 31
	v_cndmask_b32_e32 v211, v195, v208, vcc
	v_cmp_lt_i32_e32 vcc, v210, v209
	v_lshl_add_u64 v[208:209], s[74:75], 0, v[196:197]
	v_lshlrev_b32_e32 v196, 2, v211
	v_cndmask_b32_e32 v216, v195, v210, vcc
	v_lshl_add_u64 v[206:207], v[208:209], 0, v[206:207]
	s_waitcnt vmcnt(0)
	v_lshlrev_b32_e32 v208, 16, v198
	v_and_b32_e32 v209, 0xffff0000, v198
	v_lshlrev_b32_e32 v198, 16, v199
	v_and_b32_e32 v199, 0xffff0000, v199
	v_lshlrev_b32_e32 v210, 16, v200
	v_and_b32_e32 v211, 0xffff0000, v200
	v_lshlrev_b32_e32 v200, 16, v201
	v_and_b32_e32 v201, 0xffff0000, v201
	v_lshlrev_b32_e32 v212, 16, v202
	v_and_b32_e32 v213, 0xffff0000, v202
	v_lshlrev_b32_e32 v202, 16, v203
	v_and_b32_e32 v203, 0xffff0000, v203
	v_lshlrev_b32_e32 v214, 16, v204
	v_and_b32_e32 v215, 0xffff0000, v204
	v_lshlrev_b32_e32 v204, 16, v205
	v_and_b32_e32 v205, 0xffff0000, v205
	v_pk_add_f32 v[128:129], v[128:129], v[198:199]
	v_pk_add_f32 v[126:127], v[126:127], v[208:209]
	v_pk_add_f32 v[124:125], v[124:125], v[200:201]
	v_pk_add_f32 v[122:123], v[122:123], v[210:211]
	v_pk_add_f32 v[120:121], v[120:121], v[202:203]
	v_pk_add_f32 v[118:119], v[118:119], v[212:213]
	v_pk_add_f32 v[198:199], v[116:117], v[204:205]
	v_pk_add_f32 v[200:201], v[114:115], v[214:215]
	v_mul_f32_e32 v116, v127, v127
	v_mul_f32_e32 v117, v129, v129
	v_mul_f32_e32 v197, v123, v123
	v_mul_f32_e32 v202, v125, v125
	v_cvt_pk_bf16_f32 v114, v126, v127
	v_cvt_pk_bf16_f32 v115, v128, v129
	v_mul_f32_e32 v127, v119, v119
	v_mul_f32_e32 v129, v121, v121
	v_mul_f32_e32 v203, v201, v201
	v_mul_f32_e32 v204, v199, v199
	v_fmac_f32_e32 v116, v126, v126
	v_fmac_f32_e32 v117, v128, v128
	v_fmac_f32_e32 v197, v122, v122
	v_fmac_f32_e32 v202, v124, v124
	v_fmac_f32_e32 v127, v118, v118
	v_fmac_f32_e32 v129, v120, v120
	v_fmac_f32_e32 v203, v200, v200
	v_fmac_f32_e32 v204, v198, v198
	v_add_f32_e32 v116, v116, v117
	v_add_f32_e32 v117, v197, v202
	v_add_f32_e32 v126, v127, v129
	v_add_f32_e32 v127, v203, v204
	v_add_f32_e32 v116, v116, v117
	v_add_f32_e32 v117, v126, v127
	v_add_f32_e32 v126, v116, v117
	v_cvt_pk_bf16_f32 v116, v122, v123
	v_cvt_pk_bf16_f32 v117, v124, v125
	global_store_dwordx4 v[206:207], v[114:117], off
	v_cvt_pk_bf16_f32 v118, v118, v119
	v_cvt_pk_bf16_f32 v119, v120, v121
	v_cvt_pk_bf16_f32 v120, v200, v201
	v_cvt_pk_bf16_f32 v121, v198, v199
	global_store_dwordx4 v[206:207], v[118:121], off offset:256
	s_waitcnt lgkmcnt(0)
	v_mov_b32_e32 v115, v126
	v_mov_b32_e32 v127, v126
	s_nop 1
	v_permlane16_swap_b32_e32 v115, v127
	s_nop 0
	v_add_f32_e32 v115, v115, v127
	v_lshlrev_b32_e32 v114, 2, v216
	ds_bpermute_b32 v116, v114, v115
	s_and_saveexec_b64 s[28:29], s[4:5]
	s_cbranch_execz .LBB0_1101
	v_lshlrev_b64 v[118:119], 8, v[174:175]
	v_lshl_add_u64 v[118:119], s[10:11], 0, v[118:119]
	v_lshl_add_u64 v[118:119], s[26:27], 2, v[118:119]
	s_lshl_b32 s8, s39, 2
	v_lshl_add_u64 v[118:119], v[118:119], 0, s[8:9]
	s_waitcnt lgkmcnt(0)
	v_add_f32_e32 v115, v115, v116
	global_store_dword v[118:119], v115, off
; __device__ __forceinline__ unsigned cvt_pk_bf16(float lo, float hi) { unsigned r; asm volatile("v_cvt_pk_bf16_f32 %0, %1, %2" : "=v"(r) : "v"(lo), "v"(hi)); return r; }
; __device__ __forceinline__ float bflo(unsigned w) { return __uint_as_float(w << 16); }
; __device__ __forceinline__ float bfhi(unsigned w) { return __uint_as_float(w & 0xffff0000u); }
;     __device__ __forceinline__ void operator()(const f32x4 (&acc)[2][2][4][2], const Unit& u, int wr, int wc, int fr, int fq) const {
;     ...
;                 for (int bj = 0; bj < 2; ++bj) bw[m][bj] = *(const u32x4*)((const bf16_t*)base + (size_t)(row0 + ai * HALF + m * 16) * DM + col0 + bj * HALF);
; #pragma unroll
;             for (int m = 0; m < 4; ++m) { const int row = row0 + ai * HALF + m * 16; const size_t off = (size_t)row * DM + col0; float ss = 0.f;
; #pragma unroll
;                 for (int bj = 0; bj < 2; ++bj) { const u32x4 w = bw[m][bj];
;                     const f32x4 b0 = {bflo(w.x), bfhi(w.x), bflo(w.y), bfhi(w.y)}, b1 = {bflo(w.z), bfhi(w.z), bflo(w.w), bfhi(w.w)};
;                     const f32x4 o0 = b0 + acc[ai][bj][m][0], o1 = b1 + acc[ai][bj][m][1];
;                     ss += ((o0[0] * o0[0] + o0[1] * o0[1]) + (o0[2] * o0[2] + o0[3] * o0[3])) + ((o1[0] * o1[0] + o1[1] * o1[1]) + (o1[2] * o1[2] + o1[3] * o1[3]));
;                     u32x4 w2; w2.x = cvt_pk_bf16(o0[0], o0[1]); w2.y = cvt_pk_bf16(o0[2], o0[3]); w2.z = cvt_pk_bf16(o1[0], o1[1]); w2.w = cvt_pk_bf16(o1[2], o1[3]);
;                     *(u32x4*)(hout + off + bj * HALF) = w2; }
;                 ss += __shfl_xor(ss, 16); ss += __shfl_xor(ss, 32);
;                 if (fq == 0) part[(size_t)row * 64 + u.pn * 4 + wc] = ss; }
.LBB0_1101:
	s_or_b64 exec, exec, s[28:29]
	s_waitcnt lgkmcnt(0)
	v_lshlrev_b32_e32 v116, 16, v150
	v_and_b32_e32 v117, 0xffff0000, v150
	v_lshlrev_b32_e32 v118, 16, v151
	v_and_b32_e32 v119, 0xffff0000, v151
	v_lshlrev_b32_e32 v120, 16, v152
	v_and_b32_e32 v121, 0xffff0000, v152
	v_lshlrev_b32_e32 v122, 16, v153
	v_and_b32_e32 v123, 0xffff0000, v153
	v_pk_add_f32 v[112:113], v[112:113], v[118:119]
	v_pk_add_f32 v[110:111], v[110:111], v[116:117]
	v_pk_add_f32 v[116:117], v[108:109], v[122:123]
	v_pk_add_f32 v[108:109], v[106:107], v[120:121]
	v_mul_f32_e32 v106, v111, v111
	v_mul_f32_e32 v107, v113, v113
	v_fmac_f32_e32 v106, v110, v110
	v_fmac_f32_e32 v107, v112, v112
	v_add_f32_e32 v106, v106, v107
	v_mul_f32_e32 v107, v109, v109
	v_mul_f32_e32 v115, v117, v117
	v_fmac_f32_e32 v107, v108, v108
	v_fmac_f32_e32 v115, v116, v116
	v_add_f32_e32 v107, v107, v115
	v_add_f32_e32 v115, v106, v107
	v_cvt_pk_bf16_f32 v106, v110, v111
	v_cvt_pk_bf16_f32 v107, v112, v113
	v_lshlrev_b32_e32 v110, 16, v146
	v_and_b32_e32 v111, 0xffff0000, v146
	v_lshlrev_b32_e32 v112, 16, v147
	v_and_b32_e32 v113, 0xffff0000, v147
	v_cvt_pk_bf16_f32 v108, v108, v109
	v_cvt_pk_bf16_f32 v109, v116, v117
	v_lshlrev_b32_e32 v116, 16, v148
	v_and_b32_e32 v117, 0xffff0000, v148
	v_pk_add_f32 v[104:105], v[104:105], v[112:113]
	v_pk_add_f32 v[102:103], v[102:103], v[110:111]
	v_lshlrev_b32_e32 v118, 16, v149
	v_and_b32_e32 v119, 0xffff0000, v149
	v_pk_add_f32 v[112:113], v[98:99], v[116:117]
	v_mul_f32_e32 v98, v103, v103
	v_mul_f32_e32 v99, v105, v105
	v_pk_add_f32 v[110:111], v[100:101], v[118:119]
	v_fmac_f32_e32 v98, v102, v102
	v_fmac_f32_e32 v99, v104, v104
	v_add_f32_e32 v98, v98, v99
	v_mul_f32_e32 v99, v113, v113
	v_mul_f32_e32 v100, v111, v111
	v_fmac_f32_e32 v99, v112, v112
	v_fmac_f32_e32 v100, v110, v110
	v_add_f32_e32 v99, v99, v100
	v_add_f32_e32 v98, v98, v99
	v_add_f32_e32 v101, v115, v98
	v_lshl_add_u64 v[98:99], s[74:75], 0, v[188:189]
	v_lshl_add_u64 v[116:117], v[170:171], 1, v[98:99]
	global_store_dwordx4 v[116:117], v[106:109], off
	v_cvt_pk_bf16_f32 v100, v102, v103
	s_waitcnt lgkmcnt(0)
	v_mov_b32_e32 v98, v101
	v_mov_b32_e32 v115, v101
	s_nop 1
	v_permlane16_swap_b32_e32 v98, v115
	s_nop 0
	v_add_f32_e32 v98, v98, v115
	ds_bpermute_b32 v99, v114, v98
	v_cvt_pk_bf16_f32 v101, v104, v105
	v_cvt_pk_bf16_f32 v102, v112, v113
	v_cvt_pk_bf16_f32 v103, v110, v111
	global_store_dwordx4 v[116:117], v[100:103], off offset:256
	s_and_saveexec_b64 s[28:29], s[4:5]
	s_cbranch_execz .LBB0_1103
	v_lshlrev_b64 v[100:101], 8, v[186:187]
	v_lshl_add_u64 v[100:101], s[10:11], 0, v[100:101]
	v_lshl_add_u64 v[100:101], s[26:27], 2, v[100:101]
	s_lshl_b32 s8, s39, 2
	v_lshl_add_u64 v[100:101], v[100:101], 0, s[8:9]
	s_waitcnt lgkmcnt(0)
	v_add_f32_e32 v98, v98, v99
	global_store_dword v[100:101], v98, off
.LBB0_1103:
	s_or_b64 exec, exec, s[28:29]
	v_lshlrev_b32_e32 v98, 16, v142
	s_waitcnt lgkmcnt(0)
	v_and_b32_e32 v99, 0xffff0000, v142
	v_lshlrev_b32_e32 v100, 16, v143
	v_and_b32_e32 v101, 0xffff0000, v143
	v_lshlrev_b32_e32 v102, 16, v144
	v_and_b32_e32 v103, 0xffff0000, v144
	v_lshlrev_b32_e32 v104, 16, v145
	v_and_b32_e32 v105, 0xffff0000, v145
	v_pk_add_f32 v[96:97], v[96:97], v[100:101]
	v_pk_add_f32 v[94:95], v[94:95], v[98:99]
	v_pk_add_f32 v[98:99], v[92:93], v[104:105]
	v_pk_add_f32 v[92:93], v[90:91], v[102:103]
	v_mul_f32_e32 v90, v95, v95
	v_mul_f32_e32 v91, v97, v97
	v_fmac_f32_e32 v90, v94, v94
	v_fmac_f32_e32 v91, v96, v96
	v_add_f32_e32 v90, v90, v91
	v_mul_f32_e32 v91, v93, v93
	v_mul_f32_e32 v100, v99, v99
	v_fmac_f32_e32 v91, v92, v92
	v_fmac_f32_e32 v100, v98, v98
	v_add_f32_e32 v91, v91, v100
	v_add_f32_e32 v102, v90, v91
	v_cvt_pk_bf16_f32 v90, v94, v95
	v_cvt_pk_bf16_f32 v91, v96, v97
	v_lshlrev_b32_e32 v94, 16, v138
	v_and_b32_e32 v95, 0xffff0000, v138
	v_lshlrev_b32_e32 v96, 16, v139
	v_and_b32_e32 v97, 0xffff0000, v139
	v_cvt_pk_bf16_f32 v92, v92, v93
	v_cvt_pk_bf16_f32 v93, v98, v99
	v_lshlrev_b32_e32 v98, 16, v140
	v_and_b32_e32 v99, 0xffff0000, v140
	v_pk_add_f32 v[88:89], v[88:89], v[96:97]
	v_pk_add_f32 v[86:87], v[86:87], v[94:95]
	v_lshlrev_b32_e32 v100, 16, v141
	v_and_b32_e32 v101, 0xffff0000, v141
	v_pk_add_f32 v[96:97], v[82:83], v[98:99]
	v_mul_f32_e32 v82, v87, v87
	v_mul_f32_e32 v83, v89, v89
	v_pk_add_f32 v[94:95], v[84:85], v[100:101]
	v_fmac_f32_e32 v82, v86, v86
	v_fmac_f32_e32 v83, v88, v88
	v_add_f32_e32 v82, v82, v83
	v_mul_f32_e32 v83, v97, v97
	v_mul_f32_e32 v84, v95, v95
	v_fmac_f32_e32 v83, v96, v96
	v_fmac_f32_e32 v84, v94, v94
	v_add_f32_e32 v83, v83, v84
	v_add_f32_e32 v82, v82, v83
	v_add_f32_e32 v85, v102, v82
	v_lshl_add_u64 v[82:83], s[74:75], 0, v[184:185]
	v_lshl_add_u64 v[98:99], v[170:171], 1, v[82:83]
	global_store_dwordx4 v[98:99], v[90:93], off
	v_cvt_pk_bf16_f32 v84, v86, v87
	s_waitcnt lgkmcnt(0)
	v_mov_b32_e32 v82, v85
	v_mov_b32_e32 v100, v85
	s_nop 1
	v_permlane16_swap_b32_e32 v82, v100
	s_nop 0
	v_add_f32_e32 v82, v82, v100
	ds_bpermute_b32 v83, v114, v82
	v_cvt_pk_bf16_f32 v85, v88, v89
	v_cvt_pk_bf16_f32 v86, v96, v97
	v_cvt_pk_bf16_f32 v87, v94, v95
	global_store_dwordx4 v[98:99], v[84:87], off offset:256
	s_and_saveexec_b64 s[28:29], s[4:5]
	s_cbranch_execz .LBB0_1105
	v_lshlrev_b64 v[84:85], 8, v[180:181]
	v_lshl_add_u64 v[84:85], s[10:11], 0, v[84:85]
	v_lshl_add_u64 v[84:85], s[26:27], 2, v[84:85]
	s_lshl_b32 s8, s39, 2
	v_lshl_add_u64 v[84:85], v[84:85], 0, s[8:9]
	s_waitcnt lgkmcnt(0)
	v_add_f32_e32 v82, v82, v83
	global_store_dword v[84:85], v82, off
; __device__ __forceinline__ unsigned cvt_pk_bf16(float lo, float hi) { unsigned r; asm volatile("v_cvt_pk_bf16_f32 %0, %1, %2" : "=v"(r) : "v"(lo), "v"(hi)); return r; }
; __device__ __forceinline__ float bflo(unsigned w) { return __uint_as_float(w << 16); }
; __device__ __forceinline__ float bfhi(unsigned w) { return __uint_as_float(w & 0xffff0000u); }
;     __device__ __forceinline__ void operator()(const f32x4 (&acc)[2][2][4][2], const Unit& u, int wr, int wc, int fr, int fq) const {
;     ...
;                 for (int bj = 0; bj < 2; ++bj) bw[m][bj] = *(const u32x4*)((const bf16_t*)base + (size_t)(row0 + ai * HALF + m * 16) * DM + col0 + bj * HALF);
; #pragma unroll
;             for (int m = 0; m < 4; ++m) { const int row = row0 + ai * HALF + m * 16; const size_t off = (size_t)row * DM + col0; float ss = 0.f;
; #pragma unroll
;                 for (int bj = 0; bj < 2; ++bj) { const u32x4 w = bw[m][bj];
;                     const f32x4 b0 = {bflo(w.x), bfhi(w.x), bflo(w.y), bfhi(w.y)}, b1 = {bflo(w.z), bfhi(w.z), bflo(w.w), bfhi(w.w)};
;                     const f32x4 o0 = b0 + acc[ai][bj][m][0], o1 = b1 + acc[ai][bj][m][1];
;                     ss += ((o0[0] * o0[0] + o0[1] * o0[1]) + (o0[2] * o0[2] + o0[3] * o0[3])) + ((o1[0] * o1[0] + o1[1] * o1[1]) + (o1[2] * o1[2] + o1[3] * o1[3]));
;                     u32x4 w2; w2.x = cvt_pk_bf16(o0[0], o0[1]); w2.y = cvt_pk_bf16(o0[2], o0[3]); w2.z = cvt_pk_bf16(o1[0], o1[1]); w2.w = cvt_pk_bf16(o1[2], o1[3]);
;                     *(u32x4*)(hout + off + bj * HALF) = w2; }
;                 ss += __shfl_xor(ss, 16); ss += __shfl_xor(ss, 32);
;                 if (fq == 0) part[(size_t)row * 64 + u.pn * 4 + wc] = ss; }
.LBB0_1105:
	s_or_b64 exec, exec, s[28:29]
	v_lshlrev_b32_e32 v82, 16, v134
	s_waitcnt lgkmcnt(0)
	v_and_b32_e32 v83, 0xffff0000, v134
	v_lshlrev_b32_e32 v84, 16, v135
	v_and_b32_e32 v85, 0xffff0000, v135
	v_lshlrev_b32_e32 v86, 16, v136
	v_and_b32_e32 v87, 0xffff0000, v136
	v_lshlrev_b32_e32 v88, 16, v137
	v_and_b32_e32 v89, 0xffff0000, v137
	v_pk_add_f32 v[80:81], v[80:81], v[84:85]
	v_pk_add_f32 v[78:79], v[78:79], v[82:83]
	v_pk_add_f32 v[82:83], v[76:77], v[88:89]
	v_pk_add_f32 v[76:77], v[74:75], v[86:87]
	v_mul_f32_e32 v74, v79, v79
	v_mul_f32_e32 v75, v81, v81
	v_fmac_f32_e32 v74, v78, v78
	v_fmac_f32_e32 v75, v80, v80
	v_add_f32_e32 v74, v74, v75
	v_mul_f32_e32 v75, v77, v77
	v_mul_f32_e32 v84, v83, v83
	v_fmac_f32_e32 v75, v76, v76
	v_fmac_f32_e32 v84, v82, v82
	v_add_f32_e32 v75, v75, v84
	v_add_f32_e32 v86, v74, v75
	v_cvt_pk_bf16_f32 v74, v78, v79
	v_cvt_pk_bf16_f32 v75, v80, v81
	v_lshlrev_b32_e32 v78, 16, v130
	v_and_b32_e32 v79, 0xffff0000, v130
	v_lshlrev_b32_e32 v80, 16, v131
	v_and_b32_e32 v81, 0xffff0000, v131
	v_cvt_pk_bf16_f32 v76, v76, v77
	v_cvt_pk_bf16_f32 v77, v82, v83
	v_lshlrev_b32_e32 v82, 16, v132
	v_and_b32_e32 v83, 0xffff0000, v132
	v_pk_add_f32 v[72:73], v[72:73], v[80:81]
	v_pk_add_f32 v[70:71], v[70:71], v[78:79]
	v_lshlrev_b32_e32 v84, 16, v133
	v_and_b32_e32 v85, 0xffff0000, v133
	v_pk_add_f32 v[80:81], v[66:67], v[82:83]
	v_mul_f32_e32 v66, v71, v71
	v_mul_f32_e32 v67, v73, v73
	v_pk_add_f32 v[78:79], v[68:69], v[84:85]
	v_fmac_f32_e32 v66, v70, v70
	v_fmac_f32_e32 v67, v72, v72
	v_add_f32_e32 v66, v66, v67
	v_mul_f32_e32 v67, v81, v81
	v_mul_f32_e32 v68, v79, v79
	v_fmac_f32_e32 v67, v80, v80
	v_fmac_f32_e32 v68, v78, v78
	v_add_f32_e32 v67, v67, v68
	v_add_f32_e32 v66, v66, v67
	v_add_f32_e32 v69, v86, v66
	v_lshl_add_u64 v[66:67], s[74:75], 0, v[178:179]
	v_lshl_add_u64 v[82:83], v[170:171], 1, v[66:67]
	global_store_dwordx4 v[82:83], v[74:77], off
	v_cvt_pk_bf16_f32 v68, v70, v71
	s_waitcnt lgkmcnt(0)
	v_mov_b32_e32 v66, v69
	v_mov_b32_e32 v84, v69
	s_nop 1
	v_permlane16_swap_b32_e32 v66, v84
	s_nop 0
	v_add_f32_e32 v66, v66, v84
	ds_bpermute_b32 v67, v114, v66
	v_cvt_pk_bf16_f32 v69, v72, v73
	v_cvt_pk_bf16_f32 v70, v80, v81
	v_cvt_pk_bf16_f32 v71, v78, v79
	global_store_dwordx4 v[82:83], v[68:71], off offset:256
	s_and_saveexec_b64 s[28:29], s[4:5]
	s_cbranch_execz .LBB0_1107
	v_lshlrev_b64 v[68:69], 8, v[176:177]
	v_lshl_add_u64 v[68:69], s[10:11], 0, v[68:69]
	v_lshl_add_u64 v[68:69], s[26:27], 2, v[68:69]
	s_lshl_b32 s8, s39, 2
	v_lshl_add_u64 v[68:69], v[68:69], 0, s[8:9]
	s_waitcnt lgkmcnt(0)
	v_add_f32_e32 v66, v66, v67
	global_store_dword v[68:69], v66, off
.LBB0_1107:
	s_or_b64 exec, exec, s[28:29]
	v_add_u32_e32 v102, 0x80, v174
	v_ashrrev_i32_e32 v103, 31, v102
	v_lshlrev_b64 v[112:113], 13, v[102:103]
	s_waitcnt lgkmcnt(0)
	v_lshl_add_u64 v[66:67], v[172:173], 0, v[112:113]
	v_add_u32_e32 v98, 0x90, v174
	v_add_u32_e32 v94, 0xa0, v174
	v_add_u32_e32 v90, 0xb0, v174
	v_ashrrev_i32_e32 v99, 31, v98
	v_ashrrev_i32_e32 v95, 31, v94
	v_ashrrev_i32_e32 v91, 31, v90
	v_lshlrev_b64 v[100:101], 13, v[98:99]
	v_lshlrev_b64 v[96:97], 13, v[94:95]
	v_lshlrev_b64 v[92:93], 13, v[90:91]
	v_lshl_add_u64 v[66:67], v[172:173], 0, v[100:101]
	v_lshl_add_u64 v[68:69], v[172:173], 0, v[96:97]
	v_lshl_add_u64 v[116:117], v[172:173], 0, v[92:93]
	s_nop 0
	v_mov_b32_e32 v104, v220
	v_mov_b32_e32 v105, v221
	v_mov_b32_e32 v106, v222
	v_mov_b32_e32 v107, v223
	v_mov_b32_e32 v108, v224
	v_mov_b32_e32 v109, v225
	v_mov_b32_e32 v110, v226
	v_mov_b32_e32 v111, v227
	v_mov_b32_e32 v86, v228
	v_mov_b32_e32 v87, v229
	v_mov_b32_e32 v88, v230
	v_mov_b32_e32 v89, v231
	v_mov_b32_e32 v82, v232
	v_mov_b32_e32 v83, v233
	v_mov_b32_e32 v84, v234
	v_mov_b32_e32 v85, v235
	v_mov_b32_e32 v78, v236
	v_mov_b32_e32 v79, v237
	v_mov_b32_e32 v80, v238
	v_mov_b32_e32 v81, v239
	v_mov_b32_e32 v74, v240
	v_mov_b32_e32 v75, v241
	v_mov_b32_e32 v76, v242
	v_mov_b32_e32 v77, v243
	v_mov_b32_e32 v70, v244
	v_mov_b32_e32 v71, v245
	v_mov_b32_e32 v72, v246
	v_mov_b32_e32 v73, v247
	v_mov_b32_e32 v66, v248
	v_mov_b32_e32 v67, v249
	v_mov_b32_e32 v68, v250
	v_mov_b32_e32 v69, v251
	v_lshlrev_b32_e32 v116, 16, v104
	v_and_b32_e32 v117, 0xffff0000, v104
	v_lshlrev_b32_e32 v104, 16, v105
	v_and_b32_e32 v105, 0xffff0000, v105
	v_lshlrev_b32_e32 v118, 16, v106
	v_and_b32_e32 v119, 0xffff0000, v106
	v_lshlrev_b32_e32 v106, 16, v107
	v_and_b32_e32 v107, 0xffff0000, v107
	v_lshlrev_b32_e32 v120, 16, v108
	v_and_b32_e32 v121, 0xffff0000, v108
	v_lshlrev_b32_e32 v108, 16, v109
	v_and_b32_e32 v109, 0xffff0000, v109
	v_lshlrev_b32_e32 v122, 16, v110
	v_and_b32_e32 v123, 0xffff0000, v110
	v_lshlrev_b32_e32 v110, 16, v111
	v_and_b32_e32 v111, 0xffff0000, v111
	v_pk_add_f32 v[64:65], v[64:65], v[104:105]
	v_pk_add_f32 v[62:63], v[62:63], v[116:117]
	v_pk_add_f32 v[60:61], v[60:61], v[106:107]
	v_pk_add_f32 v[58:59], v[58:59], v[118:119]
	v_pk_add_f32 v[56:57], v[56:57], v[108:109]
	v_pk_add_f32 v[54:55], v[54:55], v[120:121]
	v_pk_add_f32 v[104:105], v[52:53], v[110:111]
	v_pk_add_f32 v[106:107], v[50:51], v[122:123]
	v_mul_f32_e32 v108, v63, v63
	v_mul_f32_e32 v109, v65, v65
	v_mul_f32_e32 v110, v59, v59
	v_mul_f32_e32 v111, v61, v61
	v_cvt_pk_bf16_f32 v50, v62, v63
	v_cvt_pk_bf16_f32 v51, v64, v65
	v_cvt_pk_bf16_f32 v52, v58, v59
	v_cvt_pk_bf16_f32 v53, v60, v61
	v_mul_f32_e32 v59, v55, v55
	v_mul_f32_e32 v61, v57, v57
	v_mul_f32_e32 v63, v107, v107
	v_mul_f32_e32 v65, v105, v105
	v_fmac_f32_e32 v108, v62, v62
	v_fmac_f32_e32 v109, v64, v64
	v_fmac_f32_e32 v110, v58, v58
	v_fmac_f32_e32 v111, v60, v60
	v_fmac_f32_e32 v59, v54, v54
	v_fmac_f32_e32 v61, v56, v56
	v_fmac_f32_e32 v63, v106, v106
	v_fmac_f32_e32 v65, v104, v104
	v_add_f32_e32 v58, v108, v109
	v_add_f32_e32 v60, v110, v111
	v_add_f32_e32 v59, v59, v61
	v_add_f32_e32 v61, v63, v65
	v_add_f32_e32 v58, v58, v60
	v_add_f32_e32 v59, v59, v61
	v_add_f32_e32 v60, v58, v59
	v_lshl_add_u64 v[58:59], s[74:75], 0, v[112:113]
	v_lshl_add_u64 v[58:59], v[170:171], 1, v[58:59]
	global_store_dwordx4 v[58:59], v[50:53], off
	s_waitcnt lgkmcnt(0)
	s_nop 0
	v_mov_b32_e32 v50, v60
	v_mov_b32_e32 v61, v60
	s_nop 1
	v_permlane16_swap_b32_e32 v50, v61
	s_nop 0
	v_add_f32_e32 v50, v50, v61
	ds_bpermute_b32 v51, v114, v50
	v_cvt_pk_bf16_f32 v52, v54, v55
	v_cvt_pk_bf16_f32 v53, v56, v57
	v_cvt_pk_bf16_f32 v54, v106, v107
	v_cvt_pk_bf16_f32 v55, v104, v105
	global_store_dwordx4 v[58:59], v[52:55], off offset:256
	s_and_saveexec_b64 s[28:29], s[4:5]
	s_cbranch_execz .LBB0_1109
	v_lshlrev_b64 v[52:53], 8, v[102:103]
	v_lshl_add_u64 v[52:53], s[10:11], 0, v[52:53]
	v_lshl_add_u64 v[52:53], s[26:27], 2, v[52:53]
	s_lshl_b32 s8, s39, 2
	v_lshl_add_u64 v[52:53], v[52:53], 0, s[8:9]
	s_waitcnt lgkmcnt(0)
	v_add_f32_e32 v50, v50, v51
	global_store_dword v[52:53], v50, off
; __device__ __forceinline__ unsigned cvt_pk_bf16(float lo, float hi) { unsigned r; asm volatile("v_cvt_pk_bf16_f32 %0, %1, %2" : "=v"(r) : "v"(lo), "v"(hi)); return r; }
; __device__ __forceinline__ float bflo(unsigned w) { return __uint_as_float(w << 16); }
; __device__ __forceinline__ float bfhi(unsigned w) { return __uint_as_float(w & 0xffff0000u); }
;     __device__ __forceinline__ void operator()(const f32x4 (&acc)[2][2][4][2], const Unit& u, int wr, int wc, int fr, int fq) const {
;     ...
;                 for (int bj = 0; bj < 2; ++bj) bw[m][bj] = *(const u32x4*)((const bf16_t*)base + (size_t)(row0 + ai * HALF + m * 16) * DM + col0 + bj * HALF);
; #pragma unroll
;             for (int m = 0; m < 4; ++m) { const int row = row0 + ai * HALF + m * 16; const size_t off = (size_t)row * DM + col0; float ss = 0.f;
; #pragma unroll
;                 for (int bj = 0; bj < 2; ++bj) { const u32x4 w = bw[m][bj];
;                     const f32x4 b0 = {bflo(w.x), bfhi(w.x), bflo(w.y), bfhi(w.y)}, b1 = {bflo(w.z), bfhi(w.z), bflo(w.w), bfhi(w.w)};
;                     const f32x4 o0 = b0 + acc[ai][bj][m][0], o1 = b1 + acc[ai][bj][m][1];
;                     ss += ((o0[0] * o0[0] + o0[1] * o0[1]) + (o0[2] * o0[2] + o0[3] * o0[3])) + ((o1[0] * o1[0] + o1[1] * o1[1]) + (o1[2] * o1[2] + o1[3] * o1[3]));
;                     u32x4 w2; w2.x = cvt_pk_bf16(o0[0], o0[1]); w2.y = cvt_pk_bf16(o0[2], o0[3]); w2.z = cvt_pk_bf16(o1[0], o1[1]); w2.w = cvt_pk_bf16(o1[2], o1[3]);
;                     *(u32x4*)(hout + off + bj * HALF) = w2; }
;                 ss += __shfl_xor(ss, 16); ss += __shfl_xor(ss, 32);
;                 if (fq == 0) part[(size_t)row * 64 + u.pn * 4 + wc] = ss; }
.LBB0_1109:
	s_or_b64 exec, exec, s[28:29]
	v_lshlrev_b32_e32 v50, 16, v86
	s_waitcnt lgkmcnt(0)
	v_and_b32_e32 v51, 0xffff0000, v86
	v_lshlrev_b32_e32 v52, 16, v87
	v_and_b32_e32 v53, 0xffff0000, v87
	v_lshlrev_b32_e32 v54, 16, v88
	v_and_b32_e32 v55, 0xffff0000, v88
	v_lshlrev_b32_e32 v56, 16, v89
	v_and_b32_e32 v57, 0xffff0000, v89
	v_pk_add_f32 v[48:49], v[48:49], v[52:53]
	v_pk_add_f32 v[46:47], v[46:47], v[50:51]
	v_pk_add_f32 v[50:51], v[44:45], v[56:57]
	v_pk_add_f32 v[44:45], v[42:43], v[54:55]
	v_mul_f32_e32 v42, v47, v47
	v_mul_f32_e32 v43, v49, v49
	v_fmac_f32_e32 v42, v46, v46
	v_fmac_f32_e32 v43, v48, v48
	v_add_f32_e32 v42, v42, v43
	v_mul_f32_e32 v43, v45, v45
	v_mul_f32_e32 v52, v51, v51
	v_fmac_f32_e32 v43, v44, v44
	v_fmac_f32_e32 v52, v50, v50
	v_add_f32_e32 v43, v43, v52
	v_add_f32_e32 v54, v42, v43
	v_cvt_pk_bf16_f32 v42, v46, v47
	v_cvt_pk_bf16_f32 v43, v48, v49
	v_lshlrev_b32_e32 v46, 16, v82
	v_and_b32_e32 v47, 0xffff0000, v82
	v_lshlrev_b32_e32 v48, 16, v83
	v_and_b32_e32 v49, 0xffff0000, v83
	v_cvt_pk_bf16_f32 v44, v44, v45
	v_cvt_pk_bf16_f32 v45, v50, v51
	v_lshlrev_b32_e32 v50, 16, v84
	v_and_b32_e32 v51, 0xffff0000, v84
	v_pk_add_f32 v[40:41], v[40:41], v[48:49]
	v_pk_add_f32 v[38:39], v[38:39], v[46:47]
	v_lshlrev_b32_e32 v52, 16, v85
	v_and_b32_e32 v53, 0xffff0000, v85
	v_pk_add_f32 v[48:49], v[34:35], v[50:51]
	v_mul_f32_e32 v34, v39, v39
	v_mul_f32_e32 v35, v41, v41
	v_pk_add_f32 v[46:47], v[36:37], v[52:53]
	v_fmac_f32_e32 v34, v38, v38
	v_fmac_f32_e32 v35, v40, v40
	v_add_f32_e32 v34, v34, v35
	v_mul_f32_e32 v35, v49, v49
	v_mul_f32_e32 v36, v47, v47
	v_fmac_f32_e32 v35, v48, v48
	v_fmac_f32_e32 v36, v46, v46
	v_add_f32_e32 v35, v35, v36
	v_add_f32_e32 v34, v34, v35
	v_add_f32_e32 v37, v54, v34
	v_lshl_add_u64 v[34:35], s[74:75], 0, v[100:101]
	v_lshl_add_u64 v[50:51], v[170:171], 1, v[34:35]
	global_store_dwordx4 v[50:51], v[42:45], off
	v_cvt_pk_bf16_f32 v36, v38, v39
	s_waitcnt lgkmcnt(0)
	v_mov_b32_e32 v34, v37
	v_mov_b32_e32 v52, v37
	s_nop 1
	v_permlane16_swap_b32_e32 v34, v52
	s_nop 0
	v_add_f32_e32 v34, v34, v52
	ds_bpermute_b32 v35, v114, v34
	v_cvt_pk_bf16_f32 v37, v40, v41
	v_cvt_pk_bf16_f32 v38, v48, v49
	v_cvt_pk_bf16_f32 v39, v46, v47
	global_store_dwordx4 v[50:51], v[36:39], off offset:256
	s_and_saveexec_b64 s[28:29], s[4:5]
	s_cbranch_execz .LBB0_1111
	v_lshlrev_b64 v[36:37], 8, v[98:99]
	v_lshl_add_u64 v[36:37], s[10:11], 0, v[36:37]
	v_lshl_add_u64 v[36:37], s[26:27], 2, v[36:37]
	s_lshl_b32 s8, s39, 2
	v_lshl_add_u64 v[36:37], v[36:37], 0, s[8:9]
	s_waitcnt lgkmcnt(0)
	v_add_f32_e32 v34, v34, v35
	global_store_dword v[36:37], v34, off
; __device__ __forceinline__ unsigned cvt_pk_bf16(float lo, float hi) { unsigned r; asm volatile("v_cvt_pk_bf16_f32 %0, %1, %2" : "=v"(r) : "v"(lo), "v"(hi)); return r; }
; __device__ __forceinline__ float bflo(unsigned w) { return __uint_as_float(w << 16); }
; __device__ __forceinline__ float bfhi(unsigned w) { return __uint_as_float(w & 0xffff0000u); }
;     __device__ __forceinline__ void operator()(const f32x4 (&acc)[2][2][4][2], const Unit& u, int wr, int wc, int fr, int fq) const {
;     ...
;                 for (int bj = 0; bj < 2; ++bj) bw[m][bj] = *(const u32x4*)((const bf16_t*)base + (size_t)(row0 + ai * HALF + m * 16) * DM + col0 + bj * HALF);
; #pragma unroll
;             for (int m = 0; m < 4; ++m) { const int row = row0 + ai * HALF + m * 16; const size_t off = (size_t)row * DM + col0; float ss = 0.f;
; #pragma unroll
;                 for (int bj = 0; bj < 2; ++bj) { const u32x4 w = bw[m][bj];
;                     const f32x4 b0 = {bflo(w.x), bfhi(w.x), bflo(w.y), bfhi(w.y)}, b1 = {bflo(w.z), bfhi(w.z), bflo(w.w), bfhi(w.w)};
;                     const f32x4 o0 = b0 + acc[ai][bj][m][0], o1 = b1 + acc[ai][bj][m][1];
;                     ss += ((o0[0] * o0[0] + o0[1] * o0[1]) + (o0[2] * o0[2] + o0[3] * o0[3])) + ((o1[0] * o1[0] + o1[1] * o1[1]) + (o1[2] * o1[2] + o1[3] * o1[3]));
;                     u32x4 w2; w2.x = cvt_pk_bf16(o0[0], o0[1]); w2.y = cvt_pk_bf16(o0[2], o0[3]); w2.z = cvt_pk_bf16(o1[0], o1[1]); w2.w = cvt_pk_bf16(o1[2], o1[3]);
;                     *(u32x4*)(hout + off + bj * HALF) = w2; }
;                 ss += __shfl_xor(ss, 16); ss += __shfl_xor(ss, 32);
;                 if (fq == 0) part[(size_t)row * 64 + u.pn * 4 + wc] = ss; }
.LBB0_1111:
	s_or_b64 exec, exec, s[28:29]
	v_lshlrev_b32_e32 v34, 16, v78
	s_waitcnt lgkmcnt(0)
	v_and_b32_e32 v35, 0xffff0000, v78
	v_lshlrev_b32_e32 v36, 16, v79
	v_and_b32_e32 v37, 0xffff0000, v79
	v_lshlrev_b32_e32 v38, 16, v80
	v_and_b32_e32 v39, 0xffff0000, v80
	v_lshlrev_b32_e32 v40, 16, v81
	v_and_b32_e32 v41, 0xffff0000, v81
	v_pk_add_f32 v[32:33], v[32:33], v[36:37]
	v_pk_add_f32 v[30:31], v[30:31], v[34:35]
	v_pk_add_f32 v[34:35], v[28:29], v[40:41]
	v_pk_add_f32 v[28:29], v[26:27], v[38:39]
	v_mul_f32_e32 v26, v31, v31
	v_mul_f32_e32 v27, v33, v33
	v_fmac_f32_e32 v26, v30, v30
	v_fmac_f32_e32 v27, v32, v32
	v_add_f32_e32 v26, v26, v27
	v_mul_f32_e32 v27, v29, v29
	v_mul_f32_e32 v36, v35, v35
	v_fmac_f32_e32 v27, v28, v28
	v_fmac_f32_e32 v36, v34, v34
	v_add_f32_e32 v27, v27, v36
	v_add_f32_e32 v38, v26, v27
	v_cvt_pk_bf16_f32 v26, v30, v31
	v_cvt_pk_bf16_f32 v27, v32, v33
	v_lshlrev_b32_e32 v30, 16, v74
	v_and_b32_e32 v31, 0xffff0000, v74
	v_lshlrev_b32_e32 v32, 16, v75
	v_and_b32_e32 v33, 0xffff0000, v75
	v_cvt_pk_bf16_f32 v28, v28, v29
	v_cvt_pk_bf16_f32 v29, v34, v35
	v_lshlrev_b32_e32 v34, 16, v76
	v_and_b32_e32 v35, 0xffff0000, v76
	v_pk_add_f32 v[24:25], v[24:25], v[32:33]
	v_pk_add_f32 v[22:23], v[22:23], v[30:31]
	v_lshlrev_b32_e32 v36, 16, v77
	v_and_b32_e32 v37, 0xffff0000, v77
	v_pk_add_f32 v[32:33], v[18:19], v[34:35]
	v_mul_f32_e32 v18, v23, v23
	v_mul_f32_e32 v19, v25, v25
	v_pk_add_f32 v[30:31], v[20:21], v[36:37]
	v_fmac_f32_e32 v18, v22, v22
	v_fmac_f32_e32 v19, v24, v24
	v_add_f32_e32 v18, v18, v19
	v_mul_f32_e32 v19, v33, v33
	v_mul_f32_e32 v20, v31, v31
	v_fmac_f32_e32 v19, v32, v32
	v_fmac_f32_e32 v20, v30, v30
	v_add_f32_e32 v19, v19, v20
	v_add_f32_e32 v18, v18, v19
	v_add_f32_e32 v21, v38, v18
	v_lshl_add_u64 v[18:19], s[74:75], 0, v[96:97]
	v_lshl_add_u64 v[34:35], v[170:171], 1, v[18:19]
	global_store_dwordx4 v[34:35], v[26:29], off
	v_cvt_pk_bf16_f32 v20, v22, v23
	s_waitcnt lgkmcnt(0)
	v_mov_b32_e32 v18, v21
	v_mov_b32_e32 v36, v21
	s_nop 1
	v_permlane16_swap_b32_e32 v18, v36
	s_nop 0
	v_add_f32_e32 v18, v18, v36
	ds_bpermute_b32 v19, v114, v18
	v_cvt_pk_bf16_f32 v21, v24, v25
	v_cvt_pk_bf16_f32 v22, v32, v33
	v_cvt_pk_bf16_f32 v23, v30, v31
	global_store_dwordx4 v[34:35], v[20:23], off offset:256
	s_and_saveexec_b64 s[28:29], s[4:5]
	s_cbranch_execz .LBB0_1113
	v_lshlrev_b64 v[20:21], 8, v[94:95]
	v_lshl_add_u64 v[20:21], s[10:11], 0, v[20:21]
	v_lshl_add_u64 v[20:21], s[26:27], 2, v[20:21]
	s_lshl_b32 s8, s39, 2
	v_lshl_add_u64 v[20:21], v[20:21], 0, s[8:9]
	s_waitcnt lgkmcnt(0)
	v_add_f32_e32 v18, v18, v19
	global_store_dword v[20:21], v18, off
.LBB0_1113:
	s_or_b64 exec, exec, s[28:29]
	v_lshlrev_b32_e32 v18, 16, v70
	s_waitcnt lgkmcnt(0)
	v_and_b32_e32 v19, 0xffff0000, v70
	v_lshlrev_b32_e32 v20, 16, v71
	v_and_b32_e32 v21, 0xffff0000, v71
	v_lshlrev_b32_e32 v22, 16, v72
	v_and_b32_e32 v23, 0xffff0000, v72
	v_lshlrev_b32_e32 v24, 16, v73
	v_and_b32_e32 v25, 0xffff0000, v73
	v_pk_add_f32 v[16:17], v[16:17], v[20:21]
	v_pk_add_f32 v[14:15], v[14:15], v[18:19]
	v_pk_add_f32 v[18:19], v[12:13], v[24:25]
	v_pk_add_f32 v[12:13], v[10:11], v[22:23]
	v_mul_f32_e32 v10, v15, v15
	v_mul_f32_e32 v11, v17, v17
	v_fmac_f32_e32 v10, v14, v14
	v_fmac_f32_e32 v11, v16, v16
	v_add_f32_e32 v10, v10, v11
	v_mul_f32_e32 v11, v13, v13
	v_mul_f32_e32 v20, v19, v19
	v_fmac_f32_e32 v11, v12, v12
	v_fmac_f32_e32 v20, v18, v18
	v_add_f32_e32 v11, v11, v20
	v_add_f32_e32 v22, v10, v11
	v_cvt_pk_bf16_f32 v10, v14, v15
	v_cvt_pk_bf16_f32 v11, v16, v17
	v_lshlrev_b32_e32 v14, 16, v66
	v_and_b32_e32 v15, 0xffff0000, v66
	v_lshlrev_b32_e32 v16, 16, v67
	v_and_b32_e32 v17, 0xffff0000, v67
	v_cvt_pk_bf16_f32 v12, v12, v13
	v_cvt_pk_bf16_f32 v13, v18, v19
	v_lshlrev_b32_e32 v18, 16, v68
	v_and_b32_e32 v19, 0xffff0000, v68
	v_pk_add_f32 v[8:9], v[8:9], v[16:17]
	v_pk_add_f32 v[6:7], v[6:7], v[14:15]
	v_lshlrev_b32_e32 v20, 16, v69
	v_and_b32_e32 v21, 0xffff0000, v69
	v_pk_add_f32 v[16:17], v[2:3], v[18:19]
	v_mul_f32_e32 v2, v7, v7
	v_mul_f32_e32 v3, v9, v9
	v_pk_add_f32 v[14:15], v[4:5], v[20:21]
	v_fmac_f32_e32 v2, v6, v6
	v_fmac_f32_e32 v3, v8, v8
	v_add_f32_e32 v2, v2, v3
	v_mul_f32_e32 v3, v17, v17
	v_mul_f32_e32 v4, v15, v15
	v_fmac_f32_e32 v3, v16, v16
	v_fmac_f32_e32 v4, v14, v14
	v_add_f32_e32 v3, v3, v4
	v_add_f32_e32 v2, v2, v3
	v_add_f32_e32 v5, v22, v2
	v_lshl_add_u64 v[2:3], s[74:75], 0, v[92:93]
	v_lshl_add_u64 v[18:19], v[170:171], 1, v[2:3]
	global_store_dwordx4 v[18:19], v[10:13], off
	v_cvt_pk_bf16_f32 v4, v6, v7
	s_waitcnt lgkmcnt(0)
	v_mov_b32_e32 v2, v5
	v_mov_b32_e32 v20, v5
	s_nop 1
	v_permlane16_swap_b32_e32 v2, v20
	s_nop 0
	v_add_f32_e32 v2, v2, v20
	ds_bpermute_b32 v3, v114, v2
	v_cvt_pk_bf16_f32 v5, v8, v9
	v_cvt_pk_bf16_f32 v6, v16, v17
	v_cvt_pk_bf16_f32 v7, v14, v15
	global_store_dwordx4 v[18:19], v[4:7], off offset:256
	s_and_saveexec_b64 s[28:29], s[4:5]
	s_cbranch_execz .LBB0_1115
	v_lshlrev_b64 v[4:5], 8, v[90:91]
	v_lshl_add_u64 v[4:5], s[10:11], 0, v[4:5]
	v_lshl_add_u64 v[4:5], s[26:27], 2, v[4:5]
	s_lshl_b32 s8, s39, 2
	v_lshl_add_u64 v[4:5], v[4:5], 0, s[8:9]
	s_waitcnt lgkmcnt(0)
	v_add_f32_e32 v2, v2, v3
	global_store_dword v[4:5], v2, off

;     __device__ __forceinline__ void fused(f32x4 (&acc)[2][2][4][2], const Unit& u, int wr, int wc, int fr, int fq, LAS unsigned char* lds, int wid, int lane) const {
;     ...
;         for (int ai = 0; ai < 2; ++ai)
; #pragma unroll
;             for (int m = 0; m < 4; ++m) { const int r = ai * HALF + wr * 64 + m * 16 + fr; const float sc = RS[r] * C; float mx = -3.0e38f;
; #pragma unroll
;                 for (int bj = 0; bj < 2; ++bj)
; #pragma unroll
;                     for (int n = 0; n < 2; ++n) { f32x4 v = acc[ai][bj][m][n] * sc; acc[ai][bj][m][n] = v; mx = fmaxf(fmaxf(mx, fmaxf(v[0], v[1])), fmaxf(v[2], v[3])); }
;                 mx = fmaxf(mx, __shfl_xor(mx, 16)); mx = fmaxf(mx, __shfl_xor(mx, 32));
;                 if (fq == 0) MX[r * 4 + wc] = mx; }
.LBB0_1200:
	s_or_b64 exec, exec, s[6:7]
	s_waitcnt lgkmcnt(0)
	s_barrier
	v_lshl_add_u32 v130, v196, 2, 0
	s_waitcnt lgkmcnt(0)
	ds_read_b32 v134, v130 offset:8192
	s_mov_b32 s7, 0xff61b1e6
	v_xor_b32_e32 v131, 16, v132
	v_cmp_lt_i32_e32 vcc, v131, v133
	s_lshl_b32 s4, s3, 2
	s_waitcnt lgkmcnt(0)
	v_mul_f32_e32 v134, 0x3d38aa3b, v134
	v_pk_mul_f32 v[192:193], v[128:129], v[134:135] op_sel_hi:[1,0]
	v_pk_mul_f32 v[194:195], v[126:127], v[134:135] op_sel_hi:[1,0]
	v_max_f32_e32 v127, v192, v193
	v_max_f32_e32 v126, v194, v195
	v_max3_f32 v128, v126, s7, v127
	v_pk_mul_f32 v[124:125], v[124:125], v[134:135] op_sel_hi:[1,0]
	v_pk_mul_f32 v[126:127], v[122:123], v[134:135] op_sel_hi:[1,0]
	v_max_f32_e32 v123, v124, v125
	v_max_f32_e32 v122, v126, v127
	v_max3_f32 v128, v128, v122, v123
	v_pk_mul_f32 v[122:123], v[116:117], v[134:135] op_sel_hi:[1,0]
	v_pk_mul_f32 v[190:191], v[114:115], v[134:135] op_sel_hi:[1,0]
	v_max_f32_e32 v115, v122, v123
	v_max_f32_e32 v114, v190, v191
	v_max3_f32 v116, v128, v114, v115
	v_pk_mul_f32 v[114:115], v[108:109], v[134:135] op_sel_hi:[1,0]
	v_pk_mul_f32 v[128:129], v[106:107], v[134:135] op_sel_hi:[1,0]
	v_cndmask_b32_e32 v131, v132, v131, vcc
	v_max_f32_e32 v106, v128, v129
	v_max_f32_e32 v107, v114, v115
	v_lshlrev_b32_e32 v131, 2, v131
	v_max3_f32 v106, v116, v106, v107
	v_xor_b32_e32 v108, 32, v132
	v_cmp_lt_i32_e32 vcc, v108, v133
	s_add_i32 s6, s4, 0
	s_waitcnt lgkmcnt(0)
	v_cndmask_b32_e32 v108, v132, v108, vcc
	v_lshlrev_b32_e32 v205, 2, v108
	v_mov_b32_e32 v107, v106
	s_nop 1
	v_permlane16_swap_b32_e32 v106, v107
	s_nop 0
	v_max_f32_e32 v106, v106, v107
	ds_bpermute_b32 v107, v205, v106
	v_cmp_gt_u32_e32 vcc, 16, v182
	s_and_saveexec_b64 s[4:5], vcc
	s_cbranch_execz .LBB0_1202
	s_waitcnt lgkmcnt(0)
	v_max_f32_e32 v107, v107, v107
	v_max_f32_e32 v106, v106, v106
	v_lshl_add_u32 v108, v196, 4, s6
	v_max_f32_e32 v106, v106, v107
	ds_write_b32 v108, v106
.LBB0_1202:
	s_or_b64 exec, exec, s[4:5]
	ds_read_b32 v106, v130 offset:8256
	v_or_b32_e32 v204, 16, v196
	s_waitcnt lgkmcnt(0)
	v_mul_f32_e32 v116, 0x3d38aa3b, v106
	v_pk_mul_f32 v[184:185], v[120:121], v[116:117] op_sel_hi:[1,0]
	v_pk_mul_f32 v[188:189], v[118:119], v[116:117] op_sel_hi:[1,0]
	v_pk_mul_f32 v[108:109], v[112:113], v[116:117] op_sel_hi:[1,0]
	v_pk_mul_f32 v[186:187], v[110:111], v[116:117] op_sel_hi:[1,0]
	v_max_f32_e32 v106, v188, v189
	v_max_f32_e32 v107, v184, v185
	v_max3_f32 v106, v106, s7, v107
	v_max_f32_e32 v107, v186, v187
	v_max_f32_e32 v110, v108, v109
	v_max3_f32 v110, v106, v107, v110
	v_pk_mul_f32 v[106:107], v[100:101], v[116:117] op_sel_hi:[1,0]
	v_pk_mul_f32 v[180:181], v[98:99], v[116:117] op_sel_hi:[1,0]
	v_max_f32_e32 v99, v106, v107
	v_max_f32_e32 v98, v180, v181
	v_pk_mul_f32 v[92:93], v[92:93], v[116:117] op_sel_hi:[1,0]
	v_pk_mul_f32 v[120:121], v[90:91], v[116:117] op_sel_hi:[1,0]
	v_max3_f32 v98, v110, v98, v99
	v_max_f32_e32 v90, v120, v121
	v_max_f32_e32 v91, v92, v93
	v_max3_f32 v90, v98, v90, v91
	s_waitcnt lgkmcnt(0)
	v_mov_b32_e32 v91, v90
	s_nop 1
	v_permlane16_swap_b32_e32 v90, v91
	s_nop 0
	v_max_f32_e32 v90, v90, v91
	ds_bpermute_b32 v91, v205, v90
	s_and_saveexec_b64 s[4:5], vcc
	s_cbranch_execz .LBB0_1204
	s_waitcnt lgkmcnt(0)
	v_max_f32_e32 v91, v91, v91
	v_max_f32_e32 v90, v90, v90
	v_lshl_add_u32 v98, v204, 4, s6
	v_max_f32_e32 v90, v90, v91
	ds_write_b32 v98, v90
.LBB0_1204:
	s_or_b64 exec, exec, s[4:5]
	ds_read_b32 v90, v130 offset:8320
	v_or_b32_e32 v203, 32, v196
	s_waitcnt lgkmcnt(0)
	v_mul_f32_e32 v110, 0x3d38aa3b, v90
	v_pk_mul_f32 v[176:177], v[104:105], v[110:111] op_sel_hi:[1,0]
	v_pk_mul_f32 v[178:179], v[102:103], v[110:111] op_sel_hi:[1,0]
	v_pk_mul_f32 v[98:99], v[96:97], v[110:111] op_sel_hi:[1,0]
	v_max_f32_e32 v90, v178, v179
	v_max_f32_e32 v91, v176, v177
	v_pk_mul_f32 v[174:175], v[94:95], v[110:111] op_sel_hi:[1,0]
	v_max3_f32 v90, v90, s7, v91
	v_max_f32_e32 v91, v174, v175
	v_max_f32_e32 v94, v98, v99
	v_max3_f32 v94, v90, v91, v94
	v_pk_mul_f32 v[90:91], v[84:85], v[110:111] op_sel_hi:[1,0]
	v_pk_mul_f32 v[172:173], v[82:83], v[110:111] op_sel_hi:[1,0]
	v_max_f32_e32 v83, v90, v91
	v_max_f32_e32 v82, v172, v173
	v_pk_mul_f32 v[100:101], v[76:77], v[110:111] op_sel_hi:[1,0]
	v_pk_mul_f32 v[170:171], v[74:75], v[110:111] op_sel_hi:[1,0]
	v_max3_f32 v82, v94, v82, v83
	v_max_f32_e32 v74, v170, v171
	v_max_f32_e32 v75, v100, v101
	v_max3_f32 v74, v82, v74, v75
	s_waitcnt lgkmcnt(0)
	v_mov_b32_e32 v75, v74
	s_nop 1
	v_permlane16_swap_b32_e32 v74, v75
	s_nop 0
	v_max_f32_e32 v74, v74, v75
	ds_bpermute_b32 v75, v205, v74
	s_and_saveexec_b64 s[4:5], vcc
	s_cbranch_execz .LBB0_1206
	s_waitcnt lgkmcnt(0)
	v_max_f32_e32 v75, v75, v75
	v_max_f32_e32 v74, v74, v74
	v_lshl_add_u32 v76, v203, 4, s6
	v_max_f32_e32 v74, v74, v75
	ds_write_b32 v76, v74
.LBB0_1206:
	s_or_b64 exec, exec, s[4:5]
	ds_read_b32 v74, v130 offset:8384
	v_or_b32_e32 v202, 48, v196
	s_waitcnt lgkmcnt(0)
	v_mul_f32_e32 v94, 0x3d38aa3b, v74
	v_pk_mul_f32 v[76:77], v[88:89], v[94:95] op_sel_hi:[1,0]
	v_pk_mul_f32 v[168:169], v[86:87], v[94:95] op_sel_hi:[1,0]
	v_pk_mul_f32 v[74:75], v[80:81], v[94:95] op_sel_hi:[1,0]
	v_pk_mul_f32 v[82:83], v[78:79], v[94:95] op_sel_hi:[1,0]
	v_max_f32_e32 v78, v168, v169
	v_max_f32_e32 v79, v76, v77
	v_max3_f32 v78, v78, s7, v79
	v_max_f32_e32 v79, v82, v83
	v_max_f32_e32 v80, v74, v75
	v_pk_mul_f32 v[72:73], v[72:73], v[94:95] op_sel_hi:[1,0]
	v_pk_mul_f32 v[166:167], v[70:71], v[94:95] op_sel_hi:[1,0]
	v_max3_f32 v78, v78, v79, v80
	v_max_f32_e32 v70, v166, v167
	v_max_f32_e32 v71, v72, v73
	v_pk_mul_f32 v[84:85], v[68:69], v[94:95] op_sel_hi:[1,0]
	v_pk_mul_f32 v[162:163], v[66:67], v[94:95] op_sel_hi:[1,0]
	v_max3_f32 v70, v78, v70, v71
	v_max_f32_e32 v66, v162, v163
	v_max_f32_e32 v67, v84, v85
	v_max3_f32 v66, v70, v66, v67
	s_waitcnt lgkmcnt(0)
	v_mov_b32_e32 v67, v66
	s_nop 1
	v_permlane16_swap_b32_e32 v66, v67
	s_nop 0
	v_max_f32_e32 v66, v66, v67
	ds_bpermute_b32 v67, v205, v66
	s_and_saveexec_b64 s[4:5], vcc
	s_cbranch_execz .LBB0_1208
	s_waitcnt lgkmcnt(0)
	v_max_f32_e32 v67, v67, v67
	v_max_f32_e32 v66, v66, v66
	v_lshl_add_u32 v68, v202, 4, s6
	v_max_f32_e32 v66, v66, v67
	ds_write_b32 v68, v66
;     __device__ __forceinline__ void fused(f32x4 (&acc)[2][2][4][2], const Unit& u, int wr, int wc, int fr, int fq, LAS unsigned char* lds, int wid, int lane) const {
;     ...
;         for (int ai = 0; ai < 2; ++ai)
; #pragma unroll
;             for (int m = 0; m < 4; ++m) { const int r = ai * HALF + wr * 64 + m * 16 + fr; const float sc = RS[r] * C; float mx = -3.0e38f;
; #pragma unroll
;                 for (int bj = 0; bj < 2; ++bj)
; #pragma unroll
;                     for (int n = 0; n < 2; ++n) { f32x4 v = acc[ai][bj][m][n] * sc; acc[ai][bj][m][n] = v; mx = fmaxf(fmaxf(mx, fmaxf(v[0], v[1])), fmaxf(v[2], v[3])); }
;                 mx = fmaxf(mx, __shfl_xor(mx, 16)); mx = fmaxf(mx, __shfl_xor(mx, 32));
;                 if (fq == 0) MX[r * 4 + wc] = mx; }
.LBB0_1208:
	s_or_b64 exec, exec, s[4:5]
	ds_read_b32 v66, v130 offset:8704
	v_add_u32_e32 v201, 0x80, v196
	s_waitcnt lgkmcnt(0)
	v_mul_f32_e32 v70, 0x3d38aa3b, v66
	v_pk_mul_f32 v[160:161], v[64:65], v[70:71] op_sel_hi:[1,0]
	v_pk_mul_f32 v[164:165], v[62:63], v[70:71] op_sel_hi:[1,0]
	v_pk_mul_f32 v[66:67], v[60:61], v[70:71] op_sel_hi:[1,0]
	v_max_f32_e32 v60, v164, v165
	v_max_f32_e32 v61, v160, v161
	v_pk_mul_f32 v[158:159], v[58:59], v[70:71] op_sel_hi:[1,0]
	v_max3_f32 v60, v60, s7, v61
	v_max_f32_e32 v58, v158, v159
	v_max_f32_e32 v59, v66, v67
	v_max3_f32 v60, v60, v58, v59
	v_pk_mul_f32 v[58:59], v[52:53], v[70:71] op_sel_hi:[1,0]
	v_pk_mul_f32 v[156:157], v[50:51], v[70:71] op_sel_hi:[1,0]
	v_max_f32_e32 v51, v58, v59
	v_max_f32_e32 v50, v156, v157
	v_pk_mul_f32 v[68:69], v[44:45], v[70:71] op_sel_hi:[1,0]
	v_pk_mul_f32 v[154:155], v[42:43], v[70:71] op_sel_hi:[1,0]
	v_max3_f32 v50, v60, v50, v51
	v_max_f32_e32 v42, v154, v155
	v_max_f32_e32 v43, v68, v69
	v_max3_f32 v42, v50, v42, v43
	s_waitcnt lgkmcnt(0)
	v_mov_b32_e32 v43, v42
	s_nop 1
	v_permlane16_swap_b32_e32 v42, v43
	s_nop 0
	v_max_f32_e32 v42, v42, v43
	ds_bpermute_b32 v43, v205, v42
	s_and_saveexec_b64 s[4:5], vcc
	s_cbranch_execz .LBB0_1210
	s_waitcnt lgkmcnt(0)
	v_max_f32_e32 v43, v43, v43
	v_max_f32_e32 v42, v42, v42
	v_lshl_add_u32 v44, v201, 4, s6
	v_max_f32_e32 v42, v42, v43
	ds_write_b32 v44, v42
.LBB0_1210:
	s_or_b64 exec, exec, s[4:5]
	ds_read_b32 v42, v130 offset:8768
	v_add_u32_e32 v200, 0x90, v196
	s_waitcnt lgkmcnt(0)
	v_mul_f32_e32 v52, 0x3d38aa3b, v42
	v_pk_mul_f32 v[44:45], v[56:57], v[52:53] op_sel_hi:[1,0]
	v_pk_mul_f32 v[152:153], v[54:55], v[52:53] op_sel_hi:[1,0]
	v_pk_mul_f32 v[50:51], v[48:49], v[52:53] op_sel_hi:[1,0]
	v_pk_mul_f32 v[150:151], v[46:47], v[52:53] op_sel_hi:[1,0]
	v_max_f32_e32 v42, v152, v153
	v_max_f32_e32 v43, v44, v45
	v_max3_f32 v42, v42, s7, v43
	v_max_f32_e32 v43, v150, v151
	v_max_f32_e32 v46, v50, v51
	v_max3_f32 v46, v42, v43, v46
	v_pk_mul_f32 v[42:43], v[36:37], v[52:53] op_sel_hi:[1,0]
	v_pk_mul_f32 v[148:149], v[34:35], v[52:53] op_sel_hi:[1,0]
	v_max_f32_e32 v35, v42, v43
	v_max_f32_e32 v34, v148, v149
	v_pk_mul_f32 v[28:29], v[28:29], v[52:53] op_sel_hi:[1,0]
	v_pk_mul_f32 v[52:53], v[26:27], v[52:53] op_sel_hi:[1,0]
	v_max3_f32 v34, v46, v34, v35
	v_max_f32_e32 v26, v52, v53
	v_max_f32_e32 v27, v28, v29
	v_max3_f32 v26, v34, v26, v27
	s_waitcnt lgkmcnt(0)
	v_mov_b32_e32 v27, v26
	s_nop 1
	v_permlane16_swap_b32_e32 v26, v27
	s_nop 0
	v_max_f32_e32 v26, v26, v27
	ds_bpermute_b32 v27, v205, v26
	s_and_saveexec_b64 s[4:5], vcc
	s_cbranch_execz .LBB0_1212
	s_waitcnt lgkmcnt(0)
	v_max_f32_e32 v27, v27, v27
	v_max_f32_e32 v26, v26, v26
	v_lshl_add_u32 v34, v200, 4, s6
	v_max_f32_e32 v26, v26, v27
	ds_write_b32 v34, v26
.LBB0_1212:
	s_or_b64 exec, exec, s[4:5]
	ds_read_b32 v26, v130 offset:8832
	v_add_u32_e32 v199, 0xa0, v196
	s_waitcnt lgkmcnt(0)
	v_mul_f32_e32 v46, 0x3d38aa3b, v26
	v_pk_mul_f32 v[144:145], v[40:41], v[46:47] op_sel_hi:[1,0]
	v_pk_mul_f32 v[146:147], v[38:39], v[46:47] op_sel_hi:[1,0]
	v_pk_mul_f32 v[34:35], v[32:33], v[46:47] op_sel_hi:[1,0]
	v_max_f32_e32 v26, v146, v147
	v_max_f32_e32 v27, v144, v145
	v_pk_mul_f32 v[142:143], v[30:31], v[46:47] op_sel_hi:[1,0]
	v_max3_f32 v26, v26, s7, v27
	v_max_f32_e32 v27, v142, v143
	v_max_f32_e32 v30, v34, v35
	v_max3_f32 v30, v26, v27, v30
	v_pk_mul_f32 v[26:27], v[20:21], v[46:47] op_sel_hi:[1,0]
	v_pk_mul_f32 v[140:141], v[18:19], v[46:47] op_sel_hi:[1,0]
	v_max_f32_e32 v19, v26, v27
	v_max_f32_e32 v18, v140, v141
	v_pk_mul_f32 v[36:37], v[12:13], v[46:47] op_sel_hi:[1,0]
	v_pk_mul_f32 v[138:139], v[10:11], v[46:47] op_sel_hi:[1,0]
	v_max3_f32 v18, v30, v18, v19
	v_max_f32_e32 v10, v138, v139
	v_max_f32_e32 v11, v36, v37
	v_max3_f32 v10, v18, v10, v11
	s_waitcnt lgkmcnt(0)
	v_mov_b32_e32 v11, v10
	s_nop 1
	v_permlane16_swap_b32_e32 v10, v11
	s_nop 0
	v_max_f32_e32 v10, v10, v11
	ds_bpermute_b32 v11, v205, v10
	s_and_saveexec_b64 s[4:5], vcc
	s_cbranch_execz .LBB0_1214
	s_waitcnt lgkmcnt(0)
	v_max_f32_e32 v11, v11, v11
	v_max_f32_e32 v10, v10, v10
	v_lshl_add_u32 v12, v199, 4, s6
	v_max_f32_e32 v10, v10, v11
	ds_write_b32 v12, v10
.LBB0_1214:
	s_or_b64 exec, exec, s[4:5]
	ds_read_b32 v10, v130 offset:8896
	v_add_u32_e32 v198, 0xb0, v196
	s_waitcnt lgkmcnt(0)
	v_mul_f32_e32 v30, 0x3d38aa3b, v10
	v_pk_mul_f32 v[12:13], v[24:25], v[30:31] op_sel_hi:[1,0]
	v_pk_mul_f32 v[136:137], v[22:23], v[30:31] op_sel_hi:[1,0]
	v_pk_mul_f32 v[10:11], v[16:17], v[30:31] op_sel_hi:[1,0]
	v_pk_mul_f32 v[18:19], v[14:15], v[30:31] op_sel_hi:[1,0]
	v_max_f32_e32 v14, v136, v137
	v_max_f32_e32 v15, v12, v13
	v_max3_f32 v14, v14, s7, v15
	v_max_f32_e32 v15, v18, v19
	v_max_f32_e32 v16, v10, v11
	v_pk_mul_f32 v[8:9], v[8:9], v[30:31] op_sel_hi:[1,0]
	v_pk_mul_f32 v[134:135], v[6:7], v[30:31] op_sel_hi:[1,0]
	v_max3_f32 v14, v14, v15, v16
	v_max_f32_e32 v6, v134, v135
	v_max_f32_e32 v7, v8, v9
	v_pk_mul_f32 v[20:21], v[4:5], v[30:31] op_sel_hi:[1,0]
	v_pk_mul_f32 v[132:133], v[2:3], v[30:31] op_sel_hi:[1,0]
	v_max3_f32 v6, v14, v6, v7
	v_max_f32_e32 v2, v132, v133
	v_max_f32_e32 v3, v20, v21
	v_max3_f32 v2, v6, v2, v3
	s_waitcnt lgkmcnt(0)
	v_mov_b32_e32 v3, v2
	s_nop 1
	v_permlane16_swap_b32_e32 v2, v3
	s_nop 0
	v_max_f32_e32 v2, v2, v3
	ds_bpermute_b32 v3, v205, v2
	s_and_saveexec_b64 s[4:5], vcc
	s_cbranch_execz .LBB0_1216
	s_waitcnt lgkmcnt(0)
	v_max_f32_e32 v3, v3, v3
	v_max_f32_e32 v2, v2, v2
	v_lshl_add_u32 v4, v198, 4, s6
	v_max_f32_e32 v2, v2, v3
	ds_write_b32 v4, v2
; #define LAS __attribute__((address_space(3)))
;     __device__ __forceinline__ void fused(f32x4 (&acc)[2][2][4][2], const Unit& u, int wr, int wc, int fr, int fq, LAS unsigned char* lds, int wid, int lane) const {
;     ...
; #pragma unroll
;         for (int ai = 0; ai < 2; ++ai)
; #pragma unroll
;             for (int m = 0; m < 4; ++m) { const int r = ai * HALF + wr * 64 + m * 16 + fr; const f32x4 q = *(const LAS f32x4*)(MX + r * 4); const float M = fmaxf(fmaxf(q[0], q[1]), fmaxf(q[2], q[3])); float s = 0.f;
; #pragma unroll
;                 for (int bj = 0; bj < 2; ++bj)
; #pragma unroll
;                     for (int n = 0; n < 2; ++n) { f32x4 v = acc[ai][bj][m][n];
; #pragma unroll
;                         for (int j = 0; j < 4; ++j) { v[j] = __builtin_amdgcn_exp2f(v[j] - M); s += v[j]; }
;                         acc[ai][bj][m][n] = v; }
;                 s += __shfl_xor(s, 16); s += __shfl_xor(s, 32);
;                 if (fq == 0) SM[r * 4 + wc] = s; }
.LBB0_1216:
	s_or_b64 exec, exec, s[4:5]
	s_and_b32 s4, s30, 0xffffff00
	v_lshl_or_b32 v14, v197, 2, s4
	s_waitcnt lgkmcnt(0)
	s_barrier
	v_lshl_add_u32 v2, v14, 2, 0
	ds_read_b128 v[4:7], v2
	s_waitcnt lgkmcnt(0)
	v_max_f32_e32 v3, v7, v7
	v_max_f32_e32 v6, v6, v6
	v_max_f32_e32 v3, v6, v3
	v_max3_f32 v3, v4, v5, v3
	v_sub_f32_e32 v4, v194, v3
	v_exp_f32_e32 v104, v4
	v_sub_f32_e32 v4, v195, v3
	v_exp_f32_e32 v105, v4
	v_sub_f32_e32 v4, v192, v3
	v_exp_f32_e32 v118, v4
	v_sub_f32_e32 v4, v193, v3
	v_exp_f32_e32 v119, v4
	v_sub_f32_e32 v5, v126, v3
	v_add_f32_e32 v4, 0, v104
	v_exp_f32_e32 v116, v5
	v_sub_f32_e32 v5, v127, v3
	v_add_f32_e32 v4, v105, v4
	v_exp_f32_e32 v117, v5
	v_sub_f32_e32 v5, v124, v3
	v_add_f32_e32 v4, v118, v4
	v_exp_f32_e32 v126, v5
	v_sub_f32_e32 v5, v125, v3
	v_add_f32_e32 v4, v119, v4
	v_exp_f32_e32 v127, v5
	v_sub_f32_e32 v5, v190, v3
	v_add_f32_e32 v4, v116, v4
	v_exp_f32_e32 v110, v5
	v_sub_f32_e32 v5, v191, v3
	v_add_f32_e32 v4, v117, v4
	v_exp_f32_e32 v111, v5
	v_sub_f32_e32 v5, v122, v3
	v_add_f32_e32 v4, v126, v4
	v_exp_f32_e32 v124, v5
	v_sub_f32_e32 v5, v123, v3
	v_add_f32_e32 v4, v127, v4
	v_exp_f32_e32 v125, v5
	v_sub_f32_e32 v5, v128, v3
	v_add_f32_e32 v4, v110, v4
	v_exp_f32_e32 v122, v5
	v_sub_f32_e32 v5, v129, v3
	v_add_f32_e32 v4, v111, v4
	v_exp_f32_e32 v123, v5
	v_sub_f32_e32 v5, v114, v3
	v_add_f32_e32 v4, v124, v4
	v_exp_f32_e32 v128, v5
	v_sub_f32_e32 v3, v115, v3
	v_add_f32_e32 v4, v125, v4
	v_exp_f32_e32 v129, v3
	v_add_f32_e32 v3, v122, v4
	v_add_f32_e32 v3, v123, v3
	v_add_f32_e32 v3, v128, v3
	v_add_f32_e32 v3, v129, v3
	v_lshl_add_u32 v190, v14, 2, s6
	s_waitcnt lgkmcnt(0)
	v_mov_b32_e32 v4, v3
	s_nop 1
	v_permlane16_swap_b32_e32 v3, v4
	s_nop 0
	v_add_f32_e32 v3, v3, v4
	ds_bpermute_b32 v4, v205, v3
	s_and_saveexec_b64 s[4:5], vcc
	s_cbranch_execz .LBB0_1218
	s_waitcnt lgkmcnt(0)
	v_add_f32_e32 v3, v3, v4
	ds_write_b32 v190, v3 offset:4096
.LBB0_1218:
	s_or_b64 exec, exec, s[4:5]
	s_waitcnt lgkmcnt(0)
	ds_read_b128 v[4:7], v2 offset:256
	s_waitcnt lgkmcnt(0)
	v_max_f32_e32 v3, v7, v7
	v_max_f32_e32 v6, v6, v6
	v_max_f32_e32 v3, v6, v3
	v_max3_f32 v3, v4, v5, v3
	v_sub_f32_e32 v4, v188, v3
	v_sub_f32_e32 v5, v189, v3
	v_exp_f32_e32 v96, v4
	v_sub_f32_e32 v6, v184, v3
	v_exp_f32_e32 v97, v5
	v_sub_f32_e32 v7, v185, v3
	v_exp_f32_e32 v112, v6
	v_exp_f32_e32 v113, v7
	v_sub_f32_e32 v5, v186, v3
	v_add_f32_e32 v4, 0, v96
	v_exp_f32_e32 v102, v5
	v_sub_f32_e32 v5, v187, v3
	v_add_f32_e32 v4, v97, v4
	v_exp_f32_e32 v103, v5
	v_sub_f32_e32 v5, v108, v3
	v_add_f32_e32 v4, v112, v4
	v_exp_f32_e32 v114, v5
	v_sub_f32_e32 v5, v109, v3
	v_add_f32_e32 v4, v113, v4
	v_exp_f32_e32 v115, v5
	v_sub_f32_e32 v5, v180, v3
	v_add_f32_e32 v4, v102, v4
	v_exp_f32_e32 v94, v5
	v_sub_f32_e32 v5, v181, v3
	v_add_f32_e32 v4, v103, v4
	v_exp_f32_e32 v95, v5
	v_sub_f32_e32 v5, v106, v3
	v_add_f32_e32 v4, v114, v4
	v_exp_f32_e32 v108, v5
	v_sub_f32_e32 v5, v107, v3
	v_add_f32_e32 v4, v115, v4
	v_exp_f32_e32 v109, v5
	v_sub_f32_e32 v5, v120, v3
	v_add_f32_e32 v4, v94, v4
	v_exp_f32_e32 v106, v5
	v_sub_f32_e32 v5, v121, v3
	v_add_f32_e32 v4, v95, v4
	v_exp_f32_e32 v107, v5
	v_sub_f32_e32 v5, v92, v3
	v_add_f32_e32 v4, v108, v4
	v_exp_f32_e32 v120, v5
	v_sub_f32_e32 v3, v93, v3
	v_add_f32_e32 v4, v109, v4
	v_exp_f32_e32 v121, v3
	v_add_f32_e32 v3, v106, v4
	v_add_f32_e32 v3, v107, v3
	v_add_f32_e32 v3, v120, v3
	v_add_f32_e32 v3, v121, v3
	s_waitcnt lgkmcnt(0)
	v_mov_b32_e32 v4, v3
	s_nop 1
	v_permlane16_swap_b32_e32 v3, v4
	s_nop 0
	v_add_f32_e32 v3, v3, v4
	ds_bpermute_b32 v4, v205, v3
	s_and_saveexec_b64 s[4:5], vcc
	s_cbranch_execz .LBB0_1220
	s_waitcnt lgkmcnt(0)
	v_add_f32_e32 v3, v3, v4
	ds_write_b32 v190, v3 offset:4352
.LBB0_1220:
	s_or_b64 exec, exec, s[4:5]
	s_waitcnt lgkmcnt(0)
	ds_read_b128 v[4:7], v2 offset:512
	s_waitcnt lgkmcnt(0)
	v_max_f32_e32 v3, v7, v7
	v_max_f32_e32 v6, v6, v6
	v_max_f32_e32 v3, v6, v3
	v_max3_f32 v3, v4, v5, v3
	v_sub_f32_e32 v4, v178, v3
	v_sub_f32_e32 v5, v179, v3
	v_exp_f32_e32 v80, v4
	v_sub_f32_e32 v6, v176, v3
	v_exp_f32_e32 v81, v5
	v_sub_f32_e32 v7, v177, v3
	v_exp_f32_e32 v92, v6
	v_exp_f32_e32 v93, v7
	v_sub_f32_e32 v5, v174, v3
	v_add_f32_e32 v4, 0, v80
	v_exp_f32_e32 v86, v5
	v_sub_f32_e32 v5, v175, v3
	v_add_f32_e32 v4, v81, v4
	v_exp_f32_e32 v87, v5
	v_sub_f32_e32 v5, v98, v3
	v_add_f32_e32 v4, v92, v4
	v_exp_f32_e32 v98, v5
	v_sub_f32_e32 v5, v99, v3
	v_add_f32_e32 v4, v93, v4
	v_exp_f32_e32 v99, v5
	v_sub_f32_e32 v5, v172, v3
	v_add_f32_e32 v4, v86, v4
	v_exp_f32_e32 v78, v5
	v_sub_f32_e32 v5, v173, v3
	v_add_f32_e32 v4, v87, v4
	v_exp_f32_e32 v79, v5
	v_sub_f32_e32 v5, v90, v3
	v_add_f32_e32 v4, v98, v4
	v_exp_f32_e32 v90, v5
	v_sub_f32_e32 v5, v91, v3
	v_add_f32_e32 v4, v99, v4
	v_exp_f32_e32 v91, v5
	v_sub_f32_e32 v5, v170, v3
	v_add_f32_e32 v4, v78, v4
	v_exp_f32_e32 v88, v5
	v_sub_f32_e32 v5, v171, v3
	v_add_f32_e32 v4, v79, v4
	v_exp_f32_e32 v89, v5
	v_sub_f32_e32 v5, v100, v3
	v_add_f32_e32 v4, v90, v4
	v_exp_f32_e32 v100, v5
	v_sub_f32_e32 v3, v101, v3
	v_add_f32_e32 v4, v91, v4
	v_exp_f32_e32 v101, v3
	v_add_f32_e32 v3, v88, v4
	v_add_f32_e32 v3, v89, v3
	v_add_f32_e32 v3, v100, v3
	v_add_f32_e32 v3, v101, v3
	s_waitcnt lgkmcnt(0)
	v_mov_b32_e32 v4, v3
	s_nop 1
	v_permlane16_swap_b32_e32 v3, v4
	s_nop 0
	v_add_f32_e32 v3, v3, v4
	ds_bpermute_b32 v4, v205, v3
	s_and_saveexec_b64 s[4:5], vcc
	s_cbranch_execz .LBB0_1222
	s_waitcnt lgkmcnt(0)
	v_add_f32_e32 v3, v3, v4
	ds_write_b32 v190, v3 offset:4608
; #define LAS __attribute__((address_space(3)))
;     __device__ __forceinline__ void fused(f32x4 (&acc)[2][2][4][2], const Unit& u, int wr, int wc, int fr, int fq, LAS unsigned char* lds, int wid, int lane) const {
;     ...
; #pragma unroll
;         for (int ai = 0; ai < 2; ++ai)
; #pragma unroll
;             for (int m = 0; m < 4; ++m) { const int r = ai * HALF + wr * 64 + m * 16 + fr; const f32x4 q = *(const LAS f32x4*)(MX + r * 4); const float M = fmaxf(fmaxf(q[0], q[1]), fmaxf(q[2], q[3])); float s = 0.f;
; #pragma unroll
;                 for (int bj = 0; bj < 2; ++bj)
; #pragma unroll
;                     for (int n = 0; n < 2; ++n) { f32x4 v = acc[ai][bj][m][n];
; #pragma unroll
;                         for (int j = 0; j < 4; ++j) { v[j] = __builtin_amdgcn_exp2f(v[j] - M); s += v[j]; }
;                         acc[ai][bj][m][n] = v; }
;                 s += __shfl_xor(s, 16); s += __shfl_xor(s, 32);
;                 if (fq == 0) SM[r * 4 + wc] = s; }
.LBB0_1222:
	s_or_b64 exec, exec, s[4:5]
	s_waitcnt lgkmcnt(0)
	ds_read_b128 v[4:7], v2 offset:768
	s_waitcnt lgkmcnt(0)
	v_max_f32_e32 v3, v7, v7
	v_max_f32_e32 v6, v6, v6
	v_max_f32_e32 v3, v6, v3
	v_max3_f32 v3, v4, v5, v3
	v_sub_f32_e32 v4, v168, v3
	v_sub_f32_e32 v5, v169, v3
	v_exp_f32_e32 v64, v4
	v_sub_f32_e32 v6, v76, v3
	v_exp_f32_e32 v65, v5
	v_sub_f32_e32 v7, v77, v3
	v_exp_f32_e32 v76, v6
	v_exp_f32_e32 v77, v7
	v_sub_f32_e32 v5, v82, v3
	v_add_f32_e32 v4, 0, v64
	v_exp_f32_e32 v70, v5
	v_sub_f32_e32 v5, v83, v3
	v_add_f32_e32 v4, v65, v4
	v_exp_f32_e32 v71, v5
	v_sub_f32_e32 v5, v74, v3
	v_add_f32_e32 v4, v76, v4
	v_exp_f32_e32 v82, v5
	v_sub_f32_e32 v5, v75, v3
	v_add_f32_e32 v4, v77, v4
	v_exp_f32_e32 v83, v5
	v_sub_f32_e32 v5, v166, v3
	v_add_f32_e32 v4, v70, v4
	v_exp_f32_e32 v62, v5
	v_sub_f32_e32 v5, v167, v3
	v_add_f32_e32 v4, v71, v4
	v_exp_f32_e32 v63, v5
	v_sub_f32_e32 v5, v72, v3
	v_add_f32_e32 v4, v82, v4
	v_exp_f32_e32 v74, v5
	v_sub_f32_e32 v5, v73, v3
	v_add_f32_e32 v4, v83, v4
	v_exp_f32_e32 v75, v5
	v_sub_f32_e32 v5, v162, v3
	v_add_f32_e32 v4, v62, v4
	v_exp_f32_e32 v72, v5
	v_sub_f32_e32 v5, v163, v3
	v_add_f32_e32 v4, v63, v4
	v_exp_f32_e32 v73, v5
	v_sub_f32_e32 v5, v84, v3
	v_add_f32_e32 v4, v74, v4
	v_exp_f32_e32 v84, v5
	v_sub_f32_e32 v3, v85, v3
	v_add_f32_e32 v4, v75, v4
	v_exp_f32_e32 v85, v3
	v_add_f32_e32 v3, v72, v4
	v_add_f32_e32 v3, v73, v3
	v_add_f32_e32 v3, v84, v3
	v_add_f32_e32 v3, v85, v3
	s_waitcnt lgkmcnt(0)
	v_mov_b32_e32 v4, v3
	s_nop 1
	v_permlane16_swap_b32_e32 v3, v4
	s_nop 0
	v_add_f32_e32 v3, v3, v4
	ds_bpermute_b32 v4, v205, v3
	s_and_saveexec_b64 s[4:5], vcc
	s_cbranch_execz .LBB0_1224
	s_waitcnt lgkmcnt(0)
	v_add_f32_e32 v3, v3, v4
	ds_write_b32 v190, v3 offset:4864
.LBB0_1224:
	s_or_b64 exec, exec, s[4:5]
	s_waitcnt lgkmcnt(0)
	ds_read_b128 v[4:7], v2 offset:2048
	s_waitcnt lgkmcnt(0)
	v_max_f32_e32 v3, v7, v7
	v_max_f32_e32 v6, v6, v6
	v_max_f32_e32 v3, v6, v3
	v_max3_f32 v3, v4, v5, v3
	v_sub_f32_e32 v4, v164, v3
	v_sub_f32_e32 v5, v165, v3
	v_exp_f32_e32 v48, v4
	v_sub_f32_e32 v6, v160, v3
	v_exp_f32_e32 v49, v5
	v_sub_f32_e32 v7, v161, v3
	v_exp_f32_e32 v60, v6
	v_exp_f32_e32 v61, v7
	v_sub_f32_e32 v5, v158, v3
	v_add_f32_e32 v4, 0, v48
	v_exp_f32_e32 v54, v5
	v_sub_f32_e32 v5, v159, v3
	v_add_f32_e32 v4, v49, v4
	v_exp_f32_e32 v55, v5
	v_sub_f32_e32 v5, v66, v3
	v_add_f32_e32 v4, v60, v4
	v_exp_f32_e32 v66, v5
	v_sub_f32_e32 v5, v67, v3
	v_add_f32_e32 v4, v61, v4
	v_exp_f32_e32 v67, v5
	v_sub_f32_e32 v5, v156, v3
	v_add_f32_e32 v4, v54, v4
	v_exp_f32_e32 v46, v5
	v_sub_f32_e32 v5, v157, v3
	v_add_f32_e32 v4, v55, v4
	v_exp_f32_e32 v47, v5
	v_sub_f32_e32 v5, v58, v3
	v_add_f32_e32 v4, v66, v4
	v_exp_f32_e32 v58, v5
	v_sub_f32_e32 v5, v59, v3
	v_add_f32_e32 v4, v67, v4
	v_exp_f32_e32 v59, v5
	v_sub_f32_e32 v5, v154, v3
	v_add_f32_e32 v4, v46, v4
	v_exp_f32_e32 v56, v5
	v_sub_f32_e32 v5, v155, v3
	v_add_f32_e32 v4, v47, v4
	v_exp_f32_e32 v57, v5
	v_sub_f32_e32 v5, v68, v3
	v_add_f32_e32 v4, v58, v4
	v_exp_f32_e32 v68, v5
	v_sub_f32_e32 v3, v69, v3
	v_add_f32_e32 v4, v59, v4
	v_exp_f32_e32 v69, v3
	v_add_f32_e32 v3, v56, v4
	v_add_f32_e32 v3, v57, v3
	v_add_f32_e32 v3, v68, v3
	v_add_f32_e32 v3, v69, v3
	s_waitcnt lgkmcnt(0)
	v_mov_b32_e32 v4, v3
	s_nop 1
	v_permlane16_swap_b32_e32 v3, v4
	s_nop 0
	v_add_f32_e32 v3, v3, v4
	ds_bpermute_b32 v4, v205, v3
	s_and_saveexec_b64 s[4:5], vcc
	s_cbranch_execz .LBB0_1226
	s_waitcnt lgkmcnt(0)
	v_add_f32_e32 v3, v3, v4
	ds_write_b32 v190, v3 offset:6144
.LBB0_1226:
	s_or_b64 exec, exec, s[4:5]
	s_waitcnt lgkmcnt(0)
	ds_read_b128 v[4:7], v2 offset:2304
	s_waitcnt lgkmcnt(0)
	v_max_f32_e32 v3, v7, v7
	v_max_f32_e32 v6, v6, v6
	v_max_f32_e32 v3, v6, v3
	v_max3_f32 v3, v4, v5, v3
	v_sub_f32_e32 v4, v152, v3
	v_sub_f32_e32 v5, v153, v3
	v_exp_f32_e32 v32, v4
	v_sub_f32_e32 v6, v44, v3
	v_exp_f32_e32 v33, v5
	v_sub_f32_e32 v7, v45, v3
	v_exp_f32_e32 v44, v6
	v_exp_f32_e32 v45, v7
	v_sub_f32_e32 v5, v150, v3
	v_add_f32_e32 v4, 0, v32
	v_exp_f32_e32 v38, v5
	v_sub_f32_e32 v5, v151, v3
	v_add_f32_e32 v4, v33, v4
	v_exp_f32_e32 v39, v5
	v_sub_f32_e32 v5, v50, v3
	v_add_f32_e32 v4, v44, v4
	v_exp_f32_e32 v50, v5
	v_sub_f32_e32 v5, v51, v3
	v_add_f32_e32 v4, v45, v4
	v_exp_f32_e32 v51, v5
	v_sub_f32_e32 v5, v148, v3
	v_add_f32_e32 v4, v38, v4
	v_exp_f32_e32 v30, v5
	v_sub_f32_e32 v5, v149, v3
	v_add_f32_e32 v4, v39, v4
	v_exp_f32_e32 v31, v5
	v_sub_f32_e32 v5, v42, v3
	v_add_f32_e32 v4, v50, v4
	v_exp_f32_e32 v42, v5
	v_sub_f32_e32 v5, v43, v3
	v_add_f32_e32 v4, v51, v4
	v_exp_f32_e32 v43, v5
	v_sub_f32_e32 v5, v52, v3
	v_add_f32_e32 v4, v30, v4
	v_exp_f32_e32 v40, v5
	v_sub_f32_e32 v5, v53, v3
	v_add_f32_e32 v4, v31, v4
	v_exp_f32_e32 v41, v5
	v_sub_f32_e32 v5, v28, v3
	v_add_f32_e32 v4, v42, v4
	v_exp_f32_e32 v52, v5
	v_sub_f32_e32 v3, v29, v3
	v_add_f32_e32 v4, v43, v4
	v_exp_f32_e32 v53, v3
	v_add_f32_e32 v3, v40, v4
	v_add_f32_e32 v3, v41, v3
	v_add_f32_e32 v3, v52, v3
	v_add_f32_e32 v3, v53, v3
	s_waitcnt lgkmcnt(0)
	v_mov_b32_e32 v4, v3
	s_nop 1
	v_permlane16_swap_b32_e32 v3, v4
	s_nop 0
	v_add_f32_e32 v3, v3, v4
	ds_bpermute_b32 v4, v205, v3
	s_and_saveexec_b64 s[4:5], vcc
	s_cbranch_execz .LBB0_1228
	s_waitcnt lgkmcnt(0)
	v_add_f32_e32 v3, v3, v4
	ds_write_b32 v190, v3 offset:6400
.LBB0_1228:
	s_or_b64 exec, exec, s[4:5]
	s_waitcnt lgkmcnt(0)
	ds_read_b128 v[4:7], v2 offset:2560
	s_waitcnt lgkmcnt(0)
	v_max_f32_e32 v3, v7, v7
	v_max_f32_e32 v6, v6, v6
	v_max_f32_e32 v3, v6, v3
	v_max3_f32 v3, v4, v5, v3
	v_sub_f32_e32 v4, v146, v3
	v_sub_f32_e32 v5, v147, v3
	v_exp_f32_e32 v16, v4
	v_sub_f32_e32 v6, v144, v3
	v_exp_f32_e32 v17, v5
	v_sub_f32_e32 v7, v145, v3
	v_exp_f32_e32 v28, v6
	v_exp_f32_e32 v29, v7
	v_sub_f32_e32 v5, v142, v3
	v_add_f32_e32 v4, 0, v16
	v_exp_f32_e32 v22, v5
	v_sub_f32_e32 v5, v143, v3
	v_add_f32_e32 v4, v17, v4
	v_exp_f32_e32 v23, v5
	v_sub_f32_e32 v5, v34, v3
	v_add_f32_e32 v4, v28, v4
	v_exp_f32_e32 v34, v5
	v_sub_f32_e32 v5, v35, v3
	v_add_f32_e32 v4, v29, v4
	v_exp_f32_e32 v35, v5
	v_sub_f32_e32 v5, v140, v3
	v_add_f32_e32 v4, v22, v4
	v_exp_f32_e32 v14, v5
	v_sub_f32_e32 v5, v141, v3
	v_add_f32_e32 v4, v23, v4
	v_exp_f32_e32 v15, v5
	v_sub_f32_e32 v5, v26, v3
	v_add_f32_e32 v4, v34, v4
	v_exp_f32_e32 v26, v5
	v_sub_f32_e32 v5, v27, v3
	v_add_f32_e32 v4, v35, v4
	v_exp_f32_e32 v27, v5
	v_sub_f32_e32 v5, v138, v3
	v_add_f32_e32 v4, v14, v4
	v_exp_f32_e32 v24, v5
	v_sub_f32_e32 v5, v139, v3
	v_add_f32_e32 v4, v15, v4
	v_exp_f32_e32 v25, v5
	v_sub_f32_e32 v5, v36, v3
	v_add_f32_e32 v4, v26, v4
	v_exp_f32_e32 v36, v5
	v_sub_f32_e32 v3, v37, v3
	v_add_f32_e32 v4, v27, v4
	v_exp_f32_e32 v37, v3
	v_add_f32_e32 v3, v24, v4
	v_add_f32_e32 v3, v25, v3
	v_add_f32_e32 v3, v36, v3
	v_add_f32_e32 v3, v37, v3
	s_waitcnt lgkmcnt(0)
	v_mov_b32_e32 v4, v3
	s_nop 1
	v_permlane16_swap_b32_e32 v3, v4
	s_nop 0
	v_add_f32_e32 v3, v3, v4
	ds_bpermute_b32 v4, v205, v3
	s_and_saveexec_b64 s[4:5], vcc
	s_cbranch_execz .LBB0_1230
	s_waitcnt lgkmcnt(0)
	v_add_f32_e32 v3, v3, v4
	ds_write_b32 v190, v3 offset:6656

; __device__ __forceinline__ unsigned cvt_pk_bf16(float lo, float hi) { unsigned r; asm volatile("v_cvt_pk_bf16_f32 %0, %1, %2" : "=v"(r) : "v"(lo), "v"(hi)); return r; }
; __device__ __forceinline__ float bflo(unsigned w) { return __uint_as_float(w << 16); }
; __device__ __forceinline__ float bfhi(unsigned w) { return __uint_as_float(w & 0xffff0000u); }
;     __device__ __forceinline__ void operator()(const f32x4 (&acc)[2][2][4][2], const Unit& u, int wr, int wc, int fr, int fq) const {
;         const int row0 = u.pm * BM + wr * 64 + fr, col0 = u.pn * BM + wc * 32 + 8 * fq;
; #pragma unroll
;         for (int ai = 0; ai < 2; ++ai) {
;             u32x4 bw[4][2];
; #pragma unroll
;             for (int m = 0; m < 4; ++m)
; #pragma unroll
;                 for (int bj = 0; bj < 2; ++bj) bw[m][bj] = *(const u32x4*)((const bf16_t*)base + (size_t)(row0 + ai * HALF + m * 16) * DM + col0 + bj * HALF);
; #pragma unroll
;             for (int m = 0; m < 4; ++m) { const int row = row0 + ai * HALF + m * 16; const size_t off = (size_t)row * DM + col0; float ss = 0.f;
; #pragma unroll
;                 for (int bj = 0; bj < 2; ++bj) { const u32x4 w = bw[m][bj];
;                     const f32x4 b0 = {bflo(w.x), bfhi(w.x), bflo(w.y), bfhi(w.y)}, b1 = {bflo(w.z), bfhi(w.z), bflo(w.w), bfhi(w.w)};
;                     const f32x4 o0 = b0 + acc[ai][bj][m][0], o1 = b1 + acc[ai][bj][m][1];
;                     ss += ((o0[0] * o0[0] + o0[1] * o0[1]) + (o0[2] * o0[2] + o0[3] * o0[3])) + ((o1[0] * o1[0] + o1[1] * o1[1]) + (o1[2] * o1[2] + o1[3] * o1[3]));
;                     u32x4 w2; w2.x = cvt_pk_bf16(o0[0], o0[1]); w2.y = cvt_pk_bf16(o0[2], o0[3]); w2.z = cvt_pk_bf16(o1[0], o1[1]); w2.w = cvt_pk_bf16(o1[2], o1[3]);
;                     *(u32x4*)(hout + off + bj * HALF) = w2; }
;                 ss += __shfl_xor(ss, 16); ss += __shfl_xor(ss, 32);
;                 if (fq == 0) part[(size_t)row * 64 + u.pn * 4 + wc] = ss; }
.LBB0_1312:
	v_lshl_or_b32 v170, s12, 8, v191
	v_lshl_add_u32 v174, s28, 8, v183
	v_ashrrev_i32_e32 v171, 31, v170
	v_lshlrev_b64 v[206:207], 1, v[170:171]
	v_ashrrev_i32_e32 v175, 31, v174
	v_lshl_add_u64 v[172:173], s[74:75], 0, v[206:207]
	v_lshlrev_b64 v[196:197], 13, v[174:175]
	v_lshl_add_u64 v[130:131], v[172:173], 0, v[196:197]
	global_load_dwordx4 v[198:201], v[130:131], off
	global_load_dwordx4 v[202:205], v[130:131], off offset:256
	v_or_b32_e32 v186, 16, v174
	v_or_b32_e32 v180, 32, v174
	v_or_b32_e32 v176, 48, v174
	v_ashrrev_i32_e32 v187, 31, v186
	v_ashrrev_i32_e32 v181, 31, v180
	v_ashrrev_i32_e32 v177, 31, v176
	v_lshlrev_b64 v[188:189], 13, v[186:187]
	v_lshlrev_b64 v[184:185], 13, v[180:181]
	v_lshlrev_b64 v[178:179], 13, v[176:177]
	v_lshl_add_u64 v[130:131], v[172:173], 0, v[188:189]
	v_lshl_add_u64 v[132:133], v[172:173], 0, v[184:185]
	v_lshl_add_u64 v[208:209], v[172:173], 0, v[178:179]
	global_load_dwordx4 v[150:153], v[130:131], off
	global_load_dwordx4 v[146:149], v[130:131], off offset:256
	global_load_dwordx4 v[142:145], v[132:133], off
	global_load_dwordx4 v[138:141], v[132:133], off offset:256
	global_load_dwordx4 v[134:137], v[208:209], off
	s_nop 0
	global_load_dwordx4 v[130:133], v[208:209], off offset:256
	v_add_u32_e32 v218, 0x80, v174
	v_ashrrev_i32_e32 v219, 31, v218
	v_lshlrev_b64 v[218:219], 13, v[218:219]
	v_lshl_add_u64 v[218:219], v[172:173], 0, v[218:219]
	global_load_dwordx4 v[220:223], v[218:219], off
	global_load_dwordx4 v[224:227], v[218:219], off offset:256
	v_add_co_u32_e32 v218, vcc, 0x20000, v218
	s_nop 1
	v_addc_co_u32_e32 v219, vcc, 0, v219, vcc
	global_load_dwordx4 v[228:231], v[218:219], off
	global_load_dwordx4 v[232:235], v[218:219], off offset:256
	v_add_co_u32_e32 v218, vcc, 0x20000, v218
	s_nop 1
	v_addc_co_u32_e32 v219, vcc, 0, v219, vcc
	global_load_dwordx4 v[236:239], v[218:219], off
	global_load_dwordx4 v[240:243], v[218:219], off offset:256
	v_add_co_u32_e32 v218, vcc, 0x20000, v218
	s_nop 1
	v_addc_co_u32_e32 v219, vcc, 0, v219, vcc
	global_load_dwordx4 v[244:247], v[218:219], off
	global_load_dwordx4 v[248:251], v[218:219], off offset:256
	v_and_b32_e32 v209, 64, v195
	v_xor_b32_e32 v208, 16, v195
	v_add_u32_e32 v209, 64, v209
	v_xor_b32_e32 v210, 32, v195
	v_cmp_lt_i32_e32 vcc, v208, v209
	s_lshl_b32 s8, s12, 2
	s_ashr_i32 s9, s8, 31
	v_cndmask_b32_e32 v211, v195, v208, vcc
	v_cmp_lt_i32_e32 vcc, v210, v209
	v_lshl_add_u64 v[208:209], s[74:75], 0, v[196:197]
	v_lshlrev_b32_e32 v196, 2, v211
	v_cndmask_b32_e32 v216, v195, v210, vcc
	v_lshl_add_u64 v[206:207], v[208:209], 0, v[206:207]
	s_waitcnt vmcnt(0)
	v_lshlrev_b32_e32 v208, 16, v198
	v_and_b32_e32 v209, 0xffff0000, v198
	v_lshlrev_b32_e32 v198, 16, v199
	v_and_b32_e32 v199, 0xffff0000, v199
	v_lshlrev_b32_e32 v210, 16, v200
	v_and_b32_e32 v211, 0xffff0000, v200
	v_lshlrev_b32_e32 v200, 16, v201
	v_and_b32_e32 v201, 0xffff0000, v201
	v_lshlrev_b32_e32 v212, 16, v202
	v_and_b32_e32 v213, 0xffff0000, v202
	v_lshlrev_b32_e32 v202, 16, v203
	v_and_b32_e32 v203, 0xffff0000, v203
	v_lshlrev_b32_e32 v214, 16, v204
	v_and_b32_e32 v215, 0xffff0000, v204
	v_lshlrev_b32_e32 v204, 16, v205
	v_and_b32_e32 v205, 0xffff0000, v205
	v_pk_add_f32 v[128:129], v[128:129], v[198:199]
	v_pk_add_f32 v[126:127], v[126:127], v[208:209]
	v_pk_add_f32 v[124:125], v[124:125], v[200:201]
	v_pk_add_f32 v[122:123], v[122:123], v[210:211]
	v_pk_add_f32 v[120:121], v[120:121], v[202:203]
	v_pk_add_f32 v[118:119], v[118:119], v[212:213]
	v_pk_add_f32 v[198:199], v[116:117], v[204:205]
	v_pk_add_f32 v[200:201], v[114:115], v[214:215]
	v_mul_f32_e32 v116, v127, v127
	v_mul_f32_e32 v117, v129, v129
	v_mul_f32_e32 v197, v123, v123
	v_mul_f32_e32 v202, v125, v125
	v_cvt_pk_bf16_f32 v114, v126, v127
	v_cvt_pk_bf16_f32 v115, v128, v129
	v_mul_f32_e32 v127, v119, v119
	v_mul_f32_e32 v129, v121, v121
	v_mul_f32_e32 v203, v201, v201
	v_mul_f32_e32 v204, v199, v199
	v_fmac_f32_e32 v116, v126, v126
	v_fmac_f32_e32 v117, v128, v128
	v_fmac_f32_e32 v197, v122, v122
	v_fmac_f32_e32 v202, v124, v124
	v_fmac_f32_e32 v127, v118, v118
	v_fmac_f32_e32 v129, v120, v120
	v_fmac_f32_e32 v203, v200, v200
	v_fmac_f32_e32 v204, v198, v198
	v_add_f32_e32 v116, v116, v117
	v_add_f32_e32 v117, v197, v202
	v_add_f32_e32 v126, v127, v129
	v_add_f32_e32 v127, v203, v204
	v_add_f32_e32 v116, v116, v117
	v_add_f32_e32 v117, v126, v127
	v_add_f32_e32 v126, v116, v117
	v_cvt_pk_bf16_f32 v116, v122, v123
	v_cvt_pk_bf16_f32 v117, v124, v125
	global_store_dwordx4 v[206:207], v[114:117], off
	v_cvt_pk_bf16_f32 v118, v118, v119
	v_cvt_pk_bf16_f32 v119, v120, v121
	v_cvt_pk_bf16_f32 v120, v200, v201
	v_cvt_pk_bf16_f32 v121, v198, v199
	global_store_dwordx4 v[206:207], v[118:121], off offset:256
	s_waitcnt lgkmcnt(0)
	v_mov_b32_e32 v115, v126
	v_mov_b32_e32 v127, v126
	s_nop 1
	v_permlane16_swap_b32_e32 v115, v127
	s_nop 0
	v_add_f32_e32 v115, v115, v127
	v_lshlrev_b32_e32 v114, 2, v216
	ds_bpermute_b32 v116, v114, v115
	s_and_saveexec_b64 s[28:29], s[4:5]
	s_cbranch_execz .LBB0_1314
	v_lshlrev_b64 v[118:119], 8, v[174:175]
	v_lshl_add_u64 v[118:119], s[10:11], 0, v[118:119]
	v_lshl_add_u64 v[118:119], s[8:9], 2, v[118:119]
	s_lshl_b32 s12, s39, 2
	v_lshl_add_u64 v[118:119], v[118:119], 0, s[12:13]
	s_waitcnt lgkmcnt(0)
	v_add_f32_e32 v115, v115, v116
	global_store_dword v[118:119], v115, off
; __device__ __forceinline__ unsigned cvt_pk_bf16(float lo, float hi) { unsigned r; asm volatile("v_cvt_pk_bf16_f32 %0, %1, %2" : "=v"(r) : "v"(lo), "v"(hi)); return r; }
; __device__ __forceinline__ float bflo(unsigned w) { return __uint_as_float(w << 16); }
; __device__ __forceinline__ float bfhi(unsigned w) { return __uint_as_float(w & 0xffff0000u); }
;     __device__ __forceinline__ void operator()(const f32x4 (&acc)[2][2][4][2], const Unit& u, int wr, int wc, int fr, int fq) const {
;     ...
;                 for (int bj = 0; bj < 2; ++bj) bw[m][bj] = *(const u32x4*)((const bf16_t*)base + (size_t)(row0 + ai * HALF + m * 16) * DM + col0 + bj * HALF);
; #pragma unroll
;             for (int m = 0; m < 4; ++m) { const int row = row0 + ai * HALF + m * 16; const size_t off = (size_t)row * DM + col0; float ss = 0.f;
; #pragma unroll
;                 for (int bj = 0; bj < 2; ++bj) { const u32x4 w = bw[m][bj];
;                     const f32x4 b0 = {bflo(w.x), bfhi(w.x), bflo(w.y), bfhi(w.y)}, b1 = {bflo(w.z), bfhi(w.z), bflo(w.w), bfhi(w.w)};
;                     const f32x4 o0 = b0 + acc[ai][bj][m][0], o1 = b1 + acc[ai][bj][m][1];
;                     ss += ((o0[0] * o0[0] + o0[1] * o0[1]) + (o0[2] * o0[2] + o0[3] * o0[3])) + ((o1[0] * o1[0] + o1[1] * o1[1]) + (o1[2] * o1[2] + o1[3] * o1[3]));
;                     u32x4 w2; w2.x = cvt_pk_bf16(o0[0], o0[1]); w2.y = cvt_pk_bf16(o0[2], o0[3]); w2.z = cvt_pk_bf16(o1[0], o1[1]); w2.w = cvt_pk_bf16(o1[2], o1[3]);
;                     *(u32x4*)(hout + off + bj * HALF) = w2; }
;                 ss += __shfl_xor(ss, 16); ss += __shfl_xor(ss, 32);
;                 if (fq == 0) part[(size_t)row * 64 + u.pn * 4 + wc] = ss; }
.LBB0_1314:
	s_or_b64 exec, exec, s[28:29]
	s_waitcnt lgkmcnt(0)
	v_lshlrev_b32_e32 v116, 16, v150
	v_and_b32_e32 v117, 0xffff0000, v150
	v_lshlrev_b32_e32 v118, 16, v151
	v_and_b32_e32 v119, 0xffff0000, v151
	v_lshlrev_b32_e32 v120, 16, v152
	v_and_b32_e32 v121, 0xffff0000, v152
	v_lshlrev_b32_e32 v122, 16, v153
	v_and_b32_e32 v123, 0xffff0000, v153
	v_pk_add_f32 v[112:113], v[112:113], v[118:119]
	v_pk_add_f32 v[110:111], v[110:111], v[116:117]
	v_pk_add_f32 v[116:117], v[108:109], v[122:123]
	v_pk_add_f32 v[108:109], v[106:107], v[120:121]
	v_mul_f32_e32 v106, v111, v111
	v_mul_f32_e32 v107, v113, v113
	v_fmac_f32_e32 v106, v110, v110
	v_fmac_f32_e32 v107, v112, v112
	v_add_f32_e32 v106, v106, v107
	v_mul_f32_e32 v107, v109, v109
	v_mul_f32_e32 v115, v117, v117
	v_fmac_f32_e32 v107, v108, v108
	v_fmac_f32_e32 v115, v116, v116
	v_add_f32_e32 v107, v107, v115
	v_add_f32_e32 v115, v106, v107
	v_cvt_pk_bf16_f32 v106, v110, v111
	v_cvt_pk_bf16_f32 v107, v112, v113
	v_lshlrev_b32_e32 v110, 16, v146
	v_and_b32_e32 v111, 0xffff0000, v146
	v_lshlrev_b32_e32 v112, 16, v147
	v_and_b32_e32 v113, 0xffff0000, v147
	v_cvt_pk_bf16_f32 v108, v108, v109
	v_cvt_pk_bf16_f32 v109, v116, v117
	v_lshlrev_b32_e32 v116, 16, v148
	v_and_b32_e32 v117, 0xffff0000, v148
	v_pk_add_f32 v[104:105], v[104:105], v[112:113]
	v_pk_add_f32 v[102:103], v[102:103], v[110:111]
	v_lshlrev_b32_e32 v118, 16, v149
	v_and_b32_e32 v119, 0xffff0000, v149
	v_pk_add_f32 v[112:113], v[98:99], v[116:117]
	v_mul_f32_e32 v98, v103, v103
	v_mul_f32_e32 v99, v105, v105
	v_pk_add_f32 v[110:111], v[100:101], v[118:119]
	v_fmac_f32_e32 v98, v102, v102
	v_fmac_f32_e32 v99, v104, v104
	v_add_f32_e32 v98, v98, v99
	v_mul_f32_e32 v99, v113, v113
	v_mul_f32_e32 v100, v111, v111
	v_fmac_f32_e32 v99, v112, v112
	v_fmac_f32_e32 v100, v110, v110
	v_add_f32_e32 v99, v99, v100
	v_add_f32_e32 v98, v98, v99
	v_add_f32_e32 v101, v115, v98
	v_lshl_add_u64 v[98:99], s[74:75], 0, v[188:189]
	v_lshl_add_u64 v[116:117], v[170:171], 1, v[98:99]
	global_store_dwordx4 v[116:117], v[106:109], off
	v_cvt_pk_bf16_f32 v100, v102, v103
	s_waitcnt lgkmcnt(0)
	v_mov_b32_e32 v98, v101
	v_mov_b32_e32 v115, v101
	s_nop 1
	v_permlane16_swap_b32_e32 v98, v115
	s_nop 0
	v_add_f32_e32 v98, v98, v115
	ds_bpermute_b32 v99, v114, v98
	v_cvt_pk_bf16_f32 v101, v104, v105
	v_cvt_pk_bf16_f32 v102, v112, v113
	v_cvt_pk_bf16_f32 v103, v110, v111
	global_store_dwordx4 v[116:117], v[100:103], off offset:256
	s_and_saveexec_b64 s[28:29], s[4:5]
	s_cbranch_execz .LBB0_1316
	v_lshlrev_b64 v[100:101], 8, v[186:187]
	v_lshl_add_u64 v[100:101], s[10:11], 0, v[100:101]
	v_lshl_add_u64 v[100:101], s[8:9], 2, v[100:101]
	s_lshl_b32 s12, s39, 2
	v_lshl_add_u64 v[100:101], v[100:101], 0, s[12:13]
	s_waitcnt lgkmcnt(0)
	v_add_f32_e32 v98, v98, v99
	global_store_dword v[100:101], v98, off
.LBB0_1316:
	s_or_b64 exec, exec, s[28:29]
	v_lshlrev_b32_e32 v98, 16, v142
	s_waitcnt lgkmcnt(0)
	v_and_b32_e32 v99, 0xffff0000, v142
	v_lshlrev_b32_e32 v100, 16, v143
	v_and_b32_e32 v101, 0xffff0000, v143
	v_lshlrev_b32_e32 v102, 16, v144
	v_and_b32_e32 v103, 0xffff0000, v144
	v_lshlrev_b32_e32 v104, 16, v145
	v_and_b32_e32 v105, 0xffff0000, v145
	v_pk_add_f32 v[96:97], v[96:97], v[100:101]
	v_pk_add_f32 v[94:95], v[94:95], v[98:99]
	v_pk_add_f32 v[98:99], v[92:93], v[104:105]
	v_pk_add_f32 v[92:93], v[90:91], v[102:103]
	v_mul_f32_e32 v90, v95, v95
	v_mul_f32_e32 v91, v97, v97
	v_fmac_f32_e32 v90, v94, v94
	v_fmac_f32_e32 v91, v96, v96
	v_add_f32_e32 v90, v90, v91
	v_mul_f32_e32 v91, v93, v93
	v_mul_f32_e32 v100, v99, v99
	v_fmac_f32_e32 v91, v92, v92
	v_fmac_f32_e32 v100, v98, v98
	v_add_f32_e32 v91, v91, v100
	v_add_f32_e32 v102, v90, v91
	v_cvt_pk_bf16_f32 v90, v94, v95
	v_cvt_pk_bf16_f32 v91, v96, v97
	v_lshlrev_b32_e32 v94, 16, v138
	v_and_b32_e32 v95, 0xffff0000, v138
	v_lshlrev_b32_e32 v96, 16, v139
	v_and_b32_e32 v97, 0xffff0000, v139
	v_cvt_pk_bf16_f32 v92, v92, v93
	v_cvt_pk_bf16_f32 v93, v98, v99
	v_lshlrev_b32_e32 v98, 16, v140
	v_and_b32_e32 v99, 0xffff0000, v140
	v_pk_add_f32 v[88:89], v[88:89], v[96:97]
	v_pk_add_f32 v[86:87], v[86:87], v[94:95]
	v_lshlrev_b32_e32 v100, 16, v141
	v_and_b32_e32 v101, 0xffff0000, v141
	v_pk_add_f32 v[96:97], v[82:83], v[98:99]
	v_mul_f32_e32 v82, v87, v87
	v_mul_f32_e32 v83, v89, v89
	v_pk_add_f32 v[94:95], v[84:85], v[100:101]
	v_fmac_f32_e32 v82, v86, v86
	v_fmac_f32_e32 v83, v88, v88
	v_add_f32_e32 v82, v82, v83
	v_mul_f32_e32 v83, v97, v97
	v_mul_f32_e32 v84, v95, v95
	v_fmac_f32_e32 v83, v96, v96
	v_fmac_f32_e32 v84, v94, v94
	v_add_f32_e32 v83, v83, v84
	v_add_f32_e32 v82, v82, v83
	v_add_f32_e32 v85, v102, v82
	v_lshl_add_u64 v[82:83], s[74:75], 0, v[184:185]
	v_lshl_add_u64 v[98:99], v[170:171], 1, v[82:83]
	global_store_dwordx4 v[98:99], v[90:93], off
	v_cvt_pk_bf16_f32 v84, v86, v87
	s_waitcnt lgkmcnt(0)
	v_mov_b32_e32 v82, v85
	v_mov_b32_e32 v100, v85
	s_nop 1
	v_permlane16_swap_b32_e32 v82, v100
	s_nop 0
	v_add_f32_e32 v82, v82, v100
	ds_bpermute_b32 v83, v114, v82
	v_cvt_pk_bf16_f32 v85, v88, v89
	v_cvt_pk_bf16_f32 v86, v96, v97
	v_cvt_pk_bf16_f32 v87, v94, v95
	global_store_dwordx4 v[98:99], v[84:87], off offset:256
	s_and_saveexec_b64 s[28:29], s[4:5]
	s_cbranch_execz .LBB0_1318
	v_lshlrev_b64 v[84:85], 8, v[180:181]
	v_lshl_add_u64 v[84:85], s[10:11], 0, v[84:85]
	v_lshl_add_u64 v[84:85], s[8:9], 2, v[84:85]
	s_lshl_b32 s12, s39, 2
	v_lshl_add_u64 v[84:85], v[84:85], 0, s[12:13]
	s_waitcnt lgkmcnt(0)
	v_add_f32_e32 v82, v82, v83
	global_store_dword v[84:85], v82, off
; __device__ __forceinline__ unsigned cvt_pk_bf16(float lo, float hi) { unsigned r; asm volatile("v_cvt_pk_bf16_f32 %0, %1, %2" : "=v"(r) : "v"(lo), "v"(hi)); return r; }
; __device__ __forceinline__ float bflo(unsigned w) { return __uint_as_float(w << 16); }
; __device__ __forceinline__ float bfhi(unsigned w) { return __uint_as_float(w & 0xffff0000u); }
;     __device__ __forceinline__ void operator()(const f32x4 (&acc)[2][2][4][2], const Unit& u, int wr, int wc, int fr, int fq) const {
;     ...
;         for (int ai = 0; ai < 2; ++ai) {
;             u32x4 bw[4][2];
; #pragma unroll
;             for (int m = 0; m < 4; ++m)
; #pragma unroll
;                 for (int bj = 0; bj < 2; ++bj) bw[m][bj] = *(const u32x4*)((const bf16_t*)base + (size_t)(row0 + ai * HALF + m * 16) * DM + col0 + bj * HALF);
; #pragma unroll
;             for (int m = 0; m < 4; ++m) { const int row = row0 + ai * HALF + m * 16; const size_t off = (size_t)row * DM + col0; float ss = 0.f;
; #pragma unroll
;                 for (int bj = 0; bj < 2; ++bj) { const u32x4 w = bw[m][bj];
;                     const f32x4 b0 = {bflo(w.x), bfhi(w.x), bflo(w.y), bfhi(w.y)}, b1 = {bflo(w.z), bfhi(w.z), bflo(w.w), bfhi(w.w)};
;                     const f32x4 o0 = b0 + acc[ai][bj][m][0], o1 = b1 + acc[ai][bj][m][1];
;                     ss += ((o0[0] * o0[0] + o0[1] * o0[1]) + (o0[2] * o0[2] + o0[3] * o0[3])) + ((o1[0] * o1[0] + o1[1] * o1[1]) + (o1[2] * o1[2] + o1[3] * o1[3]));
;                     u32x4 w2; w2.x = cvt_pk_bf16(o0[0], o0[1]); w2.y = cvt_pk_bf16(o0[2], o0[3]); w2.z = cvt_pk_bf16(o1[0], o1[1]); w2.w = cvt_pk_bf16(o1[2], o1[3]);
;                     *(u32x4*)(hout + off + bj * HALF) = w2; }
;                 ss += __shfl_xor(ss, 16); ss += __shfl_xor(ss, 32);
;                 if (fq == 0) part[(size_t)row * 64 + u.pn * 4 + wc] = ss; }
.LBB0_1318:
	s_or_b64 exec, exec, s[28:29]
	v_lshlrev_b32_e32 v82, 16, v134
	s_waitcnt lgkmcnt(0)
	v_and_b32_e32 v83, 0xffff0000, v134
	v_lshlrev_b32_e32 v84, 16, v135
	v_and_b32_e32 v85, 0xffff0000, v135
	v_lshlrev_b32_e32 v86, 16, v136
	v_and_b32_e32 v87, 0xffff0000, v136
	v_lshlrev_b32_e32 v88, 16, v137
	v_and_b32_e32 v89, 0xffff0000, v137
	v_pk_add_f32 v[80:81], v[80:81], v[84:85]
	v_pk_add_f32 v[78:79], v[78:79], v[82:83]
	v_pk_add_f32 v[82:83], v[76:77], v[88:89]
	v_pk_add_f32 v[76:77], v[74:75], v[86:87]
	v_mul_f32_e32 v74, v79, v79
	v_mul_f32_e32 v75, v81, v81
	v_fmac_f32_e32 v74, v78, v78
	v_fmac_f32_e32 v75, v80, v80
	v_add_f32_e32 v74, v74, v75
	v_mul_f32_e32 v75, v77, v77
	v_mul_f32_e32 v84, v83, v83
	v_fmac_f32_e32 v75, v76, v76
	v_fmac_f32_e32 v84, v82, v82
	v_add_f32_e32 v75, v75, v84
	v_add_f32_e32 v86, v74, v75
	v_cvt_pk_bf16_f32 v74, v78, v79
	v_cvt_pk_bf16_f32 v75, v80, v81
	v_lshlrev_b32_e32 v78, 16, v130
	v_and_b32_e32 v79, 0xffff0000, v130
	v_lshlrev_b32_e32 v80, 16, v131
	v_and_b32_e32 v81, 0xffff0000, v131
	v_cvt_pk_bf16_f32 v76, v76, v77
	v_cvt_pk_bf16_f32 v77, v82, v83
	v_lshlrev_b32_e32 v82, 16, v132
	v_and_b32_e32 v83, 0xffff0000, v132
	v_pk_add_f32 v[72:73], v[72:73], v[80:81]
	v_pk_add_f32 v[70:71], v[70:71], v[78:79]
	v_lshlrev_b32_e32 v84, 16, v133
	v_and_b32_e32 v85, 0xffff0000, v133
	v_pk_add_f32 v[80:81], v[66:67], v[82:83]
	v_mul_f32_e32 v66, v71, v71
	v_mul_f32_e32 v67, v73, v73
	v_pk_add_f32 v[78:79], v[68:69], v[84:85]
	v_fmac_f32_e32 v66, v70, v70
	v_fmac_f32_e32 v67, v72, v72
	v_add_f32_e32 v66, v66, v67
	v_mul_f32_e32 v67, v81, v81
	v_mul_f32_e32 v68, v79, v79
	v_fmac_f32_e32 v67, v80, v80
	v_fmac_f32_e32 v68, v78, v78
	v_add_f32_e32 v67, v67, v68
	v_add_f32_e32 v66, v66, v67
	v_add_f32_e32 v69, v86, v66
	v_lshl_add_u64 v[66:67], s[74:75], 0, v[178:179]
	v_lshl_add_u64 v[82:83], v[170:171], 1, v[66:67]
	global_store_dwordx4 v[82:83], v[74:77], off
	v_cvt_pk_bf16_f32 v68, v70, v71
	s_waitcnt lgkmcnt(0)
	v_mov_b32_e32 v66, v69
	v_mov_b32_e32 v84, v69
	s_nop 1
	v_permlane16_swap_b32_e32 v66, v84
	s_nop 0
	v_add_f32_e32 v66, v66, v84
	ds_bpermute_b32 v67, v114, v66
	v_cvt_pk_bf16_f32 v69, v72, v73
	v_cvt_pk_bf16_f32 v70, v80, v81
	v_cvt_pk_bf16_f32 v71, v78, v79
	global_store_dwordx4 v[82:83], v[68:71], off offset:256
	s_and_saveexec_b64 s[28:29], s[4:5]
	s_cbranch_execz .LBB0_1320
	v_lshlrev_b64 v[68:69], 8, v[176:177]
	v_lshl_add_u64 v[68:69], s[10:11], 0, v[68:69]
	v_lshl_add_u64 v[68:69], s[8:9], 2, v[68:69]
	s_lshl_b32 s12, s39, 2
	v_lshl_add_u64 v[68:69], v[68:69], 0, s[12:13]
	s_waitcnt lgkmcnt(0)
	v_add_f32_e32 v66, v66, v67
	global_store_dword v[68:69], v66, off
.LBB0_1320:
	s_or_b64 exec, exec, s[28:29]
	v_add_u32_e32 v102, 0x80, v174
	v_ashrrev_i32_e32 v103, 31, v102
	v_lshlrev_b64 v[112:113], 13, v[102:103]
	s_waitcnt lgkmcnt(0)
	v_lshl_add_u64 v[66:67], v[172:173], 0, v[112:113]
	v_add_u32_e32 v98, 0x90, v174
	v_add_u32_e32 v94, 0xa0, v174
	v_add_u32_e32 v90, 0xb0, v174
	v_ashrrev_i32_e32 v99, 31, v98
	v_ashrrev_i32_e32 v95, 31, v94
	v_ashrrev_i32_e32 v91, 31, v90
	v_lshlrev_b64 v[100:101], 13, v[98:99]
	v_lshlrev_b64 v[96:97], 13, v[94:95]
	v_lshlrev_b64 v[92:93], 13, v[90:91]
	v_lshl_add_u64 v[66:67], v[172:173], 0, v[100:101]
	v_lshl_add_u64 v[68:69], v[172:173], 0, v[96:97]
	v_lshl_add_u64 v[116:117], v[172:173], 0, v[92:93]
	s_nop 0
	v_mov_b32_e32 v104, v220
	v_mov_b32_e32 v105, v221
	v_mov_b32_e32 v106, v222
	v_mov_b32_e32 v107, v223
	v_mov_b32_e32 v108, v224
	v_mov_b32_e32 v109, v225
	v_mov_b32_e32 v110, v226
	v_mov_b32_e32 v111, v227
	v_mov_b32_e32 v86, v228
	v_mov_b32_e32 v87, v229
	v_mov_b32_e32 v88, v230
	v_mov_b32_e32 v89, v231
	v_mov_b32_e32 v82, v232
	v_mov_b32_e32 v83, v233
	v_mov_b32_e32 v84, v234
	v_mov_b32_e32 v85, v235
	v_mov_b32_e32 v78, v236
	v_mov_b32_e32 v79, v237
	v_mov_b32_e32 v80, v238
	v_mov_b32_e32 v81, v239
	v_mov_b32_e32 v74, v240
	v_mov_b32_e32 v75, v241
	v_mov_b32_e32 v76, v242
	v_mov_b32_e32 v77, v243
	v_mov_b32_e32 v70, v244
	v_mov_b32_e32 v71, v245
	v_mov_b32_e32 v72, v246
	v_mov_b32_e32 v73, v247
	v_mov_b32_e32 v66, v248
	v_mov_b32_e32 v67, v249
	v_mov_b32_e32 v68, v250
	v_mov_b32_e32 v69, v251
	v_lshlrev_b32_e32 v116, 16, v104
	v_and_b32_e32 v117, 0xffff0000, v104
	v_lshlrev_b32_e32 v104, 16, v105
	v_and_b32_e32 v105, 0xffff0000, v105
	v_lshlrev_b32_e32 v118, 16, v106
	v_and_b32_e32 v119, 0xffff0000, v106
	v_lshlrev_b32_e32 v106, 16, v107
	v_and_b32_e32 v107, 0xffff0000, v107
	v_lshlrev_b32_e32 v120, 16, v108
	v_and_b32_e32 v121, 0xffff0000, v108
	v_lshlrev_b32_e32 v108, 16, v109
	v_and_b32_e32 v109, 0xffff0000, v109
	v_lshlrev_b32_e32 v122, 16, v110
	v_and_b32_e32 v123, 0xffff0000, v110
	v_lshlrev_b32_e32 v110, 16, v111
	v_and_b32_e32 v111, 0xffff0000, v111
	v_pk_add_f32 v[64:65], v[64:65], v[104:105]
	v_pk_add_f32 v[62:63], v[62:63], v[116:117]
	v_pk_add_f32 v[60:61], v[60:61], v[106:107]
	v_pk_add_f32 v[58:59], v[58:59], v[118:119]
	v_pk_add_f32 v[56:57], v[56:57], v[108:109]
	v_pk_add_f32 v[54:55], v[54:55], v[120:121]
	v_pk_add_f32 v[104:105], v[52:53], v[110:111]
	v_pk_add_f32 v[106:107], v[50:51], v[122:123]
	v_mul_f32_e32 v108, v63, v63
	v_mul_f32_e32 v109, v65, v65
	v_mul_f32_e32 v110, v59, v59
	v_mul_f32_e32 v111, v61, v61
	v_cvt_pk_bf16_f32 v50, v62, v63
	v_cvt_pk_bf16_f32 v51, v64, v65
	v_cvt_pk_bf16_f32 v52, v58, v59
	v_cvt_pk_bf16_f32 v53, v60, v61
	v_mul_f32_e32 v59, v55, v55
	v_mul_f32_e32 v61, v57, v57
	v_mul_f32_e32 v63, v107, v107
	v_mul_f32_e32 v65, v105, v105
	v_fmac_f32_e32 v108, v62, v62
	v_fmac_f32_e32 v109, v64, v64
	v_fmac_f32_e32 v110, v58, v58
	v_fmac_f32_e32 v111, v60, v60
	v_fmac_f32_e32 v59, v54, v54
	v_fmac_f32_e32 v61, v56, v56
	v_fmac_f32_e32 v63, v106, v106
	v_fmac_f32_e32 v65, v104, v104
	v_add_f32_e32 v58, v108, v109
	v_add_f32_e32 v60, v110, v111
	v_add_f32_e32 v59, v59, v61
	v_add_f32_e32 v61, v63, v65
	v_add_f32_e32 v58, v58, v60
	v_add_f32_e32 v59, v59, v61
	v_add_f32_e32 v60, v58, v59
	v_lshl_add_u64 v[58:59], s[74:75], 0, v[112:113]
	v_lshl_add_u64 v[58:59], v[170:171], 1, v[58:59]
	global_store_dwordx4 v[58:59], v[50:53], off
	s_waitcnt lgkmcnt(0)
	s_nop 0
	v_mov_b32_e32 v50, v60
	v_mov_b32_e32 v61, v60
	s_nop 1
	v_permlane16_swap_b32_e32 v50, v61
	s_nop 0
	v_add_f32_e32 v50, v50, v61
	ds_bpermute_b32 v51, v114, v50
	v_cvt_pk_bf16_f32 v52, v54, v55
	v_cvt_pk_bf16_f32 v53, v56, v57
	v_cvt_pk_bf16_f32 v54, v106, v107
	v_cvt_pk_bf16_f32 v55, v104, v105
	global_store_dwordx4 v[58:59], v[52:55], off offset:256
	s_and_saveexec_b64 s[28:29], s[4:5]
	s_cbranch_execz .LBB0_1322
	v_lshlrev_b64 v[52:53], 8, v[102:103]
	v_lshl_add_u64 v[52:53], s[10:11], 0, v[52:53]
	v_lshl_add_u64 v[52:53], s[8:9], 2, v[52:53]
	s_lshl_b32 s12, s39, 2
	v_lshl_add_u64 v[52:53], v[52:53], 0, s[12:13]
	s_waitcnt lgkmcnt(0)
	v_add_f32_e32 v50, v50, v51
	global_store_dword v[52:53], v50, off
; __device__ __forceinline__ unsigned cvt_pk_bf16(float lo, float hi) { unsigned r; asm volatile("v_cvt_pk_bf16_f32 %0, %1, %2" : "=v"(r) : "v"(lo), "v"(hi)); return r; }
; __device__ __forceinline__ float bflo(unsigned w) { return __uint_as_float(w << 16); }
; __device__ __forceinline__ float bfhi(unsigned w) { return __uint_as_float(w & 0xffff0000u); }
;     __device__ __forceinline__ void operator()(const f32x4 (&acc)[2][2][4][2], const Unit& u, int wr, int wc, int fr, int fq) const {
;     ...
;             for (int m = 0; m < 4; ++m) { const int row = row0 + ai * HALF + m * 16; const size_t off = (size_t)row * DM + col0; float ss = 0.f;
; #pragma unroll
;                 for (int bj = 0; bj < 2; ++bj) { const u32x4 w = bw[m][bj];
;                     const f32x4 b0 = {bflo(w.x), bfhi(w.x), bflo(w.y), bfhi(w.y)}, b1 = {bflo(w.z), bfhi(w.z), bflo(w.w), bfhi(w.w)};
;                     const f32x4 o0 = b0 + acc[ai][bj][m][0], o1 = b1 + acc[ai][bj][m][1];
;                     ss += ((o0[0] * o0[0] + o0[1] * o0[1]) + (o0[2] * o0[2] + o0[3] * o0[3])) + ((o1[0] * o1[0] + o1[1] * o1[1]) + (o1[2] * o1[2] + o1[3] * o1[3]));
;                     u32x4 w2; w2.x = cvt_pk_bf16(o0[0], o0[1]); w2.y = cvt_pk_bf16(o0[2], o0[3]); w2.z = cvt_pk_bf16(o1[0], o1[1]); w2.w = cvt_pk_bf16(o1[2], o1[3]);
;                     *(u32x4*)(hout + off + bj * HALF) = w2; }
;                 ss += __shfl_xor(ss, 16); ss += __shfl_xor(ss, 32);
;                 if (fq == 0) part[(size_t)row * 64 + u.pn * 4 + wc] = ss; }
.LBB0_1322:
	s_or_b64 exec, exec, s[28:29]
	v_lshlrev_b32_e32 v50, 16, v86
	s_waitcnt lgkmcnt(0)
	v_and_b32_e32 v51, 0xffff0000, v86
	v_lshlrev_b32_e32 v52, 16, v87
	v_and_b32_e32 v53, 0xffff0000, v87
	v_lshlrev_b32_e32 v54, 16, v88
	v_and_b32_e32 v55, 0xffff0000, v88
	v_lshlrev_b32_e32 v56, 16, v89
	v_and_b32_e32 v57, 0xffff0000, v89
	v_pk_add_f32 v[48:49], v[48:49], v[52:53]
	v_pk_add_f32 v[46:47], v[46:47], v[50:51]
	v_pk_add_f32 v[50:51], v[44:45], v[56:57]
	v_pk_add_f32 v[44:45], v[42:43], v[54:55]
	v_mul_f32_e32 v42, v47, v47
	v_mul_f32_e32 v43, v49, v49
	v_fmac_f32_e32 v42, v46, v46
	v_fmac_f32_e32 v43, v48, v48
	v_add_f32_e32 v42, v42, v43
	v_mul_f32_e32 v43, v45, v45
	v_mul_f32_e32 v52, v51, v51
	v_fmac_f32_e32 v43, v44, v44
	v_fmac_f32_e32 v52, v50, v50
	v_add_f32_e32 v43, v43, v52
	v_add_f32_e32 v54, v42, v43
	v_cvt_pk_bf16_f32 v42, v46, v47
	v_cvt_pk_bf16_f32 v43, v48, v49
	v_lshlrev_b32_e32 v46, 16, v82
	v_and_b32_e32 v47, 0xffff0000, v82
	v_lshlrev_b32_e32 v48, 16, v83
	v_and_b32_e32 v49, 0xffff0000, v83
	v_cvt_pk_bf16_f32 v44, v44, v45
	v_cvt_pk_bf16_f32 v45, v50, v51
	v_lshlrev_b32_e32 v50, 16, v84
	v_and_b32_e32 v51, 0xffff0000, v84
	v_pk_add_f32 v[40:41], v[40:41], v[48:49]
	v_pk_add_f32 v[38:39], v[38:39], v[46:47]
	v_lshlrev_b32_e32 v52, 16, v85
	v_and_b32_e32 v53, 0xffff0000, v85
	v_pk_add_f32 v[48:49], v[34:35], v[50:51]
	v_mul_f32_e32 v34, v39, v39
	v_mul_f32_e32 v35, v41, v41
	v_pk_add_f32 v[46:47], v[36:37], v[52:53]
	v_fmac_f32_e32 v34, v38, v38
	v_fmac_f32_e32 v35, v40, v40
	v_add_f32_e32 v34, v34, v35
	v_mul_f32_e32 v35, v49, v49
	v_mul_f32_e32 v36, v47, v47
	v_fmac_f32_e32 v35, v48, v48
	v_fmac_f32_e32 v36, v46, v46
	v_add_f32_e32 v35, v35, v36
	v_add_f32_e32 v34, v34, v35
	v_add_f32_e32 v37, v54, v34
	v_lshl_add_u64 v[34:35], s[74:75], 0, v[100:101]
	v_lshl_add_u64 v[50:51], v[170:171], 1, v[34:35]
	global_store_dwordx4 v[50:51], v[42:45], off
	v_cvt_pk_bf16_f32 v36, v38, v39
	s_waitcnt lgkmcnt(0)
	v_mov_b32_e32 v34, v37
	v_mov_b32_e32 v52, v37
	s_nop 1
	v_permlane16_swap_b32_e32 v34, v52
	s_nop 0
	v_add_f32_e32 v34, v34, v52
	ds_bpermute_b32 v35, v114, v34
	v_cvt_pk_bf16_f32 v37, v40, v41
	v_cvt_pk_bf16_f32 v38, v48, v49
	v_cvt_pk_bf16_f32 v39, v46, v47
	global_store_dwordx4 v[50:51], v[36:39], off offset:256
	s_and_saveexec_b64 s[28:29], s[4:5]
	s_cbranch_execz .LBB0_1324
	v_lshlrev_b64 v[36:37], 8, v[98:99]
	v_lshl_add_u64 v[36:37], s[10:11], 0, v[36:37]
	v_lshl_add_u64 v[36:37], s[8:9], 2, v[36:37]
	s_lshl_b32 s12, s39, 2
	v_lshl_add_u64 v[36:37], v[36:37], 0, s[12:13]
	s_waitcnt lgkmcnt(0)
	v_add_f32_e32 v34, v34, v35
	global_store_dword v[36:37], v34, off
; __device__ __forceinline__ unsigned cvt_pk_bf16(float lo, float hi) { unsigned r; asm volatile("v_cvt_pk_bf16_f32 %0, %1, %2" : "=v"(r) : "v"(lo), "v"(hi)); return r; }
; __device__ __forceinline__ float bflo(unsigned w) { return __uint_as_float(w << 16); }
; __device__ __forceinline__ float bfhi(unsigned w) { return __uint_as_float(w & 0xffff0000u); }
;     __device__ __forceinline__ void operator()(const f32x4 (&acc)[2][2][4][2], const Unit& u, int wr, int wc, int fr, int fq) const {
;     ...
;             for (int m = 0; m < 4; ++m) { const int row = row0 + ai * HALF + m * 16; const size_t off = (size_t)row * DM + col0; float ss = 0.f;
; #pragma unroll
;                 for (int bj = 0; bj < 2; ++bj) { const u32x4 w = bw[m][bj];
;                     const f32x4 b0 = {bflo(w.x), bfhi(w.x), bflo(w.y), bfhi(w.y)}, b1 = {bflo(w.z), bfhi(w.z), bflo(w.w), bfhi(w.w)};
;                     const f32x4 o0 = b0 + acc[ai][bj][m][0], o1 = b1 + acc[ai][bj][m][1];
;                     ss += ((o0[0] * o0[0] + o0[1] * o0[1]) + (o0[2] * o0[2] + o0[3] * o0[3])) + ((o1[0] * o1[0] + o1[1] * o1[1]) + (o1[2] * o1[2] + o1[3] * o1[3]));
;                     u32x4 w2; w2.x = cvt_pk_bf16(o0[0], o0[1]); w2.y = cvt_pk_bf16(o0[2], o0[3]); w2.z = cvt_pk_bf16(o1[0], o1[1]); w2.w = cvt_pk_bf16(o1[2], o1[3]);
;                     *(u32x4*)(hout + off + bj * HALF) = w2; }
;                 ss += __shfl_xor(ss, 16); ss += __shfl_xor(ss, 32);
;                 if (fq == 0) part[(size_t)row * 64 + u.pn * 4 + wc] = ss; }
.LBB0_1324:
	s_or_b64 exec, exec, s[28:29]
	v_lshlrev_b32_e32 v34, 16, v78
	s_waitcnt lgkmcnt(0)
	v_and_b32_e32 v35, 0xffff0000, v78
	v_lshlrev_b32_e32 v36, 16, v79
	v_and_b32_e32 v37, 0xffff0000, v79
	v_lshlrev_b32_e32 v38, 16, v80
	v_and_b32_e32 v39, 0xffff0000, v80
	v_lshlrev_b32_e32 v40, 16, v81
	v_and_b32_e32 v41, 0xffff0000, v81
	v_pk_add_f32 v[32:33], v[32:33], v[36:37]
	v_pk_add_f32 v[30:31], v[30:31], v[34:35]
	v_pk_add_f32 v[34:35], v[28:29], v[40:41]
	v_pk_add_f32 v[28:29], v[26:27], v[38:39]
	v_mul_f32_e32 v26, v31, v31
	v_mul_f32_e32 v27, v33, v33
	v_fmac_f32_e32 v26, v30, v30
	v_fmac_f32_e32 v27, v32, v32
	v_add_f32_e32 v26, v26, v27
	v_mul_f32_e32 v27, v29, v29
	v_mul_f32_e32 v36, v35, v35
	v_fmac_f32_e32 v27, v28, v28
	v_fmac_f32_e32 v36, v34, v34
	v_add_f32_e32 v27, v27, v36
	v_add_f32_e32 v38, v26, v27
	v_cvt_pk_bf16_f32 v26, v30, v31
	v_cvt_pk_bf16_f32 v27, v32, v33
	v_lshlrev_b32_e32 v30, 16, v74
	v_and_b32_e32 v31, 0xffff0000, v74
	v_lshlrev_b32_e32 v32, 16, v75
	v_and_b32_e32 v33, 0xffff0000, v75
	v_cvt_pk_bf16_f32 v28, v28, v29
	v_cvt_pk_bf16_f32 v29, v34, v35
	v_lshlrev_b32_e32 v34, 16, v76
	v_and_b32_e32 v35, 0xffff0000, v76
	v_pk_add_f32 v[24:25], v[24:25], v[32:33]
	v_pk_add_f32 v[22:23], v[22:23], v[30:31]
	v_lshlrev_b32_e32 v36, 16, v77
	v_and_b32_e32 v37, 0xffff0000, v77
	v_pk_add_f32 v[32:33], v[18:19], v[34:35]
	v_mul_f32_e32 v18, v23, v23
	v_mul_f32_e32 v19, v25, v25
	v_pk_add_f32 v[30:31], v[20:21], v[36:37]
	v_fmac_f32_e32 v18, v22, v22
	v_fmac_f32_e32 v19, v24, v24
	v_add_f32_e32 v18, v18, v19
	v_mul_f32_e32 v19, v33, v33
	v_mul_f32_e32 v20, v31, v31
	v_fmac_f32_e32 v19, v32, v32
	v_fmac_f32_e32 v20, v30, v30
	v_add_f32_e32 v19, v19, v20
	v_add_f32_e32 v18, v18, v19
	v_add_f32_e32 v21, v38, v18
	v_lshl_add_u64 v[18:19], s[74:75], 0, v[96:97]
	v_lshl_add_u64 v[34:35], v[170:171], 1, v[18:19]
	global_store_dwordx4 v[34:35], v[26:29], off
	v_cvt_pk_bf16_f32 v20, v22, v23
	s_waitcnt lgkmcnt(0)
	v_mov_b32_e32 v18, v21
	v_mov_b32_e32 v36, v21
	s_nop 1
	v_permlane16_swap_b32_e32 v18, v36
	s_nop 0
	v_add_f32_e32 v18, v18, v36
	ds_bpermute_b32 v19, v114, v18
	v_cvt_pk_bf16_f32 v21, v24, v25
	v_cvt_pk_bf16_f32 v22, v32, v33
	v_cvt_pk_bf16_f32 v23, v30, v31
	global_store_dwordx4 v[34:35], v[20:23], off offset:256
	s_and_saveexec_b64 s[28:29], s[4:5]
	s_cbranch_execz .LBB0_1326
	v_lshlrev_b64 v[20:21], 8, v[94:95]
	v_lshl_add_u64 v[20:21], s[10:11], 0, v[20:21]
	v_lshl_add_u64 v[20:21], s[8:9], 2, v[20:21]
	s_lshl_b32 s12, s39, 2
	v_lshl_add_u64 v[20:21], v[20:21], 0, s[12:13]
	s_waitcnt lgkmcnt(0)
	v_add_f32_e32 v18, v18, v19
	global_store_dword v[20:21], v18, off
.LBB0_1326:
	s_or_b64 exec, exec, s[28:29]
	v_lshlrev_b32_e32 v18, 16, v70
	s_waitcnt lgkmcnt(0)
	v_and_b32_e32 v19, 0xffff0000, v70
	v_lshlrev_b32_e32 v20, 16, v71
	v_and_b32_e32 v21, 0xffff0000, v71
	v_lshlrev_b32_e32 v22, 16, v72
	v_and_b32_e32 v23, 0xffff0000, v72
	v_lshlrev_b32_e32 v24, 16, v73
	v_and_b32_e32 v25, 0xffff0000, v73
	v_pk_add_f32 v[16:17], v[16:17], v[20:21]
	v_pk_add_f32 v[14:15], v[14:15], v[18:19]
	v_pk_add_f32 v[18:19], v[12:13], v[24:25]
	v_pk_add_f32 v[12:13], v[10:11], v[22:23]
	v_mul_f32_e32 v10, v15, v15
	v_mul_f32_e32 v11, v17, v17
	v_fmac_f32_e32 v10, v14, v14
	v_fmac_f32_e32 v11, v16, v16
	v_add_f32_e32 v10, v10, v11
	v_mul_f32_e32 v11, v13, v13
	v_mul_f32_e32 v20, v19, v19
	v_fmac_f32_e32 v11, v12, v12
	v_fmac_f32_e32 v20, v18, v18
	v_add_f32_e32 v11, v11, v20
	v_add_f32_e32 v22, v10, v11
	v_cvt_pk_bf16_f32 v10, v14, v15
	v_cvt_pk_bf16_f32 v11, v16, v17
	v_lshlrev_b32_e32 v14, 16, v66
	v_and_b32_e32 v15, 0xffff0000, v66
	v_lshlrev_b32_e32 v16, 16, v67
	v_and_b32_e32 v17, 0xffff0000, v67
	v_cvt_pk_bf16_f32 v12, v12, v13
	v_cvt_pk_bf16_f32 v13, v18, v19
	v_lshlrev_b32_e32 v18, 16, v68
	v_and_b32_e32 v19, 0xffff0000, v68
	v_pk_add_f32 v[8:9], v[8:9], v[16:17]
	v_pk_add_f32 v[6:7], v[6:7], v[14:15]
	v_lshlrev_b32_e32 v20, 16, v69
	v_and_b32_e32 v21, 0xffff0000, v69
	v_pk_add_f32 v[16:17], v[2:3], v[18:19]
	v_mul_f32_e32 v2, v7, v7
	v_mul_f32_e32 v3, v9, v9
	v_pk_add_f32 v[14:15], v[4:5], v[20:21]
	v_fmac_f32_e32 v2, v6, v6
	v_fmac_f32_e32 v3, v8, v8
	v_add_f32_e32 v2, v2, v3
	v_mul_f32_e32 v3, v17, v17
	v_mul_f32_e32 v4, v15, v15
	v_fmac_f32_e32 v3, v16, v16
	v_fmac_f32_e32 v4, v14, v14
	v_add_f32_e32 v3, v3, v4
	v_add_f32_e32 v2, v2, v3
	v_add_f32_e32 v5, v22, v2
	v_lshl_add_u64 v[2:3], s[74:75], 0, v[92:93]
	v_lshl_add_u64 v[18:19], v[170:171], 1, v[2:3]
	global_store_dwordx4 v[18:19], v[10:13], off
	v_cvt_pk_bf16_f32 v4, v6, v7
	s_waitcnt lgkmcnt(0)
	v_mov_b32_e32 v2, v5
	v_mov_b32_e32 v20, v5
	s_nop 1
	v_permlane16_swap_b32_e32 v2, v20
	s_nop 0
	v_add_f32_e32 v2, v2, v20
	ds_bpermute_b32 v3, v114, v2
	v_cvt_pk_bf16_f32 v5, v8, v9
	v_cvt_pk_bf16_f32 v6, v16, v17
	v_cvt_pk_bf16_f32 v7, v14, v15
	global_store_dwordx4 v[18:19], v[4:7], off offset:256
	s_and_saveexec_b64 s[28:29], s[4:5]
	s_cbranch_execz .LBB0_1328
	v_lshlrev_b64 v[4:5], 8, v[90:91]
	v_lshl_add_u64 v[4:5], s[10:11], 0, v[4:5]
	v_lshl_add_u64 v[4:5], s[8:9], 2, v[4:5]
	s_lshl_b32 s12, s39, 2
	v_lshl_add_u64 v[4:5], v[4:5], 0, s[12:13]
	s_waitcnt lgkmcnt(0)
	v_add_f32_e32 v2, v2, v3
	global_store_dword v[4:5], v2, off

; __device__ __forceinline__ float bflo(unsigned w) { return __uint_as_float(w << 16); }
; __device__ __forceinline__ float bfhi(unsigned w) { return __uint_as_float(w & 0xffff0000u); }
; #pragma unroll
;     for (int j = 0; j < 8; ++j) mx = fmaxf(mx, fmaxf(fmaxf(fmaxf(fabsf(bflo(w[j].x)), fabsf(bfhi(w[j].x))), fmaxf(fabsf(bflo(w[j].y)), fabsf(bfhi(w[j].y)))), fmaxf(fmaxf(fabsf(bflo(w[j].z)), fabsf(bfhi(w[j].z))), fmaxf(fabsf(bflo(w[j].w)), fabsf(bfhi(w[j].w))))));
; #pragma unroll
;     for (int o = 1; o < 64; o <<= 1) mx = fmaxf(mx, __shfl_xor(mx, o));
;     return mx; }
; __device__ __forceinline__ void quant_rows2(const bf16_t* s0, const bf16_t* s1, signed char* d0, signed char* d1, int lane, float& step0, float& step1) {
;     const u32x4* p0 = (const u32x4*)s0 + lane; const u32x4* p1 = (const u32x4*)s1 + lane; u32x4 w0[8], w1[8];
; #pragma unroll
;     for (int j = 0; j < 8; ++j) { w0[j] = p0[64 * j]; w1[j] = p1[64 * j]; }
;     step0 = fmaxf(absmax8(w0), 1e-30f) * (1.0f / 127.0f); step1 = fmaxf(absmax8(w1), 1e-30f) * (1.0f / 127.0f);
.LBB0_1392:
	s_ashr_i32 s23, s22, 31
	s_lshl_b64 s[6:7], s[22:23], 13
	s_waitcnt lgkmcnt(0)
	v_lshl_add_u64 v[2:3], v[18:19], 0, s[6:7]
	global_load_dwordx4 v[30:33], v[2:3], off offset:1024
	global_load_dwordx4 v[42:45], v[2:3], off offset:2048
	global_load_dwordx4 v[46:49], v[2:3], off
	global_load_dwordx4 v[50:53], v[2:3], off offset:3072
	s_add_i32 s24, s22, s68
	s_ashr_i32 s25, s24, 31
	s_lshl_b64 s[6:7], s[24:25], 13
	v_lshl_add_u64 v[62:63], v[18:19], 0, s[6:7]
	v_add_co_u32_e32 v70, vcc, s3, v2
	global_load_dwordx4 v[54:57], v[62:63], off
	s_nop 0
	v_addc_co_u32_e32 v71, vcc, 0, v3, vcc
	global_load_dwordx4 v[10:13], v[62:63], off offset:1024
	global_load_dwordx4 v[6:9], v[62:63], off offset:2048
	global_load_dwordx4 v[2:5], v[62:63], off offset:3072
	global_load_dwordx4 v[58:61], v[70:71], off
	v_add_co_u32_e32 v74, vcc, s3, v62
	s_lshl_b64 s[6:7], s[22:23], 8
	s_nop 0
	v_addc_co_u32_e32 v75, vcc, 0, v63, vcc
	global_load_dwordx4 v[62:65], v[70:71], off offset:1024
	global_load_dwordx4 v[66:69], v[70:71], off offset:2048
	s_nop 0
	global_load_dwordx4 v[70:73], v[70:71], off offset:3072
	s_lshl_b64 s[26:27], s[22:23], 12
	s_waitcnt vmcnt(11)
	v_lshlrev_b32_e32 v104, 16, v30
	v_and_b32_e32 v105, 0xffff0000, v30
	v_lshlrev_b32_e32 v106, 16, v31
	v_and_b32_e32 v107, 0xffff0000, v31
	v_lshlrev_b32_e32 v110, 16, v33
	v_and_b32_e32 v111, 0xffff0000, v33
	s_waitcnt vmcnt(10)
	v_lshlrev_b32_e32 v112, 16, v42
	v_and_b32_e32 v113, 0xffff0000, v42
	v_lshlrev_b32_e32 v118, 16, v45
	v_and_b32_e32 v119, 0xffff0000, v45
	s_waitcnt vmcnt(9)
	v_lshlrev_b32_e32 v126, 16, v49
	v_and_b32_e32 v127, 0xffff0000, v49
	v_lshlrev_b32_e32 v108, 16, v32
	v_and_b32_e32 v109, 0xffff0000, v32
	v_lshlrev_b32_e32 v114, 16, v43
	v_and_b32_e32 v115, 0xffff0000, v43
	v_lshlrev_b32_e32 v116, 16, v44
	v_and_b32_e32 v117, 0xffff0000, v44
	v_lshlrev_b32_e32 v120, 16, v46
	v_and_b32_e32 v121, 0xffff0000, v46
	v_lshlrev_b32_e32 v122, 16, v47
	v_and_b32_e32 v123, 0xffff0000, v47
	v_lshlrev_b32_e32 v124, 16, v48
	v_and_b32_e32 v125, 0xffff0000, v48
	v_max_f32_e64 v29, |v105|, |v105|
	v_max_f32_e64 v30, |v104|, |v104|
	v_max_f32_e64 v31, |v107|, |v107|
	v_max_f32_e64 v32, |v106|, |v106|
	v_max_f32_e64 v33, |v111|, |v111|
	v_max_f32_e64 v42, |v110|, |v110|
	v_max_f32_e64 v43, |v113|, |v113|
	v_max_f32_e64 v44, |v112|, |v112|
	v_max_f32_e64 v47, |v119|, |v119|
	v_max_f32_e64 v48, |v118|, |v118|
	s_waitcnt vmcnt(8)
	v_lshlrev_b32_e32 v128, 16, v50
	v_and_b32_e32 v129, 0xffff0000, v50
	v_max_f32_e64 v78, |v127|, |v127|
	v_max_f32_e64 v79, |v126|, |v126|
	v_max_f32_e64 v45, |v115|, |v115|
	v_max_f32_e64 v46, |v114|, |v114|
	v_max_f32_e64 v49, |v121|, |v121|
	v_max_f32_e64 v50, |v120|, |v120|
	v_max_f32_e64 v76, |v123|, |v123|
	v_max_f32_e64 v77, |v122|, |v122|
	v_max_f32_e32 v29, v30, v29
	v_max_f32_e32 v30, v32, v31
	v_max_f32_e32 v31, v42, v33
	v_max_f32_e32 v32, v44, v43
	v_max_f32_e32 v42, v48, v47
	v_max_f32_e64 v43, |v129|, |v129|
	v_max_f32_e64 v44, |v128|, |v128|
	v_max_f32_e32 v47, v79, v78
	v_max_f32_e32 v33, v46, v45
	v_max_f32_e32 v45, v50, v49
	v_max_f32_e32 v46, v77, v76
	v_max3_f32 v31, |v108|, |v109|, v31
	v_max_f32_e32 v43, v44, v43
	v_max3_f32 v44, |v124|, |v125|, v47
	v_max3_f32 v42, |v116|, |v117|, v42
	v_max3_f32 v29, v29, v30, v31
	v_max3_f32 v31, v45, v46, v44
	v_lshlrev_b32_e32 v130, 16, v51
	v_and_b32_e32 v131, 0xffff0000, v51
	v_max3_f32 v30, v32, v33, v42
	v_max3_f32 v29, v31, 0, v29
	v_max_f32_e64 v31, |v131|, |v131|
	v_max_f32_e64 v32, |v130|, |v130|
	v_lshlrev_b32_e32 v134, 16, v53
	v_and_b32_e32 v135, 0xffff0000, v53
	v_max_f32_e32 v31, v32, v31
	v_max_f32_e64 v32, |v135|, |v135|
	v_max_f32_e64 v33, |v134|, |v134|
	v_lshlrev_b32_e32 v132, 16, v52
	v_and_b32_e32 v133, 0xffff0000, v52
	v_max_f32_e32 v32, v33, v32
	v_max3_f32 v32, |v132|, |v133|, v32
	v_max3_f32 v31, v43, v31, v32
	s_waitcnt vmcnt(3)
	v_lshlrev_b32_e32 v136, 16, v58
	v_and_b32_e32 v137, 0xffff0000, v58
	v_max3_f32 v29, v29, v30, v31
	v_max_f32_e64 v30, |v137|, |v137|
	v_max_f32_e64 v31, |v136|, |v136|
	v_lshlrev_b32_e32 v138, 16, v59
	v_and_b32_e32 v139, 0xffff0000, v59
	v_max_f32_e32 v30, v31, v30
	v_max_f32_e64 v31, |v139|, |v139|
	v_max_f32_e64 v32, |v138|, |v138|
	v_lshlrev_b32_e32 v142, 16, v61
	v_and_b32_e32 v143, 0xffff0000, v61
	v_max_f32_e32 v31, v32, v31
	v_max_f32_e64 v32, |v143|, |v143|
	v_max_f32_e64 v33, |v142|, |v142|
	v_lshlrev_b32_e32 v140, 16, v60
	v_and_b32_e32 v141, 0xffff0000, v60
	v_max_f32_e32 v32, v33, v32
	v_max3_f32 v32, |v140|, |v141|, v32
	s_waitcnt vmcnt(2)
	v_lshlrev_b32_e32 v144, 16, v62
	v_and_b32_e32 v145, 0xffff0000, v62
	v_max3_f32 v30, v30, v31, v32
	v_max_f32_e64 v31, |v145|, |v145|
	v_max_f32_e64 v32, |v144|, |v144|
	v_lshlrev_b32_e32 v146, 16, v63
	v_and_b32_e32 v147, 0xffff0000, v63
	v_max_f32_e32 v31, v32, v31
	v_max_f32_e64 v32, |v147|, |v147|
	v_max_f32_e64 v33, |v146|, |v146|
	v_lshlrev_b32_e32 v150, 16, v65
	v_and_b32_e32 v151, 0xffff0000, v65
	v_max_f32_e32 v32, v33, v32
	v_max_f32_e64 v33, |v151|, |v151|
	v_max_f32_e64 v42, |v150|, |v150|
	v_lshlrev_b32_e32 v148, 16, v64
	v_and_b32_e32 v149, 0xffff0000, v64
	v_max_f32_e32 v33, v42, v33
	v_max3_f32 v33, |v148|, |v149|, v33
	v_max3_f32 v31, v31, v32, v33
	s_waitcnt vmcnt(1)
	v_lshlrev_b32_e32 v152, 16, v66
	v_and_b32_e32 v153, 0xffff0000, v66
	v_max3_f32 v29, v29, v30, v31
	v_max_f32_e64 v30, |v153|, |v153|
	v_max_f32_e64 v31, |v152|, |v152|
	v_lshlrev_b32_e32 v154, 16, v67
	v_and_b32_e32 v155, 0xffff0000, v67
	v_max_f32_e32 v30, v31, v30
	v_max_f32_e64 v31, |v155|, |v155|
	v_max_f32_e64 v32, |v154|, |v154|
	v_lshlrev_b32_e32 v158, 16, v69
	v_and_b32_e32 v159, 0xffff0000, v69
	v_max_f32_e32 v31, v32, v31
	v_max_f32_e64 v32, |v159|, |v159|
	v_max_f32_e64 v33, |v158|, |v158|
	v_lshlrev_b32_e32 v156, 16, v68
	v_and_b32_e32 v157, 0xffff0000, v68
	v_max_f32_e32 v32, v33, v32
	v_max3_f32 v32, |v156|, |v157|, v32
	s_waitcnt vmcnt(0)
; __device__ __forceinline__ float bflo(unsigned w) { return __uint_as_float(w << 16); }
; __device__ __forceinline__ float bfhi(unsigned w) { return __uint_as_float(w & 0xffff0000u); }
; #pragma unroll
;     for (int j = 0; j < 8; ++j) mx = fmaxf(mx, fmaxf(fmaxf(fmaxf(fabsf(bflo(w[j].x)), fabsf(bfhi(w[j].x))), fmaxf(fabsf(bflo(w[j].y)), fabsf(bfhi(w[j].y)))), fmaxf(fmaxf(fabsf(bflo(w[j].z)), fabsf(bfhi(w[j].z))), fmaxf(fabsf(bflo(w[j].w)), fabsf(bfhi(w[j].w))))));
; #pragma unroll
;     for (int o = 1; o < 64; o <<= 1) mx = fmaxf(mx, __shfl_xor(mx, o));
;     return mx; }
	v_lshlrev_b32_e32 v160, 16, v70
	v_and_b32_e32 v161, 0xffff0000, v70
	v_max3_f32 v30, v30, v31, v32
	v_max_f32_e64 v31, |v161|, |v161|
	v_max_f32_e64 v32, |v160|, |v160|
	v_lshlrev_b32_e32 v162, 16, v71
	v_and_b32_e32 v163, 0xffff0000, v71
	v_max_f32_e32 v31, v32, v31
	v_max_f32_e64 v32, |v163|, |v163|
	v_max_f32_e64 v33, |v162|, |v162|
	v_lshlrev_b32_e32 v166, 16, v73
	v_and_b32_e32 v93, 0xffff0000, v73
	v_max_f32_e32 v32, v33, v32
	v_max_f32_e64 v33, |v93|, |v93|
	v_max_f32_e64 v42, |v166|, |v166|
	v_lshlrev_b32_e32 v164, 16, v72
	v_and_b32_e32 v165, 0xffff0000, v72
	v_max_f32_e32 v33, v42, v33
	v_max3_f32 v33, |v164|, |v165|, v33
	v_max3_f32 v31, v31, v32, v33
	v_max3_f32 v29, v29, v30, v31
	global_load_dwordx4 v[30:33], v[74:75], off
	global_load_dwordx4 v[42:45], v[74:75], off offset:1024
	global_load_dwordx4 v[96:99], v[74:75], off offset:2048
	global_load_dwordx4 v[100:103], v[74:75], off offset:3072
	s_nop 1
	v_mov_b32_dpp v46, v29 quad_perm:[1,0,3,2] row_mask:0xf bank_mask:0xf
	v_lshlrev_b32_e32 v95, 16, v54
	v_and_b32_e32 v92, 0xffff0000, v54
	v_lshlrev_b32_e32 v94, 16, v55
	v_and_b32_e32 v91, 0xffff0000, v55
	s_waitcnt lgkmcnt(0)
	v_max_f32_e32 v46, v46, v46
	v_max_f32_e32 v167, v29, v46
	v_max_f32_e64 v29, |v92|, |v92|
	v_max_f32_e64 v46, |v95|, |v95|
	v_max_f32_e32 v29, v46, v29
	v_max_f32_e64 v46, |v91|, |v91|
	v_max_f32_e64 v47, |v94|, |v94|
	v_lshlrev_b32_e32 v88, 16, v57
	v_and_b32_e32 v87, 0xffff0000, v57
	v_max_f32_e32 v46, v47, v46
	v_max_f32_e64 v47, |v87|, |v87|
	v_max_f32_e64 v48, |v88|, |v88|
	v_lshlrev_b32_e32 v90, 16, v56
	v_and_b32_e32 v89, 0xffff0000, v56
	v_max_f32_e32 v47, v48, v47
	v_max3_f32 v47, |v90|, |v89|, v47
	v_lshlrev_b32_e32 v86, 16, v10
	v_and_b32_e32 v84, 0xffff0000, v10
	v_lshlrev_b32_e32 v80, 16, v13
	v_and_b32_e32 v79, 0xffff0000, v13
	v_max3_f32 v29, v29, v46, v47
	v_max_f32_e64 v10, |v84|, |v84|
	v_max_f32_e64 v46, |v86|, |v86|
	v_lshlrev_b32_e32 v85, 16, v11
	v_and_b32_e32 v83, 0xffff0000, v11
	v_lshlrev_b32_e32 v82, 16, v12
	v_and_b32_e32 v81, 0xffff0000, v12
	v_max_f32_e64 v12, |v79|, |v79|
	v_max_f32_e64 v13, |v80|, |v80|
	v_max_f32_e32 v10, v46, v10
	v_max_f32_e64 v11, |v83|, |v83|
	v_max_f32_e64 v46, |v85|, |v85|
	v_max_f32_e32 v12, v13, v12
	v_max_f32_e32 v11, v46, v11
	v_max3_f32 v12, |v82|, |v81|, v12
	v_lshlrev_b32_e32 v78, 16, v6
	v_and_b32_e32 v76, 0xffff0000, v6
	v_lshlrev_b32_e32 v72, 16, v9
	v_and_b32_e32 v71, 0xffff0000, v9
	v_max3_f32 v10, v10, v11, v12
	v_max_f32_e64 v6, |v76|, |v76|
	v_max_f32_e64 v11, |v78|, |v78|
	v_lshlrev_b32_e32 v77, 16, v7
	v_and_b32_e32 v75, 0xffff0000, v7
	v_lshlrev_b32_e32 v74, 16, v8
	v_and_b32_e32 v73, 0xffff0000, v8
	v_max_f32_e64 v8, |v71|, |v71|
	v_max_f32_e64 v9, |v72|, |v72|
	v_max_f32_e32 v6, v11, v6
	v_max_f32_e64 v7, |v75|, |v75|
	v_max_f32_e64 v11, |v77|, |v77|
	v_max_f32_e32 v8, v9, v8
	v_max_f32_e32 v7, v11, v7
	v_max3_f32 v8, |v74|, |v73|, v8
	v_lshlrev_b32_e32 v70, 16, v2
	v_and_b32_e32 v68, 0xffff0000, v2
	v_lshlrev_b32_e32 v64, 16, v5
	v_and_b32_e32 v63, 0xffff0000, v5
	v_max3_f32 v6, v6, v7, v8
	v_max_f32_e64 v2, |v68|, |v68|
	v_max_f32_e64 v7, |v70|, |v70|
	v_lshlrev_b32_e32 v69, 16, v3
	v_and_b32_e32 v67, 0xffff0000, v3
	v_lshlrev_b32_e32 v66, 16, v4
	v_and_b32_e32 v65, 0xffff0000, v4
	v_max_f32_e64 v4, |v63|, |v63|
	v_max_f32_e64 v5, |v64|, |v64|
	v_max_f32_e32 v2, v7, v2
	v_max_f32_e64 v3, |v67|, |v67|
	v_max_f32_e64 v7, |v69|, |v69|
	v_max_f32_e32 v4, v5, v4
	v_max_f32_e32 v3, v7, v3
	v_max3_f32 v4, |v66|, |v65|, v4
	s_waitcnt vmcnt(3)
	v_lshlrev_b32_e32 v62, 16, v30
	v_and_b32_e32 v60, 0xffff0000, v30
	v_max3_f32 v2, v2, v3, v4
	v_max_f32_e64 v3, |v60|, |v60|
	v_max_f32_e64 v4, |v62|, |v62|
	v_lshlrev_b32_e32 v61, 16, v31
	v_and_b32_e32 v59, 0xffff0000, v31
	v_max3_f32 v10, v29, 0, v10
	v_max_f32_e32 v3, v4, v3
	v_max_f32_e64 v4, |v59|, |v59|
	v_max_f32_e64 v5, |v61|, |v61|
	v_lshlrev_b32_e32 v56, 16, v33
	v_and_b32_e32 v55, 0xffff0000, v33
	v_max3_f32 v2, v10, v6, v2
	v_max_f32_e32 v4, v5, v4
	v_max_f32_e64 v5, |v55|, |v55|
	v_max_f32_e64 v6, |v56|, |v56|
	v_lshlrev_b32_e32 v58, 16, v32
	v_and_b32_e32 v57, 0xffff0000, v32
	v_max_f32_e32 v5, v6, v5
	v_max3_f32 v5, |v58|, |v57|, v5
	s_waitcnt vmcnt(2)
	v_lshlrev_b32_e32 v54, 16, v42
	v_and_b32_e32 v52, 0xffff0000, v42
	v_max3_f32 v3, v3, v4, v5
	v_max_f32_e64 v4, |v52|, |v52|
	v_max_f32_e64 v5, |v54|, |v54|
	v_lshlrev_b32_e32 v53, 16, v43
	v_and_b32_e32 v51, 0xffff0000, v43
	v_max_f32_e32 v4, v5, v4
	v_max_f32_e64 v5, |v51|, |v51|
	v_max_f32_e64 v6, |v53|, |v53|
	v_lshlrev_b32_e32 v48, 16, v45
	v_and_b32_e32 v47, 0xffff0000, v45
	v_max_f32_e32 v5, v6, v5
	v_max_f32_e64 v6, |v47|, |v47|
	v_max_f32_e64 v7, |v48|, |v48|
	v_lshlrev_b32_e32 v50, 16, v44
	v_and_b32_e32 v49, 0xffff0000, v44
	v_max_f32_e32 v6, v7, v6
	v_max3_f32 v6, |v50|, |v49|, v6
	v_max3_f32 v4, v4, v5, v6
	s_waitcnt vmcnt(1)
	v_lshlrev_b32_e32 v46, 16, v96
	v_and_b32_e32 v44, 0xffff0000, v96
	v_max3_f32 v2, v2, v3, v4
	v_max_f32_e64 v3, |v44|, |v44|
	v_max_f32_e64 v4, |v46|, |v46|
	v_lshlrev_b32_e32 v45, 16, v97
	v_and_b32_e32 v43, 0xffff0000, v97
	v_max_f32_e32 v3, v4, v3
	v_max_f32_e64 v4, |v43|, |v43|
	v_max_f32_e64 v5, |v45|, |v45|
	v_lshlrev_b32_e32 v32, 16, v99
	v_and_b32_e32 v31, 0xffff0000, v99
	v_max_f32_e32 v4, v5, v4
	v_max_f32_e64 v5, |v31|, |v31|
	v_max_f32_e64 v6, |v32|, |v32|
	v_lshlrev_b32_e32 v42, 16, v98
	v_and_b32_e32 v33, 0xffff0000, v98
	v_max_f32_e32 v5, v6, v5
	v_max3_f32 v5, |v42|, |v33|, v5
	s_waitcnt vmcnt(0)
; __device__ __forceinline__ float bflo(unsigned w) { return __uint_as_float(w << 16); }
; __device__ __forceinline__ float bfhi(unsigned w) { return __uint_as_float(w & 0xffff0000u); }
; #pragma unroll
;     for (int j = 0; j < 8; ++j) mx = fmaxf(mx, fmaxf(fmaxf(fmaxf(fabsf(bflo(w[j].x)), fabsf(bfhi(w[j].x))), fmaxf(fabsf(bflo(w[j].y)), fabsf(bfhi(w[j].y)))), fmaxf(fmaxf(fabsf(bflo(w[j].z)), fabsf(bfhi(w[j].z))), fmaxf(fabsf(bflo(w[j].w)), fabsf(bfhi(w[j].w))))));
; #pragma unroll
;     for (int o = 1; o < 64; o <<= 1) mx = fmaxf(mx, __shfl_xor(mx, o));
;     return mx; }
; __device__ __forceinline__ void quant_store8(const u32x4 (&w)[8], float inv, signed char* dst, int lane) { u32x2* qp = (u32x2*)dst + lane;
; #pragma unroll
;     for (int j = 0; j < 8; ++j) { const unsigned ww[4] = {w[j].x, w[j].y, w[j].z, w[j].w}; unsigned o2[2];
; #pragma unroll
;         for (int h2 = 0; h2 < 2; ++h2) { const int q0 = (int)rintf(bflo(ww[2 * h2]) * inv), q1 = (int)rintf(bfhi(ww[2 * h2]) * inv), q2 = (int)rintf(bflo(ww[2 * h2 + 1]) * inv), q3 = (int)rintf(bfhi(ww[2 * h2 + 1]) * inv);
;             o2[h2] = (unsigned)(q0 & 255) | ((unsigned)(q1 & 255) << 8) | ((unsigned)(q2 & 255) << 16) | ((unsigned)(q3 & 255) << 24); }
;         u32x2 o; o.x = o2[0]; o.y = o2[1]; qp[64 * j] = o; } }
	v_lshlrev_b32_e32 v30, 16, v100
	v_and_b32_e32 v12, 0xffff0000, v100
	v_max3_f32 v3, v3, v4, v5
	v_max_f32_e64 v4, |v12|, |v12|
	v_max_f32_e64 v5, |v30|, |v30|
	v_lshlrev_b32_e32 v29, 16, v101
	v_and_b32_e32 v10, 0xffff0000, v101
	v_max_f32_e32 v4, v5, v4
	v_max_f32_e64 v5, |v10|, |v10|
	v_max_f32_e64 v6, |v29|, |v29|
	v_max_f32_e32 v5, v6, v5
	v_lshlrev_b32_e32 v7, 16, v103
	v_and_b32_e32 v6, 0xffff0000, v103
	v_max_f32_e64 v11, |v6|, |v6|
	v_max_f32_e64 v13, |v7|, |v7|
	v_lshlrev_b32_e32 v9, 16, v102
	v_and_b32_e32 v8, 0xffff0000, v102
	v_max_f32_e32 v11, v13, v11
	v_max3_f32 v11, |v9|, |v8|, v11
	v_max3_f32 v4, v4, v5, v11
	s_nop 1
	v_mov_b32_dpp v168, v167 quad_perm:[2,3,0,1] row_mask:0xf bank_mask:0xf
	v_max3_f32 v2, v2, v3, v4
	s_nop 1
	v_mov_b32_dpp v3, v2 quad_perm:[1,0,3,2] row_mask:0xf bank_mask:0xf
	s_waitcnt lgkmcnt(0)
	v_max_f32_e32 v4, v168, v168
	v_max_f32_e32 v4, v167, v4
	s_waitcnt lgkmcnt(0)
	v_max_f32_e32 v3, v3, v3
	s_nop 1
	v_mov_b32_dpp v5, v4 row_half_mirror row_mask:0xf bank_mask:0xf
	v_max_f32_e32 v11, v2, v3
	s_nop 1
	v_mov_b32_dpp v13, v11 quad_perm:[2,3,0,1] row_mask:0xf bank_mask:0xf
	v_lshl_add_u64 v[2:3], v[16:17], 0, s[6:7]
	s_lshl_b64 s[6:7], s[24:25], 8
	s_waitcnt lgkmcnt(0)
	v_max_f32_e32 v5, v5, v5
	v_max_f32_e32 v4, v4, v5
	s_waitcnt lgkmcnt(0)
	v_max_f32_e32 v13, v13, v13
	s_nop 1
	v_mov_b32_dpp v5, v4 row_mirror row_mask:0xf bank_mask:0xf
	v_max_f32_e32 v11, v11, v13
	s_nop 1
	v_mov_b32_dpp v13, v11 row_half_mirror row_mask:0xf bank_mask:0xf
	s_waitcnt lgkmcnt(0)
	v_max_f32_e32 v5, v5, v5
	v_max_f32_e32 v96, v4, v5
	s_waitcnt lgkmcnt(0)
	v_max_f32_e32 v4, v13, v13
	v_max_f32_e32 v11, v11, v4
	s_nop 1
	v_mov_b32_dpp v13, v11 row_mirror row_mask:0xf bank_mask:0xf
	v_lshl_add_u64 v[4:5], v[16:17], 0, s[6:7]
	s_waitcnt lgkmcnt(0)
	v_mov_b32_e32 v97, v96
	s_nop 1
	v_permlane16_swap_b32_e32 v96, v97
	s_nop 0
	v_max_f32_e32 v96, v96, v97
	s_waitcnt lgkmcnt(0)
	v_max_f32_e32 v13, v13, v13
	ds_bpermute_b32 v97, v27, v96
	v_max_f32_e32 v98, v11, v13
	global_load_dword v13, v[2:3], off
	global_load_dword v11, v[4:5], off
	s_waitcnt lgkmcnt(0)
	v_max3_f32 v2, v96, v97, s28
	v_mul_f32_e32 v4, 0x3c010204, v2
	s_waitcnt lgkmcnt(0)
	v_mov_b32_e32 v2, v98
	v_mov_b32_e32 v99, v98
	s_nop 1
	v_permlane16_swap_b32_e32 v2, v99
	s_nop 0
	v_max_f32_e32 v2, v2, v99
	ds_bpermute_b32 v3, v27, v2
	v_div_scale_f32 v96, s[6:7], v4, v4, 1.0
	v_rcp_f32_e32 v97, v96
	s_lshl_b64 s[6:7], s[24:25], 12
	s_waitcnt lgkmcnt(0)
	v_max3_f32 v2, v2, v3, s28
	v_mul_f32_e32 v5, 0x3c010204, v2
	v_fma_f32 v2, -v96, v97, 1.0
	v_fmac_f32_e32 v97, v2, v97
	v_div_scale_f32 v2, vcc, 1.0, v4, 1.0
	v_mul_f32_e32 v3, v2, v97
	v_fma_f32 v98, -v96, v3, v2
	v_fmac_f32_e32 v3, v98, v97
	v_fma_f32 v2, -v96, v3, v2
	v_div_fmas_f32 v2, v2, v97, v3
	v_div_fixup_f32 v98, v2, v4, 1.0
	v_mul_f32_e32 v97, v98, v121
	v_mul_f32_e32 v96, v98, v120
	v_rndne_f32_e32 v97, v97
	v_mul_f32_e32 v99, v98, v122
	v_rndne_f32_e32 v96, v96
	v_cvt_i32_f32_e32 v97, v97
	v_rndne_f32_e32 v99, v99
	v_mul_f32_e32 v100, v98, v123
	v_cvt_i32_f32_e32 v96, v96
	v_cvt_i32_f32_sdwa v99, v99 dst_sel:WORD_1 dst_unused:UNUSED_PAD src0_sel:DWORD
	v_rndne_f32_e32 v100, v100
	v_cvt_i32_f32_sdwa v100, v100 dst_sel:BYTE_3 dst_unused:UNUSED_PAD src0_sel:DWORD
	v_lshlrev_b32_e32 v97, 8, v97
	v_and_b32_e32 v99, 0xff0000, v99
	v_perm_b32 v96, v97, v96, s29
	v_or3_b32 v96, v96, v100, v99
	v_mul_f32_e32 v99, v98, v125
	v_mul_f32_e32 v97, v98, v124
	v_rndne_f32_e32 v99, v99
	v_mul_f32_e32 v100, v98, v126
	v_rndne_f32_e32 v97, v97
	v_cvt_i32_f32_e32 v99, v99
	v_rndne_f32_e32 v100, v100
	v_mul_f32_e32 v101, v98, v127
	v_cvt_i32_f32_e32 v97, v97
	v_cvt_i32_f32_sdwa v100, v100 dst_sel:WORD_1 dst_unused:UNUSED_PAD src0_sel:DWORD
	v_rndne_f32_e32 v101, v101
	v_cvt_i32_f32_sdwa v101, v101 dst_sel:BYTE_3 dst_unused:UNUSED_PAD src0_sel:DWORD
	v_lshlrev_b32_e32 v99, 8, v99
	v_and_b32_e32 v100, 0xff0000, v100
	v_perm_b32 v97, v99, v97, s29
	v_lshl_add_u64 v[2:3], v[20:21], 0, s[26:27]
	v_or3_b32 v97, v97, v101, v100
	global_store_dwordx2 v[2:3], v[96:97], off
	v_mul_f32_e32 v97, v98, v105
	v_mul_f32_e32 v96, v98, v104
	v_rndne_f32_e32 v97, v97
	v_mul_f32_e32 v99, v98, v106
	v_rndne_f32_e32 v96, v96
	v_cvt_i32_f32_e32 v97, v97
	v_rndne_f32_e32 v99, v99
	v_mul_f32_e32 v100, v98, v107
	v_cvt_i32_f32_e32 v96, v96
	v_cvt_i32_f32_sdwa v99, v99 dst_sel:WORD_1 dst_unused:UNUSED_PAD src0_sel:DWORD
	v_rndne_f32_e32 v100, v100
	v_cvt_i32_f32_sdwa v100, v100 dst_sel:BYTE_3 dst_unused:UNUSED_PAD src0_sel:DWORD
	v_lshlrev_b32_e32 v97, 8, v97
	v_and_b32_e32 v99, 0xff0000, v99
	v_perm_b32 v96, v97, v96, s29
	v_or3_b32 v96, v96, v100, v99
	v_mul_f32_e32 v99, v98, v109
	v_mul_f32_e32 v97, v98, v108
	v_rndne_f32_e32 v99, v99
	v_mul_f32_e32 v100, v98, v110
	v_rndne_f32_e32 v97, v97
	v_cvt_i32_f32_e32 v99, v99
	v_rndne_f32_e32 v100, v100
	v_mul_f32_e32 v101, v98, v111
	v_cvt_i32_f32_e32 v97, v97
	v_cvt_i32_f32_sdwa v100, v100 dst_sel:WORD_1 dst_unused:UNUSED_PAD src0_sel:DWORD
	v_rndne_f32_e32 v101, v101
	v_cvt_i32_f32_sdwa v101, v101 dst_sel:BYTE_3 dst_unused:UNUSED_PAD src0_sel:DWORD
	v_lshlrev_b32_e32 v99, 8, v99
	v_and_b32_e32 v100, 0xff0000, v100
	v_perm_b32 v97, v99, v97, s29
	v_or3_b32 v97, v97, v101, v100
	global_store_dwordx2 v[2:3], v[96:97], off offset:512
	v_mul_f32_e32 v97, v98, v113
	v_mul_f32_e32 v96, v98, v112
	v_rndne_f32_e32 v97, v97
	v_mul_f32_e32 v99, v98, v114
	v_rndne_f32_e32 v96, v96
	v_cvt_i32_f32_e32 v97, v97
	v_rndne_f32_e32 v99, v99
	v_mul_f32_e32 v100, v98, v115
	v_cvt_i32_f32_e32 v96, v96
	v_cvt_i32_f32_sdwa v99, v99 dst_sel:WORD_1 dst_unused:UNUSED_PAD src0_sel:DWORD
	v_rndne_f32_e32 v100, v100
; __device__ __forceinline__ float bflo(unsigned w) { return __uint_as_float(w << 16); }
; __device__ __forceinline__ float bfhi(unsigned w) { return __uint_as_float(w & 0xffff0000u); }
; __device__ __forceinline__ void quant_store8(const u32x4 (&w)[8], float inv, signed char* dst, int lane) { u32x2* qp = (u32x2*)dst + lane;
; #pragma unroll
;     for (int j = 0; j < 8; ++j) { const unsigned ww[4] = {w[j].x, w[j].y, w[j].z, w[j].w}; unsigned o2[2];
; #pragma unroll
;         for (int h2 = 0; h2 < 2; ++h2) { const int q0 = (int)rintf(bflo(ww[2 * h2]) * inv), q1 = (int)rintf(bfhi(ww[2 * h2]) * inv), q2 = (int)rintf(bflo(ww[2 * h2 + 1]) * inv), q3 = (int)rintf(bfhi(ww[2 * h2 + 1]) * inv);
;             o2[h2] = (unsigned)(q0 & 255) | ((unsigned)(q1 & 255) << 8) | ((unsigned)(q2 & 255) << 16) | ((unsigned)(q3 & 255) << 24); }
;         u32x2 o; o.x = o2[0]; o.y = o2[1]; qp[64 * j] = o; } }
	v_cvt_i32_f32_sdwa v100, v100 dst_sel:BYTE_3 dst_unused:UNUSED_PAD src0_sel:DWORD
	v_lshlrev_b32_e32 v97, 8, v97
	v_and_b32_e32 v99, 0xff0000, v99
	v_perm_b32 v96, v97, v96, s29
	v_or3_b32 v96, v96, v100, v99
	v_mul_f32_e32 v99, v98, v117
	v_mul_f32_e32 v97, v98, v116
	v_rndne_f32_e32 v99, v99
	v_mul_f32_e32 v100, v98, v118
	v_rndne_f32_e32 v97, v97
	v_cvt_i32_f32_e32 v99, v99
	v_rndne_f32_e32 v100, v100
	v_mul_f32_e32 v101, v98, v119
	v_cvt_i32_f32_e32 v97, v97
	v_cvt_i32_f32_sdwa v100, v100 dst_sel:WORD_1 dst_unused:UNUSED_PAD src0_sel:DWORD
	v_rndne_f32_e32 v101, v101
	v_cvt_i32_f32_sdwa v101, v101 dst_sel:BYTE_3 dst_unused:UNUSED_PAD src0_sel:DWORD
	v_lshlrev_b32_e32 v99, 8, v99
	v_and_b32_e32 v100, 0xff0000, v100
	v_perm_b32 v97, v99, v97, s29
	v_or3_b32 v97, v97, v101, v100
	global_store_dwordx2 v[2:3], v[96:97], off offset:1024
	v_mul_f32_e32 v97, v98, v129
	v_mul_f32_e32 v96, v98, v128
	v_rndne_f32_e32 v97, v97
	v_mul_f32_e32 v99, v98, v130
	v_rndne_f32_e32 v96, v96
	v_cvt_i32_f32_e32 v97, v97
	v_rndne_f32_e32 v99, v99
	v_mul_f32_e32 v100, v98, v131
	v_cvt_i32_f32_e32 v96, v96
	v_cvt_i32_f32_sdwa v99, v99 dst_sel:WORD_1 dst_unused:UNUSED_PAD src0_sel:DWORD
	v_rndne_f32_e32 v100, v100
	v_cvt_i32_f32_sdwa v100, v100 dst_sel:BYTE_3 dst_unused:UNUSED_PAD src0_sel:DWORD
	v_lshlrev_b32_e32 v97, 8, v97
	v_and_b32_e32 v99, 0xff0000, v99
	v_perm_b32 v96, v97, v96, s29
	v_or3_b32 v96, v96, v100, v99
	v_mul_f32_e32 v99, v98, v133
	v_mul_f32_e32 v97, v98, v132
	v_rndne_f32_e32 v99, v99
	v_mul_f32_e32 v100, v98, v134
	v_rndne_f32_e32 v97, v97
	v_cvt_i32_f32_e32 v99, v99
	v_rndne_f32_e32 v100, v100
	v_mul_f32_e32 v101, v98, v135
	v_cvt_i32_f32_e32 v97, v97
	v_cvt_i32_f32_sdwa v100, v100 dst_sel:WORD_1 dst_unused:UNUSED_PAD src0_sel:DWORD
	v_rndne_f32_e32 v101, v101
	v_cvt_i32_f32_sdwa v101, v101 dst_sel:BYTE_3 dst_unused:UNUSED_PAD src0_sel:DWORD
	v_lshlrev_b32_e32 v99, 8, v99
	v_and_b32_e32 v100, 0xff0000, v100
	v_perm_b32 v97, v99, v97, s29
	v_or3_b32 v97, v97, v101, v100
	global_store_dwordx2 v[2:3], v[96:97], off offset:1536
	v_mul_f32_e32 v97, v98, v137
	v_mul_f32_e32 v96, v98, v136
	v_rndne_f32_e32 v97, v97
	v_mul_f32_e32 v99, v98, v138
	v_rndne_f32_e32 v96, v96
	v_cvt_i32_f32_e32 v97, v97
	v_rndne_f32_e32 v99, v99
	v_mul_f32_e32 v100, v98, v139
	v_cvt_i32_f32_e32 v96, v96
	v_cvt_i32_f32_sdwa v99, v99 dst_sel:WORD_1 dst_unused:UNUSED_PAD src0_sel:DWORD
	v_rndne_f32_e32 v100, v100
	v_cvt_i32_f32_sdwa v100, v100 dst_sel:BYTE_3 dst_unused:UNUSED_PAD src0_sel:DWORD
	v_lshlrev_b32_e32 v97, 8, v97
	v_and_b32_e32 v99, 0xff0000, v99
	v_perm_b32 v96, v97, v96, s29
	v_or3_b32 v96, v96, v100, v99
	v_mul_f32_e32 v99, v98, v141
	v_mul_f32_e32 v97, v98, v140
	v_rndne_f32_e32 v99, v99
	v_mul_f32_e32 v100, v98, v142
	v_rndne_f32_e32 v97, v97
	v_cvt_i32_f32_e32 v99, v99
	v_rndne_f32_e32 v100, v100
	v_mul_f32_e32 v101, v98, v143
	v_cvt_i32_f32_e32 v97, v97
	v_cvt_i32_f32_sdwa v100, v100 dst_sel:WORD_1 dst_unused:UNUSED_PAD src0_sel:DWORD
	v_rndne_f32_e32 v101, v101
	v_cvt_i32_f32_sdwa v101, v101 dst_sel:BYTE_3 dst_unused:UNUSED_PAD src0_sel:DWORD
	v_lshlrev_b32_e32 v99, 8, v99
	v_and_b32_e32 v100, 0xff0000, v100
	v_perm_b32 v97, v99, v97, s29
	v_or3_b32 v97, v97, v101, v100
	global_store_dwordx2 v[2:3], v[96:97], off offset:2048
	v_mul_f32_e32 v97, v98, v145
	v_mul_f32_e32 v96, v98, v144
	v_rndne_f32_e32 v97, v97
	v_mul_f32_e32 v99, v98, v146
	v_rndne_f32_e32 v96, v96
	v_cvt_i32_f32_e32 v97, v97
	v_rndne_f32_e32 v99, v99
	v_mul_f32_e32 v100, v98, v147
	v_cvt_i32_f32_e32 v96, v96
	v_cvt_i32_f32_sdwa v99, v99 dst_sel:WORD_1 dst_unused:UNUSED_PAD src0_sel:DWORD
	v_rndne_f32_e32 v100, v100
	v_cvt_i32_f32_sdwa v100, v100 dst_sel:BYTE_3 dst_unused:UNUSED_PAD src0_sel:DWORD
	v_lshlrev_b32_e32 v97, 8, v97
	v_and_b32_e32 v99, 0xff0000, v99
	v_perm_b32 v96, v97, v96, s29
	v_or3_b32 v96, v96, v100, v99
	v_mul_f32_e32 v99, v98, v149
	v_mul_f32_e32 v97, v98, v148
	v_rndne_f32_e32 v99, v99
	v_mul_f32_e32 v100, v98, v150
	v_rndne_f32_e32 v97, v97
	v_cvt_i32_f32_e32 v99, v99
	v_rndne_f32_e32 v100, v100
	v_mul_f32_e32 v101, v98, v151
	v_cvt_i32_f32_e32 v97, v97
	v_cvt_i32_f32_sdwa v100, v100 dst_sel:WORD_1 dst_unused:UNUSED_PAD src0_sel:DWORD
	v_rndne_f32_e32 v101, v101
	v_cvt_i32_f32_sdwa v101, v101 dst_sel:BYTE_3 dst_unused:UNUSED_PAD src0_sel:DWORD
	v_lshlrev_b32_e32 v99, 8, v99
	v_and_b32_e32 v100, 0xff0000, v100
	v_perm_b32 v97, v99, v97, s29
	v_or3_b32 v97, v97, v101, v100
	global_store_dwordx2 v[2:3], v[96:97], off offset:2560
	v_mul_f32_e32 v97, v98, v153
	v_mul_f32_e32 v96, v98, v152
	v_rndne_f32_e32 v97, v97
	v_mul_f32_e32 v99, v98, v154
	v_rndne_f32_e32 v96, v96
	v_cvt_i32_f32_e32 v97, v97
	v_rndne_f32_e32 v99, v99
	v_mul_f32_e32 v100, v98, v155
	v_cvt_i32_f32_e32 v96, v96
	v_cvt_i32_f32_sdwa v99, v99 dst_sel:WORD_1 dst_unused:UNUSED_PAD src0_sel:DWORD
	v_rndne_f32_e32 v100, v100
	v_cvt_i32_f32_sdwa v100, v100 dst_sel:BYTE_3 dst_unused:UNUSED_PAD src0_sel:DWORD
	v_lshlrev_b32_e32 v97, 8, v97
	v_and_b32_e32 v99, 0xff0000, v99
	v_perm_b32 v96, v97, v96, s29
	v_or3_b32 v96, v96, v100, v99
	v_mul_f32_e32 v99, v98, v157
	v_mul_f32_e32 v97, v98, v156
	v_rndne_f32_e32 v99, v99
	v_mul_f32_e32 v100, v98, v158
	v_rndne_f32_e32 v97, v97
	v_cvt_i32_f32_e32 v99, v99
	v_rndne_f32_e32 v100, v100
	v_mul_f32_e32 v101, v98, v159
	v_cvt_i32_f32_e32 v97, v97
	v_cvt_i32_f32_sdwa v100, v100 dst_sel:WORD_1 dst_unused:UNUSED_PAD src0_sel:DWORD
	v_rndne_f32_e32 v101, v101
	v_cvt_i32_f32_sdwa v101, v101 dst_sel:BYTE_3 dst_unused:UNUSED_PAD src0_sel:DWORD
	v_lshlrev_b32_e32 v99, 8, v99
	v_and_b32_e32 v100, 0xff0000, v100
	v_perm_b32 v97, v99, v97, s29
	v_or3_b32 v97, v97, v101, v100
; __device__ __forceinline__ float bflo(unsigned w) { return __uint_as_float(w << 16); }
; __device__ __forceinline__ float bfhi(unsigned w) { return __uint_as_float(w & 0xffff0000u); }
; __device__ __forceinline__ void quant_store8(const u32x4 (&w)[8], float inv, signed char* dst, int lane) { u32x2* qp = (u32x2*)dst + lane;
; #pragma unroll
;     for (int j = 0; j < 8; ++j) { const unsigned ww[4] = {w[j].x, w[j].y, w[j].z, w[j].w}; unsigned o2[2];
; #pragma unroll
;         for (int h2 = 0; h2 < 2; ++h2) { const int q0 = (int)rintf(bflo(ww[2 * h2]) * inv), q1 = (int)rintf(bfhi(ww[2 * h2]) * inv), q2 = (int)rintf(bflo(ww[2 * h2 + 1]) * inv), q3 = (int)rintf(bfhi(ww[2 * h2 + 1]) * inv);
;             o2[h2] = (unsigned)(q0 & 255) | ((unsigned)(q1 & 255) << 8) | ((unsigned)(q2 & 255) << 16) | ((unsigned)(q3 & 255) << 24); }
;         u32x2 o; o.x = o2[0]; o.y = o2[1]; qp[64 * j] = o; } }
; __global__ void __launch_bounds__(NWAVES * 64, 2) fwd(Args args) {
;     ...
;         for (int row = gw; row < T; row += 2 * NGW) { const int row2 = row + NGW;
;             const float pa = part[(size_t)row * 64 + F.lane], pb = part[(size_t)row2 * 64 + F.lane];
;             float st0, st1; quant_rows2(hb + (size_t)row * DM, hb + (size_t)row2 * DM, hq + (size_t)row * DM, hq + (size_t)row2 * DM, F.lane, st0, st1);
;             const float rsa = 1.0f / sqrtf(wave_sum(pa) * (1.0f / DM) + EPS), rsb = 1.0f / sqrtf(wave_sum(pb) * (1.0f / DM) + EPS);
;             if (F.lane == 0) { rowq2[row] = rsa * st0; rowq2[row2] = rsb * st1; }
	global_store_dwordx2 v[2:3], v[96:97], off offset:3072
	v_mul_f32_e32 v97, v98, v161
	v_mul_f32_e32 v96, v98, v160
	v_rndne_f32_e32 v97, v97
	v_mul_f32_e32 v99, v98, v162
	v_rndne_f32_e32 v96, v96
	v_cvt_i32_f32_e32 v97, v97
	v_rndne_f32_e32 v99, v99
	v_mul_f32_e32 v100, v98, v163
	v_cvt_i32_f32_e32 v96, v96
	v_cvt_i32_f32_sdwa v99, v99 dst_sel:WORD_1 dst_unused:UNUSED_PAD src0_sel:DWORD
	v_rndne_f32_e32 v100, v100
	v_cvt_i32_f32_sdwa v100, v100 dst_sel:BYTE_3 dst_unused:UNUSED_PAD src0_sel:DWORD
	v_lshlrev_b32_e32 v97, 8, v97
	v_and_b32_e32 v99, 0xff0000, v99
	v_perm_b32 v96, v97, v96, s29
	v_or3_b32 v96, v96, v100, v99
	v_mul_f32_e32 v99, v98, v165
	v_mul_f32_e32 v100, v98, v166
	v_rndne_f32_e32 v99, v99
	v_rndne_f32_e32 v100, v100
	v_cvt_i32_f32_e32 v99, v99
	v_cvt_i32_f32_sdwa v100, v100 dst_sel:WORD_1 dst_unused:UNUSED_PAD src0_sel:DWORD
	v_mul_f32_e32 v97, v98, v164
	v_rndne_f32_e32 v97, v97
	v_mul_f32_e32 v93, v98, v93
	v_cvt_i32_f32_e32 v97, v97
	v_rndne_f32_e32 v93, v93
	v_cvt_i32_f32_sdwa v93, v93 dst_sel:BYTE_3 dst_unused:UNUSED_PAD src0_sel:DWORD
	v_lshlrev_b32_e32 v98, 8, v99
	v_and_b32_e32 v99, 0xff0000, v100
	v_div_scale_f32 v100, s[26:27], v5, v5, 1.0
	v_rcp_f32_e32 v101, v100
	v_perm_b32 v97, v98, v97, s29
	v_or3_b32 v97, v97, v93, v99
	global_store_dwordx2 v[2:3], v[96:97], off offset:3584
	v_fma_f32 v2, -v100, v101, 1.0
	v_fmac_f32_e32 v101, v2, v101
	v_div_scale_f32 v2, vcc, 1.0, v5, 1.0
	v_mul_f32_e32 v3, v2, v101
	v_fma_f32 v93, -v100, v3, v2
	v_fmac_f32_e32 v3, v93, v101
	v_fma_f32 v2, -v100, v3, v2
	v_div_fmas_f32 v2, v2, v101, v3
	v_div_fixup_f32 v96, v2, v5, 1.0
	v_mul_f32_e32 v12, v96, v12
	v_mul_f32_e32 v30, v96, v30
	v_rndne_f32_e32 v12, v12
	v_mul_f32_e32 v29, v96, v29
	v_rndne_f32_e32 v30, v30
	v_cvt_i32_f32_e32 v12, v12
	v_rndne_f32_e32 v29, v29
	v_mul_f32_e32 v10, v96, v10
	v_cvt_i32_f32_e32 v30, v30
	v_cvt_i32_f32_sdwa v29, v29 dst_sel:WORD_1 dst_unused:UNUSED_PAD src0_sel:DWORD
	v_rndne_f32_e32 v10, v10
	v_cvt_i32_f32_sdwa v10, v10 dst_sel:BYTE_3 dst_unused:UNUSED_PAD src0_sel:DWORD
	v_lshlrev_b32_e32 v12, 8, v12
	v_mul_f32_e32 v9, v96, v9
	v_and_b32_e32 v29, 0xff0000, v29
	v_perm_b32 v12, v12, v30, s29
	v_rndne_f32_e32 v9, v9
	v_or3_b32 v10, v12, v10, v29
	s_waitcnt vmcnt(9)
	s_nop 1
	v_mov_b32_dpp v12, v13 quad_perm:[1,0,3,2] row_mask:0xf bank_mask:0xf
	v_cvt_i32_f32_e32 v29, v9
	s_waitcnt vmcnt(8)
	s_nop 1
	v_mov_b32_dpp v9, v11 quad_perm:[1,0,3,2] row_mask:0xf bank_mask:0xf
	v_mul_f32_e32 v7, v96, v7
	v_rndne_f32_e32 v7, v7
	s_waitcnt lgkmcnt(0)
	v_add_f32_e32 v12, v13, v12
	s_nop 1
	v_mov_b32_dpp v13, v12 quad_perm:[2,3,0,1] row_mask:0xf bank_mask:0xf
	s_waitcnt lgkmcnt(0)
	v_add_f32_e32 v9, v11, v9
	s_nop 1
	v_mov_b32_dpp v11, v9 quad_perm:[2,3,0,1] row_mask:0xf bank_mask:0xf
	v_cvt_i32_f32_sdwa v30, v7 dst_sel:WORD_1 dst_unused:UNUSED_PAD src0_sel:DWORD
	v_mul_f32_e32 v44, v96, v44
	s_waitcnt lgkmcnt(0)
	v_add_f32_e32 v12, v12, v13
	s_nop 1
	v_mov_b32_dpp v13, v12 row_half_mirror row_mask:0xf bank_mask:0xf
	s_waitcnt lgkmcnt(0)
	v_add_f32_e32 v9, v9, v11
	s_nop 1
	v_mov_b32_dpp v11, v9 row_half_mirror row_mask:0xf bank_mask:0xf
	v_mul_f32_e32 v33, v96, v33
	v_mul_f32_e32 v46, v96, v46
	s_waitcnt lgkmcnt(0)
	v_add_f32_e32 v7, v12, v13
	s_nop 1
	v_mov_b32_dpp v12, v7 row_mirror row_mask:0xf bank_mask:0xf
	s_waitcnt lgkmcnt(0)
	v_add_f32_e32 v9, v9, v11
	s_nop 1
	v_mov_b32_dpp v11, v9 row_mirror row_mask:0xf bank_mask:0xf
	v_rndne_f32_e32 v44, v44
	v_mul_f32_e32 v45, v96, v45
	v_mul_f32_e32 v42, v96, v42
	v_rndne_f32_e32 v33, v33
	v_mul_f32_e32 v32, v96, v32
	v_rndne_f32_e32 v46, v46
	v_cvt_i32_f32_e32 v44, v44
	v_rndne_f32_e32 v45, v45
	v_mul_f32_e32 v43, v96, v43
	v_rndne_f32_e32 v42, v42
	v_cvt_i32_f32_e32 v33, v33
	v_rndne_f32_e32 v32, v32
	v_mul_f32_e32 v31, v96, v31
	v_mul_f32_e32 v8, v96, v8
	s_waitcnt lgkmcnt(0)
	v_add_f32_e32 v7, v7, v12
	s_waitcnt lgkmcnt(0)
	v_add_f32_e32 v9, v9, v11
	v_cvt_i32_f32_e32 v46, v46
	v_cvt_i32_f32_sdwa v45, v45 dst_sel:WORD_1 dst_unused:UNUSED_PAD src0_sel:DWORD
	v_rndne_f32_e32 v43, v43
	v_cvt_i32_f32_e32 v42, v42
	v_cvt_i32_f32_sdwa v32, v32 dst_sel:WORD_1 dst_unused:UNUSED_PAD src0_sel:DWORD
	v_rndne_f32_e32 v31, v31
	v_rndne_f32_e32 v8, v8
	ds_bpermute_b32 v12, v26, v7
	ds_bpermute_b32 v11, v26, v9
	v_cvt_i32_f32_sdwa v43, v43 dst_sel:BYTE_3 dst_unused:UNUSED_PAD src0_sel:DWORD
	v_cvt_i32_f32_sdwa v31, v31 dst_sel:BYTE_3 dst_unused:UNUSED_PAD src0_sel:DWORD
	v_cvt_i32_f32_e32 v8, v8
	v_mul_f32_e32 v92, v96, v92
	v_mul_f32_e32 v89, v96, v89
	v_mul_f32_e32 v84, v96, v84
	v_mul_f32_e32 v81, v96, v81
	v_mul_f32_e32 v76, v96, v76
	v_mul_f32_e32 v73, v96, v73
	v_mul_f32_e32 v68, v96, v68
	v_mul_f32_e32 v65, v96, v65
	v_mul_f32_e32 v60, v96, v60
	v_mul_f32_e32 v57, v96, v57
	v_mul_f32_e32 v52, v96, v52
	v_mul_f32_e32 v49, v96, v49
	v_mul_f32_e32 v93, v96, v95
	v_rndne_f32_e32 v92, v92
	v_mul_f32_e32 v94, v96, v94
	v_mul_f32_e32 v90, v96, v90
	v_rndne_f32_e32 v89, v89
	v_mul_f32_e32 v88, v96, v88
	v_mul_f32_e32 v86, v96, v86
	v_rndne_f32_e32 v84, v84
	v_mul_f32_e32 v85, v96, v85
	v_mul_f32_e32 v82, v96, v82
	v_rndne_f32_e32 v81, v81
	v_mul_f32_e32 v80, v96, v80
	v_mul_f32_e32 v78, v96, v78
	v_rndne_f32_e32 v76, v76
	v_mul_f32_e32 v77, v96, v77
	v_mul_f32_e32 v74, v96, v74
	v_rndne_f32_e32 v73, v73
	v_mul_f32_e32 v72, v96, v72
	v_mul_f32_e32 v70, v96, v70
	v_rndne_f32_e32 v68, v68
	v_mul_f32_e32 v69, v96, v69
	v_mul_f32_e32 v66, v96, v66
	v_rndne_f32_e32 v65, v65
	v_mul_f32_e32 v64, v96, v64
	v_mul_f32_e32 v62, v96, v62
	v_rndne_f32_e32 v60, v60
	v_mul_f32_e32 v61, v96, v61
	v_mul_f32_e32 v58, v96, v58
	v_rndne_f32_e32 v57, v57
	v_mul_f32_e32 v56, v96, v56
; __device__ __forceinline__ float bflo(unsigned w) { return __uint_as_float(w << 16); }
; __device__ __forceinline__ float bfhi(unsigned w) { return __uint_as_float(w & 0xffff0000u); }
; __device__ __forceinline__ void quant_store8(const u32x4 (&w)[8], float inv, signed char* dst, int lane) { u32x2* qp = (u32x2*)dst + lane;
; #pragma unroll
;     for (int j = 0; j < 8; ++j) { const unsigned ww[4] = {w[j].x, w[j].y, w[j].z, w[j].w}; unsigned o2[2];
; #pragma unroll
;         for (int h2 = 0; h2 < 2; ++h2) { const int q0 = (int)rintf(bflo(ww[2 * h2]) * inv), q1 = (int)rintf(bfhi(ww[2 * h2]) * inv), q2 = (int)rintf(bflo(ww[2 * h2 + 1]) * inv), q3 = (int)rintf(bfhi(ww[2 * h2 + 1]) * inv);
;             o2[h2] = (unsigned)(q0 & 255) | ((unsigned)(q1 & 255) << 8) | ((unsigned)(q2 & 255) << 16) | ((unsigned)(q3 & 255) << 24); }
;         u32x2 o; o.x = o2[0]; o.y = o2[1]; qp[64 * j] = o; } }
; __global__ void __launch_bounds__(NWAVES * 64, 2) fwd(Args args) {
;     ...
;         for (int row = gw; row < T; row += 2 * NGW) { const int row2 = row + NGW;
;             const float pa = part[(size_t)row * 64 + F.lane], pb = part[(size_t)row2 * 64 + F.lane];
;             float st0, st1; quant_rows2(hb + (size_t)row * DM, hb + (size_t)row2 * DM, hq + (size_t)row * DM, hq + (size_t)row2 * DM, F.lane, st0, st1);
;             const float rsa = 1.0f / sqrtf(wave_sum(pa) * (1.0f / DM) + EPS), rsb = 1.0f / sqrtf(wave_sum(pb) * (1.0f / DM) + EPS);
;             if (F.lane == 0) { rowq2[row] = rsa * st0; rowq2[row2] = rsb * st1; }
	v_mul_f32_e32 v54, v96, v54
	v_rndne_f32_e32 v52, v52
	v_mul_f32_e32 v53, v96, v53
	v_mul_f32_e32 v50, v96, v50
	v_rndne_f32_e32 v49, v49
	v_mul_f32_e32 v48, v96, v48
	v_lshlrev_b32_e32 v44, 8, v44
	v_lshlrev_b32_e32 v33, 8, v33
	v_mul_f32_e32 v6, v96, v6
	v_rndne_f32_e32 v93, v93
	v_cvt_i32_f32_e32 v92, v92
	v_rndne_f32_e32 v94, v94
	v_mul_f32_e32 v91, v96, v91
	v_rndne_f32_e32 v90, v90
	v_cvt_i32_f32_e32 v89, v89
	v_rndne_f32_e32 v88, v88
	v_mul_f32_e32 v87, v96, v87
	v_rndne_f32_e32 v86, v86
	v_cvt_i32_f32_e32 v84, v84
	v_rndne_f32_e32 v85, v85
	v_mul_f32_e32 v83, v96, v83
	v_rndne_f32_e32 v82, v82
	v_cvt_i32_f32_e32 v81, v81
	v_rndne_f32_e32 v80, v80
	v_mul_f32_e32 v79, v96, v79
	v_rndne_f32_e32 v78, v78
	v_cvt_i32_f32_e32 v76, v76
	v_rndne_f32_e32 v77, v77
	v_mul_f32_e32 v75, v96, v75
	v_rndne_f32_e32 v74, v74
	v_cvt_i32_f32_e32 v73, v73
	v_rndne_f32_e32 v72, v72
	v_mul_f32_e32 v71, v96, v71
	v_rndne_f32_e32 v70, v70
	v_cvt_i32_f32_e32 v68, v68
	v_rndne_f32_e32 v69, v69
	v_mul_f32_e32 v67, v96, v67
	v_rndne_f32_e32 v66, v66
	v_cvt_i32_f32_e32 v65, v65
	v_rndne_f32_e32 v64, v64
	v_mul_f32_e32 v63, v96, v63
	v_rndne_f32_e32 v62, v62
	v_cvt_i32_f32_e32 v60, v60
	v_rndne_f32_e32 v61, v61
	v_mul_f32_e32 v59, v96, v59
	v_rndne_f32_e32 v58, v58
	v_cvt_i32_f32_e32 v57, v57
	v_rndne_f32_e32 v56, v56
	v_mul_f32_e32 v55, v96, v55
	v_rndne_f32_e32 v54, v54
	v_cvt_i32_f32_e32 v52, v52
	v_rndne_f32_e32 v53, v53
	v_mul_f32_e32 v51, v96, v51
	v_rndne_f32_e32 v50, v50
	v_cvt_i32_f32_e32 v49, v49
	v_rndne_f32_e32 v48, v48
	v_mul_f32_e32 v47, v96, v47
	v_and_b32_e32 v45, 0xff0000, v45
	v_perm_b32 v44, v44, v46, s29
	v_and_b32_e32 v32, 0xff0000, v32
	v_perm_b32 v33, v33, v42, s29
	v_rndne_f32_e32 v6, v6
	v_cvt_i32_f32_e32 v93, v93
	v_cvt_i32_f32_sdwa v94, v94 dst_sel:WORD_1 dst_unused:UNUSED_PAD src0_sel:DWORD
	v_rndne_f32_e32 v91, v91
	v_cvt_i32_f32_e32 v90, v90
	v_cvt_i32_f32_sdwa v88, v88 dst_sel:WORD_1 dst_unused:UNUSED_PAD src0_sel:DWORD
	v_rndne_f32_e32 v87, v87
	v_cvt_i32_f32_e32 v86, v86
	v_cvt_i32_f32_sdwa v85, v85 dst_sel:WORD_1 dst_unused:UNUSED_PAD src0_sel:DWORD
	v_rndne_f32_e32 v83, v83
	v_cvt_i32_f32_e32 v82, v82
	v_cvt_i32_f32_sdwa v80, v80 dst_sel:WORD_1 dst_unused:UNUSED_PAD src0_sel:DWORD
	v_rndne_f32_e32 v79, v79
	v_cvt_i32_f32_e32 v78, v78
	v_cvt_i32_f32_sdwa v77, v77 dst_sel:WORD_1 dst_unused:UNUSED_PAD src0_sel:DWORD
	v_rndne_f32_e32 v75, v75
	v_cvt_i32_f32_e32 v74, v74
	v_cvt_i32_f32_sdwa v72, v72 dst_sel:WORD_1 dst_unused:UNUSED_PAD src0_sel:DWORD
	v_rndne_f32_e32 v71, v71
	v_cvt_i32_f32_e32 v70, v70
	v_cvt_i32_f32_sdwa v69, v69 dst_sel:WORD_1 dst_unused:UNUSED_PAD src0_sel:DWORD
	v_rndne_f32_e32 v67, v67
	v_cvt_i32_f32_e32 v66, v66
	v_cvt_i32_f32_sdwa v64, v64 dst_sel:WORD_1 dst_unused:UNUSED_PAD src0_sel:DWORD
	v_rndne_f32_e32 v63, v63
	v_cvt_i32_f32_e32 v62, v62
	v_cvt_i32_f32_sdwa v61, v61 dst_sel:WORD_1 dst_unused:UNUSED_PAD src0_sel:DWORD
	v_rndne_f32_e32 v59, v59
	v_cvt_i32_f32_e32 v58, v58
	v_cvt_i32_f32_sdwa v56, v56 dst_sel:WORD_1 dst_unused:UNUSED_PAD src0_sel:DWORD
	v_rndne_f32_e32 v55, v55
	v_cvt_i32_f32_e32 v54, v54
	v_cvt_i32_f32_sdwa v53, v53 dst_sel:WORD_1 dst_unused:UNUSED_PAD src0_sel:DWORD
	v_rndne_f32_e32 v51, v51
	v_cvt_i32_f32_e32 v50, v50
	v_cvt_i32_f32_sdwa v48, v48 dst_sel:WORD_1 dst_unused:UNUSED_PAD src0_sel:DWORD
	v_rndne_f32_e32 v47, v47
	v_or3_b32 v44, v44, v43, v45
	v_or3_b32 v45, v33, v31, v32
	v_cvt_i32_f32_sdwa v13, v6 dst_sel:BYTE_3 dst_unused:UNUSED_PAD src0_sel:DWORD
	v_lshlrev_b32_e32 v31, 8, v8
	s_waitcnt lgkmcnt(1)
	v_add_f32_e32 v6, v7, v12
	s_waitcnt lgkmcnt(0)
	v_add_f32_e32 v8, v9, v11
	v_cvt_i32_f32_sdwa v91, v91 dst_sel:BYTE_3 dst_unused:UNUSED_PAD src0_sel:DWORD
	v_cvt_i32_f32_sdwa v87, v87 dst_sel:BYTE_3 dst_unused:UNUSED_PAD src0_sel:DWORD
	v_cvt_i32_f32_sdwa v83, v83 dst_sel:BYTE_3 dst_unused:UNUSED_PAD src0_sel:DWORD
	v_cvt_i32_f32_sdwa v79, v79 dst_sel:BYTE_3 dst_unused:UNUSED_PAD src0_sel:DWORD
	v_cvt_i32_f32_sdwa v75, v75 dst_sel:BYTE_3 dst_unused:UNUSED_PAD src0_sel:DWORD
	v_cvt_i32_f32_sdwa v71, v71 dst_sel:BYTE_3 dst_unused:UNUSED_PAD src0_sel:DWORD
	v_cvt_i32_f32_sdwa v67, v67 dst_sel:BYTE_3 dst_unused:UNUSED_PAD src0_sel:DWORD
	v_cvt_i32_f32_sdwa v63, v63 dst_sel:BYTE_3 dst_unused:UNUSED_PAD src0_sel:DWORD
	v_cvt_i32_f32_sdwa v59, v59 dst_sel:BYTE_3 dst_unused:UNUSED_PAD src0_sel:DWORD
	v_cvt_i32_f32_sdwa v55, v55 dst_sel:BYTE_3 dst_unused:UNUSED_PAD src0_sel:DWORD
	v_cvt_i32_f32_sdwa v51, v51 dst_sel:BYTE_3 dst_unused:UNUSED_PAD src0_sel:DWORD
	v_cvt_i32_f32_sdwa v47, v47 dst_sel:BYTE_3 dst_unused:UNUSED_PAD src0_sel:DWORD
	ds_bpermute_b32 v7, v27, v6
	ds_bpermute_b32 v9, v27, v8
	v_lshlrev_b32_e32 v92, 8, v92
	v_lshlrev_b32_e32 v89, 8, v89
	v_lshlrev_b32_e32 v84, 8, v84
	v_lshlrev_b32_e32 v81, 8, v81
	v_lshlrev_b32_e32 v76, 8, v76
	v_lshlrev_b32_e32 v73, 8, v73
	v_lshlrev_b32_e32 v68, 8, v68
	v_lshlrev_b32_e32 v65, 8, v65
	v_lshlrev_b32_e32 v60, 8, v60
	v_lshlrev_b32_e32 v57, 8, v57
	v_lshlrev_b32_e32 v52, 8, v52
	v_lshlrev_b32_e32 v49, 8, v49
	v_and_b32_e32 v94, 0xff0000, v94
	v_perm_b32 v92, v92, v93, s29
	v_and_b32_e32 v88, 0xff0000, v88
	v_perm_b32 v89, v89, v90, s29
	v_and_b32_e32 v85, 0xff0000, v85
	v_perm_b32 v84, v84, v86, s29
	v_and_b32_e32 v80, 0xff0000, v80
	v_perm_b32 v81, v81, v82, s29
	v_and_b32_e32 v77, 0xff0000, v77
	v_perm_b32 v76, v76, v78, s29
	v_and_b32_e32 v72, 0xff0000, v72
	v_perm_b32 v73, v73, v74, s29
	v_and_b32_e32 v69, 0xff0000, v69
	v_perm_b32 v68, v68, v70, s29
	v_and_b32_e32 v64, 0xff0000, v64
	v_perm_b32 v65, v65, v66, s29
	v_and_b32_e32 v61, 0xff0000, v61
	v_perm_b32 v60, v60, v62, s29
	v_and_b32_e32 v56, 0xff0000, v56
	v_perm_b32 v57, v57, v58, s29
	v_and_b32_e32 v53, 0xff0000, v53
	v_perm_b32 v52, v52, v54, s29
	v_and_b32_e32 v48, 0xff0000, v48
	v_perm_b32 v49, v49, v50, s29
	v_and_b32_e32 v11, 0xff0000, v30
	v_perm_b32 v12, v31, v29, s29
	v_lshl_add_u64 v[2:3], v[20:21], 0, s[6:7]
	v_or3_b32 v92, v92, v91, v94
	v_or3_b32 v93, v89, v87, v88
	v_or3_b32 v84, v84, v83, v85
	v_or3_b32 v85, v81, v79, v80
	v_or3_b32 v76, v76, v75, v77
	v_or3_b32 v77, v73, v71, v72
	v_or3_b32 v68, v68, v67, v69
	v_or3_b32 v69, v65, v63, v64
	v_or3_b32 v60, v60, v59, v61
	v_or3_b32 v61, v57, v55, v56
	v_or3_b32 v52, v52, v51, v53
	v_or3_b32 v53, v49, v47, v48
	v_or3_b32 v11, v12, v13, v11
	global_store_dwordx2 v[2:3], v[92:93], off
	global_store_dwordx2 v[2:3], v[84:85], off offset:512
	global_store_dwordx2 v[2:3], v[76:77], off offset:1024
	global_store_dwordx2 v[2:3], v[68:69], off offset:1536
	global_store_dwordx2 v[2:3], v[60:61], off offset:2048
	global_store_dwordx2 v[2:3], v[52:53], off offset:2560
	global_store_dwordx2 v[2:3], v[44:45], off offset:3072
	global_store_dwordx2 v[2:3], v[10:11], off offset:3584
	s_and_saveexec_b64 s[26:27], s[4:5]
	s_cbranch_execz .LBB0_1391
; __global__ void __launch_bounds__(NWAVES * 64, 2) fwd(Args args) {
;     ...
;             const float rsa = 1.0f / sqrtf(wave_sum(pa) * (1.0f / DM) + EPS), rsb = 1.0f / sqrtf(wave_sum(pb) * (1.0f / DM) + EPS);
;             if (F.lane == 0) { rowq2[row] = rsa * st0; rowq2[row2] = rsb * st1; }
	s_waitcnt lgkmcnt(0)
	v_add_f32_e32 v2, v8, v9
	v_fmamk_f32 v2, v2, 0x39800000, v14
	v_mul_f32_e32 v3, 0x4f800000, v2
	v_cmp_gt_f32_e32 vcc, s30, v2
	v_add_f32_e32 v6, v6, v7
	v_fmamk_f32 v6, v6, 0x39800000, v14
	v_cndmask_b32_e32 v2, v2, v3, vcc
	v_sqrt_f32_e32 v3, v2
	v_mul_f32_e32 v7, 0x4f800000, v6
	v_add_u32_e32 v8, -1, v3
	v_fma_f32 v10, -v8, v3, v2
	v_add_u32_e32 v9, 1, v3
	v_cmp_ge_f32_e64 s[6:7], 0, v10
	s_nop 1
	v_cndmask_b32_e64 v8, v3, v8, s[6:7]
	v_fma_f32 v3, -v9, v3, v2
	v_cmp_lt_f32_e64 s[6:7], 0, v3
	s_nop 1
	v_cndmask_b32_e64 v3, v8, v9, s[6:7]
	v_cmp_gt_f32_e64 s[6:7], s30, v6
	v_mul_f32_e32 v8, 0x37800000, v3
	v_cndmask_b32_e32 v3, v3, v8, vcc
	v_cndmask_b32_e64 v6, v6, v7, s[6:7]
	v_sqrt_f32_e32 v7, v6
	v_cmp_class_f32_e32 vcc, v2, v28
	s_nop 1
	v_cndmask_b32_e32 v2, v3, v2, vcc
	v_add_u32_e32 v3, -1, v7
	v_fma_f32 v8, -v3, v7, v6
	v_cmp_ge_f32_e32 vcc, 0, v8
	v_add_u32_e32 v8, 1, v7
	s_nop 0
	v_cndmask_b32_e32 v3, v7, v3, vcc
	v_fma_f32 v7, -v8, v7, v6
	v_cmp_lt_f32_e32 vcc, 0, v7
	s_nop 1
	v_cndmask_b32_e32 v3, v3, v8, vcc
	v_div_scale_f32 v8, s[34:35], v2, v2, 1.0
	v_rcp_f32_e32 v9, v8
	v_mul_f32_e32 v7, 0x37800000, v3
	v_cndmask_b32_e64 v3, v3, v7, s[6:7]
	v_cmp_class_f32_e32 vcc, v6, v28
	s_nop 1
	v_cndmask_b32_e32 v3, v3, v6, vcc
	v_fma_f32 v6, -v8, v9, 1.0
	v_fmac_f32_e32 v9, v6, v9
	v_div_scale_f32 v6, vcc, 1.0, v2, 1.0
	v_mul_f32_e32 v7, v6, v9
	v_fma_f32 v10, -v8, v7, v6
	v_fmac_f32_e32 v7, v10, v9
	v_fma_f32 v6, -v8, v7, v6
	v_div_scale_f32 v8, s[6:7], v3, v3, 1.0
	v_rcp_f32_e32 v10, v8
	v_div_fmas_f32 v6, v6, v9, v7
	v_div_fixup_f32 v2, v6, v2, 1.0
	s_lshl_b64 s[6:7], s[22:23], 2
	v_fma_f32 v6, -v8, v10, 1.0
	v_fmac_f32_e32 v10, v6, v10
	v_div_scale_f32 v6, vcc, 1.0, v3, 1.0
	v_mul_f32_e32 v7, v6, v10
	v_fma_f32 v9, -v8, v7, v6
	v_fmac_f32_e32 v7, v9, v10
	v_fma_f32 v6, -v8, v7, v6
	v_div_fmas_f32 v6, v6, v10, v7
	v_div_fixup_f32 v3, v6, v3, 1.0
	s_add_u32 s6, s8, s6
	v_mul_f32_e32 v3, v4, v3
	s_addc_u32 s7, s9, s7
	global_store_dword v15, v3, s[6:7]
	s_add_u32 s6, s6, s20
	v_mul_f32_e32 v2, v5, v2
	s_addc_u32 s7, s7, s21
	global_store_dword v15, v2, s[6:7]
	s_branch .LBB0_1391

; #define LAS __attribute__((address_space(3)))
; __device__ __forceinline__ float bflo(unsigned w) { return __uint_as_float(w << 16); }
; __device__ __forceinline__ float bfhi(unsigned w) { return __uint_as_float(w & 0xffff0000u); }
; __device__ __forceinline__ void rot_load(u32x4 (&w)[8], const bf16_t* src, int tl) {
;     ...
;     for (int j = 0; j < 8; ++j) w[j] = __builtin_nontemporal_load((const u32x4*)src + j * 256 + tl);
; }
; template <bool CENTER>
; __device__ __forceinline__ void rot_finish(const u32x4 (&w)[8], signed char* dst, LAS float* red, int tl, int half, int wv4, int lane, float& step_out, float& sum_out) {
;     f32x2 pr[32];
; #pragma unroll
;     for (int j = 0; j < 8; ++j) { pr[4 * j] = (f32x2){bflo(w[j].x), bfhi(w[j].x)}; pr[4 * j + 1] = (f32x2){bflo(w[j].y), bfhi(w[j].y)}; pr[4 * j + 2] = (f32x2){bflo(w[j].z), bfhi(w[j].z)}; pr[4 * j + 3] = (f32x2){bflo(w[j].w), bfhi(w[j].w)}; }
; #pragma unroll
;     for (int i = 0; i < 32; ++i) { const float a = pr[i][0], b = pr[i][1]; pr[i] = (f32x2){a + b, a - b}; }
; #pragma unroll
;     for (int h = 1; h < 32; h <<= 1)
; #pragma unroll
;         for (int i = 0; i < 32; ++i) if (!(i & h)) { const f32x2 a = pr[i], b = pr[i + h]; pr[i] = a + b; pr[i + h] = a - b; }
;     float sm = pr[0][0];
; #pragma unroll
;     for (int o = 1; o < 64; o <<= 1) sm += __shfl_xor(sm, o);
.LBB0_1542:
	s_add_i32 s22, s8, 2
	v_mad_i64_i32 v[34:35], s[24:25], s22, v66, v[68:69]
	v_add_co_u32_e32 v36, vcc, s3, v34
	s_waitcnt vmcnt(1)
	v_lshlrev_b32_e32 v73, 16, v16
	v_addc_co_u32_e32 v37, vcc, 0, v35, vcc
	global_load_dwordx4 v[62:65], v[36:37], off offset:-4096 nt
	global_load_dwordx4 v[58:61], v[36:37], off nt
	v_add_co_u32_e32 v36, vcc, s28, v34
	v_and_b32_e32 v74, 0xffff0000, v16
	s_nop 0
	v_addc_co_u32_e32 v37, vcc, 0, v35, vcc
	global_load_dwordx4 v[54:57], v[36:37], off offset:-4096 nt
	global_load_dwordx4 v[50:53], v[36:37], off nt
	v_add_co_u32_e32 v36, vcc, s29, v34
	v_lshlrev_b32_e32 v75, 16, v17
	s_nop 0
	v_addc_co_u32_e32 v37, vcc, 0, v35, vcc
	v_add_co_u32_e32 v38, vcc, s30, v34
	global_load_dwordx4 v[46:49], v[36:37], off offset:-4096 nt
	global_load_dwordx4 v[42:45], v[36:37], off nt
	v_addc_co_u32_e32 v39, vcc, 0, v35, vcc
	global_load_dwordx4 v[34:37], v[34:35], off nt
	s_nop 0
	global_load_dwordx4 v[38:41], v[38:39], off nt
	v_and_b32_e32 v76, 0xffff0000, v17
	v_lshlrev_b32_e32 v77, 16, v2
	v_and_b32_e32 v78, 0xffff0000, v2
	v_lshlrev_b32_e32 v79, 16, v3
	v_and_b32_e32 v80, 0xffff0000, v3
	v_lshlrev_b32_e32 v81, 16, v4
	v_and_b32_e32 v82, 0xffff0000, v4
	v_lshlrev_b32_e32 v83, 16, v5
	v_and_b32_e32 v84, 0xffff0000, v5
	v_lshlrev_b32_e32 v85, 16, v6
	v_and_b32_e32 v86, 0xffff0000, v6
	v_lshlrev_b32_e32 v87, 16, v7
	v_and_b32_e32 v88, 0xffff0000, v7
	v_lshlrev_b32_e32 v89, 16, v8
	v_and_b32_e32 v90, 0xffff0000, v8
	v_lshlrev_b32_e32 v91, 16, v9
	v_and_b32_e32 v92, 0xffff0000, v9
	v_lshlrev_b32_e32 v93, 16, v10
	v_and_b32_e32 v94, 0xffff0000, v10
	v_lshlrev_b32_e32 v95, 16, v11
	v_and_b32_e32 v96, 0xffff0000, v11
	v_lshlrev_b32_e32 v97, 16, v12
	v_and_b32_e32 v98, 0xffff0000, v12
	v_lshlrev_b32_e32 v99, 16, v13
	v_and_b32_e32 v100, 0xffff0000, v13
	v_lshlrev_b32_e32 v101, 16, v18
	v_and_b32_e32 v102, 0xffff0000, v18
	v_lshlrev_b32_e32 v103, 16, v19
	v_and_b32_e32 v104, 0xffff0000, v19
	v_lshlrev_b32_e32 v105, 16, v20
	v_and_b32_e32 v107, 0xffff0000, v20
	v_add_f32_e32 v72, v73, v74
	v_sub_f32_e32 v73, v73, v74
	v_add_f32_e32 v74, v75, v76
	v_sub_f32_e32 v75, v75, v76
	v_add_f32_e32 v76, v77, v78
	v_sub_f32_e32 v77, v77, v78
	v_add_f32_e32 v78, v79, v80
	v_sub_f32_e32 v79, v79, v80
	v_add_f32_e32 v80, v81, v82
	v_sub_f32_e32 v81, v81, v82
	v_add_f32_e32 v82, v83, v84
	v_sub_f32_e32 v83, v83, v84
	v_add_f32_e32 v84, v85, v86
	v_sub_f32_e32 v85, v85, v86
	v_add_f32_e32 v86, v87, v88
	v_sub_f32_e32 v87, v87, v88
	v_add_f32_e32 v88, v89, v90
	v_sub_f32_e32 v89, v89, v90
	v_add_f32_e32 v90, v91, v92
	v_sub_f32_e32 v91, v91, v92
	v_add_f32_e32 v92, v93, v94
	v_sub_f32_e32 v93, v93, v94
	v_add_f32_e32 v94, v95, v96
	v_sub_f32_e32 v95, v95, v96
	v_add_f32_e32 v96, v97, v98
	v_sub_f32_e32 v97, v97, v98
	v_add_f32_e32 v98, v99, v100
	v_sub_f32_e32 v99, v99, v100
	v_add_f32_e32 v100, v101, v102
	v_sub_f32_e32 v101, v101, v102
	v_add_f32_e32 v102, v103, v104
	v_sub_f32_e32 v103, v103, v104
	v_add_f32_e32 v106, v105, v107
	v_sub_f32_e32 v107, v105, v107
	v_lshlrev_b32_e32 v104, 16, v15
	v_and_b32_e32 v105, 0xffff0000, v15
	v_lshlrev_b32_e32 v109, 16, v21
	v_and_b32_e32 v110, 0xffff0000, v21
	v_lshlrev_b32_e32 v111, 16, v22
	v_and_b32_e32 v113, 0xffff0000, v22
	v_lshlrev_b32_e32 v114, 16, v23
	v_and_b32_e32 v115, 0xffff0000, v23
	v_lshlrev_b32_e32 v119, 16, v24
	v_and_b32_e32 v120, 0xffff0000, v24
	v_lshlrev_b32_e32 v121, 16, v25
	v_and_b32_e32 v122, 0xffff0000, v25
	v_lshlrev_b32_e32 v123, 16, v26
	v_and_b32_e32 v124, 0xffff0000, v26
	v_lshlrev_b32_e32 v125, 16, v27
	v_and_b32_e32 v129, 0xffff0000, v27
	v_lshlrev_b32_e32 v131, 16, v28
	v_and_b32_e32 v132, 0xffff0000, v28
	v_lshlrev_b32_e32 v133, 16, v29
	v_and_b32_e32 v134, 0xffff0000, v29
	s_waitcnt vmcnt(8)
	v_lshlrev_b32_e32 v135, 16, v30
	v_and_b32_e32 v136, 0xffff0000, v30
	v_lshlrev_b32_e32 v137, 16, v31
	v_and_b32_e32 v140, 0xffff0000, v31
	v_lshlrev_b32_e32 v141, 16, v32
	v_and_b32_e32 v142, 0xffff0000, v32
	v_lshlrev_b32_e32 v143, 16, v33
	v_and_b32_e32 v148, 0xffff0000, v33
	v_add_f32_e32 v196, v104, v105
	v_sub_f32_e32 v197, v104, v105
	v_lshlrev_b32_e32 v104, 16, v14
	v_and_b32_e32 v105, 0xffff0000, v14
	v_add_f32_e32 v108, v109, v110
	v_sub_f32_e32 v109, v109, v110
	v_add_f32_e32 v112, v111, v113
	v_sub_f32_e32 v113, v111, v113
	v_add_f32_e32 v116, v114, v115
	v_sub_f32_e32 v117, v114, v115
	v_add_f32_e32 v118, v119, v120
	v_sub_f32_e32 v119, v119, v120
	v_add_f32_e32 v120, v121, v122
	v_sub_f32_e32 v121, v121, v122
	v_add_f32_e32 v126, v123, v124
	v_sub_f32_e32 v127, v123, v124
	v_add_f32_e32 v128, v125, v129
	v_sub_f32_e32 v129, v125, v129
	v_add_f32_e32 v130, v131, v132
	v_sub_f32_e32 v131, v131, v132
	v_add_f32_e32 v132, v133, v134
	v_sub_f32_e32 v133, v133, v134
	v_add_f32_e32 v138, v135, v136
	v_sub_f32_e32 v139, v135, v136
	v_add_f32_e32 v144, v137, v140
	v_sub_f32_e32 v145, v137, v140
	v_add_f32_e32 v146, v141, v142
	v_sub_f32_e32 v147, v141, v142
	v_add_f32_e32 v152, v143, v148
	v_sub_f32_e32 v153, v143, v148
	v_add_f32_e32 v198, v104, v105
	v_sub_f32_e32 v199, v104, v105
	v_pk_add_f32 v[190:191], v[198:199], v[196:197]
	v_pk_add_f32 v[194:195], v[72:73], v[74:75]
	v_pk_add_f32 v[186:187], v[76:77], v[78:79]
	v_pk_add_f32 v[192:193], v[80:81], v[82:83]
	v_pk_add_f32 v[180:181], v[84:85], v[86:87]
	v_pk_add_f32 v[188:189], v[88:89], v[90:91]
	v_pk_add_f32 v[176:177], v[92:93], v[94:95]
	v_pk_add_f32 v[184:185], v[96:97], v[98:99]
	v_pk_add_f32 v[172:173], v[100:101], v[102:103]
	v_pk_add_f32 v[178:179], v[106:107], v[108:109]
	v_pk_add_f32 v[168:169], v[112:113], v[116:117]
	v_pk_add_f32 v[174:175], v[118:119], v[120:121]
	v_pk_add_f32 v[164:165], v[126:127], v[128:129]
	v_pk_add_f32 v[170:171], v[130:131], v[132:133]
	v_pk_add_f32 v[160:161], v[138:139], v[144:145]
	v_pk_add_f32 v[166:167], v[146:147], v[152:153]
	v_pk_add_f32 v[158:159], v[190:191], v[194:195]
	v_pk_add_f32 v[162:163], v[186:187], v[192:193]
	v_pk_add_f32 v[154:155], v[180:181], v[188:189]
	v_pk_add_f32 v[156:157], v[176:177], v[184:185]
	v_pk_add_f32 v[148:149], v[172:173], v[178:179]
	v_pk_add_f32 v[150:151], v[168:169], v[174:175]
	v_pk_add_f32 v[140:141], v[164:165], v[170:171]
	v_pk_add_f32 v[142:143], v[160:161], v[166:167]
	v_pk_add_f32 v[134:135], v[158:159], v[162:163]
	v_pk_add_f32 v[136:137], v[154:155], v[156:157]
	v_pk_add_f32 v[122:123], v[148:149], v[150:151]
	v_pk_add_f32 v[124:125], v[140:141], v[142:143]
	v_pk_add_f32 v[110:111], v[134:135], v[136:137]
	v_pk_add_f32 v[114:115], v[122:123], v[124:125]
	s_nop 0
	v_pk_add_f32 v[104:105], v[110:111], v[114:115]
	s_nop 1
	v_mov_b32_dpp v206, v104 quad_perm:[1,0,3,2] row_mask:0xf bank_mask:0xf
	s_waitcnt lgkmcnt(0)
; template <bool CENTER>
; __device__ __forceinline__ void rot_finish(const u32x4 (&w)[8], signed char* dst, LAS float* red, int tl, int half, int wv4, int lane, float& step_out, float& sum_out) {
;     ...
;     float sm = pr[0][0];
; #pragma unroll
;     for (int o = 1; o < 64; o <<= 1) sm += __shfl_xor(sm, o);
;     float mx = 0.f;
;     if (CENTER) {
;         if (lane == 0) red[half * 4 + wv4] = sm;
;         __syncthreads();
;         sm = (red[half * 4] + red[half * 4 + 1]) + (red[half * 4 + 2] + red[half * 4 + 3]);
;         pr[0][0] -= sm * (64.0f / DFF);
	v_add_f32_e32 v206, v104, v206
	s_nop 1
	v_mov_b32_dpp v207, v206 quad_perm:[2,3,0,1] row_mask:0xf bank_mask:0xf
	s_waitcnt lgkmcnt(0)
	v_add_f32_e32 v206, v206, v207
	s_nop 1
	v_mov_b32_dpp v207, v206 row_half_mirror row_mask:0xf bank_mask:0xf
	s_waitcnt lgkmcnt(0)
	v_add_f32_e32 v206, v206, v207
	s_nop 1
	v_mov_b32_dpp v207, v206 row_mirror row_mask:0xf bank_mask:0xf
	s_waitcnt lgkmcnt(0)
	v_add_f32_e32 v206, v206, v207
	s_waitcnt lgkmcnt(0)
	v_mov_b32_e32 v207, v206
	s_nop 1
	v_permlane16_swap_b32_e32 v206, v207
	s_nop 0
	v_add_f32_e32 v206, v206, v207
	ds_bpermute_b32 v207, v204, v206
	s_and_saveexec_b64 s[24:25], s[4:5]
	s_cbranch_execz .LBB0_1544
	s_add_i32 s9, s33, s34
	s_waitcnt lgkmcnt(0)
	v_add_f32_e32 v206, v206, v207
	v_mov_b32_e32 v207, s9
	ds_write_b32 v207, v206
.LBB0_1544:
	s_or_b64 exec, exec, s[24:25]
	v_pk_add_f32 v[196:197], v[198:199], v[196:197] neg_lo:[0,1] neg_hi:[0,1]
	v_pk_add_f32 v[72:73], v[72:73], v[74:75] neg_lo:[0,1] neg_hi:[0,1]
	v_pk_add_f32 v[74:75], v[76:77], v[78:79] neg_lo:[0,1] neg_hi:[0,1]
	v_pk_add_f32 v[76:77], v[80:81], v[82:83] neg_lo:[0,1] neg_hi:[0,1]
	v_pk_add_f32 v[78:79], v[84:85], v[86:87] neg_lo:[0,1] neg_hi:[0,1]
	v_pk_add_f32 v[80:81], v[88:89], v[90:91] neg_lo:[0,1] neg_hi:[0,1]
	v_pk_add_f32 v[82:83], v[92:93], v[94:95] neg_lo:[0,1] neg_hi:[0,1]
	v_pk_add_f32 v[84:85], v[96:97], v[98:99] neg_lo:[0,1] neg_hi:[0,1]
	v_pk_add_f32 v[86:87], v[100:101], v[102:103] neg_lo:[0,1] neg_hi:[0,1]
	v_pk_add_f32 v[88:89], v[106:107], v[108:109] neg_lo:[0,1] neg_hi:[0,1]
	v_pk_add_f32 v[90:91], v[112:113], v[116:117] neg_lo:[0,1] neg_hi:[0,1]
	v_pk_add_f32 v[92:93], v[118:119], v[120:121] neg_lo:[0,1] neg_hi:[0,1]
	v_pk_add_f32 v[94:95], v[126:127], v[128:129] neg_lo:[0,1] neg_hi:[0,1]
	v_pk_add_f32 v[96:97], v[130:131], v[132:133] neg_lo:[0,1] neg_hi:[0,1]
	v_pk_add_f32 v[98:99], v[138:139], v[144:145] neg_lo:[0,1] neg_hi:[0,1]
	v_pk_add_f32 v[100:101], v[146:147], v[152:153] neg_lo:[0,1] neg_hi:[0,1]
	v_pk_add_f32 v[102:103], v[190:191], v[194:195] neg_lo:[0,1] neg_hi:[0,1]
	v_pk_add_f32 v[106:107], v[196:197], v[72:73]
	v_pk_add_f32 v[72:73], v[196:197], v[72:73] neg_lo:[0,1] neg_hi:[0,1]
	v_pk_add_f32 v[108:109], v[186:187], v[192:193] neg_lo:[0,1] neg_hi:[0,1]
	v_pk_add_f32 v[112:113], v[74:75], v[76:77]
	v_pk_add_f32 v[74:75], v[74:75], v[76:77] neg_lo:[0,1] neg_hi:[0,1]
	v_pk_add_f32 v[76:77], v[180:181], v[188:189] neg_lo:[0,1] neg_hi:[0,1]
	v_pk_add_f32 v[116:117], v[78:79], v[80:81]
	v_pk_add_f32 v[78:79], v[78:79], v[80:81] neg_lo:[0,1] neg_hi:[0,1]
	v_pk_add_f32 v[80:81], v[176:177], v[184:185] neg_lo:[0,1] neg_hi:[0,1]
	v_pk_add_f32 v[118:119], v[82:83], v[84:85]
	v_pk_add_f32 v[82:83], v[82:83], v[84:85] neg_lo:[0,1] neg_hi:[0,1]
	v_pk_add_f32 v[84:85], v[172:173], v[178:179] neg_lo:[0,1] neg_hi:[0,1]
	v_pk_add_f32 v[120:121], v[86:87], v[88:89]
	v_pk_add_f32 v[86:87], v[86:87], v[88:89] neg_lo:[0,1] neg_hi:[0,1]
	v_pk_add_f32 v[88:89], v[168:169], v[174:175] neg_lo:[0,1] neg_hi:[0,1]
	v_pk_add_f32 v[126:127], v[90:91], v[92:93]
	v_pk_add_f32 v[90:91], v[90:91], v[92:93] neg_lo:[0,1] neg_hi:[0,1]
	v_pk_add_f32 v[92:93], v[164:165], v[170:171] neg_lo:[0,1] neg_hi:[0,1]
	v_pk_add_f32 v[128:129], v[94:95], v[96:97]
	v_pk_add_f32 v[94:95], v[94:95], v[96:97] neg_lo:[0,1] neg_hi:[0,1]
	v_pk_add_f32 v[96:97], v[160:161], v[166:167] neg_lo:[0,1] neg_hi:[0,1]
	v_pk_add_f32 v[130:131], v[98:99], v[100:101]
	v_pk_add_f32 v[98:99], v[98:99], v[100:101] neg_lo:[0,1] neg_hi:[0,1]
	v_pk_add_f32 v[100:101], v[158:159], v[162:163] neg_lo:[0,1] neg_hi:[0,1]
	v_pk_add_f32 v[132:133], v[106:107], v[112:113]
	v_pk_add_f32 v[106:107], v[106:107], v[112:113] neg_lo:[0,1] neg_hi:[0,1]
	v_pk_add_f32 v[112:113], v[102:103], v[108:109]
	v_pk_add_f32 v[102:103], v[102:103], v[108:109] neg_lo:[0,1] neg_hi:[0,1]
	v_pk_add_f32 v[108:109], v[72:73], v[74:75]
	v_pk_add_f32 v[72:73], v[72:73], v[74:75] neg_lo:[0,1] neg_hi:[0,1]
	v_pk_add_f32 v[74:75], v[154:155], v[156:157] neg_lo:[0,1] neg_hi:[0,1]
	v_pk_add_f32 v[138:139], v[116:117], v[118:119]
	v_pk_add_f32 v[116:117], v[116:117], v[118:119] neg_lo:[0,1] neg_hi:[0,1]
	v_pk_add_f32 v[118:119], v[76:77], v[80:81]
	v_pk_add_f32 v[76:77], v[76:77], v[80:81] neg_lo:[0,1] neg_hi:[0,1]
	v_pk_add_f32 v[80:81], v[78:79], v[82:83]
	v_pk_add_f32 v[78:79], v[78:79], v[82:83] neg_lo:[0,1] neg_hi:[0,1]
	v_pk_add_f32 v[82:83], v[148:149], v[150:151] neg_lo:[0,1] neg_hi:[0,1]
	v_pk_add_f32 v[144:145], v[120:121], v[126:127]
	v_pk_add_f32 v[120:121], v[120:121], v[126:127] neg_lo:[0,1] neg_hi:[0,1]
	v_pk_add_f32 v[126:127], v[84:85], v[88:89]
	v_pk_add_f32 v[84:85], v[84:85], v[88:89] neg_lo:[0,1] neg_hi:[0,1]
	v_pk_add_f32 v[88:89], v[86:87], v[90:91]
	v_pk_add_f32 v[86:87], v[86:87], v[90:91] neg_lo:[0,1] neg_hi:[0,1]
	v_pk_add_f32 v[90:91], v[140:141], v[142:143] neg_lo:[0,1] neg_hi:[0,1]
	v_pk_add_f32 v[140:141], v[128:129], v[130:131]
	v_pk_add_f32 v[128:129], v[128:129], v[130:131] neg_lo:[0,1] neg_hi:[0,1]
	v_pk_add_f32 v[130:131], v[92:93], v[96:97]
	v_pk_add_f32 v[92:93], v[92:93], v[96:97] neg_lo:[0,1] neg_hi:[0,1]
	v_pk_add_f32 v[96:97], v[94:95], v[98:99]
	v_pk_add_f32 v[94:95], v[94:95], v[98:99] neg_lo:[0,1] neg_hi:[0,1]
	v_pk_add_f32 v[136:137], v[134:135], v[136:137] neg_lo:[0,1] neg_hi:[0,1]
	v_pk_add_f32 v[98:99], v[132:133], v[138:139]
	v_pk_add_f32 v[138:139], v[132:133], v[138:139] neg_lo:[0,1] neg_hi:[0,1]
	v_pk_add_f32 v[132:133], v[112:113], v[118:119]
	v_pk_add_f32 v[112:113], v[112:113], v[118:119] neg_lo:[0,1] neg_hi:[0,1]
	v_pk_add_f32 v[118:119], v[108:109], v[80:81]
	v_pk_add_f32 v[108:109], v[108:109], v[80:81] neg_lo:[0,1] neg_hi:[0,1]
; template <bool CENTER>
; __device__ __forceinline__ void rot_finish(const u32x4 (&w)[8], signed char* dst, LAS float* red, int tl, int half, int wv4, int lane, float& step_out, float& sum_out) {
;     ...
;     for (int i = 0; i < 32; ++i) { const float a = pr[i][0], b = pr[i][1]; pr[i] = (f32x2){a + b, a - b}; }
; #pragma unroll
;     for (int h = 1; h < 32; h <<= 1)
; #pragma unroll
;         for (int i = 0; i < 32; ++i) if (!(i & h)) { const f32x2 a = pr[i], b = pr[i + h]; pr[i] = a + b; pr[i + h] = a - b; }
;     float sm = pr[0][0];
; #pragma unroll
;     for (int o = 1; o < 64; o <<= 1) sm += __shfl_xor(sm, o);
;     float mx = 0.f;
;     if (CENTER) {
;         if (lane == 0) red[half * 4 + wv4] = sm;
;         __syncthreads();
;         sm = (red[half * 4] + red[half * 4 + 1]) + (red[half * 4 + 2] + red[half * 4 + 3]);
;         pr[0][0] -= sm * (64.0f / DFF);
;     }
; #pragma unroll
;     for (int i = 0; i < 32; ++i) mx = fmaxf(mx, fmaxf(fabsf(pr[i][0]), fabsf(pr[i][1])));
; #pragma unroll
;     for (int o = 1; o < 64; o <<= 1) mx = fmaxf(mx, __shfl_xor(mx, o));
;     if (lane == 0) { red[16 + half * 4 + wv4] = mx; if (!CENTER) red[half * 4 + wv4] = sm; }
	v_pk_add_f32 v[80:81], v[100:101], v[74:75]
	v_pk_add_f32 v[142:143], v[106:107], v[116:117]
	v_pk_add_f32 v[106:107], v[106:107], v[116:117] neg_lo:[0,1] neg_hi:[0,1]
	v_pk_add_f32 v[116:117], v[102:103], v[76:77]
	v_pk_add_f32 v[146:147], v[72:73], v[78:79]
	v_pk_add_f32 v[148:149], v[72:73], v[78:79] neg_lo:[0,1] neg_hi:[0,1]
	v_pk_add_f32 v[72:73], v[122:123], v[124:125] neg_lo:[0,1] neg_hi:[0,1]
	v_pk_add_f32 v[78:79], v[144:145], v[140:141]
	v_pk_add_f32 v[122:123], v[126:127], v[130:131]
	v_pk_add_f32 v[124:125], v[88:89], v[96:97]
	v_pk_add_f32 v[150:151], v[88:89], v[96:97] neg_lo:[0,1] neg_hi:[0,1]
	v_pk_add_f32 v[88:89], v[82:83], v[90:91]
	v_pk_add_f32 v[152:153], v[82:83], v[90:91] neg_lo:[0,1] neg_hi:[0,1]
	v_pk_add_f32 v[90:91], v[84:85], v[92:93]
	v_pk_add_f32 v[156:157], v[84:85], v[92:93] neg_lo:[0,1] neg_hi:[0,1]
	v_pk_add_f32 v[84:85], v[86:87], v[94:95]
	v_pk_add_f32 v[76:77], v[102:103], v[76:77] neg_lo:[0,1] neg_hi:[0,1]
	v_pk_add_f32 v[140:141], v[144:145], v[140:141] neg_lo:[0,1] neg_hi:[0,1]
	v_pk_add_f32 v[144:145], v[126:127], v[130:131] neg_lo:[0,1] neg_hi:[0,1]
	v_pk_add_f32 v[134:135], v[98:99], v[78:79]
	v_pk_add_f32 v[102:103], v[98:99], v[78:79] neg_lo:[0,1] neg_hi:[0,1]
	v_pk_add_f32 v[130:131], v[132:133], v[122:123]
	v_pk_add_f32 v[96:97], v[132:133], v[122:123] neg_lo:[0,1] neg_hi:[0,1]
	v_pk_add_f32 v[132:133], v[118:119], v[124:125]
	v_pk_add_f32 v[98:99], v[118:119], v[124:125] neg_lo:[0,1] neg_hi:[0,1]
	v_pk_add_f32 v[126:127], v[80:81], v[88:89]
	v_pk_add_f32 v[92:93], v[80:81], v[88:89] neg_lo:[0,1] neg_hi:[0,1]
	v_pk_add_f32 v[122:123], v[116:117], v[90:91]
	v_pk_add_f32 v[88:89], v[116:117], v[90:91] neg_lo:[0,1] neg_hi:[0,1]
	v_pk_add_f32 v[124:125], v[146:147], v[84:85]
	v_pk_add_f32 v[90:91], v[146:147], v[84:85] neg_lo:[0,1] neg_hi:[0,1]
	v_pk_add_f32 v[118:119], v[136:137], v[72:73]
	v_pk_add_f32 v[84:85], v[136:137], v[72:73] neg_lo:[0,1] neg_hi:[0,1]
	v_mov_b32_e32 v72, s35
	v_pk_add_f32 v[82:83], v[120:121], v[128:129]
	v_pk_add_f32 v[154:155], v[120:121], v[128:129] neg_lo:[0,1] neg_hi:[0,1]
	v_pk_add_f32 v[158:159], v[86:87], v[94:95] neg_lo:[0,1] neg_hi:[0,1]
	v_pk_add_f32 v[120:121], v[138:139], v[140:141]
	v_pk_add_f32 v[86:87], v[138:139], v[140:141] neg_lo:[0,1] neg_hi:[0,1]
	s_waitcnt lgkmcnt(0)
	s_barrier
	ds_read_b128 v[136:139], v72
	v_pk_add_f32 v[128:129], v[142:143], v[82:83]
	v_pk_add_f32 v[74:75], v[100:101], v[74:75] neg_lo:[0,1] neg_hi:[0,1]
	v_pk_add_f32 v[100:101], v[110:111], v[114:115] neg_lo:[0,1] neg_hi:[0,1]
	v_pk_add_f32 v[114:115], v[112:113], v[144:145]
	s_waitcnt lgkmcnt(0)
	v_add_f32_e32 v136, v136, v137
	v_add_f32_e32 v137, v138, v139
	v_add_f32_e32 v136, v136, v137
	v_fmamk_f32 v104, v136, 0xbb800000, v104
	v_max_f32_e64 v137, |v105|, |v105|
	v_max_f32_e64 v137, |v104|, v137
	v_max_f32_e64 v138, |v134|, |v135|
	v_max3_f32 v137, v137, 0, v138
	v_max_f32_e64 v138, |v130|, |v131|
	v_max_f32_e64 v139, |v132|, |v133|
	v_max3_f32 v137, v137, v138, v139
	v_max_f32_e64 v138, |v126|, |v127|
	v_max_f32_e64 v139, |v128|, |v129|
	v_max3_f32 v137, v137, v138, v139
	v_max_f32_e64 v138, |v122|, |v123|
	v_max_f32_e64 v139, |v124|, |v125|
	v_pk_add_f32 v[116:117], v[108:109], v[150:151]
	v_max3_f32 v137, v137, v138, v139
	v_max_f32_e64 v138, |v118|, |v119|
	v_max_f32_e64 v139, |v120|, |v121|
	v_pk_add_f32 v[94:95], v[142:143], v[82:83] neg_lo:[0,1] neg_hi:[0,1]
	v_pk_add_f32 v[80:81], v[112:113], v[144:145] neg_lo:[0,1] neg_hi:[0,1]
	v_pk_add_f32 v[82:83], v[108:109], v[150:151] neg_lo:[0,1] neg_hi:[0,1]
	v_pk_add_f32 v[108:109], v[74:75], v[152:153]
	v_pk_add_f32 v[112:113], v[106:107], v[154:155]
	v_max3_f32 v137, v137, v138, v139
	v_max_f32_e64 v138, |v114|, |v115|
	v_max_f32_e64 v139, |v116|, |v117|
	v_pk_add_f32 v[78:79], v[106:107], v[154:155] neg_lo:[0,1] neg_hi:[0,1]
	v_pk_add_f32 v[106:107], v[76:77], v[156:157]
	v_pk_add_f32 v[110:111], v[148:149], v[158:159]
	v_max3_f32 v137, v137, v138, v139
	v_max_f32_e64 v138, |v108|, |v109|
	v_max_f32_e64 v139, |v112|, |v113|
	v_max3_f32 v137, v137, v138, v139
	v_max_f32_e64 v138, |v106|, |v107|
	v_max_f32_e64 v139, |v110|, |v111|
	v_max3_f32 v137, v137, v138, v139
	v_max_f32_e64 v138, |v100|, |v101|
	v_max_f32_e64 v139, |v102|, |v103|
	v_max3_f32 v137, v137, v138, v139
	v_max_f32_e64 v138, |v96|, |v97|
	v_max_f32_e64 v139, |v98|, |v99|
	v_max3_f32 v137, v137, v138, v139
	v_max_f32_e64 v138, |v92|, |v93|
	v_max_f32_e64 v139, |v94|, |v95|
	v_max3_f32 v137, v137, v138, v139
	v_max_f32_e64 v138, |v88|, |v89|
	v_max_f32_e64 v139, |v90|, |v91|
	v_max3_f32 v137, v137, v138, v139
	v_max_f32_e64 v138, |v84|, |v85|
	v_max_f32_e64 v139, |v86|, |v87|
	v_pk_add_f32 v[74:75], v[74:75], v[152:153] neg_lo:[0,1] neg_hi:[0,1]
	v_max3_f32 v137, v137, v138, v139
	v_max_f32_e64 v138, |v80|, |v81|
	v_max_f32_e64 v139, |v82|, |v83|
	v_pk_add_f32 v[72:73], v[76:77], v[156:157] neg_lo:[0,1] neg_hi:[0,1]
	v_pk_add_f32 v[76:77], v[148:149], v[158:159] neg_lo:[0,1] neg_hi:[0,1]
	v_max3_f32 v137, v137, v138, v139
	v_max_f32_e64 v138, |v74|, |v75|
	v_max_f32_e64 v139, |v78|, |v79|
	v_max3_f32 v137, v137, v138, v139
	v_max_f32_e64 v138, |v72|, |v73|
	v_max_f32_e64 v139, |v76|, |v77|
	v_max3_f32 v137, v137, v138, v139
	s_nop 1
	v_mov_b32_dpp v138, v137 quad_perm:[1,0,3,2] row_mask:0xf bank_mask:0xf
	s_waitcnt lgkmcnt(0)
	v_max_f32_e32 v138, v138, v138
	v_max_f32_e32 v137, v137, v138
	s_nop 1
	v_mov_b32_dpp v138, v137 quad_perm:[2,3,0,1] row_mask:0xf bank_mask:0xf
	s_waitcnt lgkmcnt(0)
	v_max_f32_e32 v138, v138, v138
	v_max_f32_e32 v137, v137, v138
	s_nop 1
	v_mov_b32_dpp v138, v137 row_half_mirror row_mask:0xf bank_mask:0xf
	s_waitcnt lgkmcnt(0)
	v_max_f32_e32 v138, v138, v138
	v_max_f32_e32 v137, v137, v138
	s_nop 1
	v_mov_b32_dpp v138, v137 row_mirror row_mask:0xf bank_mask:0xf
	s_waitcnt lgkmcnt(0)
	v_max_f32_e32 v138, v138, v138
	v_max_f32_e32 v137, v137, v138
	s_waitcnt lgkmcnt(0)
	v_mov_b32_e32 v138, v137
	s_nop 1
	v_permlane16_swap_b32_e32 v137, v138
	s_nop 0
	v_max_f32_e32 v137, v137, v138
	ds_bpermute_b32 v138, v204, v137
	s_and_saveexec_b64 s[24:25], s[4:5]
	s_cbranch_execz .LBB0_1546
	s_waitcnt lgkmcnt(0)
	v_max_f32_e32 v138, v138, v138
	v_max_f32_e32 v137, v137, v137
	v_max_f32_e32 v137, v137, v138
	v_mov_b32_e32 v138, s36
	ds_write_b32 v138, v137 offset:64

; __device__ __forceinline__ float bflo(unsigned w) { return __uint_as_float(w << 16); }
; __device__ __forceinline__ float bfhi(unsigned w) { return __uint_as_float(w & 0xffff0000u); }
; template <bool CENTER>
; __device__ __forceinline__ void rot_finish(const u32x4 (&w)[8], signed char* dst, LAS float* red, int tl, int half, int wv4, int lane, float& step_out, float& sum_out) {
;     ...
;     for (int j = 0; j < 8; ++j) { pr[4 * j] = (f32x2){bflo(w[j].x), bfhi(w[j].x)}; pr[4 * j + 1] = (f32x2){bflo(w[j].y), bfhi(w[j].y)}; pr[4 * j + 2] = (f32x2){bflo(w[j].z), bfhi(w[j].z)}; pr[4 * j + 3] = (f32x2){bflo(w[j].w), bfhi(w[j].w)}; }
; #pragma unroll
;     for (int i = 0; i < 32; ++i) { const float a = pr[i][0], b = pr[i][1]; pr[i] = (f32x2){a + b, a - b}; }
; #pragma unroll
;     for (int h = 1; h < 32; h <<= 1)
; #pragma unroll
;         for (int i = 0; i < 32; ++i) if (!(i & h)) { const f32x2 a = pr[i], b = pr[i + h]; pr[i] = a + b; pr[i + h] = a - b; }
;     float sm = pr[0][0];
; #pragma unroll
;     for (int o = 1; o < 64; o <<= 1) sm += __shfl_xor(sm, o);
.LBB0_1550:
	s_waitcnt vmcnt(5)
	v_lshlrev_b32_e32 v72, 16, v36
	v_and_b32_e32 v73, 0xffff0000, v36
	v_lshlrev_b32_e32 v74, 16, v37
	v_and_b32_e32 v75, 0xffff0000, v37
	v_add_f32_e32 v36, v72, v73
	v_sub_f32_e32 v37, v72, v73
	v_lshlrev_b32_e32 v72, 16, v35
	v_and_b32_e32 v35, 0xffff0000, v35
	v_lshlrev_b32_e32 v76, 16, v62
	v_and_b32_e32 v62, 0xffff0000, v62
	v_lshlrev_b32_e32 v77, 16, v63
	v_and_b32_e32 v63, 0xffff0000, v63
	v_lshlrev_b32_e32 v78, 16, v64
	v_and_b32_e32 v64, 0xffff0000, v64
	v_lshlrev_b32_e32 v79, 16, v65
	v_and_b32_e32 v65, 0xffff0000, v65
	v_lshlrev_b32_e32 v80, 16, v58
	v_and_b32_e32 v58, 0xffff0000, v58
	v_lshlrev_b32_e32 v81, 16, v59
	v_and_b32_e32 v59, 0xffff0000, v59
	v_lshlrev_b32_e32 v82, 16, v60
	v_and_b32_e32 v60, 0xffff0000, v60
	v_lshlrev_b32_e32 v83, 16, v61
	v_and_b32_e32 v61, 0xffff0000, v61
	v_lshlrev_b32_e32 v84, 16, v54
	v_and_b32_e32 v85, 0xffff0000, v54
	v_lshlrev_b32_e32 v86, 16, v55
	v_and_b32_e32 v87, 0xffff0000, v55
	v_lshlrev_b32_e32 v88, 16, v56
	v_and_b32_e32 v89, 0xffff0000, v56
	v_lshlrev_b32_e32 v90, 16, v57
	v_and_b32_e32 v91, 0xffff0000, v57
	v_lshlrev_b32_e32 v92, 16, v50
	v_and_b32_e32 v93, 0xffff0000, v50
	v_lshlrev_b32_e32 v94, 16, v51
	v_and_b32_e32 v95, 0xffff0000, v51
	v_lshlrev_b32_e32 v96, 16, v52
	v_and_b32_e32 v97, 0xffff0000, v52
	v_lshlrev_b32_e32 v98, 16, v53
	v_and_b32_e32 v99, 0xffff0000, v53
	v_lshlrev_b32_e32 v100, 16, v46
	v_and_b32_e32 v101, 0xffff0000, v46
	v_lshlrev_b32_e32 v102, 16, v47
	v_and_b32_e32 v103, 0xffff0000, v47
	v_lshlrev_b32_e32 v104, 16, v48
	v_and_b32_e32 v105, 0xffff0000, v48
	v_lshlrev_b32_e32 v106, 16, v49
	v_and_b32_e32 v107, 0xffff0000, v49
	v_lshlrev_b32_e32 v108, 16, v42
	v_and_b32_e32 v109, 0xffff0000, v42
	v_lshlrev_b32_e32 v110, 16, v43
	v_and_b32_e32 v111, 0xffff0000, v43
	v_lshlrev_b32_e32 v112, 16, v44
	v_and_b32_e32 v113, 0xffff0000, v44
	v_lshlrev_b32_e32 v114, 16, v45
	v_and_b32_e32 v115, 0xffff0000, v45
	s_waitcnt vmcnt(4)
	v_lshlrev_b32_e32 v116, 16, v38
	v_and_b32_e32 v117, 0xffff0000, v38
	v_lshlrev_b32_e32 v118, 16, v39
	v_and_b32_e32 v119, 0xffff0000, v39
	v_lshlrev_b32_e32 v120, 16, v40
	v_and_b32_e32 v121, 0xffff0000, v40
	v_lshlrev_b32_e32 v122, 16, v41
	v_and_b32_e32 v123, 0xffff0000, v41
	v_add_f32_e32 v162, v72, v35
	v_sub_f32_e32 v163, v72, v35
	v_lshlrev_b32_e32 v35, 16, v34
	v_and_b32_e32 v34, 0xffff0000, v34
	v_add_f32_e32 v38, v74, v75
	v_sub_f32_e32 v39, v74, v75
	v_add_f32_e32 v40, v76, v62
	v_sub_f32_e32 v41, v76, v62
	v_add_f32_e32 v42, v77, v63
	v_sub_f32_e32 v43, v77, v63
	v_add_f32_e32 v44, v78, v64
	v_sub_f32_e32 v45, v78, v64
	v_add_f32_e32 v46, v79, v65
	v_sub_f32_e32 v47, v79, v65
	v_add_f32_e32 v48, v80, v58
	v_sub_f32_e32 v49, v80, v58
	v_add_f32_e32 v50, v81, v59
	v_sub_f32_e32 v51, v81, v59
	v_add_f32_e32 v52, v82, v60
	v_sub_f32_e32 v53, v82, v60
	v_add_f32_e32 v54, v83, v61
	v_sub_f32_e32 v55, v83, v61
	v_add_f32_e32 v56, v84, v85
	v_sub_f32_e32 v57, v84, v85
	v_add_f32_e32 v58, v86, v87
	v_sub_f32_e32 v59, v86, v87
	v_add_f32_e32 v60, v88, v89
	v_sub_f32_e32 v61, v88, v89
	v_add_f32_e32 v62, v90, v91
	v_sub_f32_e32 v63, v90, v91
	v_add_f32_e32 v64, v92, v93
	v_sub_f32_e32 v65, v92, v93
	v_add_f32_e32 v74, v94, v95
	v_sub_f32_e32 v75, v94, v95
	v_add_f32_e32 v76, v96, v97
	v_sub_f32_e32 v77, v96, v97
	v_add_f32_e32 v78, v98, v99
	v_sub_f32_e32 v79, v98, v99
	v_add_f32_e32 v80, v100, v101
	v_sub_f32_e32 v81, v100, v101
	v_add_f32_e32 v84, v102, v103
	v_sub_f32_e32 v85, v102, v103
	v_add_f32_e32 v86, v104, v105
	v_sub_f32_e32 v87, v104, v105
	v_add_f32_e32 v88, v106, v107
	v_sub_f32_e32 v89, v106, v107
	v_add_f32_e32 v94, v108, v109
	v_sub_f32_e32 v95, v108, v109
	v_add_f32_e32 v96, v110, v111
	v_sub_f32_e32 v97, v110, v111
	v_add_f32_e32 v98, v112, v113
	v_sub_f32_e32 v99, v112, v113
	v_add_f32_e32 v100, v114, v115
	v_sub_f32_e32 v101, v114, v115
	v_add_f32_e32 v106, v116, v117
	v_sub_f32_e32 v107, v116, v117
	v_add_f32_e32 v112, v118, v119
	v_sub_f32_e32 v113, v118, v119
	v_add_f32_e32 v114, v120, v121
	v_sub_f32_e32 v115, v120, v121
	v_add_f32_e32 v120, v122, v123
	v_sub_f32_e32 v121, v122, v123
	v_add_f32_e32 v164, v35, v34
	v_sub_f32_e32 v165, v35, v34
	v_pk_add_f32 v[156:157], v[164:165], v[162:163]
	v_pk_add_f32 v[160:161], v[36:37], v[38:39]
	v_pk_add_f32 v[152:153], v[40:41], v[42:43]
	v_pk_add_f32 v[158:159], v[44:45], v[46:47]
	v_pk_add_f32 v[148:149], v[48:49], v[50:51]
	v_pk_add_f32 v[154:155], v[52:53], v[54:55]
	v_pk_add_f32 v[144:145], v[56:57], v[58:59]
	v_pk_add_f32 v[150:151], v[60:61], v[62:63]
	v_pk_add_f32 v[140:141], v[64:65], v[74:75]
	v_pk_add_f32 v[146:147], v[76:77], v[78:79]
	v_pk_add_f32 v[136:137], v[80:81], v[84:85]
	v_pk_add_f32 v[142:143], v[86:87], v[88:89]
	v_pk_add_f32 v[132:133], v[94:95], v[96:97]
	v_pk_add_f32 v[138:139], v[98:99], v[100:101]
	v_pk_add_f32 v[128:129], v[106:107], v[112:113]
	v_pk_add_f32 v[134:135], v[114:115], v[120:121]
	v_pk_add_f32 v[126:127], v[156:157], v[160:161]
	v_pk_add_f32 v[130:131], v[152:153], v[158:159]
	v_pk_add_f32 v[122:123], v[148:149], v[154:155]
	v_pk_add_f32 v[124:125], v[144:145], v[150:151]
	v_pk_add_f32 v[116:117], v[140:141], v[146:147]
	v_pk_add_f32 v[118:119], v[136:137], v[142:143]
	v_pk_add_f32 v[108:109], v[132:133], v[138:139]
	v_pk_add_f32 v[110:111], v[128:129], v[134:135]
	v_pk_add_f32 v[102:103], v[126:127], v[130:131]
	v_pk_add_f32 v[104:105], v[122:123], v[124:125]
	v_pk_add_f32 v[90:91], v[116:117], v[118:119]
	v_pk_add_f32 v[92:93], v[108:109], v[110:111]
	v_pk_add_f32 v[34:35], v[102:103], v[104:105]
	v_pk_add_f32 v[82:83], v[90:91], v[92:93]
	s_nop 0
	v_pk_add_f32 v[72:73], v[34:35], v[82:83]
	s_nop 1
	v_mov_b32_dpp v166, v72 quad_perm:[1,0,3,2] row_mask:0xf bank_mask:0xf
	s_waitcnt lgkmcnt(0)
	v_add_f32_e32 v166, v72, v166
	s_nop 1
	v_mov_b32_dpp v167, v166 quad_perm:[2,3,0,1] row_mask:0xf bank_mask:0xf
	s_waitcnt lgkmcnt(0)
	v_add_f32_e32 v166, v166, v167
	s_nop 1
	v_mov_b32_dpp v167, v166 row_half_mirror row_mask:0xf bank_mask:0xf
	s_waitcnt lgkmcnt(0)
	v_add_f32_e32 v166, v166, v167
	s_nop 1
	v_mov_b32_dpp v167, v166 row_mirror row_mask:0xf bank_mask:0xf
	s_waitcnt lgkmcnt(0)
	v_add_f32_e32 v166, v166, v167
	s_waitcnt lgkmcnt(0)
	v_mov_b32_e32 v167, v166
	s_nop 1
	v_permlane16_swap_b32_e32 v166, v167
	s_nop 0
	v_add_f32_e32 v166, v166, v167
	ds_bpermute_b32 v167, v204, v166
	s_and_saveexec_b64 s[26:27], s[4:5]
	s_cbranch_execz .LBB0_1552
	s_add_i32 s9, s33, s34
	s_waitcnt lgkmcnt(0)
	v_add_f32_e32 v166, v166, v167
	v_mov_b32_e32 v167, s9
	ds_write_b32 v167, v166
; template <bool CENTER>
; __device__ __forceinline__ void rot_finish(const u32x4 (&w)[8], signed char* dst, LAS float* red, int tl, int half, int wv4, int lane, float& step_out, float& sum_out) {
;     ...
;     for (int i = 0; i < 32; ++i) { const float a = pr[i][0], b = pr[i][1]; pr[i] = (f32x2){a + b, a - b}; }
; #pragma unroll
;     for (int h = 1; h < 32; h <<= 1)
; #pragma unroll
;         for (int i = 0; i < 32; ++i) if (!(i & h)) { const f32x2 a = pr[i], b = pr[i + h]; pr[i] = a + b; pr[i + h] = a - b; }
.LBB0_1552:
	s_or_b64 exec, exec, s[26:27]
	v_pk_add_f32 v[162:163], v[164:165], v[162:163] neg_lo:[0,1] neg_hi:[0,1]
	v_pk_add_f32 v[36:37], v[36:37], v[38:39] neg_lo:[0,1] neg_hi:[0,1]
	v_pk_add_f32 v[38:39], v[40:41], v[42:43] neg_lo:[0,1] neg_hi:[0,1]
	v_pk_add_f32 v[40:41], v[44:45], v[46:47] neg_lo:[0,1] neg_hi:[0,1]
	v_pk_add_f32 v[42:43], v[48:49], v[50:51] neg_lo:[0,1] neg_hi:[0,1]
	v_pk_add_f32 v[44:45], v[52:53], v[54:55] neg_lo:[0,1] neg_hi:[0,1]
	v_pk_add_f32 v[46:47], v[56:57], v[58:59] neg_lo:[0,1] neg_hi:[0,1]
	v_pk_add_f32 v[48:49], v[60:61], v[62:63] neg_lo:[0,1] neg_hi:[0,1]
	v_pk_add_f32 v[50:51], v[64:65], v[74:75] neg_lo:[0,1] neg_hi:[0,1]
	v_pk_add_f32 v[52:53], v[76:77], v[78:79] neg_lo:[0,1] neg_hi:[0,1]
	v_pk_add_f32 v[54:55], v[80:81], v[84:85] neg_lo:[0,1] neg_hi:[0,1]
	v_pk_add_f32 v[56:57], v[86:87], v[88:89] neg_lo:[0,1] neg_hi:[0,1]
	v_pk_add_f32 v[58:59], v[94:95], v[96:97] neg_lo:[0,1] neg_hi:[0,1]
	v_pk_add_f32 v[60:61], v[98:99], v[100:101] neg_lo:[0,1] neg_hi:[0,1]
	v_pk_add_f32 v[62:63], v[106:107], v[112:113] neg_lo:[0,1] neg_hi:[0,1]
	v_pk_add_f32 v[64:65], v[114:115], v[120:121] neg_lo:[0,1] neg_hi:[0,1]
	v_pk_add_f32 v[74:75], v[156:157], v[160:161] neg_lo:[0,1] neg_hi:[0,1]
	v_pk_add_f32 v[76:77], v[162:163], v[36:37]
	v_pk_add_f32 v[36:37], v[162:163], v[36:37] neg_lo:[0,1] neg_hi:[0,1]
	v_pk_add_f32 v[78:79], v[152:153], v[158:159] neg_lo:[0,1] neg_hi:[0,1]
	v_pk_add_f32 v[80:81], v[38:39], v[40:41]
	v_pk_add_f32 v[38:39], v[38:39], v[40:41] neg_lo:[0,1] neg_hi:[0,1]
	v_pk_add_f32 v[40:41], v[148:149], v[154:155] neg_lo:[0,1] neg_hi:[0,1]
	v_pk_add_f32 v[84:85], v[42:43], v[44:45]
	v_pk_add_f32 v[42:43], v[42:43], v[44:45] neg_lo:[0,1] neg_hi:[0,1]
	v_pk_add_f32 v[44:45], v[144:145], v[150:151] neg_lo:[0,1] neg_hi:[0,1]
	v_pk_add_f32 v[86:87], v[46:47], v[48:49]
	v_pk_add_f32 v[46:47], v[46:47], v[48:49] neg_lo:[0,1] neg_hi:[0,1]
	v_pk_add_f32 v[48:49], v[140:141], v[146:147] neg_lo:[0,1] neg_hi:[0,1]
	v_pk_add_f32 v[88:89], v[50:51], v[52:53]
	v_pk_add_f32 v[50:51], v[50:51], v[52:53] neg_lo:[0,1] neg_hi:[0,1]
	v_pk_add_f32 v[52:53], v[136:137], v[142:143] neg_lo:[0,1] neg_hi:[0,1]
	v_pk_add_f32 v[94:95], v[54:55], v[56:57]
	v_pk_add_f32 v[54:55], v[54:55], v[56:57] neg_lo:[0,1] neg_hi:[0,1]
	v_pk_add_f32 v[56:57], v[132:133], v[138:139] neg_lo:[0,1] neg_hi:[0,1]
	v_pk_add_f32 v[96:97], v[58:59], v[60:61]
	v_pk_add_f32 v[58:59], v[58:59], v[60:61] neg_lo:[0,1] neg_hi:[0,1]
	v_pk_add_f32 v[60:61], v[128:129], v[134:135] neg_lo:[0,1] neg_hi:[0,1]
	v_pk_add_f32 v[98:99], v[62:63], v[64:65]
	v_pk_add_f32 v[62:63], v[62:63], v[64:65] neg_lo:[0,1] neg_hi:[0,1]
	v_pk_add_f32 v[64:65], v[126:127], v[130:131] neg_lo:[0,1] neg_hi:[0,1]
	v_pk_add_f32 v[100:101], v[76:77], v[80:81]
	v_pk_add_f32 v[76:77], v[76:77], v[80:81] neg_lo:[0,1] neg_hi:[0,1]
	v_pk_add_f32 v[80:81], v[74:75], v[78:79]
	v_pk_add_f32 v[74:75], v[74:75], v[78:79] neg_lo:[0,1] neg_hi:[0,1]
	v_pk_add_f32 v[78:79], v[36:37], v[38:39]
	v_pk_add_f32 v[36:37], v[36:37], v[38:39] neg_lo:[0,1] neg_hi:[0,1]
	v_pk_add_f32 v[38:39], v[122:123], v[124:125] neg_lo:[0,1] neg_hi:[0,1]
	v_pk_add_f32 v[106:107], v[84:85], v[86:87]
	v_pk_add_f32 v[84:85], v[84:85], v[86:87] neg_lo:[0,1] neg_hi:[0,1]
	v_pk_add_f32 v[86:87], v[40:41], v[44:45]
	v_pk_add_f32 v[40:41], v[40:41], v[44:45] neg_lo:[0,1] neg_hi:[0,1]
	v_pk_add_f32 v[44:45], v[42:43], v[46:47]
	v_pk_add_f32 v[42:43], v[42:43], v[46:47] neg_lo:[0,1] neg_hi:[0,1]
	v_pk_add_f32 v[46:47], v[116:117], v[118:119] neg_lo:[0,1] neg_hi:[0,1]
	v_pk_add_f32 v[112:113], v[88:89], v[94:95]
	v_pk_add_f32 v[88:89], v[88:89], v[94:95] neg_lo:[0,1] neg_hi:[0,1]
	v_pk_add_f32 v[94:95], v[48:49], v[52:53]
	v_pk_add_f32 v[48:49], v[48:49], v[52:53] neg_lo:[0,1] neg_hi:[0,1]
	v_pk_add_f32 v[52:53], v[50:51], v[54:55]
	v_pk_add_f32 v[50:51], v[50:51], v[54:55] neg_lo:[0,1] neg_hi:[0,1]
	v_pk_add_f32 v[54:55], v[108:109], v[110:111] neg_lo:[0,1] neg_hi:[0,1]
	v_pk_add_f32 v[108:109], v[96:97], v[98:99]
	v_pk_add_f32 v[96:97], v[96:97], v[98:99] neg_lo:[0,1] neg_hi:[0,1]
	v_pk_add_f32 v[98:99], v[56:57], v[60:61]
	v_pk_add_f32 v[56:57], v[56:57], v[60:61] neg_lo:[0,1] neg_hi:[0,1]
	v_pk_add_f32 v[60:61], v[58:59], v[62:63]
	v_pk_add_f32 v[58:59], v[58:59], v[62:63] neg_lo:[0,1] neg_hi:[0,1]
	v_pk_add_f32 v[104:105], v[102:103], v[104:105] neg_lo:[0,1] neg_hi:[0,1]
	v_pk_add_f32 v[110:111], v[100:101], v[106:107]
	v_pk_add_f32 v[106:107], v[100:101], v[106:107] neg_lo:[0,1] neg_hi:[0,1]
	v_pk_add_f32 v[100:101], v[80:81], v[86:87]
	v_pk_add_f32 v[80:81], v[80:81], v[86:87] neg_lo:[0,1] neg_hi:[0,1]
	v_pk_add_f32 v[86:87], v[78:79], v[44:45]
	v_pk_add_f32 v[44:45], v[78:79], v[44:45] neg_lo:[0,1] neg_hi:[0,1]
	v_pk_add_f32 v[78:79], v[64:65], v[38:39]
	v_pk_add_f32 v[114:115], v[76:77], v[84:85]
	v_pk_add_f32 v[116:117], v[76:77], v[84:85] neg_lo:[0,1] neg_hi:[0,1]
	v_pk_add_f32 v[76:77], v[74:75], v[40:41]
	v_pk_add_f32 v[118:119], v[74:75], v[40:41] neg_lo:[0,1] neg_hi:[0,1]
	v_pk_add_f32 v[40:41], v[36:37], v[42:43]
	v_pk_add_f32 v[120:121], v[36:37], v[42:43] neg_lo:[0,1] neg_hi:[0,1]
	v_pk_add_f32 v[36:37], v[90:91], v[92:93] neg_lo:[0,1] neg_hi:[0,1]
	v_pk_add_f32 v[42:43], v[112:113], v[108:109]
	v_pk_add_f32 v[74:75], v[112:113], v[108:109] neg_lo:[0,1] neg_hi:[0,1]
	v_pk_add_f32 v[84:85], v[94:95], v[98:99]
	v_pk_add_f32 v[90:91], v[52:53], v[60:61]
	v_pk_add_f32 v[112:113], v[52:53], v[60:61] neg_lo:[0,1] neg_hi:[0,1]
	v_pk_add_f32 v[52:53], v[46:47], v[54:55]
	v_pk_add_f32 v[122:123], v[46:47], v[54:55] neg_lo:[0,1] neg_hi:[0,1]
	v_pk_add_f32 v[46:47], v[88:89], v[96:97]
	v_pk_add_f32 v[124:125], v[88:89], v[96:97] neg_lo:[0,1] neg_hi:[0,1]
	v_pk_add_f32 v[88:89], v[48:49], v[56:57]
	v_pk_add_f32 v[126:127], v[48:49], v[56:57] neg_lo:[0,1] neg_hi:[0,1]
	v_pk_add_f32 v[48:49], v[50:51], v[58:59]
	v_pk_add_f32 v[62:63], v[34:35], v[82:83] neg_lo:[0,1] neg_hi:[0,1]
	v_mov_b32_e32 v34, s35
	v_pk_add_f32 v[108:109], v[94:95], v[98:99] neg_lo:[0,1] neg_hi:[0,1]
	v_pk_add_f32 v[128:129], v[50:51], v[58:59] neg_lo:[0,1] neg_hi:[0,1]
	v_pk_add_f32 v[98:99], v[100:101], v[84:85]
	v_pk_add_f32 v[58:59], v[100:101], v[84:85] neg_lo:[0,1] neg_hi:[0,1]
	v_pk_add_f32 v[100:101], v[86:87], v[90:91]
	v_pk_add_f32 v[60:61], v[86:87], v[90:91] neg_lo:[0,1] neg_hi:[0,1]
	v_pk_add_f32 v[94:95], v[78:79], v[52:53]
	v_pk_add_f32 v[54:55], v[78:79], v[52:53] neg_lo:[0,1] neg_hi:[0,1]
	v_pk_add_f32 v[96:97], v[114:115], v[46:47]
	v_pk_add_f32 v[56:57], v[114:115], v[46:47] neg_lo:[0,1] neg_hi:[0,1]
	v_pk_add_f32 v[90:91], v[76:77], v[88:89]
	v_pk_add_f32 v[50:51], v[76:77], v[88:89] neg_lo:[0,1] neg_hi:[0,1]
	v_pk_add_f32 v[92:93], v[40:41], v[48:49]
	v_pk_add_f32 v[52:53], v[40:41], v[48:49] neg_lo:[0,1] neg_hi:[0,1]
	v_pk_add_f32 v[86:87], v[104:105], v[36:37]
	v_pk_add_f32 v[46:47], v[104:105], v[36:37] neg_lo:[0,1] neg_hi:[0,1]
	v_pk_add_f32 v[88:89], v[106:107], v[74:75]
	v_pk_add_f32 v[48:49], v[106:107], v[74:75] neg_lo:[0,1] neg_hi:[0,1]
	s_waitcnt lgkmcnt(0)
	s_barrier
; template <bool CENTER>
; __device__ __forceinline__ void rot_finish(const u32x4 (&w)[8], signed char* dst, LAS float* red, int tl, int half, int wv4, int lane, float& step_out, float& sum_out) {
;     ...
;     if (CENTER) {
;         if (lane == 0) red[half * 4 + wv4] = sm;
;         __syncthreads();
;         sm = (red[half * 4] + red[half * 4 + 1]) + (red[half * 4 + 2] + red[half * 4 + 3]);
;         pr[0][0] -= sm * (64.0f / DFF);
;     }
; #pragma unroll
;     for (int i = 0; i < 32; ++i) mx = fmaxf(mx, fmaxf(fabsf(pr[i][0]), fabsf(pr[i][1])));
; #pragma unroll
;     for (int o = 1; o < 64; o <<= 1) mx = fmaxf(mx, __shfl_xor(mx, o));
;     if (lane == 0) { red[16 + half * 4 + wv4] = mx; if (!CENTER) red[half * 4 + wv4] = sm; }
	ds_read_b128 v[104:107], v34
	v_pk_add_f32 v[102:103], v[110:111], v[42:43]
	v_pk_add_f32 v[38:39], v[64:65], v[38:39] neg_lo:[0,1] neg_hi:[0,1]
	v_pk_add_f32 v[82:83], v[80:81], v[108:109]
	v_pk_add_f32 v[84:85], v[44:45], v[112:113]
	s_waitcnt lgkmcnt(0)
	v_add_f32_e32 v104, v104, v105
	v_add_f32_e32 v105, v106, v107
	v_add_f32_e32 v104, v104, v105
	v_fmamk_f32 v72, v104, 0xbb800000, v72
	v_max_f32_e64 v105, |v73|, |v73|
	v_max_f32_e64 v105, |v72|, v105
	v_max_f32_e64 v106, |v102|, |v103|
	v_max3_f32 v105, v105, 0, v106
	v_max_f32_e64 v106, |v98|, |v99|
	v_max_f32_e64 v107, |v100|, |v101|
	v_max3_f32 v105, v105, v106, v107
	v_max_f32_e64 v106, |v94|, |v95|
	v_max_f32_e64 v107, |v96|, |v97|
	v_max3_f32 v105, v105, v106, v107
	v_max_f32_e64 v106, |v90|, |v91|
	v_max_f32_e64 v107, |v92|, |v93|
	v_max3_f32 v105, v105, v106, v107
	v_max_f32_e64 v106, |v86|, |v87|
	v_max_f32_e64 v107, |v88|, |v89|
	v_pk_add_f32 v[64:65], v[110:111], v[42:43] neg_lo:[0,1] neg_hi:[0,1]
	v_pk_add_f32 v[42:43], v[80:81], v[108:109] neg_lo:[0,1] neg_hi:[0,1]
	v_pk_add_f32 v[76:77], v[38:39], v[122:123]
	v_pk_add_f32 v[80:81], v[116:117], v[124:125]
	v_max3_f32 v105, v105, v106, v107
	v_max_f32_e64 v106, |v82|, |v83|
	v_max_f32_e64 v107, |v84|, |v85|
	v_pk_add_f32 v[74:75], v[118:119], v[126:127]
	v_pk_add_f32 v[78:79], v[120:121], v[128:129]
	v_max3_f32 v105, v105, v106, v107
	v_max_f32_e64 v106, |v76|, |v77|
	v_max_f32_e64 v107, |v80|, |v81|
	v_max3_f32 v105, v105, v106, v107
	v_max_f32_e64 v106, |v74|, |v75|
	v_max_f32_e64 v107, |v78|, |v79|
	v_max3_f32 v105, v105, v106, v107
	v_max_f32_e64 v106, |v62|, |v63|
	v_max_f32_e64 v107, |v64|, |v65|
	v_max3_f32 v105, v105, v106, v107
	v_max_f32_e64 v106, |v58|, |v59|
	v_max_f32_e64 v107, |v60|, |v61|
	v_max3_f32 v105, v105, v106, v107
	v_max_f32_e64 v106, |v54|, |v55|
	v_max_f32_e64 v107, |v56|, |v57|
	v_max3_f32 v105, v105, v106, v107
	v_max_f32_e64 v106, |v50|, |v51|
	v_max_f32_e64 v107, |v52|, |v53|
	v_pk_add_f32 v[44:45], v[44:45], v[112:113] neg_lo:[0,1] neg_hi:[0,1]
	v_max3_f32 v105, v105, v106, v107
	v_max_f32_e64 v106, |v46|, |v47|
	v_max_f32_e64 v107, |v48|, |v49|
	v_pk_add_f32 v[36:37], v[38:39], v[122:123] neg_lo:[0,1] neg_hi:[0,1]
	v_pk_add_f32 v[40:41], v[116:117], v[124:125] neg_lo:[0,1] neg_hi:[0,1]
	v_max3_f32 v105, v105, v106, v107
	v_max_f32_e64 v106, |v42|, |v43|
	v_max_f32_e64 v107, |v44|, |v45|
	v_pk_add_f32 v[34:35], v[118:119], v[126:127] neg_lo:[0,1] neg_hi:[0,1]
	v_pk_add_f32 v[38:39], v[120:121], v[128:129] neg_lo:[0,1] neg_hi:[0,1]
	v_max3_f32 v105, v105, v106, v107
	v_max_f32_e64 v106, |v36|, |v37|
	v_max_f32_e64 v107, |v40|, |v41|
	v_max3_f32 v105, v105, v106, v107
	v_max_f32_e64 v106, |v34|, |v35|
	v_max_f32_e64 v107, |v38|, |v39|
	v_max3_f32 v105, v105, v106, v107
	s_nop 1
	v_mov_b32_dpp v106, v105 quad_perm:[1,0,3,2] row_mask:0xf bank_mask:0xf
	s_waitcnt lgkmcnt(0)
	v_max_f32_e32 v106, v106, v106
	v_max_f32_e32 v105, v105, v106
	s_nop 1
	v_mov_b32_dpp v106, v105 quad_perm:[2,3,0,1] row_mask:0xf bank_mask:0xf
	s_waitcnt lgkmcnt(0)
	v_max_f32_e32 v106, v106, v106
	v_max_f32_e32 v105, v105, v106
	s_nop 1
	v_mov_b32_dpp v106, v105 row_half_mirror row_mask:0xf bank_mask:0xf
	s_waitcnt lgkmcnt(0)
	v_max_f32_e32 v106, v106, v106
	v_max_f32_e32 v105, v105, v106
	s_nop 1
	v_mov_b32_dpp v106, v105 row_mirror row_mask:0xf bank_mask:0xf
	s_waitcnt lgkmcnt(0)
	v_max_f32_e32 v106, v106, v106
	v_max_f32_e32 v105, v105, v106
	s_waitcnt lgkmcnt(0)
	v_mov_b32_e32 v106, v105
	s_nop 1
	v_permlane16_swap_b32_e32 v105, v106
	s_nop 0
	v_max_f32_e32 v105, v105, v106
	ds_bpermute_b32 v106, v204, v105
	s_and_saveexec_b64 s[26:27], s[4:5]
	s_cbranch_execz .LBB0_1554
	s_waitcnt lgkmcnt(0)
	v_max_f32_e32 v106, v106, v106
	v_max_f32_e32 v105, v105, v105
	v_max_f32_e32 v105, v105, v106
	v_mov_b32_e32 v106, s36
	ds_write_b32 v106, v105 offset:64

; __device__ __forceinline__ unsigned cvt_pk_bf16(float lo, float hi) { unsigned r; asm volatile("v_cvt_pk_bf16_f32 %0, %1, %2" : "=v"(r) : "v"(lo), "v"(hi)); return r; }
; __device__ __forceinline__ float bflo(unsigned w) { return __uint_as_float(w << 16); }
;     __device__ __forceinline__ void operator()(const i32x4 (&acc)[2][2][4][2], const Unit& u, int wr, int wc, int fr, int fq) const {
;     ...
;         for (int bj = 0; bj < 2; ++bj) { cs[bj][0] = *(const f32x4*)(sw + col0 + bj * HALF); cs[bj][1] = *(const f32x4*)(sw + col0 + bj * HALF + 4); cc[bj][0] = *(const f32x4*)(cw + col0 + bj * HALF); cc[bj][1] = *(const f32x4*)(cw + col0 + bj * HALF + 4); }
; #pragma unroll
;         for (int ai = 0; ai < 2; ++ai) {
;             u32x4 bw[4][2]; float rs[4], rm[4];
; #pragma unroll
;             for (int m = 0; m < 4; ++m) { rs[m] = sa[row0 + ai * HALF + m * 16]; rm[m] = mrow[row0 + ai * HALF + m * 16];
; #pragma unroll
;                 for (int bj = 0; bj < 2; ++bj) bw[m][bj] = *(const u32x4*)(base + (size_t)(row0 + ai * HALF + m * 16) * DM + col0 + bj * HALF); }
; #pragma unroll
;             for (int m = 0; m < 4; ++m) { const int row = row0 + ai * HALF + m * 16; const size_t off = (size_t)row * DM + col0; float ss = 0.f;
; #pragma unroll
;                 for (int bj = 0; bj < 2; ++bj) { const u32x4 w = bw[m][bj]; const i32x4 a0 = acc[ai][bj][m][0], a1 = acc[ai][bj][m][1];
;                     const f32x4 b0 = {bflo(w.x), bfhi(w.x), bflo(w.y), bfhi(w.y)}, b1 = {bflo(w.z), bfhi(w.z), bflo(w.w), bfhi(w.w)};
;                     const f32x4 o0 = b0 + (f32x4){(float)a0[0], (float)a0[1], (float)a0[2], (float)a0[3]} * cs[bj][0] * rs[m] + cc[bj][0] * rm[m];
;                     const f32x4 o1 = b1 + (f32x4){(float)a1[0], (float)a1[1], (float)a1[2], (float)a1[3]} * cs[bj][1] * rs[m] + cc[bj][1] * rm[m];
;                     ss += ((o0[0] * o0[0] + o0[1] * o0[1]) + (o0[2] * o0[2] + o0[3] * o0[3])) + ((o1[0] * o1[0] + o1[1] * o1[1]) + (o1[2] * o1[2] + o1[3] * o1[3]));
;                     u32x4 w2; w2.x = cvt_pk_bf16(o0[0], o0[1]); w2.y = cvt_pk_bf16(o0[2], o0[3]); w2.z = cvt_pk_bf16(o1[0], o1[1]); w2.w = cvt_pk_bf16(o1[2], o1[3]);
;                     *(u32x4*)(hout + off + bj * HALF) = w2; }
;                 ss += __shfl_xor(ss, 16); ss += __shfl_xor(ss, 32);
;                 if (fq == 0) part[(size_t)row * 64 + u.pn * 4 + wc] = ss; }
.LBB0_1637:
	v_lshl_or_b32 v194, s22, 8, v211
	v_ashrrev_i32_e32 v195, 31, v194
	v_lshl_add_u32 v202, s53, 8, v183
	v_lshlrev_b64 v[228:229], 1, v[194:195]
	v_ashrrev_i32_e32 v203, 31, v202
	v_lshlrev_b64 v[64:65], 2, v[194:195]
	v_lshl_add_u64 v[196:197], s[74:75], 0, v[228:229]
	v_lshlrev_b64 v[230:231], 13, v[202:203]
	v_lshl_add_u64 v[152:153], s[14:15], 0, v[64:65]
	v_lshl_add_u64 v[92:93], v[196:197], 0, v[230:231]
	v_lshlrev_b64 v[66:67], 2, v[202:203]
	global_load_dwordx4 v[68:71], v[152:153], off offset:16
	global_load_dwordx4 v[72:75], v[152:153], off
	global_load_dwordx4 v[232:235], v[92:93], off
	v_lshl_add_u64 v[198:199], s[0:1], 0, v[66:67]
	global_load_dword v240, v[198:199], off
	v_lshl_add_u64 v[154:155], s[16:17], 0, v[64:65]
	v_lshl_add_u64 v[200:201], s[18:19], 0, v[66:67]
	global_load_dwordx4 v[80:83], v[154:155], off
	global_load_dword v242, v[200:201], off
	global_load_dwordx4 v[76:79], v[154:155], off offset:16
	global_load_dwordx4 v[64:67], v[154:155], off offset:528
	global_load_dwordx4 v[236:239], v[92:93], off offset:256
	v_cvt_f32_i32_e32 v249, v85
	v_cvt_f32_i32_e32 v248, v84
	v_cvt_f32_i32_e32 v251, v87
	v_cvt_f32_i32_e32 v250, v86
	global_load_dwordx4 v[84:87], v[152:153], off offset:528
	global_load_dwordx4 v[92:95], v[152:153], off offset:512
	v_cvt_f32_i32_e32 v245, v89
	v_cvt_f32_i32_e32 v244, v88
	v_cvt_f32_i32_e32 v247, v91
	v_cvt_f32_i32_e32 v246, v90
	global_load_dwordx4 v[88:91], v[154:155], off offset:512
	v_or_b32_e32 v220, 16, v202
	v_or_b32_e32 v212, 32, v202
	v_or_b32_e32 v204, 48, v202
	v_ashrrev_i32_e32 v221, 31, v220
	v_ashrrev_i32_e32 v213, 31, v212
	v_ashrrev_i32_e32 v205, 31, v204
	v_lshlrev_b64 v[156:157], 2, v[220:221]
	v_lshlrev_b64 v[222:223], 13, v[220:221]
	v_lshlrev_b64 v[158:159], 2, v[212:213]
	v_lshlrev_b64 v[154:155], 2, v[204:205]
	v_lshlrev_b64 v[214:215], 13, v[212:213]
	v_lshlrev_b64 v[206:207], 13, v[204:205]
	v_lshl_add_u64 v[152:153], s[0:1], 0, v[156:157]
	v_lshl_add_u64 v[156:157], s[18:19], 0, v[156:157]
	v_lshl_add_u64 v[160:161], v[196:197], 0, v[222:223]
	v_lshl_add_u64 v[162:163], s[0:1], 0, v[158:159]
	v_lshl_add_u64 v[158:159], s[18:19], 0, v[158:159]
	v_lshl_add_u64 v[190:191], s[0:1], 0, v[154:155]
	v_lshl_add_u64 v[154:155], s[18:19], 0, v[154:155]
	v_lshl_add_u64 v[252:253], v[196:197], 0, v[214:215]
	v_lshl_add_u64 v[192:193], v[196:197], 0, v[206:207]
	global_load_dword v226, v[152:153], off
	global_load_dword v224, v[156:157], off
	global_load_dwordx4 v[172:175], v[160:161], off
	global_load_dwordx4 v[168:171], v[160:161], off offset:256
	global_load_dword v218, v[162:163], off
	global_load_dword v216, v[158:159], off
	global_load_dwordx4 v[164:167], v[252:253], off
	s_nop 0
	global_load_dwordx4 v[160:163], v[252:253], off offset:256
	global_load_dword v210, v[190:191], off
	global_load_dword v208, v[154:155], off
	global_load_dwordx4 v[156:159], v[192:193], off
	s_nop 0
	global_load_dwordx4 v[152:155], v[192:193], off offset:256
	v_cvt_f32_i32_e32 v149, v149
	v_cvt_f32_i32_e32 v151, v151
	v_cvt_f32_i32_e32 v150, v150
	v_cvt_f32_i32_e32 v148, v148
	v_cvt_f32_i32_e32 v145, v145
	v_cvt_f32_i32_e32 v144, v144
	v_cvt_f32_i32_e32 v147, v147
	v_cvt_f32_i32_e32 v146, v146
	s_lshl_b32 s34, s22, 2
	s_ashr_i32 s35, s34, 31
	s_waitcnt vmcnt(0)
	v_pk_mul_f32 v[190:191], v[74:75], v[246:247]
	v_pk_mul_f32 v[192:193], v[72:73], v[244:245]
	v_pk_mul_f32 v[246:247], v[68:69], v[248:249]
	v_lshlrev_b32_e32 v248, 16, v232
	v_and_b32_e32 v249, 0xffff0000, v232
	v_lshlrev_b32_e32 v232, 16, v233
	v_and_b32_e32 v233, 0xffff0000, v233
	v_pk_mul_f32 v[244:245], v[70:71], v[250:251]
	v_lshlrev_b32_e32 v250, 16, v234
	v_and_b32_e32 v251, 0xffff0000, v234
	v_lshlrev_b32_e32 v234, 16, v235
	v_and_b32_e32 v235, 0xffff0000, v235
	v_pk_fma_f32 v[192:193], v[192:193], v[240:241], v[248:249] op_sel_hi:[1,0,1]
	v_pk_fma_f32 v[190:191], v[190:191], v[240:241], v[232:233] op_sel_hi:[1,0,1]
	v_pk_fma_f32 v[232:233], v[246:247], v[240:241], v[250:251] op_sel_hi:[1,0,1]
	v_pk_fma_f32 v[234:235], v[244:245], v[240:241], v[234:235] op_sel_hi:[1,0,1]
	v_pk_fma_f32 v[190:191], v[82:83], v[242:243], v[190:191] op_sel_hi:[1,0,1]
	v_pk_fma_f32 v[192:193], v[80:81], v[242:243], v[192:193] op_sel_hi:[1,0,1]
	v_pk_fma_f32 v[244:245], v[78:79], v[242:243], v[234:235] op_sel_hi:[1,0,1]
	v_pk_fma_f32 v[234:235], v[76:77], v[242:243], v[232:233] op_sel_hi:[1,0,1]
	v_mul_f32_e32 v232, v193, v193
	v_mul_f32_e32 v233, v191, v191
	v_fmac_f32_e32 v232, v192, v192
	v_fmac_f32_e32 v233, v190, v190
	v_add_f32_e32 v232, v232, v233
	v_mul_f32_e32 v233, v235, v235
	v_mul_f32_e32 v241, v245, v245
	v_fmac_f32_e32 v233, v234, v234
	v_fmac_f32_e32 v241, v244, v244
	v_add_f32_e32 v233, v233, v241
	v_add_f32_e32 v241, v232, v233
	v_cvt_pk_bf16_f32 v232, v192, v193
	v_cvt_pk_bf16_f32 v233, v190, v191
	v_lshlrev_b32_e32 v190, 16, v236
	v_and_b32_e32 v191, 0xffff0000, v236
	v_lshlrev_b32_e32 v192, 16, v237
	v_and_b32_e32 v193, 0xffff0000, v237
	v_pk_mul_f32 v[150:151], v[94:95], v[150:151]
	v_pk_mul_f32 v[148:149], v[92:93], v[148:149]
	v_lshlrev_b32_e32 v236, 16, v238
	v_and_b32_e32 v237, 0xffff0000, v238
	v_pk_fma_f32 v[148:149], v[148:149], v[240:241], v[190:191] op_sel_hi:[1,0,1]
	v_pk_fma_f32 v[150:151], v[150:151], v[240:241], v[192:193] op_sel_hi:[1,0,1]
	v_pk_mul_f32 v[144:145], v[84:85], v[144:145]
	v_lshlrev_b32_e32 v238, 16, v239
	v_and_b32_e32 v239, 0xffff0000, v239
	v_pk_fma_f32 v[150:151], v[90:91], v[242:243], v[150:151] op_sel_hi:[1,0,1]
	v_pk_fma_f32 v[148:149], v[88:89], v[242:243], v[148:149] op_sel_hi:[1,0,1]
	v_pk_mul_f32 v[146:147], v[86:87], v[146:147]
	v_pk_fma_f32 v[144:145], v[144:145], v[240:241], v[236:237] op_sel_hi:[1,0,1]
	v_pk_fma_f32 v[146:147], v[146:147], v[240:241], v[238:239] op_sel_hi:[1,0,1]
	v_pk_fma_f32 v[192:193], v[64:65], v[242:243], v[144:145] op_sel_hi:[1,0,1]
	v_mul_f32_e32 v144, v149, v149
	v_mul_f32_e32 v145, v151, v151
	v_pk_fma_f32 v[190:191], v[66:67], v[242:243], v[146:147] op_sel_hi:[1,0,1]
	v_fmac_f32_e32 v144, v148, v148
	v_fmac_f32_e32 v145, v150, v150
	v_add_f32_e32 v144, v144, v145
	v_mul_f32_e32 v145, v193, v193
	v_mul_f32_e32 v146, v191, v191
	v_fmac_f32_e32 v145, v192, v192
	v_fmac_f32_e32 v146, v190, v190
	v_add_f32_e32 v145, v145, v146
	v_add_f32_e32 v144, v144, v145
	v_and_b32_e32 v146, 64, v227
	v_add_f32_e32 v145, v241, v144
	v_xor_b32_e32 v144, 16, v227
	v_add_u32_e32 v236, 64, v146
	v_cmp_lt_i32_e32 vcc, v144, v236
	v_lshl_add_u64 v[146:147], s[74:75], 0, v[230:231]
	v_lshl_add_u64 v[228:229], v[146:147], 0, v[228:229]
	v_cndmask_b32_e32 v144, v227, v144, vcc
	v_lshlrev_b32_e32 v144, 2, v144
	v_cvt_pk_bf16_f32 v234, v234, v235
	v_cvt_pk_bf16_f32 v235, v244, v245
	global_store_dwordx4 v[228:229], v[232:235], off
	v_cvt_pk_bf16_f32 v148, v148, v149
	s_waitcnt lgkmcnt(0)
; __device__ __forceinline__ unsigned cvt_pk_bf16(float lo, float hi) { unsigned r; asm volatile("v_cvt_pk_bf16_f32 %0, %1, %2" : "=v"(r) : "v"(lo), "v"(hi)); return r; }
; __device__ __forceinline__ float bflo(unsigned w) { return __uint_as_float(w << 16); }
; __device__ __forceinline__ float bfhi(unsigned w) { return __uint_as_float(w & 0xffff0000u); }
;     __device__ __forceinline__ void operator()(const i32x4 (&acc)[2][2][4][2], const Unit& u, int wr, int wc, int fr, int fq) const {
;     ...
;             for (int m = 0; m < 4; ++m) { const int row = row0 + ai * HALF + m * 16; const size_t off = (size_t)row * DM + col0; float ss = 0.f;
; #pragma unroll
;                 for (int bj = 0; bj < 2; ++bj) { const u32x4 w = bw[m][bj]; const i32x4 a0 = acc[ai][bj][m][0], a1 = acc[ai][bj][m][1];
;                     const f32x4 b0 = {bflo(w.x), bfhi(w.x), bflo(w.y), bfhi(w.y)}, b1 = {bflo(w.z), bfhi(w.z), bflo(w.w), bfhi(w.w)};
;                     const f32x4 o0 = b0 + (f32x4){(float)a0[0], (float)a0[1], (float)a0[2], (float)a0[3]} * cs[bj][0] * rs[m] + cc[bj][0] * rm[m];
;                     const f32x4 o1 = b1 + (f32x4){(float)a1[0], (float)a1[1], (float)a1[2], (float)a1[3]} * cs[bj][1] * rs[m] + cc[bj][1] * rm[m];
;                     ss += ((o0[0] * o0[0] + o0[1] * o0[1]) + (o0[2] * o0[2] + o0[3] * o0[3])) + ((o1[0] * o1[0] + o1[1] * o1[1]) + (o1[2] * o1[2] + o1[3] * o1[3]));
;                     u32x4 w2; w2.x = cvt_pk_bf16(o0[0], o0[1]); w2.y = cvt_pk_bf16(o0[2], o0[3]); w2.z = cvt_pk_bf16(o1[0], o1[1]); w2.w = cvt_pk_bf16(o1[2], o1[3]);
;                     *(u32x4*)(hout + off + bj * HALF) = w2; }
;                 ss += __shfl_xor(ss, 16); ss += __shfl_xor(ss, 32);
;                 if (fq == 0) part[(size_t)row * 64 + u.pn * 4 + wc] = ss; }
	v_mov_b32_e32 v146, v145
	v_mov_b32_e32 v237, v145
	s_nop 1
	v_permlane16_swap_b32_e32 v146, v237
	s_nop 0
	v_add_f32_e32 v146, v146, v237
	v_xor_b32_e32 v145, 32, v227
	v_cmp_lt_i32_e32 vcc, v145, v236
	v_cvt_pk_bf16_f32 v149, v150, v151
	v_cvt_pk_bf16_f32 v150, v192, v193
	v_cvt_pk_bf16_f32 v151, v190, v191
	global_store_dwordx4 v[228:229], v[148:151], off offset:256
	s_nop 0
	v_cndmask_b32_e32 v145, v227, v145, vcc
	v_lshlrev_b32_e32 v145, 2, v145
	ds_bpermute_b32 v147, v145, v146
	s_and_saveexec_b64 s[36:37], s[4:5]
	s_cbranch_execz .LBB0_1639
	v_lshlrev_b64 v[148:149], 8, v[202:203]
	v_lshl_add_u64 v[148:149], s[10:11], 0, v[148:149]
	v_lshl_add_u64 v[148:149], s[34:35], 2, v[148:149]
	s_lshl_b32 s22, s43, 2
	v_lshl_add_u64 v[148:149], v[148:149], 0, s[22:23]
	s_waitcnt lgkmcnt(0)
	v_add_f32_e32 v146, v146, v147
	global_store_dword v[148:149], v146, off
.LBB0_1639:
	s_or_b64 exec, exec, s[36:37]
	v_cvt_f32_i32_e32 v141, v141
	v_cvt_f32_i32_e32 v143, v143
	v_cvt_f32_i32_e32 v142, v142
	v_cvt_f32_i32_e32 v140, v140
	v_cvt_f32_i32_e32 v137, v137
	v_cvt_f32_i32_e32 v139, v139
	v_cvt_f32_i32_e32 v138, v138
	v_cvt_f32_i32_e32 v136, v136
	v_lshlrev_b32_e32 v146, 16, v172
	s_waitcnt lgkmcnt(0)
	v_and_b32_e32 v147, 0xffff0000, v172
	v_lshlrev_b32_e32 v148, 16, v173
	v_and_b32_e32 v149, 0xffff0000, v173
	v_pk_mul_f32 v[142:143], v[74:75], v[142:143]
	v_pk_mul_f32 v[140:141], v[72:73], v[140:141]
	v_lshlrev_b32_e32 v150, 16, v174
	v_and_b32_e32 v151, 0xffff0000, v174
	v_lshlrev_b32_e32 v172, 16, v175
	v_and_b32_e32 v173, 0xffff0000, v175
	v_pk_fma_f32 v[142:143], v[142:143], v[226:227], v[148:149] op_sel_hi:[1,0,1]
	v_pk_fma_f32 v[140:141], v[140:141], v[226:227], v[146:147] op_sel_hi:[1,0,1]
	v_pk_mul_f32 v[138:139], v[70:71], v[138:139]
	v_pk_mul_f32 v[136:137], v[68:69], v[136:137]
	v_pk_fma_f32 v[142:143], v[82:83], v[224:225], v[142:143] op_sel_hi:[1,0,1]
	v_pk_fma_f32 v[140:141], v[80:81], v[224:225], v[140:141] op_sel_hi:[1,0,1]
	v_pk_fma_f32 v[138:139], v[138:139], v[226:227], v[172:173] op_sel_hi:[1,0,1]
	v_pk_fma_f32 v[136:137], v[136:137], v[226:227], v[150:151] op_sel_hi:[1,0,1]
	v_pk_fma_f32 v[146:147], v[78:79], v[224:225], v[138:139] op_sel_hi:[1,0,1]
	v_pk_fma_f32 v[138:139], v[76:77], v[224:225], v[136:137] op_sel_hi:[1,0,1]
	v_mul_f32_e32 v136, v141, v141
	v_mul_f32_e32 v137, v143, v143
	v_fmac_f32_e32 v136, v140, v140
	v_fmac_f32_e32 v137, v142, v142
	v_cvt_f32_i32_e32 v133, v133
	v_cvt_f32_i32_e32 v135, v135
	v_cvt_f32_i32_e32 v134, v134
	v_cvt_f32_i32_e32 v132, v132
	v_add_f32_e32 v136, v136, v137
	v_mul_f32_e32 v137, v139, v139
	v_mul_f32_e32 v148, v147, v147
	v_cvt_f32_i32_e32 v129, v129
	v_cvt_f32_i32_e32 v128, v128
	v_fmac_f32_e32 v137, v138, v138
	v_fmac_f32_e32 v148, v146, v146
	v_cvt_f32_i32_e32 v131, v131
	v_cvt_f32_i32_e32 v130, v130
	v_add_f32_e32 v137, v137, v148
	v_add_f32_e32 v150, v136, v137
	v_cvt_pk_bf16_f32 v136, v140, v141
	v_cvt_pk_bf16_f32 v137, v142, v143
	v_lshlrev_b32_e32 v140, 16, v168
	v_and_b32_e32 v141, 0xffff0000, v168
	v_lshlrev_b32_e32 v142, 16, v169
	v_and_b32_e32 v143, 0xffff0000, v169
	v_pk_mul_f32 v[134:135], v[94:95], v[134:135]
	v_pk_mul_f32 v[132:133], v[92:93], v[132:133]
	v_cvt_pk_bf16_f32 v138, v138, v139
	v_cvt_pk_bf16_f32 v139, v146, v147
	v_lshlrev_b32_e32 v146, 16, v170
	v_and_b32_e32 v147, 0xffff0000, v170
	v_pk_fma_f32 v[134:135], v[134:135], v[226:227], v[142:143] op_sel_hi:[1,0,1]
	v_pk_fma_f32 v[132:133], v[132:133], v[226:227], v[140:141] op_sel_hi:[1,0,1]
	v_pk_mul_f32 v[128:129], v[84:85], v[128:129]
	v_lshlrev_b32_e32 v148, 16, v171
	v_and_b32_e32 v149, 0xffff0000, v171
	v_pk_fma_f32 v[134:135], v[90:91], v[224:225], v[134:135] op_sel_hi:[1,0,1]
	v_pk_fma_f32 v[132:133], v[88:89], v[224:225], v[132:133] op_sel_hi:[1,0,1]
	v_pk_mul_f32 v[130:131], v[86:87], v[130:131]
	v_pk_fma_f32 v[128:129], v[128:129], v[226:227], v[146:147] op_sel_hi:[1,0,1]
	v_pk_fma_f32 v[130:131], v[130:131], v[226:227], v[148:149] op_sel_hi:[1,0,1]
	v_pk_fma_f32 v[142:143], v[64:65], v[224:225], v[128:129] op_sel_hi:[1,0,1]
	v_mul_f32_e32 v128, v133, v133
	v_mul_f32_e32 v129, v135, v135
	v_pk_fma_f32 v[140:141], v[66:67], v[224:225], v[130:131] op_sel_hi:[1,0,1]
	v_fmac_f32_e32 v128, v132, v132
	v_fmac_f32_e32 v129, v134, v134
	v_add_f32_e32 v128, v128, v129
	v_mul_f32_e32 v129, v143, v143
	v_mul_f32_e32 v130, v141, v141
	v_fmac_f32_e32 v129, v142, v142
	v_fmac_f32_e32 v130, v140, v140
	v_add_f32_e32 v129, v129, v130
	v_add_f32_e32 v128, v128, v129
	v_add_f32_e32 v131, v150, v128
	v_lshl_add_u64 v[128:129], s[74:75], 0, v[222:223]
	v_lshl_add_u64 v[146:147], v[194:195], 1, v[128:129]
	global_store_dwordx4 v[146:147], v[136:139], off
	v_cvt_pk_bf16_f32 v130, v132, v133
	s_waitcnt lgkmcnt(0)
	v_mov_b32_e32 v128, v131
	v_mov_b32_e32 v148, v131
	s_nop 1
	v_permlane16_swap_b32_e32 v128, v148
	s_nop 0
	v_add_f32_e32 v128, v128, v148
	ds_bpermute_b32 v129, v145, v128
	v_cvt_pk_bf16_f32 v131, v134, v135
	v_cvt_pk_bf16_f32 v132, v142, v143
	v_cvt_pk_bf16_f32 v133, v140, v141
	global_store_dwordx4 v[146:147], v[130:133], off offset:256
	s_and_saveexec_b64 s[36:37], s[4:5]
	s_cbranch_execz .LBB0_1641
	v_lshlrev_b64 v[130:131], 8, v[220:221]
	v_lshl_add_u64 v[130:131], s[10:11], 0, v[130:131]
	v_lshl_add_u64 v[130:131], s[34:35], 2, v[130:131]
	s_lshl_b32 s22, s43, 2
	v_lshl_add_u64 v[130:131], v[130:131], 0, s[22:23]
	s_waitcnt lgkmcnt(0)
	v_add_f32_e32 v128, v128, v129
	global_store_dword v[130:131], v128, off
; __device__ __forceinline__ unsigned cvt_pk_bf16(float lo, float hi) { unsigned r; asm volatile("v_cvt_pk_bf16_f32 %0, %1, %2" : "=v"(r) : "v"(lo), "v"(hi)); return r; }
; __device__ __forceinline__ float bflo(unsigned w) { return __uint_as_float(w << 16); }
; __device__ __forceinline__ float bfhi(unsigned w) { return __uint_as_float(w & 0xffff0000u); }
;     __device__ __forceinline__ void operator()(const i32x4 (&acc)[2][2][4][2], const Unit& u, int wr, int wc, int fr, int fq) const {
;     ...
;             for (int m = 0; m < 4; ++m) { const int row = row0 + ai * HALF + m * 16; const size_t off = (size_t)row * DM + col0; float ss = 0.f;
; #pragma unroll
;                 for (int bj = 0; bj < 2; ++bj) { const u32x4 w = bw[m][bj]; const i32x4 a0 = acc[ai][bj][m][0], a1 = acc[ai][bj][m][1];
;                     const f32x4 b0 = {bflo(w.x), bfhi(w.x), bflo(w.y), bfhi(w.y)}, b1 = {bflo(w.z), bfhi(w.z), bflo(w.w), bfhi(w.w)};
;                     const f32x4 o0 = b0 + (f32x4){(float)a0[0], (float)a0[1], (float)a0[2], (float)a0[3]} * cs[bj][0] * rs[m] + cc[bj][0] * rm[m];
;                     const f32x4 o1 = b1 + (f32x4){(float)a1[0], (float)a1[1], (float)a1[2], (float)a1[3]} * cs[bj][1] * rs[m] + cc[bj][1] * rm[m];
;                     ss += ((o0[0] * o0[0] + o0[1] * o0[1]) + (o0[2] * o0[2] + o0[3] * o0[3])) + ((o1[0] * o1[0] + o1[1] * o1[1]) + (o1[2] * o1[2] + o1[3] * o1[3]));
;                     u32x4 w2; w2.x = cvt_pk_bf16(o0[0], o0[1]); w2.y = cvt_pk_bf16(o0[2], o0[3]); w2.z = cvt_pk_bf16(o1[0], o1[1]); w2.w = cvt_pk_bf16(o1[2], o1[3]);
;                     *(u32x4*)(hout + off + bj * HALF) = w2; }
;                 ss += __shfl_xor(ss, 16); ss += __shfl_xor(ss, 32);
;                 if (fq == 0) part[(size_t)row * 64 + u.pn * 4 + wc] = ss; }
.LBB0_1641:
	s_or_b64 exec, exec, s[36:37]
	v_cvt_f32_i32_e32 v125, v125
	v_cvt_f32_i32_e32 v127, v127
	v_cvt_f32_i32_e32 v126, v126
	v_cvt_f32_i32_e32 v124, v124
	v_cvt_f32_i32_e32 v121, v121
	v_cvt_f32_i32_e32 v123, v123
	v_cvt_f32_i32_e32 v122, v122
	v_cvt_f32_i32_e32 v120, v120
	v_lshlrev_b32_e32 v128, 16, v164
	s_waitcnt lgkmcnt(0)
	v_and_b32_e32 v129, 0xffff0000, v164
	v_lshlrev_b32_e32 v130, 16, v165
	v_and_b32_e32 v131, 0xffff0000, v165
	v_pk_mul_f32 v[126:127], v[74:75], v[126:127]
	v_pk_mul_f32 v[124:125], v[72:73], v[124:125]
	v_lshlrev_b32_e32 v132, 16, v166
	v_and_b32_e32 v133, 0xffff0000, v166
	v_lshlrev_b32_e32 v134, 16, v167
	v_and_b32_e32 v135, 0xffff0000, v167
	v_pk_fma_f32 v[126:127], v[126:127], v[218:219], v[130:131] op_sel_hi:[1,0,1]
	v_pk_fma_f32 v[124:125], v[124:125], v[218:219], v[128:129] op_sel_hi:[1,0,1]
	v_pk_mul_f32 v[122:123], v[70:71], v[122:123]
	v_pk_mul_f32 v[120:121], v[68:69], v[120:121]
	v_pk_fma_f32 v[126:127], v[82:83], v[216:217], v[126:127] op_sel_hi:[1,0,1]
	v_pk_fma_f32 v[124:125], v[80:81], v[216:217], v[124:125] op_sel_hi:[1,0,1]
	v_pk_fma_f32 v[122:123], v[122:123], v[218:219], v[134:135] op_sel_hi:[1,0,1]
	v_pk_fma_f32 v[120:121], v[120:121], v[218:219], v[132:133] op_sel_hi:[1,0,1]
	v_pk_fma_f32 v[128:129], v[78:79], v[216:217], v[122:123] op_sel_hi:[1,0,1]
	v_pk_fma_f32 v[122:123], v[76:77], v[216:217], v[120:121] op_sel_hi:[1,0,1]
	v_mul_f32_e32 v120, v125, v125
	v_mul_f32_e32 v121, v127, v127
	v_fmac_f32_e32 v120, v124, v124
	v_fmac_f32_e32 v121, v126, v126
	v_cvt_f32_i32_e32 v117, v117
	v_cvt_f32_i32_e32 v119, v119
	v_cvt_f32_i32_e32 v118, v118
	v_cvt_f32_i32_e32 v116, v116
	v_add_f32_e32 v120, v120, v121
	v_mul_f32_e32 v121, v123, v123
	v_mul_f32_e32 v130, v129, v129
	v_cvt_f32_i32_e32 v113, v113
	v_cvt_f32_i32_e32 v112, v112
	v_fmac_f32_e32 v121, v122, v122
	v_fmac_f32_e32 v130, v128, v128
	v_cvt_f32_i32_e32 v115, v115
	v_cvt_f32_i32_e32 v114, v114
	v_add_f32_e32 v121, v121, v130
	v_add_f32_e32 v132, v120, v121
	v_cvt_pk_bf16_f32 v120, v124, v125
	v_cvt_pk_bf16_f32 v121, v126, v127
	v_lshlrev_b32_e32 v124, 16, v160
	v_and_b32_e32 v125, 0xffff0000, v160
	v_lshlrev_b32_e32 v126, 16, v161
	v_and_b32_e32 v127, 0xffff0000, v161
	v_pk_mul_f32 v[118:119], v[94:95], v[118:119]
	v_pk_mul_f32 v[116:117], v[92:93], v[116:117]
	v_cvt_pk_bf16_f32 v122, v122, v123
	v_cvt_pk_bf16_f32 v123, v128, v129
	v_lshlrev_b32_e32 v128, 16, v162
	v_and_b32_e32 v129, 0xffff0000, v162
	v_pk_fma_f32 v[118:119], v[118:119], v[218:219], v[126:127] op_sel_hi:[1,0,1]
	v_pk_fma_f32 v[116:117], v[116:117], v[218:219], v[124:125] op_sel_hi:[1,0,1]
	v_pk_mul_f32 v[112:113], v[84:85], v[112:113]
	v_lshlrev_b32_e32 v130, 16, v163
	v_and_b32_e32 v131, 0xffff0000, v163
	v_pk_fma_f32 v[118:119], v[90:91], v[216:217], v[118:119] op_sel_hi:[1,0,1]
	v_pk_fma_f32 v[116:117], v[88:89], v[216:217], v[116:117] op_sel_hi:[1,0,1]
	v_pk_mul_f32 v[114:115], v[86:87], v[114:115]
	v_pk_fma_f32 v[112:113], v[112:113], v[218:219], v[128:129] op_sel_hi:[1,0,1]
	v_pk_fma_f32 v[114:115], v[114:115], v[218:219], v[130:131] op_sel_hi:[1,0,1]
	v_pk_fma_f32 v[126:127], v[64:65], v[216:217], v[112:113] op_sel_hi:[1,0,1]
	v_mul_f32_e32 v112, v117, v117
	v_mul_f32_e32 v113, v119, v119
	v_pk_fma_f32 v[124:125], v[66:67], v[216:217], v[114:115] op_sel_hi:[1,0,1]
	v_fmac_f32_e32 v112, v116, v116
	v_fmac_f32_e32 v113, v118, v118
	v_add_f32_e32 v112, v112, v113
	v_mul_f32_e32 v113, v127, v127
	v_mul_f32_e32 v114, v125, v125
	v_fmac_f32_e32 v113, v126, v126
	v_fmac_f32_e32 v114, v124, v124
	v_add_f32_e32 v113, v113, v114
	v_add_f32_e32 v112, v112, v113
	v_add_f32_e32 v115, v132, v112
	v_lshl_add_u64 v[112:113], s[74:75], 0, v[214:215]
	v_lshl_add_u64 v[128:129], v[194:195], 1, v[112:113]
	global_store_dwordx4 v[128:129], v[120:123], off
	v_cvt_pk_bf16_f32 v114, v116, v117
	s_waitcnt lgkmcnt(0)
	v_mov_b32_e32 v112, v115
	v_mov_b32_e32 v130, v115
	s_nop 1
	v_permlane16_swap_b32_e32 v112, v130
	s_nop 0
	v_add_f32_e32 v112, v112, v130
	ds_bpermute_b32 v113, v145, v112
	v_cvt_pk_bf16_f32 v115, v118, v119
	v_cvt_pk_bf16_f32 v116, v126, v127
	v_cvt_pk_bf16_f32 v117, v124, v125
	global_store_dwordx4 v[128:129], v[114:117], off offset:256
	s_and_saveexec_b64 s[36:37], s[4:5]
	s_cbranch_execz .LBB0_1643
	v_lshlrev_b64 v[114:115], 8, v[212:213]
	v_lshl_add_u64 v[114:115], s[10:11], 0, v[114:115]
	v_lshl_add_u64 v[114:115], s[34:35], 2, v[114:115]
	s_lshl_b32 s22, s43, 2
	v_lshl_add_u64 v[114:115], v[114:115], 0, s[22:23]
	s_waitcnt lgkmcnt(0)
	v_add_f32_e32 v112, v112, v113
	global_store_dword v[114:115], v112, off
; __device__ __forceinline__ unsigned cvt_pk_bf16(float lo, float hi) { unsigned r; asm volatile("v_cvt_pk_bf16_f32 %0, %1, %2" : "=v"(r) : "v"(lo), "v"(hi)); return r; }
; __device__ __forceinline__ float bflo(unsigned w) { return __uint_as_float(w << 16); }
; __device__ __forceinline__ float bfhi(unsigned w) { return __uint_as_float(w & 0xffff0000u); }
;     __device__ __forceinline__ void operator()(const i32x4 (&acc)[2][2][4][2], const Unit& u, int wr, int wc, int fr, int fq) const {
;     ...
;             for (int m = 0; m < 4; ++m) { const int row = row0 + ai * HALF + m * 16; const size_t off = (size_t)row * DM + col0; float ss = 0.f;
; #pragma unroll
;                 for (int bj = 0; bj < 2; ++bj) { const u32x4 w = bw[m][bj]; const i32x4 a0 = acc[ai][bj][m][0], a1 = acc[ai][bj][m][1];
;                     const f32x4 b0 = {bflo(w.x), bfhi(w.x), bflo(w.y), bfhi(w.y)}, b1 = {bflo(w.z), bfhi(w.z), bflo(w.w), bfhi(w.w)};
;                     const f32x4 o0 = b0 + (f32x4){(float)a0[0], (float)a0[1], (float)a0[2], (float)a0[3]} * cs[bj][0] * rs[m] + cc[bj][0] * rm[m];
;                     const f32x4 o1 = b1 + (f32x4){(float)a1[0], (float)a1[1], (float)a1[2], (float)a1[3]} * cs[bj][1] * rs[m] + cc[bj][1] * rm[m];
;                     ss += ((o0[0] * o0[0] + o0[1] * o0[1]) + (o0[2] * o0[2] + o0[3] * o0[3])) + ((o1[0] * o1[0] + o1[1] * o1[1]) + (o1[2] * o1[2] + o1[3] * o1[3]));
;                     u32x4 w2; w2.x = cvt_pk_bf16(o0[0], o0[1]); w2.y = cvt_pk_bf16(o0[2], o0[3]); w2.z = cvt_pk_bf16(o1[0], o1[1]); w2.w = cvt_pk_bf16(o1[2], o1[3]);
;                     *(u32x4*)(hout + off + bj * HALF) = w2; }
;                 ss += __shfl_xor(ss, 16); ss += __shfl_xor(ss, 32);
;                 if (fq == 0) part[(size_t)row * 64 + u.pn * 4 + wc] = ss; }
.LBB0_1643:
	s_or_b64 exec, exec, s[36:37]
	v_cvt_f32_i32_e32 v109, v109
	v_cvt_f32_i32_e32 v111, v111
	v_cvt_f32_i32_e32 v110, v110
	v_cvt_f32_i32_e32 v108, v108
	v_cvt_f32_i32_e32 v105, v105
	v_cvt_f32_i32_e32 v107, v107
	v_cvt_f32_i32_e32 v106, v106
	v_cvt_f32_i32_e32 v104, v104
	v_lshlrev_b32_e32 v112, 16, v156
	s_waitcnt lgkmcnt(0)
	v_and_b32_e32 v113, 0xffff0000, v156
	v_lshlrev_b32_e32 v114, 16, v157
	v_and_b32_e32 v115, 0xffff0000, v157
	v_pk_mul_f32 v[110:111], v[74:75], v[110:111]
	v_pk_mul_f32 v[108:109], v[72:73], v[108:109]
	v_lshlrev_b32_e32 v116, 16, v158
	v_and_b32_e32 v117, 0xffff0000, v158
	v_lshlrev_b32_e32 v118, 16, v159
	v_and_b32_e32 v119, 0xffff0000, v159
	v_pk_fma_f32 v[110:111], v[110:111], v[210:211], v[114:115] op_sel_hi:[1,0,1]
	v_pk_fma_f32 v[108:109], v[108:109], v[210:211], v[112:113] op_sel_hi:[1,0,1]
	v_pk_mul_f32 v[106:107], v[70:71], v[106:107]
	v_pk_mul_f32 v[104:105], v[68:69], v[104:105]
	v_pk_fma_f32 v[110:111], v[82:83], v[208:209], v[110:111] op_sel_hi:[1,0,1]
	v_pk_fma_f32 v[108:109], v[80:81], v[208:209], v[108:109] op_sel_hi:[1,0,1]
	v_pk_fma_f32 v[106:107], v[106:107], v[210:211], v[118:119] op_sel_hi:[1,0,1]
	v_pk_fma_f32 v[104:105], v[104:105], v[210:211], v[116:117] op_sel_hi:[1,0,1]
	v_pk_fma_f32 v[112:113], v[78:79], v[208:209], v[106:107] op_sel_hi:[1,0,1]
	v_pk_fma_f32 v[106:107], v[76:77], v[208:209], v[104:105] op_sel_hi:[1,0,1]
	v_mul_f32_e32 v104, v109, v109
	v_mul_f32_e32 v105, v111, v111
	v_fmac_f32_e32 v104, v108, v108
	v_fmac_f32_e32 v105, v110, v110
	v_cvt_f32_i32_e32 v101, v101
	v_cvt_f32_i32_e32 v103, v103
	v_cvt_f32_i32_e32 v102, v102
	v_cvt_f32_i32_e32 v100, v100
	v_add_f32_e32 v104, v104, v105
	v_mul_f32_e32 v105, v107, v107
	v_mul_f32_e32 v114, v113, v113
	v_cvt_f32_i32_e32 v97, v97
	v_cvt_f32_i32_e32 v96, v96
	v_fmac_f32_e32 v105, v106, v106
	v_fmac_f32_e32 v114, v112, v112
	v_cvt_f32_i32_e32 v99, v99
	v_cvt_f32_i32_e32 v98, v98
	v_add_f32_e32 v105, v105, v114
	v_add_f32_e32 v116, v104, v105
	v_cvt_pk_bf16_f32 v104, v108, v109
	v_cvt_pk_bf16_f32 v105, v110, v111
	v_lshlrev_b32_e32 v108, 16, v152
	v_and_b32_e32 v109, 0xffff0000, v152
	v_lshlrev_b32_e32 v110, 16, v153
	v_and_b32_e32 v111, 0xffff0000, v153
	v_pk_mul_f32 v[102:103], v[94:95], v[102:103]
	v_pk_mul_f32 v[100:101], v[92:93], v[100:101]
	v_cvt_pk_bf16_f32 v106, v106, v107
	v_cvt_pk_bf16_f32 v107, v112, v113
	v_lshlrev_b32_e32 v112, 16, v154
	v_and_b32_e32 v113, 0xffff0000, v154
	v_pk_fma_f32 v[102:103], v[102:103], v[210:211], v[110:111] op_sel_hi:[1,0,1]
	v_pk_fma_f32 v[100:101], v[100:101], v[210:211], v[108:109] op_sel_hi:[1,0,1]
	v_pk_mul_f32 v[96:97], v[84:85], v[96:97]
	v_lshlrev_b32_e32 v114, 16, v155
	v_and_b32_e32 v115, 0xffff0000, v155
	v_pk_fma_f32 v[102:103], v[90:91], v[208:209], v[102:103] op_sel_hi:[1,0,1]
	v_pk_fma_f32 v[100:101], v[88:89], v[208:209], v[100:101] op_sel_hi:[1,0,1]
	v_pk_mul_f32 v[98:99], v[86:87], v[98:99]
	v_pk_fma_f32 v[96:97], v[96:97], v[210:211], v[112:113] op_sel_hi:[1,0,1]
	v_pk_fma_f32 v[98:99], v[98:99], v[210:211], v[114:115] op_sel_hi:[1,0,1]
	v_pk_fma_f32 v[110:111], v[64:65], v[208:209], v[96:97] op_sel_hi:[1,0,1]
	v_mul_f32_e32 v96, v101, v101
	v_mul_f32_e32 v97, v103, v103
	v_pk_fma_f32 v[108:109], v[66:67], v[208:209], v[98:99] op_sel_hi:[1,0,1]
	v_fmac_f32_e32 v96, v100, v100
	v_fmac_f32_e32 v97, v102, v102
	v_add_f32_e32 v96, v96, v97
	v_mul_f32_e32 v97, v111, v111
	v_mul_f32_e32 v98, v109, v109
	v_fmac_f32_e32 v97, v110, v110
	v_fmac_f32_e32 v98, v108, v108
	v_add_f32_e32 v97, v97, v98
	v_add_f32_e32 v96, v96, v97
	v_add_f32_e32 v99, v116, v96
	v_lshl_add_u64 v[96:97], s[74:75], 0, v[206:207]
	v_lshl_add_u64 v[112:113], v[194:195], 1, v[96:97]
	global_store_dwordx4 v[112:113], v[104:107], off
	v_cvt_pk_bf16_f32 v98, v100, v101
	s_waitcnt lgkmcnt(0)
	v_mov_b32_e32 v96, v99
	v_mov_b32_e32 v114, v99
	s_nop 1
	v_permlane16_swap_b32_e32 v96, v114
	s_nop 0
	v_add_f32_e32 v96, v96, v114
	ds_bpermute_b32 v97, v145, v96
	v_cvt_pk_bf16_f32 v99, v102, v103
	v_cvt_pk_bf16_f32 v100, v110, v111
	v_cvt_pk_bf16_f32 v101, v108, v109
	global_store_dwordx4 v[112:113], v[98:101], off offset:256
	s_and_saveexec_b64 s[36:37], s[4:5]
	s_cbranch_execz .LBB0_1645
	v_lshlrev_b64 v[98:99], 8, v[204:205]
	v_lshl_add_u64 v[98:99], s[10:11], 0, v[98:99]
	v_lshl_add_u64 v[98:99], s[34:35], 2, v[98:99]
	s_lshl_b32 s22, s43, 2
	v_lshl_add_u64 v[98:99], v[98:99], 0, s[22:23]
	s_waitcnt lgkmcnt(0)
	v_add_f32_e32 v96, v96, v97
	global_store_dword v[98:99], v96, off
; __device__ __forceinline__ unsigned cvt_pk_bf16(float lo, float hi) { unsigned r; asm volatile("v_cvt_pk_bf16_f32 %0, %1, %2" : "=v"(r) : "v"(lo), "v"(hi)); return r; }
; __device__ __forceinline__ float bflo(unsigned w) { return __uint_as_float(w << 16); }
; __device__ __forceinline__ float bfhi(unsigned w) { return __uint_as_float(w & 0xffff0000u); }
;     __device__ __forceinline__ void operator()(const i32x4 (&acc)[2][2][4][2], const Unit& u, int wr, int wc, int fr, int fq) const {
;     ...
;         for (int ai = 0; ai < 2; ++ai) {
;             u32x4 bw[4][2]; float rs[4], rm[4];
; #pragma unroll
;             for (int m = 0; m < 4; ++m) { rs[m] = sa[row0 + ai * HALF + m * 16]; rm[m] = mrow[row0 + ai * HALF + m * 16];
; #pragma unroll
;                 for (int bj = 0; bj < 2; ++bj) bw[m][bj] = *(const u32x4*)(base + (size_t)(row0 + ai * HALF + m * 16) * DM + col0 + bj * HALF); }
; #pragma unroll
;             for (int m = 0; m < 4; ++m) { const int row = row0 + ai * HALF + m * 16; const size_t off = (size_t)row * DM + col0; float ss = 0.f;
; #pragma unroll
;                 for (int bj = 0; bj < 2; ++bj) { const u32x4 w = bw[m][bj]; const i32x4 a0 = acc[ai][bj][m][0], a1 = acc[ai][bj][m][1];
;                     const f32x4 b0 = {bflo(w.x), bfhi(w.x), bflo(w.y), bfhi(w.y)}, b1 = {bflo(w.z), bfhi(w.z), bflo(w.w), bfhi(w.w)};
;                     const f32x4 o0 = b0 + (f32x4){(float)a0[0], (float)a0[1], (float)a0[2], (float)a0[3]} * cs[bj][0] * rs[m] + cc[bj][0] * rm[m];
;                     const f32x4 o1 = b1 + (f32x4){(float)a1[0], (float)a1[1], (float)a1[2], (float)a1[3]} * cs[bj][1] * rs[m] + cc[bj][1] * rm[m];
;                     ss += ((o0[0] * o0[0] + o0[1] * o0[1]) + (o0[2] * o0[2] + o0[3] * o0[3])) + ((o1[0] * o1[0] + o1[1] * o1[1]) + (o1[2] * o1[2] + o1[3] * o1[3]));
;                     u32x4 w2; w2.x = cvt_pk_bf16(o0[0], o0[1]); w2.y = cvt_pk_bf16(o0[2], o0[3]); w2.z = cvt_pk_bf16(o1[0], o1[1]); w2.w = cvt_pk_bf16(o1[2], o1[3]);
;                     *(u32x4*)(hout + off + bj * HALF) = w2; }
;                 ss += __shfl_xor(ss, 16); ss += __shfl_xor(ss, 32);
;                 if (fq == 0) part[(size_t)row * 64 + u.pn * 4 + wc] = ss; }
.LBB0_1645:
	s_or_b64 exec, exec, s[36:37]
	v_add_u32_e32 v128, 0x80, v202
	v_ashrrev_i32_e32 v129, 31, v128
	v_lshlrev_b64 v[134:135], 13, v[128:129]
	s_waitcnt lgkmcnt(0)
	v_lshl_add_u64 v[96:97], v[196:197], 0, v[134:135]
	global_load_dwordx4 v[136:139], v[96:97], off
	global_load_dwordx4 v[140:143], v[96:97], off offset:256
	global_load_dword v146, v[198:199], off offset:512
	global_load_dword v148, v[200:201], off offset:512
	v_add_u32_e32 v124, 0x90, v202
	v_add_u32_e32 v116, 0xa0, v202
	v_add_u32_e32 v108, 0xb0, v202
	v_ashrrev_i32_e32 v125, 31, v124
	v_ashrrev_i32_e32 v117, 31, v116
	v_ashrrev_i32_e32 v109, 31, v108
	v_lshlrev_b64 v[126:127], 13, v[124:125]
	v_lshlrev_b64 v[118:119], 13, v[116:117]
	v_cvt_f32_i32_e32 v159, v53
	v_cvt_f32_i32_e32 v158, v52
	v_cvt_f32_i32_e32 v161, v55
	v_cvt_f32_i32_e32 v160, v54
	v_lshlrev_b64 v[110:111], 13, v[108:109]
	v_lshl_add_u64 v[52:53], v[196:197], 0, v[126:127]
	v_lshl_add_u64 v[54:55], v[196:197], 0, v[118:119]
	v_cvt_f32_i32_e32 v151, v61
	v_cvt_f32_i32_e32 v150, v60
	v_cvt_f32_i32_e32 v153, v63
	v_cvt_f32_i32_e32 v152, v62
	v_cvt_f32_i32_e32 v155, v57
	v_cvt_f32_i32_e32 v154, v56
	v_cvt_f32_i32_e32 v157, v59
	v_cvt_f32_i32_e32 v156, v58
	global_load_dword v132, v[198:199], off offset:576
	global_load_dword v130, v[200:201], off offset:576
	global_load_dword v122, v[198:199], off offset:640
	global_load_dword v120, v[200:201], off offset:640
	global_load_dword v112, v[200:201], off offset:704
	global_load_dword v114, v[198:199], off offset:704
	v_lshl_add_u64 v[162:163], v[196:197], 0, v[110:111]
	global_load_dwordx4 v[104:107], v[52:53], off
	global_load_dwordx4 v[100:103], v[52:53], off offset:256
	global_load_dwordx4 v[96:99], v[54:55], off
	global_load_dwordx4 v[60:63], v[54:55], off offset:256
	global_load_dwordx4 v[56:59], v[162:163], off
	s_nop 0
	global_load_dwordx4 v[52:55], v[162:163], off offset:256
	v_cvt_f32_i32_e32 v49, v49
	v_cvt_f32_i32_e32 v48, v48
	v_pk_mul_f32 v[150:151], v[72:73], v[150:151]
	v_cvt_f32_i32_e32 v51, v51
	v_cvt_f32_i32_e32 v50, v50
	v_pk_mul_f32 v[152:153], v[74:75], v[152:153]
	v_pk_mul_f32 v[156:157], v[70:71], v[156:157]
	v_pk_mul_f32 v[154:155], v[68:69], v[154:155]
	v_pk_mul_f32 v[160:161], v[94:95], v[160:161]
	v_pk_mul_f32 v[158:159], v[92:93], v[158:159]
	v_pk_mul_f32 v[48:49], v[84:85], v[48:49]
	v_pk_mul_f32 v[50:51], v[86:87], v[50:51]
	s_waitcnt vmcnt(15)
	v_lshlrev_b32_e32 v162, 16, v136
	v_and_b32_e32 v163, 0xffff0000, v136
	v_lshlrev_b32_e32 v136, 16, v137
	v_and_b32_e32 v137, 0xffff0000, v137
	v_lshlrev_b32_e32 v164, 16, v138
	v_and_b32_e32 v165, 0xffff0000, v138
	v_lshlrev_b32_e32 v138, 16, v139
	v_and_b32_e32 v139, 0xffff0000, v139
	s_waitcnt vmcnt(13)
	v_pk_fma_f32 v[150:151], v[150:151], v[146:147], v[162:163] op_sel_hi:[1,0,1]
	v_lshlrev_b32_e32 v166, 16, v140
	v_and_b32_e32 v167, 0xffff0000, v140
	v_lshlrev_b32_e32 v140, 16, v141
	v_and_b32_e32 v141, 0xffff0000, v141
	v_pk_fma_f32 v[136:137], v[152:153], v[146:147], v[136:137] op_sel_hi:[1,0,1]
	v_pk_fma_f32 v[152:153], v[154:155], v[146:147], v[164:165] op_sel_hi:[1,0,1]
	v_pk_fma_f32 v[138:139], v[156:157], v[146:147], v[138:139] op_sel_hi:[1,0,1]
	s_waitcnt vmcnt(12)
	v_pk_fma_f32 v[150:151], v[80:81], v[148:149], v[150:151] op_sel_hi:[1,0,1]
	v_lshlrev_b32_e32 v168, 16, v142
	v_and_b32_e32 v169, 0xffff0000, v142
	v_pk_fma_f32 v[154:155], v[158:159], v[146:147], v[166:167] op_sel_hi:[1,0,1]
	v_pk_fma_f32 v[156:157], v[82:83], v[148:149], v[136:137] op_sel_hi:[1,0,1]
	v_pk_fma_f32 v[158:159], v[78:79], v[148:149], v[138:139] op_sel_hi:[1,0,1]
	v_pk_fma_f32 v[152:153], v[76:77], v[148:149], v[152:153] op_sel_hi:[1,0,1]
	v_mul_f32_e32 v113, v151, v151
	v_pk_fma_f32 v[140:141], v[160:161], v[146:147], v[140:141] op_sel_hi:[1,0,1]
	v_lshlrev_b32_e32 v142, 16, v143
	v_and_b32_e32 v143, 0xffff0000, v143
	v_mul_f32_e32 v115, v157, v157
	v_mul_f32_e32 v121, v153, v153
	v_mul_f32_e32 v123, v159, v159
	v_cvt_pk_bf16_f32 v136, v150, v151
	v_fmac_f32_e32 v113, v150, v150
	v_pk_fma_f32 v[140:141], v[90:91], v[148:149], v[140:141] op_sel_hi:[1,0,1]
	v_pk_fma_f32 v[150:151], v[88:89], v[148:149], v[154:155] op_sel_hi:[1,0,1]
	v_pk_fma_f32 v[48:49], v[48:49], v[146:147], v[168:169] op_sel_hi:[1,0,1]
	v_fmac_f32_e32 v115, v156, v156
	v_fmac_f32_e32 v121, v152, v152
	v_fmac_f32_e32 v123, v158, v158
	v_pk_fma_f32 v[50:51], v[50:51], v[146:147], v[142:143] op_sel_hi:[1,0,1]
	v_pk_fma_f32 v[142:143], v[64:65], v[148:149], v[48:49] op_sel_hi:[1,0,1]
	v_mul_f32_e32 v48, v151, v151
	v_mul_f32_e32 v49, v141, v141
	v_add_f32_e32 v113, v113, v115
	v_add_f32_e32 v115, v121, v123
	v_pk_fma_f32 v[50:51], v[66:67], v[148:149], v[50:51] op_sel_hi:[1,0,1]
	v_fmac_f32_e32 v48, v150, v150
	v_fmac_f32_e32 v49, v140, v140
	v_add_f32_e32 v113, v113, v115
	v_add_f32_e32 v48, v48, v49
	v_mul_f32_e32 v49, v143, v143
	v_mul_f32_e32 v115, v51, v51
	v_fmac_f32_e32 v49, v142, v142
	v_fmac_f32_e32 v115, v50, v50
	v_add_f32_e32 v49, v49, v115
	v_add_f32_e32 v48, v48, v49
	v_add_f32_e32 v113, v113, v48
	v_lshl_add_u64 v[48:49], s[74:75], 0, v[134:135]
	v_lshl_add_u64 v[146:147], v[194:195], 1, v[48:49]
	v_cvt_pk_bf16_f32 v137, v156, v157
	v_cvt_pk_bf16_f32 v138, v152, v153
	s_waitcnt lgkmcnt(0)
	v_mov_b32_e32 v48, v113
	v_mov_b32_e32 v115, v113
	s_nop 1
	v_permlane16_swap_b32_e32 v48, v115
	s_nop 0
	v_add_f32_e32 v48, v48, v115
	ds_bpermute_b32 v49, v145, v48
	v_cvt_pk_bf16_f32 v139, v158, v159
	global_store_dwordx4 v[146:147], v[136:139], off
	v_cvt_pk_bf16_f32 v134, v150, v151
	v_cvt_pk_bf16_f32 v135, v140, v141
	s_nop 1
	v_cvt_pk_bf16_f32 v136, v142, v143
	v_cvt_pk_bf16_f32 v137, v50, v51
	global_store_dwordx4 v[146:147], v[134:137], off offset:256
	s_and_saveexec_b64 s[36:37], s[4:5]
	s_cbranch_execz .LBB0_1647
	v_lshlrev_b64 v[50:51], 8, v[128:129]
	v_lshl_add_u64 v[50:51], s[10:11], 0, v[50:51]
	v_lshl_add_u64 v[50:51], s[34:35], 2, v[50:51]
	s_lshl_b32 s22, s43, 2
	v_lshl_add_u64 v[50:51], v[50:51], 0, s[22:23]
	s_waitcnt lgkmcnt(0)
	v_add_f32_e32 v48, v48, v49
	global_store_dword v[50:51], v48, off
; __device__ __forceinline__ unsigned cvt_pk_bf16(float lo, float hi) { unsigned r; asm volatile("v_cvt_pk_bf16_f32 %0, %1, %2" : "=v"(r) : "v"(lo), "v"(hi)); return r; }
; __device__ __forceinline__ float bflo(unsigned w) { return __uint_as_float(w << 16); }
; __device__ __forceinline__ float bfhi(unsigned w) { return __uint_as_float(w & 0xffff0000u); }
;     __device__ __forceinline__ void operator()(const i32x4 (&acc)[2][2][4][2], const Unit& u, int wr, int wc, int fr, int fq) const {
;     ...
;             for (int m = 0; m < 4; ++m) { const int row = row0 + ai * HALF + m * 16; const size_t off = (size_t)row * DM + col0; float ss = 0.f;
; #pragma unroll
;                 for (int bj = 0; bj < 2; ++bj) { const u32x4 w = bw[m][bj]; const i32x4 a0 = acc[ai][bj][m][0], a1 = acc[ai][bj][m][1];
;                     const f32x4 b0 = {bflo(w.x), bfhi(w.x), bflo(w.y), bfhi(w.y)}, b1 = {bflo(w.z), bfhi(w.z), bflo(w.w), bfhi(w.w)};
;                     const f32x4 o0 = b0 + (f32x4){(float)a0[0], (float)a0[1], (float)a0[2], (float)a0[3]} * cs[bj][0] * rs[m] + cc[bj][0] * rm[m];
;                     const f32x4 o1 = b1 + (f32x4){(float)a1[0], (float)a1[1], (float)a1[2], (float)a1[3]} * cs[bj][1] * rs[m] + cc[bj][1] * rm[m];
;                     ss += ((o0[0] * o0[0] + o0[1] * o0[1]) + (o0[2] * o0[2] + o0[3] * o0[3])) + ((o1[0] * o1[0] + o1[1] * o1[1]) + (o1[2] * o1[2] + o1[3] * o1[3]));
;                     u32x4 w2; w2.x = cvt_pk_bf16(o0[0], o0[1]); w2.y = cvt_pk_bf16(o0[2], o0[3]); w2.z = cvt_pk_bf16(o1[0], o1[1]); w2.w = cvt_pk_bf16(o1[2], o1[3]);
;                     *(u32x4*)(hout + off + bj * HALF) = w2; }
;                 ss += __shfl_xor(ss, 16); ss += __shfl_xor(ss, 32);
;                 if (fq == 0) part[(size_t)row * 64 + u.pn * 4 + wc] = ss; }
.LBB0_1647:
	s_or_b64 exec, exec, s[36:37]
	v_cvt_f32_i32_e32 v45, v45
	v_cvt_f32_i32_e32 v47, v47
	v_cvt_f32_i32_e32 v46, v46
	v_cvt_f32_i32_e32 v44, v44
	v_cvt_f32_i32_e32 v41, v41
	v_cvt_f32_i32_e32 v43, v43
	v_cvt_f32_i32_e32 v42, v42
	v_cvt_f32_i32_e32 v40, v40
	s_waitcnt vmcnt(7)
	v_lshlrev_b32_e32 v48, 16, v104
	s_waitcnt lgkmcnt(0)
	v_and_b32_e32 v49, 0xffff0000, v104
	v_lshlrev_b32_e32 v50, 16, v105
	v_and_b32_e32 v51, 0xffff0000, v105
	v_pk_mul_f32 v[46:47], v[74:75], v[46:47]
	v_pk_mul_f32 v[44:45], v[72:73], v[44:45]
	v_lshlrev_b32_e32 v104, 16, v106
	v_and_b32_e32 v105, 0xffff0000, v106
	v_lshlrev_b32_e32 v106, 16, v107
	v_and_b32_e32 v107, 0xffff0000, v107
	v_pk_fma_f32 v[46:47], v[46:47], v[132:133], v[50:51] op_sel_hi:[1,0,1]
	v_pk_fma_f32 v[44:45], v[44:45], v[132:133], v[48:49] op_sel_hi:[1,0,1]
	v_pk_mul_f32 v[42:43], v[70:71], v[42:43]
	v_pk_mul_f32 v[40:41], v[68:69], v[40:41]
	v_pk_fma_f32 v[46:47], v[82:83], v[130:131], v[46:47] op_sel_hi:[1,0,1]
	v_pk_fma_f32 v[44:45], v[80:81], v[130:131], v[44:45] op_sel_hi:[1,0,1]
	v_pk_fma_f32 v[42:43], v[42:43], v[132:133], v[106:107] op_sel_hi:[1,0,1]
	v_pk_fma_f32 v[40:41], v[40:41], v[132:133], v[104:105] op_sel_hi:[1,0,1]
	v_pk_fma_f32 v[48:49], v[78:79], v[130:131], v[42:43] op_sel_hi:[1,0,1]
	v_pk_fma_f32 v[42:43], v[76:77], v[130:131], v[40:41] op_sel_hi:[1,0,1]
	v_mul_f32_e32 v40, v45, v45
	v_mul_f32_e32 v41, v47, v47
	v_fmac_f32_e32 v40, v44, v44
	v_fmac_f32_e32 v41, v46, v46
	v_cvt_f32_i32_e32 v37, v37
	v_cvt_f32_i32_e32 v39, v39
	v_cvt_f32_i32_e32 v38, v38
	v_cvt_f32_i32_e32 v36, v36
	v_add_f32_e32 v40, v40, v41
	v_mul_f32_e32 v41, v43, v43
	v_mul_f32_e32 v50, v49, v49
	v_cvt_f32_i32_e32 v33, v33
	v_cvt_f32_i32_e32 v32, v32
	v_fmac_f32_e32 v41, v42, v42
	v_fmac_f32_e32 v50, v48, v48
	v_cvt_f32_i32_e32 v35, v35
	v_cvt_f32_i32_e32 v34, v34
	v_add_f32_e32 v41, v41, v50
	v_add_f32_e32 v104, v40, v41
	v_cvt_pk_bf16_f32 v40, v44, v45
	v_cvt_pk_bf16_f32 v41, v46, v47
	s_waitcnt vmcnt(6)
	v_lshlrev_b32_e32 v44, 16, v100
	v_and_b32_e32 v45, 0xffff0000, v100
	v_lshlrev_b32_e32 v46, 16, v101
	v_and_b32_e32 v47, 0xffff0000, v101
	v_pk_mul_f32 v[38:39], v[94:95], v[38:39]
	v_pk_mul_f32 v[36:37], v[92:93], v[36:37]
	v_cvt_pk_bf16_f32 v42, v42, v43
	v_cvt_pk_bf16_f32 v43, v48, v49
	v_lshlrev_b32_e32 v48, 16, v102
	v_and_b32_e32 v49, 0xffff0000, v102
	v_pk_fma_f32 v[38:39], v[38:39], v[132:133], v[46:47] op_sel_hi:[1,0,1]
	v_pk_fma_f32 v[36:37], v[36:37], v[132:133], v[44:45] op_sel_hi:[1,0,1]
	v_pk_mul_f32 v[32:33], v[84:85], v[32:33]
	v_lshlrev_b32_e32 v50, 16, v103
	v_and_b32_e32 v51, 0xffff0000, v103
	v_pk_fma_f32 v[38:39], v[90:91], v[130:131], v[38:39] op_sel_hi:[1,0,1]
	v_pk_fma_f32 v[36:37], v[88:89], v[130:131], v[36:37] op_sel_hi:[1,0,1]
	v_pk_mul_f32 v[34:35], v[86:87], v[34:35]
	v_pk_fma_f32 v[32:33], v[32:33], v[132:133], v[48:49] op_sel_hi:[1,0,1]
	v_pk_fma_f32 v[34:35], v[34:35], v[132:133], v[50:51] op_sel_hi:[1,0,1]
	v_pk_fma_f32 v[46:47], v[64:65], v[130:131], v[32:33] op_sel_hi:[1,0,1]
	v_mul_f32_e32 v32, v37, v37
	v_mul_f32_e32 v33, v39, v39
	v_pk_fma_f32 v[44:45], v[66:67], v[130:131], v[34:35] op_sel_hi:[1,0,1]
	v_fmac_f32_e32 v32, v36, v36
	v_fmac_f32_e32 v33, v38, v38
	v_add_f32_e32 v32, v32, v33
	v_mul_f32_e32 v33, v47, v47
	v_mul_f32_e32 v34, v45, v45
	v_fmac_f32_e32 v33, v46, v46
	v_fmac_f32_e32 v34, v44, v44
	v_add_f32_e32 v33, v33, v34
	v_add_f32_e32 v32, v32, v33
	v_add_f32_e32 v35, v104, v32
	v_lshl_add_u64 v[32:33], s[74:75], 0, v[126:127]
	v_lshl_add_u64 v[48:49], v[194:195], 1, v[32:33]
	global_store_dwordx4 v[48:49], v[40:43], off
	v_cvt_pk_bf16_f32 v34, v36, v37
	s_waitcnt lgkmcnt(0)
	v_mov_b32_e32 v32, v35
	v_mov_b32_e32 v50, v35
	s_nop 1
	v_permlane16_swap_b32_e32 v32, v50
	s_nop 0
	v_add_f32_e32 v32, v32, v50
	ds_bpermute_b32 v33, v145, v32
	v_cvt_pk_bf16_f32 v35, v38, v39
	v_cvt_pk_bf16_f32 v36, v46, v47
	v_cvt_pk_bf16_f32 v37, v44, v45
	global_store_dwordx4 v[48:49], v[34:37], off offset:256
	s_and_saveexec_b64 s[36:37], s[4:5]
	s_cbranch_execz .LBB0_1649
	v_lshlrev_b64 v[34:35], 8, v[124:125]
	v_lshl_add_u64 v[34:35], s[10:11], 0, v[34:35]
	v_lshl_add_u64 v[34:35], s[34:35], 2, v[34:35]
	s_lshl_b32 s22, s43, 2
	v_lshl_add_u64 v[34:35], v[34:35], 0, s[22:23]
	s_waitcnt lgkmcnt(0)
	v_add_f32_e32 v32, v32, v33
	global_store_dword v[34:35], v32, off
; __device__ __forceinline__ unsigned cvt_pk_bf16(float lo, float hi) { unsigned r; asm volatile("v_cvt_pk_bf16_f32 %0, %1, %2" : "=v"(r) : "v"(lo), "v"(hi)); return r; }
; __device__ __forceinline__ float bflo(unsigned w) { return __uint_as_float(w << 16); }
; __device__ __forceinline__ float bfhi(unsigned w) { return __uint_as_float(w & 0xffff0000u); }
;     __device__ __forceinline__ void operator()(const i32x4 (&acc)[2][2][4][2], const Unit& u, int wr, int wc, int fr, int fq) const {
;     ...
;             for (int m = 0; m < 4; ++m) { const int row = row0 + ai * HALF + m * 16; const size_t off = (size_t)row * DM + col0; float ss = 0.f;
; #pragma unroll
;                 for (int bj = 0; bj < 2; ++bj) { const u32x4 w = bw[m][bj]; const i32x4 a0 = acc[ai][bj][m][0], a1 = acc[ai][bj][m][1];
;                     const f32x4 b0 = {bflo(w.x), bfhi(w.x), bflo(w.y), bfhi(w.y)}, b1 = {bflo(w.z), bfhi(w.z), bflo(w.w), bfhi(w.w)};
;                     const f32x4 o0 = b0 + (f32x4){(float)a0[0], (float)a0[1], (float)a0[2], (float)a0[3]} * cs[bj][0] * rs[m] + cc[bj][0] * rm[m];
;                     const f32x4 o1 = b1 + (f32x4){(float)a1[0], (float)a1[1], (float)a1[2], (float)a1[3]} * cs[bj][1] * rs[m] + cc[bj][1] * rm[m];
;                     ss += ((o0[0] * o0[0] + o0[1] * o0[1]) + (o0[2] * o0[2] + o0[3] * o0[3])) + ((o1[0] * o1[0] + o1[1] * o1[1]) + (o1[2] * o1[2] + o1[3] * o1[3]));
;                     u32x4 w2; w2.x = cvt_pk_bf16(o0[0], o0[1]); w2.y = cvt_pk_bf16(o0[2], o0[3]); w2.z = cvt_pk_bf16(o1[0], o1[1]); w2.w = cvt_pk_bf16(o1[2], o1[3]);
;                     *(u32x4*)(hout + off + bj * HALF) = w2; }
;                 ss += __shfl_xor(ss, 16); ss += __shfl_xor(ss, 32);
;                 if (fq == 0) part[(size_t)row * 64 + u.pn * 4 + wc] = ss; }
.LBB0_1649:
	s_or_b64 exec, exec, s[36:37]
	v_cvt_f32_i32_e32 v29, v29
	v_cvt_f32_i32_e32 v31, v31
	v_cvt_f32_i32_e32 v30, v30
	v_cvt_f32_i32_e32 v28, v28
	v_cvt_f32_i32_e32 v25, v25
	v_cvt_f32_i32_e32 v27, v27
	v_cvt_f32_i32_e32 v26, v26
	v_cvt_f32_i32_e32 v24, v24
	s_waitcnt vmcnt(7)
	v_lshlrev_b32_e32 v32, 16, v96
	s_waitcnt lgkmcnt(0)
	v_and_b32_e32 v33, 0xffff0000, v96
	v_lshlrev_b32_e32 v34, 16, v97
	v_and_b32_e32 v35, 0xffff0000, v97
	v_pk_mul_f32 v[30:31], v[74:75], v[30:31]
	v_pk_mul_f32 v[28:29], v[72:73], v[28:29]
	v_lshlrev_b32_e32 v36, 16, v98
	v_and_b32_e32 v37, 0xffff0000, v98
	v_lshlrev_b32_e32 v38, 16, v99
	v_and_b32_e32 v39, 0xffff0000, v99
	v_pk_fma_f32 v[30:31], v[30:31], v[122:123], v[34:35] op_sel_hi:[1,0,1]
	v_pk_fma_f32 v[28:29], v[28:29], v[122:123], v[32:33] op_sel_hi:[1,0,1]
	v_pk_mul_f32 v[26:27], v[70:71], v[26:27]
	v_pk_mul_f32 v[24:25], v[68:69], v[24:25]
	v_pk_fma_f32 v[30:31], v[82:83], v[120:121], v[30:31] op_sel_hi:[1,0,1]
	v_pk_fma_f32 v[28:29], v[80:81], v[120:121], v[28:29] op_sel_hi:[1,0,1]
	v_pk_fma_f32 v[26:27], v[26:27], v[122:123], v[38:39] op_sel_hi:[1,0,1]
	v_pk_fma_f32 v[24:25], v[24:25], v[122:123], v[36:37] op_sel_hi:[1,0,1]
	v_pk_fma_f32 v[32:33], v[78:79], v[120:121], v[26:27] op_sel_hi:[1,0,1]
	v_pk_fma_f32 v[26:27], v[76:77], v[120:121], v[24:25] op_sel_hi:[1,0,1]
	v_mul_f32_e32 v24, v29, v29
	v_mul_f32_e32 v25, v31, v31
	v_fmac_f32_e32 v24, v28, v28
	v_fmac_f32_e32 v25, v30, v30
	v_cvt_f32_i32_e32 v21, v21
	v_cvt_f32_i32_e32 v23, v23
	v_cvt_f32_i32_e32 v22, v22
	v_cvt_f32_i32_e32 v20, v20
	v_add_f32_e32 v24, v24, v25
	v_mul_f32_e32 v25, v27, v27
	v_mul_f32_e32 v34, v33, v33
	v_cvt_f32_i32_e32 v17, v17
	v_cvt_f32_i32_e32 v16, v16
	v_fmac_f32_e32 v25, v26, v26
	v_fmac_f32_e32 v34, v32, v32
	v_cvt_f32_i32_e32 v19, v19
	v_cvt_f32_i32_e32 v18, v18
	v_add_f32_e32 v25, v25, v34
	v_add_f32_e32 v36, v24, v25
	v_cvt_pk_bf16_f32 v24, v28, v29
	v_cvt_pk_bf16_f32 v25, v30, v31
	s_waitcnt vmcnt(6)
	v_lshlrev_b32_e32 v28, 16, v60
	v_and_b32_e32 v29, 0xffff0000, v60
	v_lshlrev_b32_e32 v30, 16, v61
	v_and_b32_e32 v31, 0xffff0000, v61
	v_pk_mul_f32 v[22:23], v[94:95], v[22:23]
	v_pk_mul_f32 v[20:21], v[92:93], v[20:21]
	v_cvt_pk_bf16_f32 v26, v26, v27
	v_cvt_pk_bf16_f32 v27, v32, v33
	v_lshlrev_b32_e32 v32, 16, v62
	v_and_b32_e32 v33, 0xffff0000, v62
	v_pk_fma_f32 v[22:23], v[22:23], v[122:123], v[30:31] op_sel_hi:[1,0,1]
	v_pk_fma_f32 v[20:21], v[20:21], v[122:123], v[28:29] op_sel_hi:[1,0,1]
	v_pk_mul_f32 v[16:17], v[84:85], v[16:17]
	v_lshlrev_b32_e32 v34, 16, v63
	v_and_b32_e32 v35, 0xffff0000, v63
	v_pk_fma_f32 v[22:23], v[90:91], v[120:121], v[22:23] op_sel_hi:[1,0,1]
	v_pk_fma_f32 v[20:21], v[88:89], v[120:121], v[20:21] op_sel_hi:[1,0,1]
	v_pk_mul_f32 v[18:19], v[86:87], v[18:19]
	v_pk_fma_f32 v[16:17], v[16:17], v[122:123], v[32:33] op_sel_hi:[1,0,1]
	v_pk_fma_f32 v[18:19], v[18:19], v[122:123], v[34:35] op_sel_hi:[1,0,1]
	v_pk_fma_f32 v[30:31], v[64:65], v[120:121], v[16:17] op_sel_hi:[1,0,1]
	v_mul_f32_e32 v16, v21, v21
	v_mul_f32_e32 v17, v23, v23
	v_pk_fma_f32 v[28:29], v[66:67], v[120:121], v[18:19] op_sel_hi:[1,0,1]
	v_fmac_f32_e32 v16, v20, v20
	v_fmac_f32_e32 v17, v22, v22
	v_add_f32_e32 v16, v16, v17
	v_mul_f32_e32 v17, v31, v31
	v_mul_f32_e32 v18, v29, v29
	v_fmac_f32_e32 v17, v30, v30
	v_fmac_f32_e32 v18, v28, v28
	v_add_f32_e32 v17, v17, v18
	v_add_f32_e32 v16, v16, v17
	v_add_f32_e32 v19, v36, v16
	v_lshl_add_u64 v[16:17], s[74:75], 0, v[118:119]
	v_lshl_add_u64 v[32:33], v[194:195], 1, v[16:17]
	global_store_dwordx4 v[32:33], v[24:27], off
	v_cvt_pk_bf16_f32 v18, v20, v21
	s_waitcnt lgkmcnt(0)
	v_mov_b32_e32 v16, v19
	v_mov_b32_e32 v34, v19
	s_nop 1
	v_permlane16_swap_b32_e32 v16, v34
	s_nop 0
	v_add_f32_e32 v16, v16, v34
	ds_bpermute_b32 v17, v145, v16
	v_cvt_pk_bf16_f32 v19, v22, v23
	v_cvt_pk_bf16_f32 v20, v30, v31
	v_cvt_pk_bf16_f32 v21, v28, v29
	global_store_dwordx4 v[32:33], v[18:21], off offset:256
	s_and_saveexec_b64 s[36:37], s[4:5]
	s_cbranch_execz .LBB0_1651
	v_lshlrev_b64 v[18:19], 8, v[116:117]
	v_lshl_add_u64 v[18:19], s[10:11], 0, v[18:19]
	v_lshl_add_u64 v[18:19], s[34:35], 2, v[18:19]
	s_lshl_b32 s22, s43, 2
	v_lshl_add_u64 v[18:19], v[18:19], 0, s[22:23]
	s_waitcnt lgkmcnt(0)
	v_add_f32_e32 v16, v16, v17
	global_store_dword v[18:19], v16, off
; __device__ __forceinline__ unsigned cvt_pk_bf16(float lo, float hi) { unsigned r; asm volatile("v_cvt_pk_bf16_f32 %0, %1, %2" : "=v"(r) : "v"(lo), "v"(hi)); return r; }
; __device__ __forceinline__ float bflo(unsigned w) { return __uint_as_float(w << 16); }
; __device__ __forceinline__ float bfhi(unsigned w) { return __uint_as_float(w & 0xffff0000u); }
;     __device__ __forceinline__ void operator()(const i32x4 (&acc)[2][2][4][2], const Unit& u, int wr, int wc, int fr, int fq) const {
;     ...
;             for (int m = 0; m < 4; ++m) { const int row = row0 + ai * HALF + m * 16; const size_t off = (size_t)row * DM + col0; float ss = 0.f;
; #pragma unroll
;                 for (int bj = 0; bj < 2; ++bj) { const u32x4 w = bw[m][bj]; const i32x4 a0 = acc[ai][bj][m][0], a1 = acc[ai][bj][m][1];
;                     const f32x4 b0 = {bflo(w.x), bfhi(w.x), bflo(w.y), bfhi(w.y)}, b1 = {bflo(w.z), bfhi(w.z), bflo(w.w), bfhi(w.w)};
;                     const f32x4 o0 = b0 + (f32x4){(float)a0[0], (float)a0[1], (float)a0[2], (float)a0[3]} * cs[bj][0] * rs[m] + cc[bj][0] * rm[m];
;                     const f32x4 o1 = b1 + (f32x4){(float)a1[0], (float)a1[1], (float)a1[2], (float)a1[3]} * cs[bj][1] * rs[m] + cc[bj][1] * rm[m];
;                     ss += ((o0[0] * o0[0] + o0[1] * o0[1]) + (o0[2] * o0[2] + o0[3] * o0[3])) + ((o1[0] * o1[0] + o1[1] * o1[1]) + (o1[2] * o1[2] + o1[3] * o1[3]));
;                     u32x4 w2; w2.x = cvt_pk_bf16(o0[0], o0[1]); w2.y = cvt_pk_bf16(o0[2], o0[3]); w2.z = cvt_pk_bf16(o1[0], o1[1]); w2.w = cvt_pk_bf16(o1[2], o1[3]);
;                     *(u32x4*)(hout + off + bj * HALF) = w2; }
;                 ss += __shfl_xor(ss, 16); ss += __shfl_xor(ss, 32);
;                 if (fq == 0) part[(size_t)row * 64 + u.pn * 4 + wc] = ss; }
.LBB0_1651:
	s_or_b64 exec, exec, s[36:37]
	v_cvt_f32_i32_e32 v13, v13
	v_cvt_f32_i32_e32 v15, v15
	v_cvt_f32_i32_e32 v14, v14
	v_cvt_f32_i32_e32 v12, v12
	v_cvt_f32_i32_e32 v9, v9
	v_cvt_f32_i32_e32 v11, v11
	v_cvt_f32_i32_e32 v10, v10
	v_cvt_f32_i32_e32 v8, v8
	s_waitcnt vmcnt(7)
	v_lshlrev_b32_e32 v16, 16, v56
	s_waitcnt lgkmcnt(0)
	v_and_b32_e32 v17, 0xffff0000, v56
	v_lshlrev_b32_e32 v18, 16, v57
	v_and_b32_e32 v19, 0xffff0000, v57
	v_pk_mul_f32 v[14:15], v[74:75], v[14:15]
	v_pk_mul_f32 v[12:13], v[72:73], v[12:13]
	v_lshlrev_b32_e32 v20, 16, v58
	v_and_b32_e32 v21, 0xffff0000, v58
	v_lshlrev_b32_e32 v22, 16, v59
	v_and_b32_e32 v23, 0xffff0000, v59
	v_pk_fma_f32 v[14:15], v[14:15], v[114:115], v[18:19] op_sel_hi:[1,0,1]
	v_pk_fma_f32 v[12:13], v[12:13], v[114:115], v[16:17] op_sel_hi:[1,0,1]
	v_pk_mul_f32 v[10:11], v[70:71], v[10:11]
	v_pk_mul_f32 v[8:9], v[68:69], v[8:9]
	v_pk_fma_f32 v[14:15], v[82:83], v[112:113], v[14:15] op_sel_hi:[1,0,1]
	v_pk_fma_f32 v[12:13], v[80:81], v[112:113], v[12:13] op_sel_hi:[1,0,1]
	v_pk_fma_f32 v[10:11], v[10:11], v[114:115], v[22:23] op_sel_hi:[1,0,1]
	v_pk_fma_f32 v[8:9], v[8:9], v[114:115], v[20:21] op_sel_hi:[1,0,1]
	v_pk_fma_f32 v[16:17], v[78:79], v[112:113], v[10:11] op_sel_hi:[1,0,1]
	v_pk_fma_f32 v[10:11], v[76:77], v[112:113], v[8:9] op_sel_hi:[1,0,1]
	v_mul_f32_e32 v8, v13, v13
	v_mul_f32_e32 v9, v15, v15
	v_fmac_f32_e32 v8, v12, v12
	v_fmac_f32_e32 v9, v14, v14
	v_cvt_f32_i32_e32 v5, v5
	v_cvt_f32_i32_e32 v7, v7
	v_cvt_f32_i32_e32 v6, v6
	v_cvt_f32_i32_e32 v4, v4
	v_add_f32_e32 v8, v8, v9
	v_mul_f32_e32 v9, v11, v11
	v_mul_f32_e32 v18, v17, v17
	v_cvt_f32_i32_e32 v1, v1
	v_cvt_f32_i32_e32 v0, v0
	v_fmac_f32_e32 v9, v10, v10
	v_fmac_f32_e32 v18, v16, v16
	v_cvt_f32_i32_e32 v3, v3
	v_cvt_f32_i32_e32 v2, v2
	v_add_f32_e32 v9, v9, v18
	v_add_f32_e32 v20, v8, v9
	v_cvt_pk_bf16_f32 v8, v12, v13
	v_cvt_pk_bf16_f32 v9, v14, v15
	s_waitcnt vmcnt(6)
	v_lshlrev_b32_e32 v12, 16, v52
	v_and_b32_e32 v13, 0xffff0000, v52
	v_lshlrev_b32_e32 v14, 16, v53
	v_and_b32_e32 v15, 0xffff0000, v53
	v_pk_mul_f32 v[6:7], v[94:95], v[6:7]
	v_pk_mul_f32 v[4:5], v[92:93], v[4:5]
	v_cvt_pk_bf16_f32 v10, v10, v11
	v_cvt_pk_bf16_f32 v11, v16, v17
	v_lshlrev_b32_e32 v16, 16, v54
	v_and_b32_e32 v17, 0xffff0000, v54
	v_pk_fma_f32 v[6:7], v[6:7], v[114:115], v[14:15] op_sel_hi:[1,0,1]
	v_pk_fma_f32 v[4:5], v[4:5], v[114:115], v[12:13] op_sel_hi:[1,0,1]
	v_pk_mul_f32 v[0:1], v[84:85], v[0:1]
	v_lshlrev_b32_e32 v18, 16, v55
	v_and_b32_e32 v19, 0xffff0000, v55
	v_pk_fma_f32 v[6:7], v[90:91], v[112:113], v[6:7] op_sel_hi:[1,0,1]
	v_pk_fma_f32 v[4:5], v[88:89], v[112:113], v[4:5] op_sel_hi:[1,0,1]
	v_pk_mul_f32 v[2:3], v[86:87], v[2:3]
	v_pk_fma_f32 v[0:1], v[0:1], v[114:115], v[16:17] op_sel_hi:[1,0,1]
	v_pk_fma_f32 v[2:3], v[2:3], v[114:115], v[18:19] op_sel_hi:[1,0,1]
	v_pk_fma_f32 v[14:15], v[64:65], v[112:113], v[0:1] op_sel_hi:[1,0,1]
	v_mul_f32_e32 v0, v5, v5
	v_mul_f32_e32 v1, v7, v7
	v_pk_fma_f32 v[12:13], v[66:67], v[112:113], v[2:3] op_sel_hi:[1,0,1]
	v_fmac_f32_e32 v0, v4, v4
	v_fmac_f32_e32 v1, v6, v6
	v_add_f32_e32 v0, v0, v1
	v_mul_f32_e32 v1, v15, v15
	v_mul_f32_e32 v2, v13, v13
	v_fmac_f32_e32 v1, v14, v14
	v_fmac_f32_e32 v2, v12, v12
	v_add_f32_e32 v1, v1, v2
	v_add_f32_e32 v0, v0, v1
	v_add_f32_e32 v3, v20, v0
	v_lshl_add_u64 v[0:1], s[74:75], 0, v[110:111]
	v_lshl_add_u64 v[16:17], v[194:195], 1, v[0:1]
	global_store_dwordx4 v[16:17], v[8:11], off
	v_cvt_pk_bf16_f32 v2, v4, v5
	s_waitcnt lgkmcnt(0)
	v_mov_b32_e32 v0, v3
	v_mov_b32_e32 v18, v3
	s_nop 1
	v_permlane16_swap_b32_e32 v0, v18
	s_nop 0
	v_add_f32_e32 v0, v0, v18
	ds_bpermute_b32 v1, v145, v0
	v_cvt_pk_bf16_f32 v3, v6, v7
	v_cvt_pk_bf16_f32 v4, v14, v15
	v_cvt_pk_bf16_f32 v5, v12, v13
	global_store_dwordx4 v[16:17], v[2:5], off offset:256
	s_and_saveexec_b64 s[36:37], s[4:5]
	s_cbranch_execz .LBB0_1653
	v_lshlrev_b64 v[2:3], 8, v[108:109]
	v_lshl_add_u64 v[2:3], s[10:11], 0, v[2:3]
	v_lshl_add_u64 v[2:3], s[34:35], 2, v[2:3]
	s_lshl_b32 s22, s43, 2
	v_lshl_add_u64 v[2:3], v[2:3], 0, s[22:23]
	s_waitcnt lgkmcnt(0)
	v_add_f32_e32 v0, v0, v1
	global_store_dword v[2:3], v0, off

; __device__ __forceinline__ float wave_sum(float v) {
; #pragma unroll
;     for (int o = 1; o < 64; o <<= 1) v += __shfl_xor(v, o);
;     return v;
; }
; __global__ void __launch_bounds__(NWAVES * 64, 2) fwd(Args args) {
;     ...
;         for (int row = gw; row < T; row += 2 * NGW) {
;             const int row2 = row + NGW;
;             const float pa = part[(size_t)row * 64 + F.lane], pb = part[(size_t)row2 * 64 + F.lane];
;             const u32x4* hp = (const u32x4*)(hb + (size_t)row * DM) + F.lane; const u32x4* hq = (const u32x4*)(hb + (size_t)row2 * DM) + F.lane; u32x4 wa[8], wb[8];
; #pragma unroll
;             for (int j = 0; j < 8; ++j) { wa[j] = hp[64 * j]; wb[j] = hq[64 * j]; }
;             const float rsa = 1.0f / sqrtf(wave_sum(pa) * (1.0f / DM) + EPS), rsb = 1.0f / sqrtf(wave_sum(pb) * (1.0f / DM) + EPS);
.LBB0_1714:
	v_lshl_add_u64 v[4:5], s[78:79], 0, v[72:73]
	v_lshl_add_u64 v[6:7], s[78:79], 0, v[70:71]
	v_lshl_add_u64 v[2:3], s[78:79], 0, v[68:69]
	flat_load_dwordx4 v[28:31], v[42:43]
	flat_load_dwordx4 v[24:27], v[42:43] offset:16
	global_load_dword v163, v[4:5], off
	global_load_dword v164, v[6:7], off
	v_add_co_u32_e32 v4, vcc, 0x26000000, v2
	v_lshl_add_u64 v[0:1], s[78:79], 0, v[74:75]
	s_nop 0
	v_addc_co_u32_e32 v5, vcc, 0, v3, vcc
	global_load_dwordx4 v[98:101], v[4:5], off
	global_load_dwordx4 v[102:105], v[4:5], off offset:1024
	global_load_dwordx4 v[106:109], v[4:5], off offset:2048
	v_add_co_u32_e32 v6, vcc, 0x26000000, v0
	v_lshl_add_u64 v[78:79], s[10:11], 0, v[40:41]
	s_nop 0
	v_addc_co_u32_e32 v7, vcc, 0, v1, vcc
	global_load_dwordx4 v[110:113], v[6:7], off
	global_load_dwordx4 v[114:117], v[6:7], off offset:1024
	global_load_dwordx4 v[118:121], v[6:7], off offset:2048
	global_load_dwordx4 v[122:125], v[4:5], off offset:3072
	global_load_dwordx4 v[126:129], v[6:7], off offset:3072
	v_add_co_u32_e64 v84, s[0:1], s19, v78
	v_lshl_add_u64 v[76:77], s[16:17], 0, v[40:41]
	s_nop 0
	v_addc_co_u32_e64 v85, s[0:1], 0, v79, s[0:1]
	v_add_co_u32_e64 v80, s[0:1], s20, v78
	v_add_co_u32_e32 v2, vcc, s7, v2
	s_nop 0
	v_addc_co_u32_e64 v81, s[0:1], 0, v79, s[0:1]
	v_add_co_u32_e64 v86, s[0:1], s19, v76
	v_addc_co_u32_e32 v3, vcc, 0, v3, vcc
	s_nop 0
	v_addc_co_u32_e64 v87, s[0:1], 0, v77, s[0:1]
	v_add_co_u32_e64 v82, s[0:1], s20, v76
	v_add_co_u32_e32 v0, vcc, s7, v0
	s_nop 0
	v_addc_co_u32_e64 v83, s[0:1], 0, v77, s[0:1]
	v_addc_co_u32_e32 v1, vcc, 0, v1, vcc
	global_load_dwordx4 v[36:39], v[2:3], off
	global_load_dwordx4 v[20:23], v[2:3], off offset:1024
	global_load_dwordx4 v[12:15], v[2:3], off offset:2048
	global_load_dwordx4 v[16:19], v[0:1], off offset:1024
	global_load_dwordx4 v[8:11], v[0:1], off offset:2048
	global_load_dwordx4 v[32:35], v[0:1], off
	global_load_dwordx4 v[4:7], v[2:3], off offset:3072
	s_nop 0
	global_load_dwordx4 v[0:3], v[0:1], off offset:3072
	s_add_i32 s82, s82, s6
	s_add_u32 s10, s10, s12
	s_addc_u32 s11, s11, s13
	s_add_u32 s16, s16, s12
	s_addc_u32 s17, s17, s13
	v_lshl_add_u64 v[68:69], v[68:69], 0, s[8:9]
	v_lshl_add_u64 v[70:71], v[70:71], 0, s[14:15]
	v_lshl_add_u64 v[72:73], v[72:73], 0, s[14:15]
	v_lshl_add_u64 v[74:75], v[74:75], 0, s[8:9]
	s_cmpk_lt_i32 s82, 0x4000
	s_waitcnt vmcnt(0)
	s_nop 1
	v_mov_b32_dpp v165, v163 quad_perm:[1,0,3,2] row_mask:0xf bank_mask:0xf
	s_nop 1
	v_mov_b32_dpp v166, v164 quad_perm:[1,0,3,2] row_mask:0xf bank_mask:0xf
	v_lshlrev_b32_e32 v132, 16, v100
	v_and_b32_e32 v133, 0xffff0000, v100
	v_lshlrev_b32_e32 v88, 16, v106
	v_and_b32_e32 v89, 0xffff0000, v106
	v_lshlrev_b32_e32 v142, 16, v107
	v_and_b32_e32 v143, 0xffff0000, v107
	v_lshlrev_b32_e32 v144, 16, v108
	v_and_b32_e32 v145, 0xffff0000, v108
	v_lshlrev_b32_e32 v146, 16, v109
	v_and_b32_e32 v147, 0xffff0000, v109
	v_lshlrev_b32_e32 v106, 16, v110
	v_and_b32_e32 v107, 0xffff0000, v110
	v_lshlrev_b32_e32 v108, 16, v111
	v_and_b32_e32 v109, 0xffff0000, v111
	v_lshlrev_b32_e32 v110, 16, v112
	v_and_b32_e32 v111, 0xffff0000, v112
	v_lshlrev_b32_e32 v100, 16, v101
	v_and_b32_e32 v101, 0xffff0000, v101
	v_lshlrev_b32_e32 v138, 16, v104
	v_and_b32_e32 v139, 0xffff0000, v104
	v_lshlrev_b32_e32 v140, 16, v105
	v_and_b32_e32 v141, 0xffff0000, v105
	s_waitcnt lgkmcnt(0)
	v_pk_mul_f32 v[104:105], v[24:25], v[132:133]
	v_lshlrev_b32_e32 v112, 16, v113
	v_and_b32_e32 v113, 0xffff0000, v113
	v_pk_mul_f32 v[110:111], v[24:25], v[110:111]
	v_add_f32_e32 v24, v163, v165
	v_pk_mul_f32 v[100:101], v[26:27], v[100:101]
	v_pk_mul_f32 v[112:113], v[26:27], v[112:113]
	v_add_f32_e32 v25, v164, v166
	s_nop 1
	v_mov_b32_dpp v26, v24 quad_perm:[2,3,0,1] row_mask:0xf bank_mask:0xf
	s_nop 1
	v_mov_b32_dpp v27, v25 quad_perm:[2,3,0,1] row_mask:0xf bank_mask:0xf
	v_lshlrev_b32_e32 v130, 16, v98
	v_and_b32_e32 v131, 0xffff0000, v98
	v_lshlrev_b32_e32 v98, 16, v99
	s_waitcnt lgkmcnt(0)
	v_add_f32_e32 v24, v24, v26
	s_waitcnt lgkmcnt(0)
	v_add_f32_e32 v25, v25, v27
	s_nop 1
	v_mov_b32_dpp v26, v24 row_half_mirror row_mask:0xf bank_mask:0xf
	s_nop 1
	v_mov_b32_dpp v27, v25 row_half_mirror row_mask:0xf bank_mask:0xf
	v_and_b32_e32 v99, 0xffff0000, v99
	v_lshlrev_b32_e32 v134, 16, v102
	v_and_b32_e32 v135, 0xffff0000, v102
	s_waitcnt lgkmcnt(0)
	v_add_f32_e32 v24, v24, v26
	s_waitcnt lgkmcnt(0)
	v_add_f32_e32 v25, v25, v27
	s_nop 1
	v_mov_b32_dpp v26, v24 row_mirror row_mask:0xf bank_mask:0xf
	s_nop 1
	v_mov_b32_dpp v27, v25 row_mirror row_mask:0xf bank_mask:0xf
	v_lshlrev_b32_e32 v136, 16, v103
	v_and_b32_e32 v137, 0xffff0000, v103
	v_pk_mul_f32 v[102:103], v[28:29], v[130:131]
	s_waitcnt lgkmcnt(0)
	v_add_f32_e32 v24, v24, v26
	s_waitcnt lgkmcnt(0)
	v_add_f32_e32 v25, v25, v27
	v_pk_mul_f32 v[106:107], v[28:29], v[106:107]
	v_pk_mul_f32 v[98:99], v[30:31], v[98:99]
	v_pk_mul_f32 v[108:109], v[30:31], v[108:109]
	s_waitcnt lgkmcnt(0)
	v_mov_b32_e32 v26, v24
	s_nop 1
	v_permlane16_swap_b32_e32 v24, v26
	s_nop 0
	v_add_f32_e32 v24, v24, v26
	s_waitcnt lgkmcnt(0)
	v_mov_b32_e32 v27, v25
	s_nop 1
	v_permlane16_swap_b32_e32 v25, v27
	s_nop 0
	v_add_f32_e32 v25, v25, v27
	v_lshlrev_b32_e32 v130, 16, v114
	v_and_b32_e32 v131, 0xffff0000, v114
	v_lshlrev_b32_e32 v114, 16, v115
	s_waitcnt lgkmcnt(0)
	v_mov_b32_e32 v26, v24
	s_nop 1
	v_permlane32_swap_b32_e32 v24, v26
	s_nop 0
	v_add_f32_e32 v24, v24, v26
	s_waitcnt lgkmcnt(0)
; __device__ __forceinline__ float bflo(unsigned w) { return __uint_as_float(w << 16); }
; __device__ __forceinline__ float bfhi(unsigned w) { return __uint_as_float(w & 0xffff0000u); }
; __global__ void __launch_bounds__(NWAVES * 64, 2) fwd(Args args) {
;     ...
;             const float rsa = 1.0f / sqrtf(wave_sum(pa) * (1.0f / DM) + EPS), rsb = 1.0f / sqrtf(wave_sum(pb) * (1.0f / DM) + EPS);
;             f32x4* oa = (f32x4*)(F.out + (size_t)row * DM) + 2 * F.lane; f32x4* ob = (f32x4*)(F.out + (size_t)row2 * DM) + 2 * F.lane;
; #pragma unroll
;             for (int j = 0; j < 8; ++j) { const f32x4 g0 = gfp[128 * j], g1 = gfp[128 * j + 1]; const u32x4 w = wa[j], w2 = wb[j];
;                 const f32x4 v0 = {bflo(w.x) * g0[0] * rsa, bfhi(w.x) * g0[1] * rsa, bflo(w.y) * g0[2] * rsa, bfhi(w.y) * g0[3] * rsa}, v1 = {bflo(w.z) * g1[0] * rsa, bfhi(w.z) * g1[1] * rsa, bflo(w.w) * g1[2] * rsa, bfhi(w.w) * g1[3] * rsa};
;                 const f32x4 u0 = {bflo(w2.x) * g0[0] * rsb, bfhi(w2.x) * g0[1] * rsb, bflo(w2.y) * g0[2] * rsb, bfhi(w2.y) * g0[3] * rsb}, u1 = {bflo(w2.z) * g1[0] * rsb, bfhi(w2.z) * g1[1] * rsb, bflo(w2.w) * g1[2] * rsb, bfhi(w2.w) * g1[3] * rsb};
;                 __builtin_nontemporal_store(v0, oa + 128 * j); __builtin_nontemporal_store(v1, oa + 128 * j + 1); __builtin_nontemporal_store(u0, ob + 128 * j); __builtin_nontemporal_store(u1, ob + 128 * j + 1); } }
	v_mov_b32_e32 v27, v25
	s_nop 1
	v_permlane32_swap_b32_e32 v25, v27
	s_nop 0
	v_add_f32_e32 v25, v25, v27
	v_fmamk_f32 v24, v24, 0x39800000, v96
	v_fmamk_f32 v25, v25, 0x39800000, v96
	v_mul_f32_e32 v26, 0x4f800000, v24
	v_cmp_gt_f32_e64 s[0:1], s18, v24
	v_mul_f32_e32 v27, 0x4f800000, v25
	v_cmp_gt_f32_e32 vcc, s18, v25
	v_cndmask_b32_e64 v24, v24, v26, s[0:1]
	v_sqrt_f32_e32 v26, v24
	v_cndmask_b32_e32 v25, v25, v27, vcc
	v_sqrt_f32_e32 v27, v25
	v_and_b32_e32 v115, 0xffff0000, v115
	v_add_u32_e32 v28, -1, v26
	v_add_u32_e32 v29, 1, v26
	v_add_u32_e32 v30, -1, v27
	v_fma_f32 v163, -v28, v26, v24
	v_add_u32_e32 v31, 1, v27
	v_fma_f32 v164, -v29, v26, v24
	v_fma_f32 v165, -v30, v27, v25
	v_cmp_ge_f32_e64 s[2:3], 0, v163
	v_fma_f32 v166, -v31, v27, v25
	v_cmp_lt_f32_e64 s[4:5], 0, v164
	v_cndmask_b32_e64 v26, v26, v28, s[2:3]
	v_cmp_ge_f32_e64 s[2:3], 0, v165
	v_cndmask_b32_e64 v26, v26, v29, s[4:5]
	v_mul_f32_e32 v28, 0x37800000, v26
	v_cndmask_b32_e64 v27, v27, v30, s[2:3]
	v_cmp_lt_f32_e64 s[2:3], 0, v166
	v_cndmask_b32_e64 v26, v26, v28, s[0:1]
	v_cmp_class_f32_e64 s[0:1], v24, v97
	v_cndmask_b32_e64 v27, v27, v31, s[2:3]
	v_mul_f32_e32 v29, 0x37800000, v27
	v_cndmask_b32_e32 v27, v27, v29, vcc
	v_cmp_class_f32_e32 vcc, v25, v97
	v_cndmask_b32_e64 v24, v26, v24, s[0:1]
	v_div_scale_f32 v26, s[0:1], v24, v24, 1.0
	v_cndmask_b32_e32 v25, v27, v25, vcc
	v_div_scale_f32 v28, s[0:1], v25, v25, 1.0
	v_rcp_f32_e32 v30, v26
	v_rcp_f32_e32 v31, v28
	v_div_scale_f32 v27, vcc, 1.0, v24, 1.0
	v_fma_f32 v163, -v26, v30, 1.0
	v_fma_f32 v164, -v28, v31, 1.0
	v_fmac_f32_e32 v30, v163, v30
	v_div_scale_f32 v29, s[0:1], 1.0, v25, 1.0
	v_fmac_f32_e32 v31, v164, v31
	v_mul_f32_e32 v163, v27, v30
	v_mul_f32_e32 v164, v29, v31
	v_fma_f32 v165, -v26, v163, v27
	v_fma_f32 v166, -v28, v164, v29
	v_fmac_f32_e32 v163, v165, v30
	v_fmac_f32_e32 v164, v166, v31
	v_fma_f32 v26, -v26, v163, v27
	v_fma_f32 v27, -v28, v164, v29
	v_div_fmas_f32 v26, v26, v30, v163
	s_mov_b64 vcc, s[0:1]
	v_div_fixup_f32 v26, v26, v24, 1.0
	v_div_fmas_f32 v24, v27, v31, v164
	v_div_fixup_f32 v24, v24, v25, 1.0
	v_pk_mul_f32 v[28:29], v[26:27], v[102:103] op_sel_hi:[0,1]
	v_pk_mul_f32 v[30:31], v[26:27], v[98:99] op_sel_hi:[0,1]
	v_pk_mul_f32 v[98:99], v[26:27], v[104:105] op_sel_hi:[0,1]
	v_pk_mul_f32 v[100:101], v[26:27], v[100:101] op_sel_hi:[0,1]
	v_pk_mul_f32 v[102:103], v[24:25], v[106:107] op_sel_hi:[0,1]
	v_pk_mul_f32 v[104:105], v[24:25], v[108:109] op_sel_hi:[0,1]
	v_pk_mul_f32 v[106:107], v[24:25], v[110:111] op_sel_hi:[0,1]
	v_pk_mul_f32 v[108:109], v[24:25], v[112:113] op_sel_hi:[0,1]
	global_store_dwordx4 v[78:79], v[28:31], off nt
	global_store_dwordx4 v[78:79], v[98:101], off offset:16 nt
	global_store_dwordx4 v[76:77], v[102:105], off nt
	global_store_dwordx4 v[76:77], v[106:109], off offset:16 nt
	flat_load_dwordx4 v[28:31], v[42:43] offset:2048
	s_nop 0
	flat_load_dwordx4 v[98:101], v[42:43] offset:2064
	v_lshlrev_b32_e32 v132, 16, v116
	v_and_b32_e32 v133, 0xffff0000, v116
	v_lshlrev_b32_e32 v116, 16, v117
	v_and_b32_e32 v117, 0xffff0000, v117
	v_lshlrev_b32_e32 v148, 16, v118
	v_and_b32_e32 v149, 0xffff0000, v118
	v_lshlrev_b32_e32 v118, 16, v119
	v_and_b32_e32 v119, 0xffff0000, v119
	v_lshlrev_b32_e32 v150, 16, v120
	v_and_b32_e32 v151, 0xffff0000, v120
	v_lshlrev_b32_e32 v120, 16, v121
	v_and_b32_e32 v121, 0xffff0000, v121
	v_lshlrev_b32_e32 v152, 16, v122
	v_and_b32_e32 v153, 0xffff0000, v122
	v_lshlrev_b32_e32 v122, 16, v123
	v_and_b32_e32 v123, 0xffff0000, v123
	v_lshlrev_b32_e32 v154, 16, v124
	v_and_b32_e32 v155, 0xffff0000, v124
	v_lshlrev_b32_e32 v124, 16, v125
	v_and_b32_e32 v125, 0xffff0000, v125
	v_lshlrev_b32_e32 v156, 16, v126
	v_and_b32_e32 v157, 0xffff0000, v126
	v_lshlrev_b32_e32 v126, 16, v127
	v_and_b32_e32 v127, 0xffff0000, v127
	v_lshlrev_b32_e32 v158, 16, v128
	v_and_b32_e32 v159, 0xffff0000, v128
	v_lshlrev_b32_e32 v128, 16, v129
	v_and_b32_e32 v129, 0xffff0000, v129
	v_lshlrev_b32_e32 v160, 16, v36
	v_and_b32_e32 v161, 0xffff0000, v36
	v_lshlrev_b32_e32 v36, 16, v37
	v_and_b32_e32 v37, 0xffff0000, v37
	v_lshlrev_b32_e32 v162, 16, v38
	v_and_b32_e32 v163, 0xffff0000, v38
	v_lshlrev_b32_e32 v38, 16, v39
	v_and_b32_e32 v39, 0xffff0000, v39
	s_waitcnt vmcnt(0) lgkmcnt(0)
	v_pk_mul_f32 v[102:103], v[28:29], v[134:135]
	v_pk_mul_f32 v[104:105], v[30:31], v[136:137]
	v_pk_mul_f32 v[106:107], v[98:99], v[138:139]
	v_pk_mul_f32 v[108:109], v[100:101], v[140:141]
	v_pk_mul_f32 v[110:111], v[28:29], v[130:131]
	v_pk_mul_f32 v[112:113], v[30:31], v[114:115]
	v_pk_mul_f32 v[114:115], v[98:99], v[132:133]
	v_pk_mul_f32 v[116:117], v[100:101], v[116:117]
	v_pk_mul_f32 v[28:29], v[26:27], v[102:103] op_sel_hi:[0,1]
	v_pk_mul_f32 v[30:31], v[26:27], v[104:105] op_sel_hi:[0,1]
	v_pk_mul_f32 v[98:99], v[26:27], v[106:107] op_sel_hi:[0,1]
	v_pk_mul_f32 v[100:101], v[26:27], v[108:109] op_sel_hi:[0,1]
	v_pk_mul_f32 v[102:103], v[24:25], v[110:111] op_sel_hi:[0,1]
	v_pk_mul_f32 v[104:105], v[24:25], v[112:113] op_sel_hi:[0,1]
	v_pk_mul_f32 v[106:107], v[24:25], v[114:115] op_sel_hi:[0,1]
	v_pk_mul_f32 v[108:109], v[24:25], v[116:117] op_sel_hi:[0,1]
	global_store_dwordx4 v[78:79], v[28:31], off offset:2048 nt
	global_store_dwordx4 v[78:79], v[98:101], off offset:2064 nt
	global_store_dwordx4 v[76:77], v[102:105], off offset:2048 nt
	global_store_dwordx4 v[76:77], v[106:109], off offset:2064 nt
	flat_load_dwordx4 v[28:31], v[44:45]
	s_nop 0
	flat_load_dwordx4 v[98:101], v[46:47]
	s_waitcnt vmcnt(0) lgkmcnt(0)
; __device__ __forceinline__ float bflo(unsigned w) { return __uint_as_float(w << 16); }
; __device__ __forceinline__ float bfhi(unsigned w) { return __uint_as_float(w & 0xffff0000u); }
; __global__ void __launch_bounds__(NWAVES * 64, 2) fwd(Args args) {
;     ...
; #pragma unroll
;             for (int j = 0; j < 8; ++j) { const f32x4 g0 = gfp[128 * j], g1 = gfp[128 * j + 1]; const u32x4 w = wa[j], w2 = wb[j];
;                 const f32x4 v0 = {bflo(w.x) * g0[0] * rsa, bfhi(w.x) * g0[1] * rsa, bflo(w.y) * g0[2] * rsa, bfhi(w.y) * g0[3] * rsa}, v1 = {bflo(w.z) * g1[0] * rsa, bfhi(w.z) * g1[1] * rsa, bflo(w.w) * g1[2] * rsa, bfhi(w.w) * g1[3] * rsa};
;                 const f32x4 u0 = {bflo(w2.x) * g0[0] * rsb, bfhi(w2.x) * g0[1] * rsb, bflo(w2.y) * g0[2] * rsb, bfhi(w2.y) * g0[3] * rsb}, u1 = {bflo(w2.z) * g1[0] * rsb, bfhi(w2.z) * g1[1] * rsb, bflo(w2.w) * g1[2] * rsb, bfhi(w2.w) * g1[3] * rsb};
;                 __builtin_nontemporal_store(v0, oa + 128 * j); __builtin_nontemporal_store(v1, oa + 128 * j + 1); __builtin_nontemporal_store(u0, ob + 128 * j); __builtin_nontemporal_store(u1, ob + 128 * j + 1); } }
	v_pk_mul_f32 v[88:89], v[28:29], v[88:89]
	v_pk_mul_f32 v[102:103], v[30:31], v[142:143]
	v_pk_mul_f32 v[104:105], v[98:99], v[144:145]
	v_pk_mul_f32 v[106:107], v[100:101], v[146:147]
	v_pk_mul_f32 v[108:109], v[28:29], v[148:149]
	v_pk_mul_f32 v[110:111], v[30:31], v[118:119]
	v_pk_mul_f32 v[112:113], v[98:99], v[150:151]
	v_pk_mul_f32 v[114:115], v[100:101], v[120:121]
	v_pk_mul_f32 v[28:29], v[26:27], v[88:89] op_sel_hi:[0,1]
	v_pk_mul_f32 v[30:31], v[26:27], v[102:103] op_sel_hi:[0,1]
	v_pk_mul_f32 v[98:99], v[26:27], v[104:105] op_sel_hi:[0,1]
	v_pk_mul_f32 v[100:101], v[26:27], v[106:107] op_sel_hi:[0,1]
	v_pk_mul_f32 v[102:103], v[24:25], v[108:109] op_sel_hi:[0,1]
	v_pk_mul_f32 v[104:105], v[24:25], v[110:111] op_sel_hi:[0,1]
	v_pk_mul_f32 v[106:107], v[24:25], v[112:113] op_sel_hi:[0,1]
	v_pk_mul_f32 v[108:109], v[24:25], v[114:115] op_sel_hi:[0,1]
	global_store_dwordx4 v[80:81], v[28:31], off offset:-4096 nt
	global_store_dwordx4 v[84:85], v[98:101], off offset:16 nt
	global_store_dwordx4 v[82:83], v[102:105], off offset:-4096 nt
	global_store_dwordx4 v[86:87], v[106:109], off offset:16 nt
	flat_load_dwordx4 v[28:31], v[48:49]
	s_nop 0
	flat_load_dwordx4 v[98:101], v[50:51]
	s_waitcnt vmcnt(0) lgkmcnt(0)
	v_pk_mul_f32 v[88:89], v[28:29], v[152:153]
	v_pk_mul_f32 v[102:103], v[30:31], v[122:123]
	v_pk_mul_f32 v[104:105], v[98:99], v[154:155]
	v_pk_mul_f32 v[106:107], v[100:101], v[124:125]
	v_pk_mul_f32 v[108:109], v[28:29], v[156:157]
	v_pk_mul_f32 v[110:111], v[30:31], v[126:127]
	v_pk_mul_f32 v[112:113], v[98:99], v[158:159]
	v_pk_mul_f32 v[114:115], v[100:101], v[128:129]
	v_pk_mul_f32 v[28:29], v[26:27], v[88:89] op_sel_hi:[0,1]
	v_pk_mul_f32 v[30:31], v[26:27], v[102:103] op_sel_hi:[0,1]
	v_pk_mul_f32 v[98:99], v[26:27], v[104:105] op_sel_hi:[0,1]
	v_pk_mul_f32 v[100:101], v[26:27], v[106:107] op_sel_hi:[0,1]
	v_pk_mul_f32 v[102:103], v[24:25], v[108:109] op_sel_hi:[0,1]
	v_pk_mul_f32 v[104:105], v[24:25], v[110:111] op_sel_hi:[0,1]
	v_pk_mul_f32 v[106:107], v[24:25], v[112:113] op_sel_hi:[0,1]
	v_pk_mul_f32 v[108:109], v[24:25], v[114:115] op_sel_hi:[0,1]
	global_store_dwordx4 v[84:85], v[28:31], off offset:2048 nt
	global_store_dwordx4 v[84:85], v[98:101], off offset:2064 nt
	global_store_dwordx4 v[86:87], v[102:105], off offset:2048 nt
	global_store_dwordx4 v[86:87], v[106:109], off offset:2064 nt
	flat_load_dwordx4 v[28:31], v[52:53]
	s_nop 0
	flat_load_dwordx4 v[84:87], v[54:55]
	v_lshlrev_b32_e32 v88, 16, v32
	v_and_b32_e32 v89, 0xffff0000, v32
	v_lshlrev_b32_e32 v32, 16, v33
	v_and_b32_e32 v33, 0xffff0000, v33
	v_lshlrev_b32_e32 v98, 16, v34
	v_and_b32_e32 v99, 0xffff0000, v34
	v_lshlrev_b32_e32 v34, 16, v35
	v_and_b32_e32 v35, 0xffff0000, v35
	s_waitcnt vmcnt(0) lgkmcnt(0)
	v_pk_mul_f32 v[100:101], v[28:29], v[160:161]
	v_pk_mul_f32 v[36:37], v[30:31], v[36:37]
	v_pk_mul_f32 v[102:103], v[84:85], v[162:163]
	v_pk_mul_f32 v[38:39], v[86:87], v[38:39]
	v_pk_mul_f32 v[88:89], v[28:29], v[88:89]
	v_pk_mul_f32 v[104:105], v[30:31], v[32:33]
	v_pk_mul_f32 v[84:85], v[84:85], v[98:99]
	v_pk_mul_f32 v[86:87], v[86:87], v[34:35]
	v_pk_mul_f32 v[28:29], v[26:27], v[100:101] op_sel_hi:[0,1]
	v_pk_mul_f32 v[30:31], v[26:27], v[36:37] op_sel_hi:[0,1]
	v_pk_mul_f32 v[32:33], v[26:27], v[102:103] op_sel_hi:[0,1]
	v_pk_mul_f32 v[34:35], v[26:27], v[38:39] op_sel_hi:[0,1]
	v_pk_mul_f32 v[36:37], v[24:25], v[88:89] op_sel_hi:[0,1]
	v_pk_mul_f32 v[38:39], v[24:25], v[104:105] op_sel_hi:[0,1]
	v_pk_mul_f32 v[84:85], v[24:25], v[84:85] op_sel_hi:[0,1]
	v_pk_mul_f32 v[86:87], v[24:25], v[86:87] op_sel_hi:[0,1]
	global_store_dwordx4 v[80:81], v[28:31], off nt
	global_store_dwordx4 v[80:81], v[32:35], off offset:16 nt
	global_store_dwordx4 v[82:83], v[36:39], off nt
	global_store_dwordx4 v[82:83], v[84:87], off offset:16 nt
	flat_load_dwordx4 v[28:31], v[56:57]
	s_nop 0
	flat_load_dwordx4 v[32:35], v[58:59]
	v_lshlrev_b32_e32 v36, 16, v20
	v_and_b32_e32 v37, 0xffff0000, v20
	v_lshlrev_b32_e32 v20, 16, v21
	v_and_b32_e32 v21, 0xffff0000, v21
	v_lshlrev_b32_e32 v38, 16, v22
	v_and_b32_e32 v39, 0xffff0000, v22
	v_lshlrev_b32_e32 v22, 16, v23
	v_and_b32_e32 v23, 0xffff0000, v23
	v_lshlrev_b32_e32 v84, 16, v16
	v_and_b32_e32 v85, 0xffff0000, v16
	v_lshlrev_b32_e32 v16, 16, v17
	v_and_b32_e32 v17, 0xffff0000, v17
	v_lshlrev_b32_e32 v86, 16, v18
	v_and_b32_e32 v87, 0xffff0000, v18
	v_lshlrev_b32_e32 v18, 16, v19
	v_and_b32_e32 v19, 0xffff0000, v19
	s_waitcnt vmcnt(0) lgkmcnt(0)
; __device__ __forceinline__ float bflo(unsigned w) { return __uint_as_float(w << 16); }
; __device__ __forceinline__ float bfhi(unsigned w) { return __uint_as_float(w & 0xffff0000u); }
; __global__ void __launch_bounds__(NWAVES * 64, 2) fwd(Args args) {
;     ...
; #pragma unroll
;             for (int j = 0; j < 8; ++j) { const f32x4 g0 = gfp[128 * j], g1 = gfp[128 * j + 1]; const u32x4 w = wa[j], w2 = wb[j];
;                 const f32x4 v0 = {bflo(w.x) * g0[0] * rsa, bfhi(w.x) * g0[1] * rsa, bflo(w.y) * g0[2] * rsa, bfhi(w.y) * g0[3] * rsa}, v1 = {bflo(w.z) * g1[0] * rsa, bfhi(w.z) * g1[1] * rsa, bflo(w.w) * g1[2] * rsa, bfhi(w.w) * g1[3] * rsa};
;                 const f32x4 u0 = {bflo(w2.x) * g0[0] * rsb, bfhi(w2.x) * g0[1] * rsb, bflo(w2.y) * g0[2] * rsb, bfhi(w2.y) * g0[3] * rsb}, u1 = {bflo(w2.z) * g1[0] * rsb, bfhi(w2.z) * g1[1] * rsb, bflo(w2.w) * g1[2] * rsb, bfhi(w2.w) * g1[3] * rsb};
;                 __builtin_nontemporal_store(v0, oa + 128 * j); __builtin_nontemporal_store(v1, oa + 128 * j + 1); __builtin_nontemporal_store(u0, ob + 128 * j); __builtin_nontemporal_store(u1, ob + 128 * j + 1); } }
	v_pk_mul_f32 v[36:37], v[28:29], v[36:37]
	v_pk_mul_f32 v[20:21], v[30:31], v[20:21]
	v_pk_mul_f32 v[38:39], v[32:33], v[38:39]
	v_pk_mul_f32 v[22:23], v[34:35], v[22:23]
	v_pk_mul_f32 v[28:29], v[28:29], v[84:85]
	v_pk_mul_f32 v[30:31], v[30:31], v[16:17]
	v_pk_mul_f32 v[32:33], v[32:33], v[86:87]
	v_pk_mul_f32 v[34:35], v[34:35], v[18:19]
	v_pk_mul_f32 v[16:17], v[26:27], v[36:37] op_sel_hi:[0,1]
	v_pk_mul_f32 v[18:19], v[26:27], v[20:21] op_sel_hi:[0,1]
	v_pk_mul_f32 v[20:21], v[26:27], v[38:39] op_sel_hi:[0,1]
	v_pk_mul_f32 v[22:23], v[26:27], v[22:23] op_sel_hi:[0,1]
	v_pk_mul_f32 v[28:29], v[24:25], v[28:29] op_sel_hi:[0,1]
	v_pk_mul_f32 v[30:31], v[24:25], v[30:31] op_sel_hi:[0,1]
	v_pk_mul_f32 v[32:33], v[24:25], v[32:33] op_sel_hi:[0,1]
	v_pk_mul_f32 v[34:35], v[24:25], v[34:35] op_sel_hi:[0,1]
	global_store_dwordx4 v[80:81], v[16:19], off offset:2048 nt
	global_store_dwordx4 v[80:81], v[20:23], off offset:2064 nt
	global_store_dwordx4 v[82:83], v[28:31], off offset:2048 nt
	global_store_dwordx4 v[82:83], v[32:35], off offset:2064 nt
	flat_load_dwordx4 v[16:19], v[60:61]
	s_nop 0
	flat_load_dwordx4 v[20:23], v[62:63]
	v_add_co_u32_e32 v28, vcc, s21, v78
	v_lshlrev_b32_e32 v32, 16, v12
	v_and_b32_e32 v33, 0xffff0000, v12
	v_lshlrev_b32_e32 v12, 16, v13
	v_and_b32_e32 v13, 0xffff0000, v13
	v_addc_co_u32_e32 v29, vcc, 0, v79, vcc
	v_lshlrev_b32_e32 v34, 16, v14
	v_and_b32_e32 v35, 0xffff0000, v14
	v_lshlrev_b32_e32 v14, 16, v15
	v_and_b32_e32 v15, 0xffff0000, v15
	v_lshlrev_b32_e32 v36, 16, v8
	v_and_b32_e32 v37, 0xffff0000, v8
	v_lshlrev_b32_e32 v8, 16, v9
	v_and_b32_e32 v9, 0xffff0000, v9
	v_lshlrev_b32_e32 v38, 16, v10
	v_and_b32_e32 v39, 0xffff0000, v10
	v_lshlrev_b32_e32 v10, 16, v11
	v_and_b32_e32 v11, 0xffff0000, v11
	v_add_co_u32_e32 v30, vcc, s21, v76
	s_waitcnt vmcnt(0) lgkmcnt(0)
	v_pk_mul_f32 v[32:33], v[16:17], v[32:33]
	v_pk_mul_f32 v[12:13], v[18:19], v[12:13]
	v_pk_mul_f32 v[34:35], v[20:21], v[34:35]
	v_pk_mul_f32 v[14:15], v[22:23], v[14:15]
	v_pk_mul_f32 v[16:17], v[16:17], v[36:37]
	v_pk_mul_f32 v[18:19], v[18:19], v[8:9]
	v_pk_mul_f32 v[20:21], v[20:21], v[38:39]
	v_pk_mul_f32 v[22:23], v[22:23], v[10:11]
	v_pk_mul_f32 v[8:9], v[26:27], v[32:33] op_sel_hi:[0,1]
	v_pk_mul_f32 v[10:11], v[26:27], v[12:13] op_sel_hi:[0,1]
	v_addc_co_u32_e32 v31, vcc, 0, v77, vcc
	v_pk_mul_f32 v[12:13], v[26:27], v[34:35] op_sel_hi:[0,1]
	v_pk_mul_f32 v[14:15], v[26:27], v[14:15] op_sel_hi:[0,1]
	v_pk_mul_f32 v[16:17], v[24:25], v[16:17] op_sel_hi:[0,1]
	v_pk_mul_f32 v[18:19], v[24:25], v[18:19] op_sel_hi:[0,1]
	v_pk_mul_f32 v[20:21], v[24:25], v[20:21] op_sel_hi:[0,1]
	v_pk_mul_f32 v[22:23], v[24:25], v[22:23] op_sel_hi:[0,1]
	global_store_dwordx4 v[28:29], v[8:11], off nt
	global_store_dwordx4 v[28:29], v[12:15], off offset:16 nt
	global_store_dwordx4 v[30:31], v[16:19], off nt
	global_store_dwordx4 v[30:31], v[20:23], off offset:16 nt
	flat_load_dwordx4 v[8:11], v[64:65]
	s_nop 0
	flat_load_dwordx4 v[12:15], v[66:67]
	v_lshlrev_b32_e32 v16, 16, v4
	v_and_b32_e32 v17, 0xffff0000, v4
	v_lshlrev_b32_e32 v4, 16, v5
	v_and_b32_e32 v5, 0xffff0000, v5
	v_lshlrev_b32_e32 v18, 16, v6
	v_and_b32_e32 v19, 0xffff0000, v6
	v_lshlrev_b32_e32 v6, 16, v7
	v_and_b32_e32 v7, 0xffff0000, v7
	v_lshlrev_b32_e32 v20, 16, v0
	v_and_b32_e32 v21, 0xffff0000, v0
	v_lshlrev_b32_e32 v0, 16, v1
	v_and_b32_e32 v1, 0xffff0000, v1
	v_lshlrev_b32_e32 v22, 16, v2
	v_and_b32_e32 v23, 0xffff0000, v2
	v_lshlrev_b32_e32 v2, 16, v3
	v_and_b32_e32 v3, 0xffff0000, v3
	s_waitcnt vmcnt(0) lgkmcnt(0)
	v_pk_mul_f32 v[16:17], v[8:9], v[16:17]
	v_pk_mul_f32 v[4:5], v[10:11], v[4:5]
	v_pk_mul_f32 v[18:19], v[12:13], v[18:19]
	v_pk_mul_f32 v[6:7], v[14:15], v[6:7]
	v_pk_mul_f32 v[8:9], v[8:9], v[20:21]
	v_pk_mul_f32 v[10:11], v[10:11], v[0:1]
	v_pk_mul_f32 v[12:13], v[12:13], v[22:23]
	v_pk_mul_f32 v[14:15], v[14:15], v[2:3]
	v_pk_mul_f32 v[0:1], v[26:27], v[16:17] op_sel_hi:[0,1]
	v_pk_mul_f32 v[2:3], v[26:27], v[4:5] op_sel_hi:[0,1]
	v_pk_mul_f32 v[4:5], v[26:27], v[18:19] op_sel_hi:[0,1]
	v_pk_mul_f32 v[6:7], v[26:27], v[6:7] op_sel_hi:[0,1]
	v_pk_mul_f32 v[8:9], v[24:25], v[8:9] op_sel_hi:[0,1]
	v_pk_mul_f32 v[10:11], v[24:25], v[10:11] op_sel_hi:[0,1]
	v_pk_mul_f32 v[12:13], v[24:25], v[12:13] op_sel_hi:[0,1]
	v_pk_mul_f32 v[14:15], v[24:25], v[14:15] op_sel_hi:[0,1]
	global_store_dwordx4 v[28:29], v[0:3], off offset:2048 nt
	global_store_dwordx4 v[28:29], v[4:7], off offset:2064 nt
	global_store_dwordx4 v[30:31], v[8:11], off offset:2048 nt
	global_store_dwordx4 v[30:31], v[12:15], off offset:2064 nt
	s_cbranch_scc1 .LBB0_1714
